# GEMM phases: per-segment s_setprio flips dropped, one static s_setprio 1 for waves 4-7 per GEMM phase (cleared at the next grid barrier)
# speedup vs baseline: 1.0133x; 1.0133x over previous
.LBB0_45:
	s_waitcnt vmcnt(0)
	s_waitcnt lgkmcnt(0)
	s_setprio 0
	s_barrier
	s_mov_b64 s[6:7], exec
	v_readlane_b32 s0, v255, 4
	v_readlane_b32 s1, v255, 5
	s_and_b64 s[0:1], s[6:7], s[0:1]
	v_writelane_b32 v255, s29, 9
	s_mov_b64 exec, s[0:1]
	s_cbranch_execz .LBB0_97
	s_add_i32 s0, 0, 0x25800
	v_mov_b32_e32 v0, s0
	s_waitcnt vmcnt(0) expcnt(0) lgkmcnt(0)
	ds_read_b32 v2, v0
	s_add_i32 s0, 0, 0x25804
	v_mov_b32_e32 v0, s0
	ds_read_b32 v0, v0
	s_waitcnt lgkmcnt(1)
	v_cmp_ne_u32_e32 vcc, 0, v2
	s_cbranch_vccnz .LBB0_61
	s_add_u32 s8, s26, 0xc0200
	s_addc_u32 s9, s27, 0
	s_add_u32 s4, s26, 0xc0400
	s_addc_u32 s5, s27, 0
	s_add_u32 s10, s26, 0xc0500
	s_addc_u32 s11, s27, 0
	s_add_u32 s12, s26, 0xc0600
	s_addc_u32 s13, s27, 0
	s_add_u32 s14, s26, 0xc0700
	s_addc_u32 s15, s27, 0
	s_add_u32 s16, s26, 0xc0800
	s_addc_u32 s17, s27, 0
	s_add_u32 s18, s26, 0xc0900
	s_addc_u32 s19, s27, 0
	s_add_u32 s20, s26, 0xc0a00
	s_addc_u32 s21, s27, 0
	s_add_u32 s36, s26, 0xc0b00
	s_addc_u32 s37, s27, 0
	s_add_u32 s38, s26, 0xc0c00
	s_addc_u32 s39, s27, 0
	s_add_u32 s40, s26, 0xc0d00
	s_addc_u32 s41, s27, 0
	s_add_u32 s42, s26, 0xc0e00
	s_addc_u32 s43, s27, 0
	s_add_u32 s44, s26, 0xc0f00
	s_addc_u32 s45, s27, 0
	s_add_u32 s46, s26, 0xc1000
	s_load_dword s0, s[88:89], 0x180
	s_addc_u32 s47, s27, 0
	s_add_u32 s48, s26, 0xc1100
	s_addc_u32 s49, s27, 0
	s_add_u32 s50, s26, 0xc1200
	s_addc_u32 s51, s27, 0
	s_waitcnt lgkmcnt(0)
	s_mul_i32 s23, s31, s0
	s_add_u32 s52, s26, 0xc1300
	s_mul_i32 s23, s23, s30
	s_addc_u32 s53, s27, 0
	s_mov_b32 s24, 1
	v_mov_b32_e32 v16, 0
	s_branch .LBB0_49

.LBB0_243:
	s_waitcnt vmcnt(0)
	s_setprio 0
	s_barrier
	s_mov_b64 s[0:1], exec
	v_readlane_b32 s4, v255, 4
	v_readlane_b32 s5, v255, 5
	s_and_b64 s[4:5], s[0:1], s[4:5]
	s_xor_b64 s[6:7], s[4:5], s[0:1]
	s_mov_b64 exec, s[4:5]
	s_cbranch_execz .LBB0_296
	s_add_i32 s0, 0, 0x25800
	v_mov_b32_e32 v0, s0
	s_waitcnt vmcnt(0) expcnt(0) lgkmcnt(0)
	ds_read_b32 v2, v0
	s_add_i32 s0, 0, 0x25804
	v_mov_b32_e32 v0, s0
	ds_read_b32 v0, v0
	s_waitcnt lgkmcnt(1)
	v_cmp_ne_u32_e32 vcc, 0, v2
	s_cbranch_vccnz .LBB0_259
	s_add_u32 s8, s26, 0xc0200
	s_addc_u32 s9, s27, 0
	s_add_u32 s4, s26, 0xc0400
	s_addc_u32 s5, s27, 0
	s_add_u32 s10, s26, 0xc0500
	s_addc_u32 s11, s27, 0
	s_add_u32 s12, s26, 0xc0600
	s_addc_u32 s13, s27, 0
	s_add_u32 s14, s26, 0xc0700
	s_addc_u32 s15, s27, 0
	s_add_u32 s16, s26, 0xc0800
	s_addc_u32 s17, s27, 0
	s_add_u32 s36, s26, 0xc0900
	s_addc_u32 s37, s27, 0
	s_add_u32 s40, s26, 0xc0a00
	s_addc_u32 s41, s27, 0
	s_add_u32 s42, s26, 0xc0b00
	s_addc_u32 s43, s27, 0
	s_add_u32 s44, s26, 0xc0c00
	s_addc_u32 s45, s27, 0
	s_add_u32 s46, s26, 0xc0d00
	s_addc_u32 s47, s27, 0
	s_add_u32 s48, s26, 0xc0e00
	s_addc_u32 s49, s27, 0
	s_add_u32 s50, s26, 0xc0f00
	s_addc_u32 s51, s27, 0
	s_add_u32 s52, s26, 0xc1000
	s_load_dword s0, s[88:89], 0x180
	s_addc_u32 s53, s27, 0
	s_add_u32 s54, s26, 0xc1100
	s_addc_u32 s55, s27, 0
	s_add_u32 s56, s26, 0xc1200
	s_addc_u32 s57, s27, 0
	s_waitcnt lgkmcnt(0)
	s_mul_i32 s23, s31, s0
	s_add_u32 s58, s26, 0xc1300
	s_mul_i32 s23, s23, s30
	s_addc_u32 s59, s27, 0
	s_mov_b32 s24, 1
	v_mov_b32_e32 v16, 0
	s_branch .LBB0_247

.LBB0_296:
	s_or_b64 exec, exec, s[6:7]
	s_cmpk_lt_i32 s2, 0x37b
	s_cselect_b64 s[0:1], -1, 0
	v_mov_b32_e32 v128, v254
	v_mov_b32_e32 v8, v254
	s_waitcnt lgkmcnt(0)
	s_barrier
	v_cmp_lt_u32_e32 vcc, 0xff, v254
	s_cbranch_vccz .Lprio_skip1
	s_setprio 1
.Lprio_skip1:
	s_and_b64 vcc, exec, s[0:1]
	v_readfirstlane_b32 s23, v8
	s_cbranch_vccz .LBB0_298
	s_lshr_b32 s4, s3, 29
	s_add_i32 s4, s2, s4
	s_and_b32 s5, s4, -8
	s_sub_i32 s5, s2, s5
	s_mul_i32 s7, s5, 0x6f
	s_add_i32 s7, s7, 3
	s_ashr_i32 s4, s4, 3
	s_mul_i32 s6, s5, 0x70
	s_cmp_lt_i32 s5, 3
	s_cselect_b32 s5, s6, s7
	s_add_i32 s5, s5, s4
	s_mul_hi_i32 s4, s5, 0x4bda12f7
	s_lshr_b32 s6, s4, 31
	s_ashr_i32 s4, s4, 6
	s_add_i32 s4, s4, s6
	s_lshl_b32 s6, s4, 3
	s_sub_i32 s7, 33, s6
	s_mulk_i32 s4, 0xd8
	s_min_u32 s7, s7, 8
	s_sub_i32 s8, s5, s4
	s_sext_i32_i16 s4, s8
	v_cvt_f32_ubyte0_e32 v1, s7
	v_cvt_f32_i32_e32 v0, s4
	v_rcp_iflag_f32_e32 v2, v1
	s_ashr_i32 s4, s4, 30
	s_or_b32 s9, s4, 1
	v_mul_f32_e32 v2, v0, v2
	v_trunc_f32_e32 v2, v2
	v_fma_f32 v0, -v2, v1, v0
	v_cvt_i32_f32_e32 v2, v2
	v_cmp_ge_f32_e64 s[4:5], |v0|, v1
	s_and_b64 s[4:5], s[4:5], exec
	s_cselect_b32 s4, s9, 0
	v_readfirstlane_b32 s5, v2
	s_add_i32 s4, s5, s4
	s_sext_i32_i16 s10, s4
	s_mul_i32 s4, s4, s7
	s_sub_i32 s4, s8, s4
	s_sext_i32_i16 s4, s4
	s_add_i32 s72, s6, s4

.LBB0_316:
	ds_read_b128 v[150:153], v167
	ds_read_b128 v[154:157], v167 offset:1024
	ds_read_b128 v[158:161], v167 offset:2048
	ds_read_b128 v[172:175], v167 offset:3072
	s_add_u32 s4, s8, 0xfff80080
	s_addc_u32 s5, s9, -1
	s_cmp_eq_u32 s25, 28
	s_cselect_b32 s5, s69, s5
	s_cselect_b32 s4, s68, s4
	s_cselect_b32 s75, s0, s24
	s_cselect_b32 s74, s1, s12
	v_lshl_add_u64 v[162:163], s[8:9], 0, v[142:143]
	s_add_i32 m0, s11, 0xc000
	ds_read_b128 v[176:179], v168
	ds_read_b128 v[180:183], v168 offset:1024
	ds_read_b128 v[184:187], v168 offset:2048
	ds_read_b128 v[188:191], v168 offset:3072
	ds_read_b128 v[192:195], v168 offset:4096
	ds_read_b128 v[196:199], v168 offset:5120
	ds_read_b128 v[200:203], v168 offset:6144
	ds_read_b128 v[204:207], v168 offset:7168
	global_load_lds_dwordx4 v[162:163], off
	v_lshl_add_u64 v[162:163], s[8:9], 0, v[144:145]
	s_add_i32 m0, s11, 0xe000
	s_nop 0
	global_load_lds_dwordx4 v[162:163], off
	s_waitcnt lgkmcnt(8)
	s_barrier
	s_waitcnt lgkmcnt(0)
	s_waitcnt lgkmcnt(0)
	v_mfma_f32_16x16x32_bf16 v[124:127], v[150:153], v[176:179], v[124:127]
	v_mfma_f32_16x16x32_bf16 v[120:123], v[158:161], v[176:179], v[120:123]
	v_mfma_f32_16x16x32_bf16 v[116:119], v[150:153], v[184:187], v[116:119]
	v_mfma_f32_16x16x32_bf16 v[112:115], v[158:161], v[184:187], v[112:115]
	v_mfma_f32_16x16x32_bf16 v[100:103], v[150:153], v[192:195], v[100:103]
	v_mfma_f32_16x16x32_bf16 v[96:99], v[158:161], v[192:195], v[96:99]
	v_mfma_f32_16x16x32_bf16 v[84:87], v[150:153], v[200:203], v[84:87]
	v_mfma_f32_16x16x32_bf16 v[80:83], v[158:161], v[200:203], v[80:83]
	v_mfma_f32_16x16x32_bf16 v[124:127], v[154:157], v[180:183], v[124:127]
	v_mfma_f32_16x16x32_bf16 v[120:123], v[172:175], v[180:183], v[120:123]
	v_mfma_f32_16x16x32_bf16 v[116:119], v[154:157], v[188:191], v[116:119]
	v_mfma_f32_16x16x32_bf16 v[112:115], v[172:175], v[188:191], v[112:115]
	v_mfma_f32_16x16x32_bf16 v[100:103], v[154:157], v[196:199], v[100:103]
	v_mfma_f32_16x16x32_bf16 v[96:99], v[172:175], v[196:199], v[96:99]
	v_mfma_f32_16x16x32_bf16 v[84:87], v[154:157], v[204:207], v[84:87]
	v_mfma_f32_16x16x32_bf16 v[80:83], v[172:175], v[204:207], v[80:83]
	s_barrier
	s_add_i32 s33, s80, s28
	v_lshl_add_u64 v[162:163], s[74:75], 0, v[132:133]
	s_mov_b32 m0, s33
	ds_read_b128 v[208:211], v169
	ds_read_b128 v[212:215], v169 offset:1024
	ds_read_b128 v[218:221], v169 offset:2048
	ds_read_b128 v[222:225], v169 offset:3072
	global_load_lds_dwordx4 v[162:163], off
	v_lshl_add_u64 v[216:217], s[74:75], 0, v[136:137]
	s_add_i32 m0, s33, 0x2000
	s_nop 0
	global_load_lds_dwordx4 v[216:217], off
	s_barrier
	s_waitcnt lgkmcnt(0)
	s_waitcnt lgkmcnt(0)
	v_mfma_f32_16x16x32_bf16 v[108:111], v[208:211], v[176:179], v[108:111]
	v_mfma_f32_16x16x32_bf16 v[104:107], v[218:221], v[176:179], v[104:107]
	v_mfma_f32_16x16x32_bf16 v[92:95], v[208:211], v[184:187], v[92:95]
	v_mfma_f32_16x16x32_bf16 v[88:91], v[218:221], v[184:187], v[88:91]
	v_mfma_f32_16x16x32_bf16 v[76:79], v[208:211], v[192:195], v[76:79]
	v_mfma_f32_16x16x32_bf16 v[72:75], v[218:221], v[192:195], v[72:75]
	v_mfma_f32_16x16x32_bf16 v[68:71], v[208:211], v[200:203], v[68:71]
	v_mfma_f32_16x16x32_bf16 v[64:67], v[218:221], v[200:203], v[64:67]
	v_mfma_f32_16x16x32_bf16 v[108:111], v[212:215], v[180:183], v[108:111]
	v_mfma_f32_16x16x32_bf16 v[104:107], v[222:225], v[180:183], v[104:107]
	v_mfma_f32_16x16x32_bf16 v[92:95], v[212:215], v[188:191], v[92:95]
	v_mfma_f32_16x16x32_bf16 v[88:91], v[222:225], v[188:191], v[88:91]
	v_mfma_f32_16x16x32_bf16 v[76:79], v[212:215], v[196:199], v[76:79]
	v_mfma_f32_16x16x32_bf16 v[72:75], v[222:225], v[196:199], v[72:75]
	v_mfma_f32_16x16x32_bf16 v[68:71], v[212:215], v[204:207], v[68:71]
	v_mfma_f32_16x16x32_bf16 v[64:67], v[222:225], v[204:207], v[64:67]
	s_mov_b32 m0, s11
	v_lshl_add_u64 v[226:227], s[4:5], 0, v[130:131]
	s_barrier
	ds_read_b128 v[176:179], v168 offset:16384
	ds_read_b128 v[180:183], v168 offset:17408
	ds_read_b128 v[184:187], v168 offset:18432
	ds_read_b128 v[188:191], v168 offset:19456
	ds_read_b128 v[192:195], v168 offset:20480
	ds_read_b128 v[196:199], v168 offset:21504
	ds_read_b128 v[200:203], v168 offset:22528
	ds_read_b128 v[204:207], v168 offset:23552
	global_load_lds_dwordx4 v[226:227], off
	v_lshl_add_u64 v[228:229], s[4:5], 0, v[134:135]
	s_mov_b32 m0, s29
	s_nop 0
	global_load_lds_dwordx4 v[228:229], off
	s_barrier
	s_waitcnt lgkmcnt(0)
	s_waitcnt lgkmcnt(0)
	v_mfma_f32_16x16x32_bf16 v[60:63], v[150:153], v[176:179], v[60:63]
	v_mfma_f32_16x16x32_bf16 v[56:59], v[158:161], v[176:179], v[56:59]
	v_mfma_f32_16x16x32_bf16 v[52:55], v[150:153], v[184:187], v[52:55]
	v_mfma_f32_16x16x32_bf16 v[48:51], v[158:161], v[184:187], v[48:51]
	v_mfma_f32_16x16x32_bf16 v[40:43], v[150:153], v[192:195], v[40:43]
	v_mfma_f32_16x16x32_bf16 v[32:35], v[158:161], v[192:195], v[32:35]
	v_mfma_f32_16x16x32_bf16 v[24:27], v[150:153], v[200:203], v[24:27]
	v_mfma_f32_16x16x32_bf16 v[16:19], v[158:161], v[200:203], v[16:19]
	v_mfma_f32_16x16x32_bf16 v[60:63], v[154:157], v[180:183], v[60:63]
	v_mfma_f32_16x16x32_bf16 v[56:59], v[172:175], v[180:183], v[56:59]
	v_mfma_f32_16x16x32_bf16 v[52:55], v[154:157], v[188:191], v[52:55]
	v_mfma_f32_16x16x32_bf16 v[48:51], v[172:175], v[188:191], v[48:51]
	v_mfma_f32_16x16x32_bf16 v[40:43], v[154:157], v[196:199], v[40:43]
	v_mfma_f32_16x16x32_bf16 v[32:35], v[172:175], v[196:199], v[32:35]
	v_mfma_f32_16x16x32_bf16 v[24:27], v[154:157], v[204:207], v[24:27]
	v_mfma_f32_16x16x32_bf16 v[16:19], v[172:175], v[204:207], v[16:19]
	s_barrier
	s_add_u32 s76, s74, 0x80000
	s_addc_u32 s77, s75, 0
	s_add_i32 s33, s81, s28
	v_lshl_add_u64 v[150:151], s[76:77], 0, v[132:133]
	s_mov_b32 m0, s33
	s_nop 0
	global_load_lds_dwordx4 v[150:151], off
	v_lshl_add_u64 v[150:151], s[76:77], 0, v[136:137]
	s_add_i32 m0, s33, 0x2000
	s_nop 0
	global_load_lds_dwordx4 v[150:151], off
	s_waitcnt vmcnt(6)
	s_barrier
	v_mfma_f32_16x16x32_bf16 v[44:47], v[208:211], v[176:179], v[44:47]
	v_mfma_f32_16x16x32_bf16 v[36:39], v[218:221], v[176:179], v[36:39]
	v_mfma_f32_16x16x32_bf16 v[28:31], v[208:211], v[184:187], v[28:31]
	v_mfma_f32_16x16x32_bf16 v[20:23], v[218:221], v[184:187], v[20:23]
	v_mfma_f32_16x16x32_bf16 v[12:15], v[208:211], v[192:195], v[12:15]
	v_mfma_f32_16x16x32_bf16 v[8:11], v[218:221], v[192:195], v[8:11]
	v_mfma_f32_16x16x32_bf16 v[4:7], v[208:211], v[200:203], v[4:7]
	v_mfma_f32_16x16x32_bf16 v[0:3], v[218:221], v[200:203], v[0:3]
	v_mfma_f32_16x16x32_bf16 v[44:47], v[212:215], v[180:183], v[44:47]
	v_mfma_f32_16x16x32_bf16 v[36:39], v[222:225], v[180:183], v[36:39]
	v_mfma_f32_16x16x32_bf16 v[28:31], v[212:215], v[188:191], v[28:31]
	v_mfma_f32_16x16x32_bf16 v[20:23], v[222:225], v[188:191], v[20:23]
	v_mfma_f32_16x16x32_bf16 v[12:15], v[212:215], v[196:199], v[12:15]
	v_mfma_f32_16x16x32_bf16 v[8:11], v[222:225], v[196:199], v[8:11]
	v_mfma_f32_16x16x32_bf16 v[4:7], v[212:215], v[204:207], v[4:7]
	v_mfma_f32_16x16x32_bf16 v[0:3], v[222:225], v[204:207], v[0:3]
	s_add_i32 s33, 0, 0x18000
	v_add_u32_e32 v138, s33, v164
	s_barrier
	ds_read_b128 v[150:153], v138
	ds_read_b128 v[154:157], v138 offset:1024
	ds_read_b128 v[158:161], v138 offset:2048
	ds_read_b128 v[172:175], v138 offset:3072
	s_add_u32 s4, s4, 0x80000
	s_addc_u32 s5, s5, 0
	s_mov_b32 m0, s36
	v_lshl_add_u64 v[208:209], s[4:5], 0, v[130:131]
	ds_read_b128 v[176:179], v168 offset:32768
	ds_read_b128 v[180:183], v168 offset:33792
	ds_read_b128 v[184:187], v168 offset:34816
	ds_read_b128 v[188:191], v168 offset:35840
	ds_read_b128 v[192:195], v168 offset:36864
	ds_read_b128 v[196:199], v168 offset:37888
	ds_read_b128 v[200:203], v168 offset:38912
	ds_read_b128 v[204:207], v168 offset:39936
	global_load_lds_dwordx4 v[208:209], off
	v_lshl_add_u64 v[208:209], s[4:5], 0, v[134:135]
	s_mov_b32 m0, s37
	s_nop 0
	global_load_lds_dwordx4 v[208:209], off
	s_waitcnt lgkmcnt(8)
	s_barrier
	s_waitcnt lgkmcnt(0)
	s_waitcnt lgkmcnt(0)
	v_mfma_f32_16x16x32_bf16 v[124:127], v[150:153], v[176:179], v[124:127]
	v_mfma_f32_16x16x32_bf16 v[120:123], v[158:161], v[176:179], v[120:123]
	v_mfma_f32_16x16x32_bf16 v[116:119], v[150:153], v[184:187], v[116:119]
	v_mfma_f32_16x16x32_bf16 v[112:115], v[158:161], v[184:187], v[112:115]
	v_mfma_f32_16x16x32_bf16 v[100:103], v[150:153], v[192:195], v[100:103]
	v_mfma_f32_16x16x32_bf16 v[96:99], v[158:161], v[192:195], v[96:99]
	v_mfma_f32_16x16x32_bf16 v[84:87], v[150:153], v[200:203], v[84:87]
	v_mfma_f32_16x16x32_bf16 v[80:83], v[158:161], v[200:203], v[80:83]
	v_mfma_f32_16x16x32_bf16 v[124:127], v[154:157], v[180:183], v[124:127]
	v_mfma_f32_16x16x32_bf16 v[120:123], v[172:175], v[180:183], v[120:123]
	v_mfma_f32_16x16x32_bf16 v[116:119], v[154:157], v[188:191], v[116:119]
	v_mfma_f32_16x16x32_bf16 v[112:115], v[172:175], v[188:191], v[112:115]
	v_mfma_f32_16x16x32_bf16 v[100:103], v[154:157], v[196:199], v[100:103]
	v_mfma_f32_16x16x32_bf16 v[96:99], v[172:175], v[196:199], v[96:99]
	v_mfma_f32_16x16x32_bf16 v[84:87], v[154:157], v[204:207], v[84:87]
	v_mfma_f32_16x16x32_bf16 v[80:83], v[172:175], v[204:207], v[80:83]
	s_barrier
	s_add_i32 s65, 0, 0x1c000
	s_add_i32 s4, s33, s28
	v_add_u32_e32 v138, s65, v164
	v_lshl_add_u64 v[162:163], v[162:163], 0, s[14:15]
	s_mov_b32 m0, s4
	ds_read_b128 v[208:211], v138
	ds_read_b128 v[212:215], v138 offset:1024
	ds_read_b128 v[218:221], v138 offset:2048
	ds_read_b128 v[222:225], v138 offset:3072
	global_load_lds_dwordx4 v[162:163], off
	v_lshl_add_u64 v[162:163], v[216:217], 0, s[14:15]
	s_add_i32 m0, s4, 0x2000
	s_nop 0
	global_load_lds_dwordx4 v[162:163], off
	s_barrier
	s_waitcnt lgkmcnt(0)
	s_waitcnt lgkmcnt(0)
	v_mfma_f32_16x16x32_bf16 v[108:111], v[208:211], v[176:179], v[108:111]
	v_mfma_f32_16x16x32_bf16 v[104:107], v[218:221], v[176:179], v[104:107]
	v_mfma_f32_16x16x32_bf16 v[92:95], v[208:211], v[184:187], v[92:95]
	v_mfma_f32_16x16x32_bf16 v[88:91], v[218:221], v[184:187], v[88:91]
	v_mfma_f32_16x16x32_bf16 v[76:79], v[208:211], v[192:195], v[76:79]
	v_mfma_f32_16x16x32_bf16 v[72:75], v[218:221], v[192:195], v[72:75]
	v_mfma_f32_16x16x32_bf16 v[68:71], v[208:211], v[200:203], v[68:71]
	v_mfma_f32_16x16x32_bf16 v[64:67], v[218:221], v[200:203], v[64:67]
	v_mfma_f32_16x16x32_bf16 v[108:111], v[212:215], v[180:183], v[108:111]
	v_mfma_f32_16x16x32_bf16 v[104:107], v[222:225], v[180:183], v[104:107]
	v_mfma_f32_16x16x32_bf16 v[92:95], v[212:215], v[188:191], v[92:95]
	v_mfma_f32_16x16x32_bf16 v[88:91], v[222:225], v[188:191], v[88:91]
	v_mfma_f32_16x16x32_bf16 v[76:79], v[212:215], v[196:199], v[76:79]
	v_mfma_f32_16x16x32_bf16 v[72:75], v[222:225], v[196:199], v[72:75]
	v_mfma_f32_16x16x32_bf16 v[68:71], v[212:215], v[204:207], v[68:71]
	v_mfma_f32_16x16x32_bf16 v[64:67], v[222:225], v[204:207], v[64:67]
	s_mov_b32 m0, s73
	v_lshl_add_u64 v[162:163], v[226:227], 0, s[14:15]
	s_barrier
	ds_read_b128 v[176:179], v168 offset:49152
	ds_read_b128 v[180:183], v168 offset:50176
	ds_read_b128 v[184:187], v168 offset:51200
	ds_read_b128 v[188:191], v168 offset:52224
	ds_read_b128 v[192:195], v168 offset:53248
	ds_read_b128 v[196:199], v168 offset:54272
	ds_read_b128 v[200:203], v168 offset:55296
	ds_read_b128 v[204:207], v168 offset:56320
	global_load_lds_dwordx4 v[162:163], off
	v_lshl_add_u64 v[162:163], v[228:229], 0, s[14:15]
	s_mov_b32 m0, s78
	s_nop 0
	global_load_lds_dwordx4 v[162:163], off
	s_barrier
	s_waitcnt lgkmcnt(0)
	s_waitcnt lgkmcnt(0)
	v_mfma_f32_16x16x32_bf16 v[60:63], v[150:153], v[176:179], v[60:63]
	v_mfma_f32_16x16x32_bf16 v[56:59], v[158:161], v[176:179], v[56:59]
	v_mfma_f32_16x16x32_bf16 v[52:55], v[150:153], v[184:187], v[52:55]
	v_mfma_f32_16x16x32_bf16 v[48:51], v[158:161], v[184:187], v[48:51]
	v_mfma_f32_16x16x32_bf16 v[40:43], v[150:153], v[192:195], v[40:43]
	v_mfma_f32_16x16x32_bf16 v[32:35], v[158:161], v[192:195], v[32:35]
	v_mfma_f32_16x16x32_bf16 v[24:27], v[150:153], v[200:203], v[24:27]
	v_mfma_f32_16x16x32_bf16 v[16:19], v[158:161], v[200:203], v[16:19]
	v_mfma_f32_16x16x32_bf16 v[60:63], v[154:157], v[180:183], v[60:63]
	v_mfma_f32_16x16x32_bf16 v[56:59], v[172:175], v[180:183], v[56:59]
	v_mfma_f32_16x16x32_bf16 v[52:55], v[154:157], v[188:191], v[52:55]
	v_mfma_f32_16x16x32_bf16 v[48:51], v[172:175], v[188:191], v[48:51]
	v_mfma_f32_16x16x32_bf16 v[40:43], v[154:157], v[196:199], v[40:43]
	v_mfma_f32_16x16x32_bf16 v[32:35], v[172:175], v[196:199], v[32:35]
	v_mfma_f32_16x16x32_bf16 v[24:27], v[154:157], v[204:207], v[24:27]
	v_mfma_f32_16x16x32_bf16 v[16:19], v[172:175], v[204:207], v[16:19]
	s_barrier
	s_add_u32 s4, s74, 0x80080
	s_addc_u32 s5, s75, 0
	s_add_i32 s33, s65, s28
	v_lshl_add_u64 v[150:151], s[4:5], 0, v[132:133]
	s_mov_b32 m0, s33
	s_nop 0
	global_load_lds_dwordx4 v[150:151], off
	v_lshl_add_u64 v[150:151], s[4:5], 0, v[136:137]
	s_add_i32 m0, s33, 0x2000
	s_nop 0
	global_load_lds_dwordx4 v[150:151], off
	s_waitcnt vmcnt(6)
	s_barrier
	v_mfma_f32_16x16x32_bf16 v[44:47], v[208:211], v[176:179], v[44:47]
	v_mfma_f32_16x16x32_bf16 v[36:39], v[218:221], v[176:179], v[36:39]
	v_mfma_f32_16x16x32_bf16 v[28:31], v[208:211], v[184:187], v[28:31]
	v_mfma_f32_16x16x32_bf16 v[20:23], v[218:221], v[184:187], v[20:23]
	v_mfma_f32_16x16x32_bf16 v[12:15], v[208:211], v[192:195], v[12:15]
	v_mfma_f32_16x16x32_bf16 v[8:11], v[218:221], v[192:195], v[8:11]
	v_mfma_f32_16x16x32_bf16 v[4:7], v[208:211], v[200:203], v[4:7]
	v_mfma_f32_16x16x32_bf16 v[0:3], v[218:221], v[200:203], v[0:3]
	v_mfma_f32_16x16x32_bf16 v[44:47], v[212:215], v[180:183], v[44:47]
	v_mfma_f32_16x16x32_bf16 v[36:39], v[222:225], v[180:183], v[36:39]
	v_mfma_f32_16x16x32_bf16 v[28:31], v[212:215], v[188:191], v[28:31]
	v_mfma_f32_16x16x32_bf16 v[20:23], v[222:225], v[188:191], v[20:23]
	v_mfma_f32_16x16x32_bf16 v[12:15], v[212:215], v[196:199], v[12:15]
	v_mfma_f32_16x16x32_bf16 v[8:11], v[222:225], v[196:199], v[8:11]
	v_mfma_f32_16x16x32_bf16 v[4:7], v[212:215], v[204:207], v[4:7]
	v_mfma_f32_16x16x32_bf16 v[0:3], v[222:225], v[204:207], v[0:3]
	s_add_i32 s25, s25, 2
	s_add_u32 s8, s8, 0x100
	s_addc_u32 s9, s9, 0
	s_add_u32 s12, s12, 0x100
	s_addc_u32 s24, s24, 0
	s_cmp_gt_u32 s25, 29
	s_barrier
	s_cbranch_scc0 .LBB0_316
	s_and_b32 s0, s10, -8
	v_lshl_add_u32 v150, s72, 8, v129
	s_cmp_lg_u32 s0, 8
	s_mov_b64 s[0:1], -1
	s_cbranch_scc0 .LBB0_435
	s_cmp_gt_i32 s10, 23
	s_cbranch_scc0 .LBB0_432
	s_cmp_lt_i32 s10, 26
	s_cbranch_scc1 .LBB0_323
	s_cmp_eq_u32 s10, 26
	v_mov_b32_e32 v161, v123
	v_mov_b32_e32 v160, v122
	v_mov_b32_e32 v157, v121
	v_mov_b32_e32 v156, v120
	v_mov_b32_e32 v163, v127
	v_mov_b32_e32 v162, v126
	v_mov_b32_e32 v159, v125
	v_mov_b32_e32 v158, v124
	s_cbranch_scc0 .LBB0_322
	v_mul_f32_e32 v138, 0xbfb8aa3b, v124
	v_exp_f32_e32 v138, v138
	v_mul_f32_e32 v151, 0xbfb8aa3b, v120
	v_exp_f32_e32 v151, v151
	v_mul_f32_e32 v152, 0xbfb8aa3b, v121
	v_add_f32_e32 v138, 1.0, v138
	v_rcp_f32_e32 v158, v138
	v_mul_f32_e32 v138, 0xbfb8aa3b, v125
	v_exp_f32_e32 v138, v138
	v_exp_f32_e32 v152, v152
	v_add_f32_e32 v151, 1.0, v151
	v_rcp_f32_e32 v156, v151
	v_add_f32_e32 v138, 1.0, v138
	v_mul_f32_e32 v151, 0xbfb8aa3b, v126
	v_rcp_f32_e32 v159, v138
	v_add_f32_e32 v138, 1.0, v152
	v_exp_f32_e32 v151, v151
	v_mul_f32_e32 v152, 0xbfb8aa3b, v122
	v_exp_f32_e32 v152, v152
	v_rcp_f32_e32 v157, v138
	v_add_f32_e32 v138, 1.0, v151
	v_mul_f32_e32 v151, 0xbfb8aa3b, v127
	v_rcp_f32_e32 v162, v138
	v_add_f32_e32 v138, 1.0, v152
	v_exp_f32_e32 v151, v151
	v_mul_f32_e32 v152, 0xbfb8aa3b, v123
	v_exp_f32_e32 v152, v152
	v_rcp_f32_e32 v160, v138
	v_add_f32_e32 v138, 1.0, v151
	v_rcp_f32_e32 v163, v138
	v_add_f32_e32 v138, 1.0, v152
	v_rcp_f32_e32 v161, v138

.LBB0_474:
	s_waitcnt vmcnt(0)
	s_waitcnt vmcnt(0) lgkmcnt(0)
	s_setprio 0
	s_barrier
	s_mov_b64 s[0:1], exec
	v_readlane_b32 s4, v255, 4
	v_readlane_b32 s5, v255, 5
	s_and_b64 s[4:5], s[0:1], s[4:5]
	s_xor_b64 s[6:7], s[4:5], s[0:1]
	s_mov_b64 exec, s[4:5]
	s_cbranch_execz .LBB0_527
	s_add_i32 s0, 0, 0x25800
	v_mov_b32_e32 v0, s0
	s_waitcnt vmcnt(0) expcnt(0) lgkmcnt(0)
	ds_read_b32 v2, v0
	s_add_i32 s0, 0, 0x25804
	v_mov_b32_e32 v0, s0
	ds_read_b32 v0, v0
	s_waitcnt lgkmcnt(1)
	v_cmp_ne_u32_e32 vcc, 0, v2
	s_cbranch_vccnz .LBB0_490
	s_add_u32 s8, s26, 0xc0200
	s_addc_u32 s9, s27, 0
	s_add_u32 s4, s26, 0xc0400
	s_addc_u32 s5, s27, 0
	s_add_u32 s10, s26, 0xc0500
	s_addc_u32 s11, s27, 0
	s_add_u32 s12, s26, 0xc0600
	s_addc_u32 s13, s27, 0
	s_add_u32 s14, s26, 0xc0700
	s_addc_u32 s15, s27, 0
	s_add_u32 s36, s26, 0xc0800
	s_addc_u32 s37, s27, 0
	s_add_u32 s40, s26, 0xc0900
	s_addc_u32 s41, s27, 0
	s_add_u32 s42, s26, 0xc0a00
	s_addc_u32 s43, s27, 0
	s_add_u32 s44, s26, 0xc0b00
	s_addc_u32 s45, s27, 0
	s_add_u32 s50, s26, 0xc0c00
	s_addc_u32 s51, s27, 0
	s_add_u32 s52, s26, 0xc0d00
	s_addc_u32 s53, s27, 0
	s_add_u32 s54, s26, 0xc0e00
	s_addc_u32 s55, s27, 0
	s_add_u32 s56, s26, 0xc0f00
	s_addc_u32 s57, s27, 0
	s_add_u32 s58, s26, 0xc1000
	s_addc_u32 s59, s27, 0
	s_add_u32 s60, s26, 0xc1100
	s_addc_u32 s61, s27, 0
	s_add_u32 s62, s26, 0xc1200
	v_readlane_b32 s0, v255, 0
	s_addc_u32 s63, s27, 0
	s_mul_i32 s20, s31, s0
	s_add_u32 s64, s26, 0xc1300
	s_mul_i32 s20, s20, s30
	s_addc_u32 s65, s27, 0
	s_mov_b32 s21, 1
	v_mov_b32_e32 v16, 0
	s_branch .LBB0_478

.LBB0_527:
	s_or_b64 exec, exec, s[6:7]
	s_waitcnt lgkmcnt(0)
	v_mov_b32_e32 v0, v254
	s_barrier
	v_cmp_lt_u32_e32 vcc, 0xff, v254
	s_cbranch_vccz .Lprio_skip2
	s_setprio 1
.Lprio_skip2:
	s_add_u32 s60, s26, 0x1c900000
	v_mov_b64_e32 v[0:1], s[58:59]
	flat_load_dwordx2 v[2:3], v[0:1] offset:128 sc0 sc1
	flat_load_dwordx2 v[4:5], v[0:1] offset:152 sc0 sc1
	s_waitcnt vmcnt(0)
	s_addc_u32 s61, s27, 0
	s_add_u32 s52, s26, 0x24d00000
	s_addc_u32 s53, s27, 0
	s_add_u32 s56, s26, 0x28f00000
	v_mov_b32_e32 v8, v254
	s_addc_u32 s57, s27, 0
	s_cmpk_lt_i32 s2, 0x528
	v_readfirstlane_b32 s4, v8
	s_waitcnt lgkmcnt(0)
	v_readfirstlane_b32 s41, v3
	v_readfirstlane_b32 s40, v2
	v_readfirstlane_b32 s43, v5
	v_readfirstlane_b32 s42, v4
	s_cbranch_scc0 .LBB0_547
	v_lshlrev_b32_e32 v0, 4, v8
	v_add_u32_e32 v1, 0x2000, v0
	v_ashrrev_i32_e32 v2, 31, v1
	v_lshrrev_b32_e32 v2, 22, v2
	v_add_u32_e32 v2, v1, v2
	v_ashrrev_i32_e32 v2, 10, v2
	v_mul_i32_i24_e32 v3, 0x400, v2
	v_sub_u32_e32 v1, v1, v3
	v_lshrrev_b32_e32 v3, 4, v1
	v_bitop3_b32 v1, v3, v1, 32 bitop3:0x6c
	v_ashrrev_i32_e32 v3, 31, v1
	v_lshrrev_b32_e32 v3, 26, v3
	v_add_u32_e32 v3, v1, v3
	v_lshlrev_b32_e32 v5, 3, v2
	v_ashrrev_i32_e32 v4, 6, v3
	v_and_b32_e32 v5, -16, v5
	v_and_b32_e32 v3, 0xc0, v3
	v_add_u32_e32 v5, v4, v5
	v_sub_u32_e32 v1, v1, v3
	v_mov_b32_e32 v3, 1
	v_and_b32_e32 v4, 3, v4
	s_mov_b32 s6, 0x7fffe0
	v_lshrrev_b32_e32 v6, 2, v5
	v_lshlrev_b32_e32 v7, 1, v5
	v_lshlrev_b32_e32 v2, 5, v2
	v_ashrrev_i16_sdwa v1, v3, sext(v1) dst_sel:DWORD dst_unused:UNUSED_PAD src0_sel:DWORD src1_sel:BYTE_0
	v_and_or_b32 v4, v5, s6, v4
	v_and_b32_e32 v6, 4, v6
	v_and_b32_e32 v7, 24, v7
	v_and_b32_e32 v2, 32, v2
	v_bfe_i32 v1, v1, 0, 16
	v_or3_b32 v4, v4, v6, v7
	v_add_lshl_u32 v1, v2, v1, 1
	v_lshl_add_u32 v136, v4, 9, v1
	v_lshl_add_u32 v138, v5, 9, v1
	v_bfe_i32 v1, v8, 27, 1
	v_lshrrev_b32_e32 v1, 22, v1
	v_add_u32_e32 v1, v0, v1
	v_and_b32_e32 v1, 0xfffffc00, v1
	v_sub_u32_e32 v0, v0, v1
	v_ashrrev_i32_e32 v2, 31, v8
	v_lshrrev_b32_e32 v1, 4, v0
	v_lshrrev_b32_e32 v2, 26, v2
	v_bitop3_b32 v1, v1, v0, 32 bitop3:0x6c
	v_ashrrev_i32_e32 v0, 31, v0
	v_add_u32_e32 v2, v8, v2
	v_lshrrev_b32_e32 v0, 26, v0
	v_ashrrev_i32_e32 v2, 6, v2
	v_add_u32_e32 v0, v1, v0
	v_lshlrev_b32_e32 v4, 3, v2
	v_ashrrev_i32_e32 v0, 6, v0
	v_and_b32_e32 v4, -16, v4
	v_add_u32_e32 v4, v0, v4
	v_and_b32_e32 v5, 3, v0
	v_and_or_b32 v5, v4, s6, v5
	s_lshr_b32 s6, s3, 29
	s_add_i32 s6, s2, s6
	s_ashr_i32 s1, s4, 6
	s_ashr_i32 s7, s6, 3
	s_and_b32 s6, s6, -8
	s_ashr_i32 s0, s4, 8
	s_lshl_b32 s5, s1, 10
	s_sub_i32 s6, s2, s6
	s_cmp_lt_i32 s6, 0
	s_movk_i32 s28, 0xa6
	s_cselect_b32 s8, s28, 0xa5
	s_mul_i32 s6, s6, s8
	s_add_i32 s6, s6, s7
	s_mul_hi_i32 s7, s6, 0x66666667
	s_lshr_b32 s8, s7, 31
	s_ashr_i32 s7, s7, 7
	v_mul_i32_i24_e32 v0, 64, v0
	s_add_i32 s7, s7, s8
	v_sub_u32_e32 v0, v1, v0
	s_lshl_b32 s8, s7, 3
	v_lshlrev_b32_e32 v2, 5, v2
	v_ashrrev_i16_sdwa v0, v3, sext(v0) dst_sel:DWORD dst_unused:UNUSED_PAD src0_sel:DWORD src1_sel:BYTE_0
	s_sub_i32 s9, 33, s8
	s_mulk_i32 s7, 0x140
	v_and_b32_e32 v2, 32, v2
	v_bfe_i32 v0, v0, 0, 16
	s_min_u32 s9, s9, 8
	s_sub_i32 s10, s6, s7
	v_add_lshl_u32 v0, v2, v0, 1
	s_sext_i32_i16 s6, s10
	v_cvt_f32_ubyte0_e32 v2, s9
	v_cvt_f32_i32_e32 v1, s6
	v_rcp_iflag_f32_e32 v3, v2
	v_lshrrev_b32_e32 v6, 2, v4
	v_lshlrev_b32_e32 v7, 1, v4
	v_and_b32_e32 v6, 4, v6
	v_and_b32_e32 v7, 24, v7
	v_or3_b32 v5, v5, v6, v7
	v_lshl_add_u32 v140, v5, 9, v0
	v_lshl_add_u32 v142, v4, 9, v0
	v_mul_f32_e32 v0, v1, v3
	v_trunc_f32_e32 v0, v0
	v_fma_f32 v1, -v0, v2, v1
	v_cvt_i32_f32_e32 v0, v0
	s_ashr_i32 s6, s6, 30
	s_or_b32 s11, s6, 1
	v_cmp_ge_f32_e64 s[6:7], |v1|, v2
	s_and_b64 s[6:7], s[6:7], exec
	s_cselect_b32 s6, s11, 0
	v_readfirstlane_b32 s7, v0
	s_add_i32 s6, s7, s6
	s_mul_i32 s7, s6, s9
	s_sub_i32 s7, s10, s7
	s_sext_i32_i16 s7, s7
	s_add_i32 s10, s8, s7
	s_and_b32 s7, s6, 0xffff
	s_cmp_lt_u32 s7, 32
	s_mov_b32 s29, 0x420000
	s_sext_i32_i16 s20, s6
	s_cselect_b32 s7, s29, 0x840000
	s_cmp_gt_i32 s20, 15
	s_cselect_b32 s12, s7, 0
	s_ashr_i32 s11, s10, 31
	s_bfe_i64 s[6:7], s[6:7], 0x100000
	s_lshl_b64 s[8:9], s[10:11], 17
	s_lshl_b64 s[6:7], s[6:7], 17
	s_add_u32 s14, s18, s6
	s_addc_u32 s15, s19, s7
	s_add_i32 s36, s5, 0
	s_add_i32 m0, s36, 0x10000
	v_mov_b32_e32 v145, 0
	global_load_lds_dwordx4 v140, s[14:15]
	s_add_i32 m0, s36, 0x12000
	s_add_u32 s6, s16, s12
	s_addc_u32 s7, s17, 0
	s_add_u32 s12, s6, s8
	global_load_lds_dwordx4 v136, s[14:15]
	s_addc_u32 s13, s7, s9
	s_mov_b32 m0, s36
	s_add_i32 s37, s36, 0x2000
	global_load_lds_dwordx4 v142, s[12:13]
	s_mov_b32 m0, s37
	s_add_u32 s6, s14, 0x10000
	global_load_lds_dwordx4 v138, s[12:13]
	s_addc_u32 s7, s15, 0
	s_add_i32 m0, s36, 0x14000
	v_mov_b32_e32 v141, v145
	global_load_lds_dwordx4 v140, s[6:7]
	s_add_i32 m0, s36, 0x16000
	v_mov_b32_e32 v137, v145
	global_load_lds_dwordx4 v136, s[6:7]
	s_add_u32 s6, s12, 0x10000
	s_addc_u32 s7, s13, 0
	s_add_i32 s50, s36, 0x4000
	s_mov_b32 m0, s50
	s_add_i32 s51, s36, 0x6000
	global_load_lds_dwordx4 v142, s[6:7]
	s_mov_b32 m0, s51
	v_mov_b32_e32 v143, v145
	global_load_lds_dwordx4 v138, s[6:7]
	v_mov_b32_e32 v139, v145
	v_lshl_add_u64 v[6:7], s[14:15], 0, v[140:141]
	v_lshl_add_u64 v[4:5], s[14:15], 0, v[136:137]
	v_lshl_add_u64 v[2:3], s[12:13], 0, v[142:143]
	s_cmp_lg_u32 s0, 1
	v_lshl_add_u64 v[0:1], s[12:13], 0, v[138:139]
	s_cbranch_scc1 .LBB0_530
	s_barrier

.LBB0_536:
	ds_read_b128 v[0:3], v173
	ds_read_b128 v[4:7], v173 offset:1024
	ds_read_b128 v[8:11], v173 offset:2048
	ds_read_b128 v[12:15], v173 offset:3072
	s_ashr_i32 s65, s64, 31
	s_lshl_b64 s[0:1], s[64:65], 17
	s_add_u32 s70, s18, s0
	s_addc_u32 s71, s19, s1
	s_and_b64 s[0:1], s[8:9], exec
	s_cselect_b32 s9, s71, s15
	s_cselect_b32 s8, s70, s14
	s_add_u32 s0, s12, 0x10080
	s_addc_u32 s1, s13, 0
	s_mov_b32 m0, s76
	v_lshl_add_u64 v[48:49], s[0:1], 0, v[142:143]
	ds_read_b128 v[16:19], v174
	ds_read_b128 v[20:23], v174 offset:1024
	ds_read_b128 v[24:27], v174 offset:2048
	ds_read_b128 v[28:31], v174 offset:3072
	ds_read_b128 v[32:35], v174 offset:4096
	ds_read_b128 v[36:39], v174 offset:5120
	ds_read_b128 v[40:43], v174 offset:6144
	ds_read_b128 v[44:47], v174 offset:7168
	global_load_lds_dwordx4 v[48:49], off
	v_lshl_add_u64 v[48:49], s[0:1], 0, v[138:139]
	s_mov_b32 m0, s77
	s_nop 0
	global_load_lds_dwordx4 v[48:49], off
	s_waitcnt lgkmcnt(8)
	s_barrier
	s_waitcnt lgkmcnt(0)
	s_waitcnt lgkmcnt(0)
	v_mfma_f32_16x16x32_bf16 v[48:51], v[0:3], v[16:19], 0
	v_mfma_f32_16x16x32_bf16 v[52:55], v[8:11], v[16:19], 0
	v_mfma_f32_16x16x32_bf16 v[56:59], v[0:3], v[24:27], 0
	v_mfma_f32_16x16x32_bf16 v[60:63], v[8:11], v[24:27], 0
	v_mfma_f32_16x16x32_bf16 v[64:67], v[0:3], v[32:35], 0
	v_mfma_f32_16x16x32_bf16 v[68:71], v[8:11], v[32:35], 0
	v_mfma_f32_16x16x32_bf16 v[72:75], v[0:3], v[40:43], 0
	v_mfma_f32_16x16x32_bf16 v[76:79], v[8:11], v[40:43], 0
	v_mfma_f32_16x16x32_bf16 v[48:51], v[4:7], v[20:23], v[48:51]
	v_mfma_f32_16x16x32_bf16 v[52:55], v[12:15], v[20:23], v[52:55]
	v_mfma_f32_16x16x32_bf16 v[56:59], v[4:7], v[28:31], v[56:59]
	v_mfma_f32_16x16x32_bf16 v[60:63], v[12:15], v[28:31], v[60:63]
	v_mfma_f32_16x16x32_bf16 v[64:67], v[4:7], v[36:39], v[64:67]
	v_mfma_f32_16x16x32_bf16 v[68:71], v[12:15], v[36:39], v[68:71]
	v_mfma_f32_16x16x32_bf16 v[72:75], v[4:7], v[44:47], v[72:75]
	v_mfma_f32_16x16x32_bf16 v[76:79], v[12:15], v[44:47], v[76:79]
	s_barrier
	v_lshl_add_u64 v[166:167], s[14:15], 0, v[140:141]
	s_add_i32 s11, s75, s5
	v_lshl_add_u64 v[96:97], v[166:167], 0, s[54:55]
	s_mov_b32 m0, s11
	v_lshl_add_u64 v[214:215], s[14:15], 0, v[136:137]
	s_add_i32 s0, s11, 0x2000
	ds_read_b128 v[80:83], v175
	ds_read_b128 v[84:87], v175 offset:1024
	ds_read_b128 v[88:91], v175 offset:2048
	ds_read_b128 v[92:95], v175 offset:3072
	global_load_lds_dwordx4 v[96:97], off
	v_lshl_add_u64 v[96:97], v[214:215], 0, s[54:55]
	s_mov_b32 m0, s0
	s_nop 0
	global_load_lds_dwordx4 v[96:97], off
	s_barrier
	s_waitcnt lgkmcnt(0)
	s_waitcnt lgkmcnt(0)
	v_mfma_f32_16x16x32_bf16 v[96:99], v[80:83], v[16:19], 0
	v_mfma_f32_16x16x32_bf16 v[16:19], v[88:91], v[16:19], 0
	v_mfma_f32_16x16x32_bf16 v[96:99], v[84:87], v[20:23], v[96:99]
	v_mfma_f32_16x16x32_bf16 v[16:19], v[92:95], v[20:23], v[16:19]
	v_mfma_f32_16x16x32_bf16 v[20:23], v[80:83], v[24:27], 0
	v_mfma_f32_16x16x32_bf16 v[24:27], v[88:91], v[24:27], 0
	v_mfma_f32_16x16x32_bf16 v[20:23], v[84:87], v[28:31], v[20:23]
	v_mfma_f32_16x16x32_bf16 v[24:27], v[92:95], v[28:31], v[24:27]
	v_mfma_f32_16x16x32_bf16 v[28:31], v[80:83], v[32:35], 0
	v_mfma_f32_16x16x32_bf16 v[32:35], v[88:91], v[32:35], 0
	v_mfma_f32_16x16x32_bf16 v[28:31], v[84:87], v[36:39], v[28:31]
	v_mfma_f32_16x16x32_bf16 v[32:35], v[92:95], v[36:39], v[32:35]
	v_mfma_f32_16x16x32_bf16 v[36:39], v[80:83], v[40:43], 0
	v_mfma_f32_16x16x32_bf16 v[40:43], v[88:91], v[40:43], 0
	v_mfma_f32_16x16x32_bf16 v[36:39], v[84:87], v[44:47], v[36:39]
	v_mfma_f32_16x16x32_bf16 v[40:43], v[92:95], v[44:47], v[40:43]
	v_lshl_add_u64 v[216:217], s[12:13], 0, v[142:143]
	s_mov_b32 m0, s36
	v_lshl_add_u64 v[128:129], v[216:217], 0, s[54:55]
	v_lshl_add_u64 v[222:223], s[12:13], 0, v[138:139]
	s_barrier
	ds_read_b128 v[44:47], v174 offset:16384
	ds_read_b128 v[100:103], v174 offset:17408
	ds_read_b128 v[104:107], v174 offset:18432
	ds_read_b128 v[108:111], v174 offset:19456
	ds_read_b128 v[112:115], v174 offset:20480
	ds_read_b128 v[116:119], v174 offset:21504
	ds_read_b128 v[120:123], v174 offset:22528
	ds_read_b128 v[124:127], v174 offset:23552
	global_load_lds_dwordx4 v[128:129], off
	v_lshl_add_u64 v[128:129], v[222:223], 0, s[54:55]
	s_mov_b32 m0, s37
	s_nop 0
	global_load_lds_dwordx4 v[128:129], off
	s_barrier
	s_waitcnt lgkmcnt(0)
	s_waitcnt lgkmcnt(0)
	v_mfma_f32_16x16x32_bf16 v[128:131], v[0:3], v[44:47], 0
	v_mfma_f32_16x16x32_bf16 v[150:153], v[0:3], v[104:107], 0
	v_mfma_f32_16x16x32_bf16 v[158:161], v[0:3], v[112:115], 0
	v_mfma_f32_16x16x32_bf16 v[0:3], v[0:3], v[120:123], 0
	v_mfma_f32_16x16x32_bf16 v[128:131], v[4:7], v[100:103], v[128:131]
	v_mfma_f32_16x16x32_bf16 v[150:153], v[4:7], v[108:111], v[150:153]
	v_mfma_f32_16x16x32_bf16 v[158:161], v[4:7], v[116:119], v[158:161]
	v_mfma_f32_16x16x32_bf16 v[0:3], v[4:7], v[124:127], v[0:3]
	v_mfma_f32_16x16x32_bf16 v[4:7], v[8:11], v[120:123], 0
	v_mfma_f32_16x16x32_bf16 v[132:135], v[8:11], v[44:47], 0
	v_mfma_f32_16x16x32_bf16 v[154:157], v[8:11], v[104:107], 0
	v_mfma_f32_16x16x32_bf16 v[162:165], v[8:11], v[112:115], 0
	v_mfma_f32_16x16x32_bf16 v[4:7], v[12:15], v[124:127], v[4:7]
	v_mfma_f32_16x16x32_bf16 v[132:135], v[12:15], v[100:103], v[132:135]
	v_mfma_f32_16x16x32_bf16 v[154:157], v[12:15], v[108:111], v[154:157]
	v_mfma_f32_16x16x32_bf16 v[162:165], v[12:15], v[116:119], v[162:165]
	s_barrier
	s_add_u32 s24, s14, 0x10100
	s_addc_u32 s25, s15, 0
	s_add_i32 s21, s78, s5
	v_lshl_add_u64 v[8:9], s[24:25], 0, v[140:141]
	s_mov_b32 m0, s21
	s_add_i32 s1, s21, 0x2000
	global_load_lds_dwordx4 v[8:9], off
	v_lshl_add_u64 v[8:9], s[24:25], 0, v[136:137]
	s_mov_b32 m0, s1
	s_nop 0
	global_load_lds_dwordx4 v[8:9], off
	s_waitcnt vmcnt(6)
	s_barrier
	v_mfma_f32_16x16x32_bf16 v[8:11], v[80:83], v[44:47], 0
	v_mfma_f32_16x16x32_bf16 v[12:15], v[88:91], v[44:47], 0
	v_mfma_f32_16x16x32_bf16 v[8:11], v[84:87], v[100:103], v[8:11]
	v_mfma_f32_16x16x32_bf16 v[12:15], v[92:95], v[100:103], v[12:15]
	v_mfma_f32_16x16x32_bf16 v[44:47], v[80:83], v[104:107], 0
	v_mfma_f32_16x16x32_bf16 v[100:103], v[88:91], v[104:107], 0
	v_mfma_f32_16x16x32_bf16 v[104:107], v[80:83], v[112:115], 0
	v_mfma_f32_16x16x32_bf16 v[80:83], v[80:83], v[120:123], 0
	v_mfma_f32_16x16x32_bf16 v[44:47], v[84:87], v[108:111], v[44:47]
	v_mfma_f32_16x16x32_bf16 v[100:103], v[92:95], v[108:111], v[100:103]
	v_mfma_f32_16x16x32_bf16 v[104:107], v[84:87], v[116:119], v[104:107]
	v_mfma_f32_16x16x32_bf16 v[108:111], v[88:91], v[112:115], 0
	v_mfma_f32_16x16x32_bf16 v[80:83], v[84:87], v[124:127], v[80:83]
	v_mfma_f32_16x16x32_bf16 v[84:87], v[88:91], v[120:123], 0
	v_mfma_f32_16x16x32_bf16 v[108:111], v[92:95], v[116:119], v[108:111]
	v_mfma_f32_16x16x32_bf16 v[84:87], v[92:95], v[124:127], v[84:87]
	s_add_i32 s23, 0, 0x18000
	v_add_u32_e32 v144, s23, v169
	s_barrier
	ds_read_b128 v[88:91], v144
	ds_read_b128 v[92:95], v144 offset:1024
	ds_read_b128 v[112:115], v144 offset:2048
	ds_read_b128 v[116:119], v144 offset:3072
	s_add_u32 s24, s12, 0x10100
	s_addc_u32 s25, s13, 0
	s_mov_b32 m0, s50
	v_lshl_add_u64 v[202:203], s[24:25], 0, v[142:143]
	ds_read_b128 v[120:123], v174 offset:32768
	ds_read_b128 v[124:127], v174 offset:33792
	ds_read_b128 v[178:181], v174 offset:34816
	ds_read_b128 v[182:185], v174 offset:35840
	ds_read_b128 v[186:189], v174 offset:36864
	ds_read_b128 v[190:193], v174 offset:37888
	ds_read_b128 v[194:197], v174 offset:38912
	ds_read_b128 v[198:201], v174 offset:39936
	global_load_lds_dwordx4 v[202:203], off
	v_lshl_add_u64 v[202:203], s[24:25], 0, v[138:139]
	s_mov_b32 m0, s51
	s_nop 0
	global_load_lds_dwordx4 v[202:203], off
	s_waitcnt lgkmcnt(8)
	s_barrier
	s_waitcnt lgkmcnt(0)
	s_waitcnt lgkmcnt(0)
	v_mfma_f32_16x16x32_bf16 v[48:51], v[88:91], v[120:123], v[48:51]
	v_mfma_f32_16x16x32_bf16 v[52:55], v[112:115], v[120:123], v[52:55]
	v_mfma_f32_16x16x32_bf16 v[56:59], v[88:91], v[178:181], v[56:59]
	v_mfma_f32_16x16x32_bf16 v[60:63], v[112:115], v[178:181], v[60:63]
	v_mfma_f32_16x16x32_bf16 v[64:67], v[88:91], v[186:189], v[64:67]
	v_mfma_f32_16x16x32_bf16 v[68:71], v[112:115], v[186:189], v[68:71]
	v_mfma_f32_16x16x32_bf16 v[72:75], v[88:91], v[194:197], v[72:75]
	v_mfma_f32_16x16x32_bf16 v[76:79], v[112:115], v[194:197], v[76:79]
	v_mfma_f32_16x16x32_bf16 v[48:51], v[92:95], v[124:127], v[48:51]
	v_mfma_f32_16x16x32_bf16 v[52:55], v[116:119], v[124:127], v[52:55]
	v_mfma_f32_16x16x32_bf16 v[56:59], v[92:95], v[182:185], v[56:59]
	v_mfma_f32_16x16x32_bf16 v[60:63], v[116:119], v[182:185], v[60:63]
	v_mfma_f32_16x16x32_bf16 v[64:67], v[92:95], v[190:193], v[64:67]
	v_mfma_f32_16x16x32_bf16 v[68:71], v[116:119], v[190:193], v[68:71]
	v_mfma_f32_16x16x32_bf16 v[72:75], v[92:95], v[198:201], v[72:75]
	v_mfma_f32_16x16x32_bf16 v[76:79], v[116:119], v[198:201], v[76:79]
	s_barrier
	s_add_i32 s25, 0, 0x1c000
	s_add_i32 s24, s23, s5
	v_add_u32_e32 v177, s25, v169
	v_lshl_add_u64 v[166:167], v[166:167], 0, s[58:59]
	s_mov_b32 m0, s24
	s_add_i32 s23, s24, 0x2000
	ds_read_b128 v[202:205], v177
	ds_read_b128 v[206:209], v177 offset:1024
	ds_read_b128 v[210:213], v177 offset:2048
	ds_read_b128 v[218:221], v177 offset:3072
	global_load_lds_dwordx4 v[166:167], off
	v_lshl_add_u64 v[166:167], v[214:215], 0, s[58:59]
	s_mov_b32 m0, s23
	s_nop 0
	global_load_lds_dwordx4 v[166:167], off
	s_barrier
	s_waitcnt lgkmcnt(0)
	s_waitcnt lgkmcnt(0)
	v_mfma_f32_16x16x32_bf16 v[96:99], v[202:205], v[120:123], v[96:99]
	v_mfma_f32_16x16x32_bf16 v[16:19], v[210:213], v[120:123], v[16:19]
	v_mfma_f32_16x16x32_bf16 v[20:23], v[202:205], v[178:181], v[20:23]
	v_mfma_f32_16x16x32_bf16 v[24:27], v[210:213], v[178:181], v[24:27]
	v_mfma_f32_16x16x32_bf16 v[28:31], v[202:205], v[186:189], v[28:31]
	v_mfma_f32_16x16x32_bf16 v[32:35], v[210:213], v[186:189], v[32:35]
	v_mfma_f32_16x16x32_bf16 v[36:39], v[202:205], v[194:197], v[36:39]
	v_mfma_f32_16x16x32_bf16 v[40:43], v[210:213], v[194:197], v[40:43]
	v_mfma_f32_16x16x32_bf16 v[96:99], v[206:209], v[124:127], v[96:99]
	v_mfma_f32_16x16x32_bf16 v[16:19], v[218:221], v[124:127], v[16:19]
	v_mfma_f32_16x16x32_bf16 v[20:23], v[206:209], v[182:185], v[20:23]
	v_mfma_f32_16x16x32_bf16 v[24:27], v[218:221], v[182:185], v[24:27]
	v_mfma_f32_16x16x32_bf16 v[28:31], v[206:209], v[190:193], v[28:31]
	v_mfma_f32_16x16x32_bf16 v[32:35], v[218:221], v[190:193], v[32:35]
	v_mfma_f32_16x16x32_bf16 v[36:39], v[206:209], v[198:201], v[36:39]
	v_mfma_f32_16x16x32_bf16 v[40:43], v[218:221], v[198:201], v[40:43]
	s_mov_b32 m0, s72
	v_lshl_add_u64 v[166:167], v[216:217], 0, s[58:59]
	s_barrier
	ds_read_b128 v[120:123], v174 offset:49152
	ds_read_b128 v[124:127], v174 offset:50176
	ds_read_b128 v[178:181], v174 offset:51200
	ds_read_b128 v[182:185], v174 offset:52224
	ds_read_b128 v[186:189], v174 offset:53248
	ds_read_b128 v[190:193], v174 offset:54272
	ds_read_b128 v[194:197], v174 offset:55296
	ds_read_b128 v[198:201], v174 offset:56320
	global_load_lds_dwordx4 v[166:167], off
	v_lshl_add_u64 v[166:167], v[222:223], 0, s[58:59]
	s_mov_b32 m0, s73
	s_nop 0
	global_load_lds_dwordx4 v[166:167], off
	s_barrier
	s_waitcnt lgkmcnt(0)
	s_waitcnt lgkmcnt(0)
	v_mfma_f32_16x16x32_bf16 v[128:131], v[88:91], v[120:123], v[128:131]
	v_mfma_f32_16x16x32_bf16 v[150:153], v[88:91], v[178:181], v[150:153]
	v_mfma_f32_16x16x32_bf16 v[0:3], v[88:91], v[194:197], v[0:3]
	v_mfma_f32_16x16x32_bf16 v[4:7], v[112:115], v[194:197], v[4:7]
	v_mfma_f32_16x16x32_bf16 v[128:131], v[92:95], v[124:127], v[128:131]
	v_mfma_f32_16x16x32_bf16 v[132:135], v[112:115], v[120:123], v[132:135]
	v_mfma_f32_16x16x32_bf16 v[150:153], v[92:95], v[182:185], v[150:153]
	v_mfma_f32_16x16x32_bf16 v[154:157], v[112:115], v[178:181], v[154:157]
	v_mfma_f32_16x16x32_bf16 v[158:161], v[88:91], v[186:189], v[158:161]
	v_mfma_f32_16x16x32_bf16 v[162:165], v[112:115], v[186:189], v[162:165]
	v_mfma_f32_16x16x32_bf16 v[0:3], v[92:95], v[198:201], v[0:3]
	v_mfma_f32_16x16x32_bf16 v[4:7], v[116:119], v[198:201], v[4:7]
	v_mfma_f32_16x16x32_bf16 v[132:135], v[116:119], v[124:127], v[132:135]
	v_mfma_f32_16x16x32_bf16 v[154:157], v[116:119], v[182:185], v[154:157]
	v_mfma_f32_16x16x32_bf16 v[158:161], v[92:95], v[190:193], v[158:161]
	v_mfma_f32_16x16x32_bf16 v[162:165], v[116:119], v[190:193], v[162:165]
	s_barrier
	s_add_u32 s46, s14, 0x10180
	s_addc_u32 s47, s15, 0
	s_add_i32 s15, s25, s5
	v_lshl_add_u64 v[88:89], s[46:47], 0, v[140:141]
	s_mov_b32 m0, s15
	s_add_i32 s14, s15, 0x2000
	global_load_lds_dwordx4 v[88:89], off
	v_lshl_add_u64 v[88:89], s[46:47], 0, v[136:137]
	s_mov_b32 m0, s14
	s_nop 0
	global_load_lds_dwordx4 v[88:89], off
	s_waitcnt vmcnt(6)
	s_barrier
	v_mfma_f32_16x16x32_bf16 v[8:11], v[202:205], v[120:123], v[8:11]
	v_mfma_f32_16x16x32_bf16 v[12:15], v[210:213], v[120:123], v[12:15]
	v_mfma_f32_16x16x32_bf16 v[44:47], v[202:205], v[178:181], v[44:47]
	v_mfma_f32_16x16x32_bf16 v[88:91], v[210:213], v[178:181], v[100:103]
	v_mfma_f32_16x16x32_bf16 v[92:95], v[202:205], v[186:189], v[104:107]
	v_mfma_f32_16x16x32_bf16 v[100:103], v[210:213], v[186:189], v[108:111]
	v_mfma_f32_16x16x32_bf16 v[80:83], v[202:205], v[194:197], v[80:83]
	v_mfma_f32_16x16x32_bf16 v[84:87], v[210:213], v[194:197], v[84:87]
	v_mfma_f32_16x16x32_bf16 v[8:11], v[206:209], v[124:127], v[8:11]
	v_mfma_f32_16x16x32_bf16 v[12:15], v[218:221], v[124:127], v[12:15]
	v_mfma_f32_16x16x32_bf16 v[44:47], v[206:209], v[182:185], v[44:47]
	v_mfma_f32_16x16x32_bf16 v[88:91], v[218:221], v[182:185], v[88:91]
	v_mfma_f32_16x16x32_bf16 v[92:95], v[206:209], v[190:193], v[92:95]
	v_mfma_f32_16x16x32_bf16 v[100:103], v[218:221], v[190:193], v[100:103]
	v_mfma_f32_16x16x32_bf16 v[80:83], v[206:209], v[198:201], v[80:83]
	v_mfma_f32_16x16x32_bf16 v[84:87], v[218:221], v[198:201], v[84:87]
	s_barrier
	ds_read_b128 v[104:107], v173
	ds_read_b128 v[108:111], v173 offset:1024
	ds_read_b128 v[112:115], v173 offset:2048
	ds_read_b128 v[116:119], v173 offset:3072
	s_add_u32 s12, s12, 0x10180
	s_addc_u32 s13, s13, 0
	s_mov_b32 m0, s76
	v_lshl_add_u64 v[166:167], s[12:13], 0, v[142:143]
	ds_read_b128 v[120:123], v174
	ds_read_b128 v[124:127], v174 offset:1024
	ds_read_b128 v[178:181], v174 offset:2048
	ds_read_b128 v[182:185], v174 offset:3072
	ds_read_b128 v[186:189], v174 offset:4096
	ds_read_b128 v[190:193], v174 offset:5120
	ds_read_b128 v[194:197], v174 offset:6144
	ds_read_b128 v[198:201], v174 offset:7168
	global_load_lds_dwordx4 v[166:167], off
	v_lshl_add_u64 v[166:167], s[12:13], 0, v[138:139]
	s_mov_b32 m0, s77
	s_nop 0
	global_load_lds_dwordx4 v[166:167], off
	s_waitcnt lgkmcnt(8)
	s_barrier
	s_waitcnt lgkmcnt(0)
	s_waitcnt lgkmcnt(0)
	v_mfma_f32_16x16x32_bf16 v[48:51], v[104:107], v[120:123], v[48:51]
	v_mfma_f32_16x16x32_bf16 v[52:55], v[112:115], v[120:123], v[52:55]
	v_mfma_f32_16x16x32_bf16 v[56:59], v[104:107], v[178:181], v[56:59]
	v_mfma_f32_16x16x32_bf16 v[60:63], v[112:115], v[178:181], v[60:63]
	v_mfma_f32_16x16x32_bf16 v[64:67], v[104:107], v[186:189], v[64:67]
	v_mfma_f32_16x16x32_bf16 v[68:71], v[112:115], v[186:189], v[68:71]
	v_mfma_f32_16x16x32_bf16 v[72:75], v[104:107], v[194:197], v[72:75]
	v_mfma_f32_16x16x32_bf16 v[76:79], v[112:115], v[194:197], v[76:79]
	v_mfma_f32_16x16x32_bf16 v[48:51], v[108:111], v[124:127], v[48:51]
	v_mfma_f32_16x16x32_bf16 v[52:55], v[116:119], v[124:127], v[52:55]
	v_mfma_f32_16x16x32_bf16 v[56:59], v[108:111], v[182:185], v[56:59]
	v_mfma_f32_16x16x32_bf16 v[60:63], v[116:119], v[182:185], v[60:63]
	v_mfma_f32_16x16x32_bf16 v[64:67], v[108:111], v[190:193], v[64:67]
	v_mfma_f32_16x16x32_bf16 v[68:71], v[116:119], v[190:193], v[68:71]
	v_mfma_f32_16x16x32_bf16 v[72:75], v[108:111], v[198:201], v[72:75]
	v_mfma_f32_16x16x32_bf16 v[76:79], v[116:119], v[198:201], v[76:79]
	s_barrier
	s_mov_b32 m0, s11
	v_lshl_add_u64 v[166:167], s[8:9], 0, v[140:141]
	ds_read_b128 v[202:205], v175
	ds_read_b128 v[206:209], v175 offset:1024
	ds_read_b128 v[210:213], v175 offset:2048
	ds_read_b128 v[218:221], v175 offset:3072
	global_load_lds_dwordx4 v[166:167], off
	v_lshl_add_u64 v[214:215], s[8:9], 0, v[136:137]
	s_mov_b32 m0, s0
	s_nop 0
	global_load_lds_dwordx4 v[214:215], off
	s_barrier
	s_waitcnt lgkmcnt(0)
	s_waitcnt lgkmcnt(0)
	v_mfma_f32_16x16x32_bf16 v[28:31], v[202:205], v[186:189], v[28:31]
	v_mfma_f32_16x16x32_bf16 v[96:99], v[202:205], v[120:123], v[96:99]
	v_mfma_f32_16x16x32_bf16 v[16:19], v[210:213], v[120:123], v[16:19]
	v_mfma_f32_16x16x32_bf16 v[120:123], v[206:209], v[190:193], v[28:31]
	v_mfma_f32_16x16x32_bf16 v[28:31], v[210:213], v[186:189], v[32:35]
	v_mfma_f32_16x16x32_bf16 v[32:35], v[218:221], v[190:193], v[28:31]
	v_mfma_f32_16x16x32_bf16 v[28:31], v[202:205], v[194:197], v[36:39]
	v_mfma_f32_16x16x32_bf16 v[20:23], v[202:205], v[178:181], v[20:23]
	v_mfma_f32_16x16x32_bf16 v[24:27], v[210:213], v[178:181], v[24:27]
	v_mfma_f32_16x16x32_bf16 v[36:39], v[206:209], v[198:201], v[28:31]
	v_mfma_f32_16x16x32_bf16 v[28:31], v[210:213], v[194:197], v[40:43]
	v_mfma_f32_16x16x32_bf16 v[96:99], v[206:209], v[124:127], v[96:99]
	v_mfma_f32_16x16x32_bf16 v[16:19], v[218:221], v[124:127], v[16:19]
	v_mfma_f32_16x16x32_bf16 v[20:23], v[206:209], v[182:185], v[20:23]
	v_mfma_f32_16x16x32_bf16 v[24:27], v[218:221], v[182:185], v[24:27]
	v_mfma_f32_16x16x32_bf16 v[40:43], v[218:221], v[198:201], v[28:31]
	s_mov_b32 m0, s36
	v_lshl_add_u64 v[146:147], s[68:69], 0, v[142:143]
	s_barrier
	ds_read_b128 v[28:31], v174 offset:16384
	ds_read_b128 v[124:127], v174 offset:17408
	ds_read_b128 v[178:181], v174 offset:18432
	ds_read_b128 v[182:185], v174 offset:19456
	ds_read_b128 v[186:189], v174 offset:20480
	ds_read_b128 v[190:193], v174 offset:21504
	ds_read_b128 v[194:197], v174 offset:22528
	ds_read_b128 v[198:201], v174 offset:23552
	global_load_lds_dwordx4 v[146:147], off
	v_lshl_add_u64 v[148:149], s[68:69], 0, v[138:139]
	s_mov_b32 m0, s37
	s_nop 0
	global_load_lds_dwordx4 v[148:149], off
	s_barrier
	s_waitcnt lgkmcnt(0)
	s_waitcnt lgkmcnt(0)
	v_mfma_f32_16x16x32_bf16 v[128:131], v[104:107], v[28:31], v[128:131]
	v_mfma_f32_16x16x32_bf16 v[222:225], v[108:111], v[124:127], v[128:131]
	v_mfma_f32_16x16x32_bf16 v[128:131], v[112:115], v[28:31], v[132:135]
	v_mfma_f32_16x16x32_bf16 v[132:135], v[116:119], v[124:127], v[128:131]
	v_mfma_f32_16x16x32_bf16 v[128:131], v[104:107], v[178:181], v[150:153]
	v_mfma_f32_16x16x32_bf16 v[150:153], v[108:111], v[182:185], v[128:131]
	v_mfma_f32_16x16x32_bf16 v[128:131], v[112:115], v[178:181], v[154:157]
	v_mfma_f32_16x16x32_bf16 v[154:157], v[116:119], v[182:185], v[128:131]
	v_mfma_f32_16x16x32_bf16 v[128:131], v[104:107], v[186:189], v[158:161]
	v_mfma_f32_16x16x32_bf16 v[0:3], v[104:107], v[194:197], v[0:3]
	v_mfma_f32_16x16x32_bf16 v[4:7], v[112:115], v[194:197], v[4:7]
	v_mfma_f32_16x16x32_bf16 v[158:161], v[108:111], v[190:193], v[128:131]
	v_mfma_f32_16x16x32_bf16 v[128:131], v[112:115], v[186:189], v[162:165]
	v_mfma_f32_16x16x32_bf16 v[0:3], v[108:111], v[198:201], v[0:3]
	v_mfma_f32_16x16x32_bf16 v[4:7], v[116:119], v[198:201], v[4:7]
	v_mfma_f32_16x16x32_bf16 v[162:165], v[116:119], v[190:193], v[128:131]
	s_barrier
	s_add_u32 s12, s8, 0x10000
	s_addc_u32 s13, s9, 0
	s_mov_b32 m0, s21
	v_lshl_add_u64 v[104:105], s[12:13], 0, v[140:141]
	global_load_lds_dwordx4 v[104:105], off
	v_lshl_add_u64 v[104:105], s[12:13], 0, v[136:137]
	s_mov_b32 m0, s1
	s_nop 0
	global_load_lds_dwordx4 v[104:105], off
	s_waitcnt vmcnt(6)
	s_barrier
	v_mfma_f32_16x16x32_bf16 v[8:11], v[202:205], v[28:31], v[8:11]
	v_mfma_f32_16x16x32_bf16 v[12:15], v[210:213], v[28:31], v[12:15]
	v_mfma_f32_16x16x32_bf16 v[28:31], v[202:205], v[178:181], v[44:47]
	v_mfma_f32_16x16x32_bf16 v[226:229], v[206:209], v[182:185], v[28:31]
	v_mfma_f32_16x16x32_bf16 v[28:31], v[210:213], v[178:181], v[88:91]
	v_mfma_f32_16x16x32_bf16 v[178:181], v[218:221], v[182:185], v[28:31]
	v_mfma_f32_16x16x32_bf16 v[28:31], v[202:205], v[186:189], v[92:95]
	v_mfma_f32_16x16x32_bf16 v[182:185], v[206:209], v[190:193], v[28:31]
	v_mfma_f32_16x16x32_bf16 v[28:31], v[210:213], v[186:189], v[100:103]
	v_mfma_f32_16x16x32_bf16 v[186:189], v[218:221], v[190:193], v[28:31]
	v_mfma_f32_16x16x32_bf16 v[28:31], v[202:205], v[194:197], v[80:83]
	v_mfma_f32_16x16x32_bf16 v[8:11], v[206:209], v[124:127], v[8:11]
	v_mfma_f32_16x16x32_bf16 v[12:15], v[218:221], v[124:127], v[12:15]
	v_mfma_f32_16x16x32_bf16 v[190:193], v[206:209], v[198:201], v[28:31]
	v_mfma_f32_16x16x32_bf16 v[28:31], v[210:213], v[194:197], v[84:87]
	v_mfma_f32_16x16x32_bf16 v[194:197], v[218:221], v[198:201], v[28:31]
	s_barrier
	ds_read_b128 v[44:47], v144
	ds_read_b128 v[198:201], v144 offset:1024
	ds_read_b128 v[202:205], v144 offset:2048
	ds_read_b128 v[206:209], v144 offset:3072
	s_add_u32 s0, s68, 0x10000
	s_addc_u32 s1, s69, 0
	s_mov_b32 m0, s50
	v_lshl_add_u64 v[80:81], s[0:1], 0, v[142:143]
	ds_read_b128 v[28:31], v174 offset:32768
	ds_read_b128 v[100:103], v174 offset:33792
	ds_read_b128 v[104:107], v174 offset:34816
	ds_read_b128 v[108:111], v174 offset:35840
	ds_read_b128 v[210:213], v174 offset:36864
	ds_read_b128 v[218:221], v174 offset:37888
	ds_read_b128 v[230:233], v174 offset:38912
	ds_read_b128 v[234:237], v174 offset:39936
	global_load_lds_dwordx4 v[80:81], off
	v_lshl_add_u64 v[80:81], s[0:1], 0, v[138:139]
	s_mov_b32 m0, s51
	s_nop 0
	global_load_lds_dwordx4 v[80:81], off
	s_waitcnt lgkmcnt(8)
	s_barrier
	s_waitcnt lgkmcnt(0)
	s_waitcnt lgkmcnt(0)
	v_mfma_f32_16x16x32_bf16 v[48:51], v[44:47], v[28:31], v[48:51]
	v_mfma_f32_16x16x32_bf16 v[128:131], v[198:201], v[100:103], v[48:51]
	v_mfma_f32_16x16x32_bf16 v[48:51], v[202:205], v[28:31], v[52:55]
	v_mfma_f32_16x16x32_bf16 v[92:95], v[206:209], v[100:103], v[48:51]
	v_mfma_f32_16x16x32_bf16 v[48:51], v[44:47], v[104:107], v[56:59]
	v_mfma_f32_16x16x32_bf16 v[124:127], v[198:201], v[108:111], v[48:51]
	v_mfma_f32_16x16x32_bf16 v[48:51], v[202:205], v[104:107], v[60:63]
	v_mfma_f32_16x16x32_bf16 v[88:91], v[206:209], v[108:111], v[48:51]
	v_mfma_f32_16x16x32_bf16 v[48:51], v[44:47], v[210:213], v[64:67]
	v_mfma_f32_16x16x32_bf16 v[116:119], v[198:201], v[218:221], v[48:51]
	v_mfma_f32_16x16x32_bf16 v[48:51], v[202:205], v[210:213], v[68:71]
	v_mfma_f32_16x16x32_bf16 v[84:87], v[206:209], v[218:221], v[48:51]
	v_mfma_f32_16x16x32_bf16 v[48:51], v[44:47], v[230:233], v[72:75]
	v_mfma_f32_16x16x32_bf16 v[112:115], v[198:201], v[234:237], v[48:51]
	v_mfma_f32_16x16x32_bf16 v[48:51], v[202:205], v[230:233], v[76:79]
	v_mfma_f32_16x16x32_bf16 v[80:83], v[206:209], v[234:237], v[48:51]
	s_barrier
	s_mov_b32 m0, s24
	s_nop 3
	v_lshl_add_u64 v[48:49], v[166:167], 0, s[44:45]
	ds_read_b128 v[238:241], v177
	ds_read_b128 v[242:245], v177 offset:1024
	ds_read_b128 v[246:249], v177 offset:2048
	ds_read_b128 v[250:253], v177 offset:3072
	global_load_lds_dwordx4 v[48:49], off
	v_lshl_add_u64 v[48:49], v[214:215], 0, s[44:45]
	s_mov_b32 m0, s23
	s_nop 0
	global_load_lds_dwordx4 v[48:49], off
	s_barrier
	s_waitcnt lgkmcnt(0)
	s_waitcnt lgkmcnt(0)
	v_mfma_f32_16x16x32_bf16 v[16:19], v[246:249], v[28:31], v[16:19]
	v_mfma_f32_16x16x32_bf16 v[48:51], v[238:241], v[28:31], v[96:99]
	v_mfma_f32_16x16x32_bf16 v[28:31], v[250:253], v[100:103], v[16:19]
	v_mfma_f32_16x16x32_bf16 v[16:19], v[238:241], v[104:107], v[20:23]
	v_mfma_f32_16x16x32_bf16 v[56:59], v[242:245], v[108:111], v[16:19]
	v_mfma_f32_16x16x32_bf16 v[16:19], v[246:249], v[104:107], v[24:27]
	v_mfma_f32_16x16x32_bf16 v[24:27], v[250:253], v[108:111], v[16:19]
	v_mfma_f32_16x16x32_bf16 v[16:19], v[238:241], v[210:213], v[120:123]
	v_mfma_f32_16x16x32_bf16 v[52:55], v[242:245], v[218:221], v[16:19]
	v_mfma_f32_16x16x32_bf16 v[16:19], v[246:249], v[210:213], v[32:35]
	v_mfma_f32_16x16x32_bf16 v[20:23], v[250:253], v[218:221], v[16:19]
	v_mfma_f32_16x16x32_bf16 v[16:19], v[238:241], v[230:233], v[36:39]
	v_mfma_f32_16x16x32_bf16 v[60:63], v[242:245], v[100:103], v[48:51]
	v_mfma_f32_16x16x32_bf16 v[48:51], v[242:245], v[234:237], v[16:19]
	v_mfma_f32_16x16x32_bf16 v[16:19], v[246:249], v[230:233], v[40:43]
	v_mfma_f32_16x16x32_bf16 v[16:19], v[250:253], v[234:237], v[16:19]
	s_mov_b32 m0, s72
	v_lshl_add_u64 v[40:41], v[146:147], 0, s[44:45]
	s_barrier
	ds_read_b128 v[32:35], v174 offset:49152
	ds_read_b128 v[36:39], v174 offset:50176
	ds_read_b128 v[120:123], v174 offset:51200
	ds_read_b128 v[210:213], v174 offset:52224
	ds_read_b128 v[218:221], v174 offset:53248
	ds_read_b128 v[230:233], v174 offset:54272
	ds_read_b128 v[234:237], v174 offset:55296
	ds_read_b128 v[214:217], v174 offset:56320
	global_load_lds_dwordx4 v[40:41], off
	v_lshl_add_u64 v[40:41], v[148:149], 0, s[44:45]
	s_mov_b32 m0, s73
	s_nop 0
	global_load_lds_dwordx4 v[40:41], off
	s_barrier
	s_waitcnt lgkmcnt(0)
	s_waitcnt lgkmcnt(0)
	v_mfma_f32_16x16x32_bf16 v[40:43], v[44:47], v[32:35], v[222:225]
	v_mfma_f32_16x16x32_bf16 v[108:111], v[198:201], v[36:39], v[40:43]
	v_mfma_f32_16x16x32_bf16 v[40:43], v[202:205], v[32:35], v[132:135]
	v_mfma_f32_16x16x32_bf16 v[76:79], v[206:209], v[36:39], v[40:43]
	v_mfma_f32_16x16x32_bf16 v[40:43], v[44:47], v[120:123], v[150:153]
	v_mfma_f32_16x16x32_bf16 v[104:107], v[198:201], v[210:213], v[40:43]
	v_mfma_f32_16x16x32_bf16 v[40:43], v[202:205], v[120:123], v[154:157]
	v_mfma_f32_16x16x32_bf16 v[72:75], v[206:209], v[210:213], v[40:43]
	v_mfma_f32_16x16x32_bf16 v[40:43], v[44:47], v[218:221], v[158:161]
	v_mfma_f32_16x16x32_bf16 v[0:3], v[44:47], v[234:237], v[0:3]
	v_mfma_f32_16x16x32_bf16 v[100:103], v[198:201], v[230:233], v[40:43]
	v_mfma_f32_16x16x32_bf16 v[40:43], v[202:205], v[218:221], v[162:165]
	v_mfma_f32_16x16x32_bf16 v[96:99], v[198:201], v[214:217], v[0:3]
	v_mfma_f32_16x16x32_bf16 v[0:3], v[202:205], v[234:237], v[4:7]
	v_mfma_f32_16x16x32_bf16 v[68:71], v[206:209], v[230:233], v[40:43]
	v_mfma_f32_16x16x32_bf16 v[64:67], v[206:209], v[214:217], v[0:3]
	s_barrier
	s_add_u32 s0, s8, 0x10080
	s_addc_u32 s1, s9, 0
	s_mov_b32 m0, s15
	s_nop 0
	v_lshl_add_u64 v[0:1], s[0:1], 0, v[140:141]
	global_load_lds_dwordx4 v[0:1], off
	v_lshl_add_u64 v[0:1], s[0:1], 0, v[136:137]
	s_mov_b32 m0, s14
	s_nop 0
	global_load_lds_dwordx4 v[0:1], off
	s_waitcnt vmcnt(6)
	s_barrier
	v_mfma_f32_16x16x32_bf16 v[0:3], v[238:241], v[32:35], v[8:11]
	v_mfma_f32_16x16x32_bf16 v[44:47], v[242:245], v[36:39], v[0:3]
	v_mfma_f32_16x16x32_bf16 v[0:3], v[246:249], v[32:35], v[12:15]
	v_mfma_f32_16x16x32_bf16 v[12:15], v[250:253], v[36:39], v[0:3]
	v_mfma_f32_16x16x32_bf16 v[0:3], v[238:241], v[120:123], v[226:229]
	v_mfma_f32_16x16x32_bf16 v[40:43], v[242:245], v[210:213], v[0:3]
	v_mfma_f32_16x16x32_bf16 v[0:3], v[246:249], v[120:123], v[178:181]
	v_mfma_f32_16x16x32_bf16 v[8:11], v[250:253], v[210:213], v[0:3]
	v_mfma_f32_16x16x32_bf16 v[0:3], v[238:241], v[218:221], v[182:185]
	v_mfma_f32_16x16x32_bf16 v[36:39], v[242:245], v[230:233], v[0:3]
	v_mfma_f32_16x16x32_bf16 v[0:3], v[246:249], v[218:221], v[186:189]
	v_mfma_f32_16x16x32_bf16 v[4:7], v[250:253], v[230:233], v[0:3]
	v_mfma_f32_16x16x32_bf16 v[0:3], v[238:241], v[234:237], v[190:193]
	v_mfma_f32_16x16x32_bf16 v[32:35], v[242:245], v[214:217], v[0:3]
	v_mfma_f32_16x16x32_bf16 v[0:3], v[246:249], v[234:237], v[194:197]
	v_mfma_f32_16x16x32_bf16 v[0:3], v[250:253], v[214:217], v[0:3]
	v_lshl_add_u32 v150, s10, 8, v168
	s_cmp_gt_i32 s20, 15
	s_mov_b64 s[0:1], -1
	s_barrier
	s_cbranch_scc0 .LBB0_542
	s_lshl_b32 s8, s20, 8
	s_cmp_gt_u32 s20, 31
	s_cbranch_scc0 .LBB0_539
	v_ashrrev_i32_e32 v151, 31, v150
	v_add_u32_e32 v144, s8, v171
	v_lshlrev_b64 v[120:121], 12, v[150:151]
	v_lshl_add_u64 v[120:121], s[56:57], 0, v[120:121]
	v_lshlrev_b64 v[122:123], 1, v[144:145]
	v_lshl_add_u64 v[120:121], v[120:121], 0, v[122:123]
	s_nop 1
	v_cvt_pk_bf16_f32 v132, v128, v129
	s_nop 1
	v_cvt_pk_bf16_f32 v133, v130, v131
	s_nop 1
	v_cvt_pk_bf16_f32 v134, v92, v93
	s_nop 1
	v_cvt_pk_bf16_f32 v135, v94, v95
	global_store_dwordx4 v[120:121], v[132:135], off
	s_mov_b64 s[0:1], 0x80000
	s_nop 0
	s_nop 1
	v_cvt_pk_bf16_f32 v132, v60, v61
	s_nop 1
	v_cvt_pk_bf16_f32 v133, v62, v63
	s_nop 1
	v_cvt_pk_bf16_f32 v134, v28, v29
	s_nop 1
	v_cvt_pk_bf16_f32 v135, v30, v31
	global_store_dwordx4 v[120:121], v[132:135], off offset:256
	s_nop 1
	v_or_b32_e32 v132, 16, v150
	v_ashrrev_i32_e32 v133, 31, v132
	v_lshlrev_b64 v[132:133], 12, v[132:133]
	v_lshl_add_u64 v[132:133], s[56:57], 0, v[132:133]
	v_lshl_add_u64 v[146:147], v[132:133], 0, v[122:123]
	s_nop 1
	v_cvt_pk_bf16_f32 v132, v124, v125
	s_nop 1
	v_cvt_pk_bf16_f32 v133, v126, v127
	s_nop 1
	v_cvt_pk_bf16_f32 v134, v88, v89
	s_nop 1
	v_cvt_pk_bf16_f32 v135, v90, v91
	global_store_dwordx4 v[146:147], v[132:135], off
	s_nop 1
	s_nop 1
	v_cvt_pk_bf16_f32 v132, v56, v57
	s_nop 1
	v_cvt_pk_bf16_f32 v133, v58, v59
	s_nop 1
	v_cvt_pk_bf16_f32 v134, v24, v25
	s_nop 1
	v_cvt_pk_bf16_f32 v135, v26, v27
	global_store_dwordx4 v[146:147], v[132:135], off offset:256
	s_nop 1
	v_or_b32_e32 v132, 32, v150
	v_ashrrev_i32_e32 v133, 31, v132
	v_lshlrev_b64 v[132:133], 12, v[132:133]
	v_lshl_add_u64 v[132:133], s[56:57], 0, v[132:133]
	v_lshl_add_u64 v[146:147], v[132:133], 0, v[122:123]
	s_nop 1
	v_cvt_pk_bf16_f32 v132, v116, v117
	s_nop 1
	v_cvt_pk_bf16_f32 v133, v118, v119
	s_nop 1
	v_cvt_pk_bf16_f32 v134, v84, v85
	s_nop 1
	v_cvt_pk_bf16_f32 v135, v86, v87
	global_store_dwordx4 v[146:147], v[132:135], off
	s_nop 1
	s_nop 1
	v_cvt_pk_bf16_f32 v132, v52, v53
	s_nop 1
	v_cvt_pk_bf16_f32 v133, v54, v55
	s_nop 1
	v_cvt_pk_bf16_f32 v134, v20, v21
	s_nop 1
	v_cvt_pk_bf16_f32 v135, v22, v23
	global_store_dwordx4 v[146:147], v[132:135], off offset:256
	s_nop 1
	v_or_b32_e32 v132, 48, v150
	v_ashrrev_i32_e32 v133, 31, v132
	v_lshlrev_b64 v[132:133], 12, v[132:133]
	v_lshl_add_u64 v[132:133], s[56:57], 0, v[132:133]
	v_lshl_add_u64 v[122:123], v[132:133], 0, v[122:123]
	s_nop 1
	v_cvt_pk_bf16_f32 v132, v112, v113
	s_nop 1
	v_cvt_pk_bf16_f32 v133, v114, v115
	s_nop 1
	v_cvt_pk_bf16_f32 v134, v80, v81
	s_nop 1
	v_cvt_pk_bf16_f32 v135, v82, v83
	global_store_dwordx4 v[122:123], v[132:135], off
	s_nop 1
	s_nop 1
	v_cvt_pk_bf16_f32 v132, v48, v49
	s_nop 1
	v_cvt_pk_bf16_f32 v133, v50, v51
	s_nop 1
	v_cvt_pk_bf16_f32 v134, v16, v17
	s_nop 1
	v_cvt_pk_bf16_f32 v135, v18, v19
	global_store_dwordx4 v[122:123], v[132:135], off offset:256
	v_lshl_add_u64 v[122:123], v[120:121], 0, s[0:1]
	s_mov_b32 s0, 0x80000
	v_add_co_u32_e32 v146, vcc, s0, v120
	s_nop 1
	v_cvt_pk_bf16_f32 v132, v108, v109
	s_nop 1
	v_cvt_pk_bf16_f32 v133, v110, v111
	s_nop 1
	v_cvt_pk_bf16_f32 v134, v76, v77
	s_nop 1
	v_cvt_pk_bf16_f32 v135, v78, v79
	s_nop 1
	v_addc_co_u32_e32 v147, vcc, 0, v121, vcc
	s_mov_b64 s[0:1], 0x90000
	global_store_dwordx4 v[146:147], v[132:135], off
	s_nop 1
	s_nop 1
	v_cvt_pk_bf16_f32 v132, v44, v45
	s_nop 1
	v_cvt_pk_bf16_f32 v133, v46, v47
	s_nop 1
	v_cvt_pk_bf16_f32 v134, v12, v13
	s_nop 1
	v_cvt_pk_bf16_f32 v135, v14, v15
	global_store_dwordx4 v[122:123], v[132:135], off offset:256
	v_lshl_add_u64 v[122:123], v[120:121], 0, s[0:1]
	s_mov_b32 s0, 0x90000
	v_add_co_u32_e32 v146, vcc, s0, v120
	s_nop 1
	v_cvt_pk_bf16_f32 v132, v104, v105
	s_nop 1
	v_cvt_pk_bf16_f32 v133, v106, v107
	s_nop 1
	v_cvt_pk_bf16_f32 v134, v72, v73
	s_nop 1
	v_cvt_pk_bf16_f32 v135, v74, v75
	s_nop 1
	v_addc_co_u32_e32 v147, vcc, 0, v121, vcc
	s_mov_b64 s[0:1], 0xa0000
	global_store_dwordx4 v[146:147], v[132:135], off
	s_nop 1
	s_nop 1
	v_cvt_pk_bf16_f32 v132, v40, v41
	s_nop 1
	v_cvt_pk_bf16_f32 v133, v42, v43
	s_nop 1
	v_cvt_pk_bf16_f32 v134, v8, v9
	s_nop 1
	v_cvt_pk_bf16_f32 v135, v10, v11
	global_store_dwordx4 v[122:123], v[132:135], off offset:256
	v_lshl_add_u64 v[122:123], v[120:121], 0, s[0:1]
	s_mov_b32 s0, 0xa0000
	v_add_co_u32_e32 v146, vcc, s0, v120
	s_mov_b64 s[0:1], 0xb0000
	s_nop 0
	v_addc_co_u32_e32 v147, vcc, 0, v121, vcc
	s_nop 1
	v_cvt_pk_bf16_f32 v132, v100, v101
	s_nop 1
	v_cvt_pk_bf16_f32 v133, v102, v103
	s_nop 1
	v_cvt_pk_bf16_f32 v134, v68, v69
	s_nop 1
	v_cvt_pk_bf16_f32 v135, v70, v71
	global_store_dwordx4 v[146:147], v[132:135], off
	v_lshl_add_u64 v[146:147], v[120:121], 0, s[0:1]
	s_mov_b32 s0, 0xb0000
	v_add_co_u32_e32 v120, vcc, s0, v120
	s_nop 1
	v_cvt_pk_bf16_f32 v132, v36, v37
	s_nop 1
	v_cvt_pk_bf16_f32 v133, v38, v39
	s_nop 1
	v_cvt_pk_bf16_f32 v134, v4, v5
	s_nop 1
	v_cvt_pk_bf16_f32 v135, v6, v7
	s_nop 1
	v_addc_co_u32_e32 v121, vcc, 0, v121, vcc
	global_store_dwordx4 v[122:123], v[132:135], off offset:256
	s_mov_b64 s[0:1], 0
	s_nop 0
	s_nop 1
	v_cvt_pk_bf16_f32 v132, v96, v97
	s_nop 1
	v_cvt_pk_bf16_f32 v133, v98, v99
	s_nop 1
	v_cvt_pk_bf16_f32 v134, v64, v65
	s_nop 1
	v_cvt_pk_bf16_f32 v135, v66, v67
	global_store_dwordx4 v[120:121], v[132:135], off
	s_nop 1
	v_cvt_pk_bf16_f32 v120, v32, v33
	s_nop 1
	v_cvt_pk_bf16_f32 v121, v34, v35
	s_nop 1
	v_cvt_pk_bf16_f32 v122, v0, v1
	s_nop 1
	v_cvt_pk_bf16_f32 v123, v2, v3
	global_store_dwordx4 v[146:147], v[120:123], off offset:256

.LBB0_547:
	s_waitcnt vmcnt(0)
	s_waitcnt vmcnt(0) lgkmcnt(0)
	s_setprio 0
	s_barrier
	s_mov_b64 s[0:1], exec
	v_readlane_b32 s4, v255, 4
	v_readlane_b32 s5, v255, 5
	s_and_b64 s[4:5], s[0:1], s[4:5]
	s_xor_b64 s[6:7], s[4:5], s[0:1]
	s_mov_b64 exec, s[4:5]
	s_cbranch_execz .LBB0_600
	s_add_i32 s0, 0, 0x25800
	v_mov_b32_e32 v0, s0
	s_waitcnt vmcnt(0) expcnt(0) lgkmcnt(0)
	ds_read_b32 v2, v0
	s_add_i32 s0, 0, 0x25804
	v_mov_b32_e32 v0, s0
	ds_read_b32 v0, v0
	s_waitcnt lgkmcnt(1)
	v_cmp_ne_u32_e32 vcc, 0, v2
	s_cbranch_vccnz .LBB0_563
	s_add_u32 s8, s26, 0xc0200
	s_addc_u32 s9, s27, 0
	s_add_u32 s4, s26, 0xc0400
	s_addc_u32 s5, s27, 0
	s_add_u32 s10, s26, 0xc0500
	s_addc_u32 s11, s27, 0
	s_add_u32 s12, s26, 0xc0600
	s_addc_u32 s13, s27, 0
	s_add_u32 s14, s26, 0xc0700
	s_addc_u32 s15, s27, 0
	s_add_u32 s16, s26, 0xc0800
	s_addc_u32 s17, s27, 0
	s_add_u32 s18, s26, 0xc0900
	s_addc_u32 s19, s27, 0
	s_add_u32 s36, s26, 0xc0a00
	s_addc_u32 s37, s27, 0
	s_add_u32 s40, s26, 0xc0b00
	s_addc_u32 s41, s27, 0
	s_add_u32 s42, s26, 0xc0c00
	s_addc_u32 s43, s27, 0
	s_add_u32 s44, s26, 0xc0d00
	s_addc_u32 s45, s27, 0
	s_add_u32 s50, s26, 0xc0e00
	s_addc_u32 s51, s27, 0
	s_add_u32 s54, s26, 0xc0f00
	s_addc_u32 s55, s27, 0
	s_add_u32 s58, s26, 0xc1000
	s_addc_u32 s59, s27, 0
	s_add_u32 s62, s26, 0xc1100
	s_addc_u32 s63, s27, 0
	s_add_u32 s64, s26, 0xc1200
	v_readlane_b32 s0, v255, 0
	s_addc_u32 s65, s27, 0
	s_mul_i32 s20, s31, s0
	s_add_u32 s66, s26, 0xc1300
	s_mul_i32 s20, s20, s30
	s_addc_u32 s67, s27, 0
	s_mov_b32 s21, 1
	v_mov_b32_e32 v16, 0
	s_branch .LBB0_551

.LBB0_732:
	s_waitcnt vmcnt(0)
	s_setprio 0
	s_barrier
	s_mov_b64 s[6:7], exec
	v_readlane_b32 s0, v255, 4
	v_readlane_b32 s1, v255, 5
	v_readlane_b32 s88, v255, 20
	s_and_b64 s[0:1], s[6:7], s[0:1]
	v_readlane_b32 s89, v255, 21
	s_mov_b64 exec, s[0:1]
	s_cbranch_execz .LBB0_784
	s_add_i32 s0, 0, 0x25800
	v_mov_b32_e32 v0, s0
	s_waitcnt vmcnt(0) expcnt(0) lgkmcnt(0)
	ds_read_b32 v2, v0
	s_add_i32 s0, 0, 0x25804
	v_mov_b32_e32 v0, s0
	ds_read_b32 v0, v0
	s_waitcnt lgkmcnt(1)
	v_cmp_ne_u32_e32 vcc, 0, v2
	s_cbranch_vccnz .LBB0_748
	s_add_u32 s8, s26, 0xc0200
	s_addc_u32 s9, s27, 0
	s_add_u32 s4, s26, 0xc0400
	s_addc_u32 s5, s27, 0
	s_add_u32 s10, s26, 0xc0500
	s_addc_u32 s11, s27, 0
	s_add_u32 s12, s26, 0xc0600
	s_addc_u32 s13, s27, 0
	s_add_u32 s14, s26, 0xc0700
	s_addc_u32 s15, s27, 0
	s_add_u32 s16, s26, 0xc0800
	s_addc_u32 s17, s27, 0
	s_add_u32 s18, s26, 0xc0900
	s_addc_u32 s19, s27, 0
	s_add_u32 s36, s26, 0xc0a00
	s_addc_u32 s37, s27, 0
	s_add_u32 s50, s26, 0xc0b00
	s_addc_u32 s51, s27, 0
	s_add_u32 s60, s26, 0xc0c00
	s_addc_u32 s61, s27, 0
	s_add_u32 s70, s26, 0xc0d00
	s_addc_u32 s71, s27, 0
	s_add_u32 s72, s26, 0xc0e00
	s_addc_u32 s73, s27, 0
	s_add_u32 s74, s26, 0xc0f00
	s_addc_u32 s75, s27, 0
	s_add_u32 s76, s26, 0xc1000
	s_addc_u32 s77, s27, 0
	s_add_u32 s78, s26, 0xc1100
	s_addc_u32 s79, s27, 0
	s_add_u32 s80, s26, 0xc1200
	v_readlane_b32 s0, v255, 0
	s_addc_u32 s81, s27, 0
	s_mul_i32 s20, s31, s0
	s_add_u32 s82, s26, 0xc1300
	s_mul_i32 s20, s20, s30
	s_addc_u32 s83, s27, 0
	s_mov_b32 s21, 1
	v_mov_b32_e32 v16, 0
	s_branch .LBB0_736

.LBB0_787:
	s_waitcnt vmcnt(0)
	s_setprio 0
	s_barrier
	s_mov_b64 s[6:7], exec
	v_readlane_b32 s0, v255, 4
	v_readlane_b32 s1, v255, 5
	s_and_b64 s[0:1], s[6:7], s[0:1]
	s_mov_b64 exec, s[0:1]
	s_cbranch_execz .LBB0_839
	s_add_i32 s0, 0, 0x25800
	v_mov_b32_e32 v0, s0
	s_waitcnt vmcnt(0) expcnt(0) lgkmcnt(0)
	ds_read_b32 v2, v0
	s_add_i32 s0, 0, 0x25804
	v_mov_b32_e32 v0, s0
	ds_read_b32 v0, v0
	s_waitcnt lgkmcnt(1)
	v_cmp_ne_u32_e32 vcc, 0, v2
	s_cbranch_vccnz .LBB0_803
	s_add_u32 s10, s26, 0xc0200
	s_addc_u32 s11, s27, 0
	s_add_u32 s4, s26, 0xc0400
	s_addc_u32 s5, s27, 0
	s_add_u32 s12, s26, 0xc0500
	s_addc_u32 s13, s27, 0
	s_add_u32 s14, s26, 0xc0600
	s_addc_u32 s15, s27, 0
	s_add_u32 s16, s26, 0xc0700
	s_addc_u32 s17, s27, 0
	s_add_u32 s18, s26, 0xc0800
	s_addc_u32 s19, s27, 0
	s_add_u32 s36, s26, 0xc0900
	s_addc_u32 s37, s27, 0
	s_add_u32 s48, s26, 0xc0a00
	s_addc_u32 s49, s27, 0
	s_add_u32 s50, s26, 0xc0b00
	s_addc_u32 s51, s27, 0
	s_add_u32 s52, s26, 0xc0c00
	s_addc_u32 s53, s27, 0
	s_add_u32 s56, s26, 0xc0d00
	s_addc_u32 s57, s27, 0
	s_add_u32 s60, s26, 0xc0e00
	s_addc_u32 s61, s27, 0
	s_add_u32 s66, s26, 0xc0f00
	s_addc_u32 s67, s27, 0
	s_add_u32 s68, s26, 0xc1000
	s_addc_u32 s69, s27, 0
	s_add_u32 s70, s26, 0xc1100
	s_addc_u32 s71, s27, 0
	s_add_u32 s72, s26, 0xc1200
	v_readlane_b32 s0, v255, 0
	s_addc_u32 s73, s27, 0
	s_mul_i32 s20, s31, s0
	s_add_u32 s74, s26, 0xc1300
	s_mul_i32 s20, s20, s30
	s_addc_u32 s75, s27, 0
	s_mov_b32 s21, 1
	v_mov_b32_e32 v16, 0
	s_branch .LBB0_791

.LBB0_839:
	s_or_b64 exec, exec, s[6:7]
	s_waitcnt lgkmcnt(0)
	v_mov_b32_e32 v0, v254
	v_readlane_b32 s0, v255, 10
	s_barrier
	v_cmp_lt_u32_e32 vcc, 0xff, v254
	s_cbranch_vccz .Lprio_skip5
	s_setprio 1
.Lprio_skip5:
	v_readlane_b32 s1, v255, 11
	v_mov_b32_e32 v8, v254
	s_nop 0
	v_mov_b64_e32 v[0:1], s[0:1]
	flat_load_dwordx2 v[0:1], v[0:1] sc0 sc1
	s_waitcnt vmcnt(0)
	v_readlane_b32 s0, v255, 7
	v_readlane_b32 s1, v255, 8
	s_and_b64 vcc, exec, s[0:1]
	s_waitcnt lgkmcnt(0)
	v_readfirstlane_b32 s11, v1
	v_readfirstlane_b32 s20, v8
	v_readfirstlane_b32 s10, v0
	s_cbranch_vccz .LBB0_855
	v_lshlrev_b32_e32 v0, 4, v8
	v_add_u32_e32 v1, 0x2000, v0
	v_ashrrev_i32_e32 v2, 31, v1
	v_lshrrev_b32_e32 v2, 22, v2
	v_add_u32_e32 v2, v1, v2
	v_ashrrev_i32_e32 v9, 10, v2
	v_mul_i32_i24_e32 v2, 0x400, v9
	v_sub_u32_e32 v1, v1, v2
	v_lshrrev_b32_e32 v2, 4, v1
	v_bitop3_b32 v1, v2, v1, 32 bitop3:0x6c
	v_ashrrev_i32_e32 v2, 31, v1
	s_lshr_b32 s4, s3, 29
	v_lshrrev_b32_e32 v2, 26, v2
	s_add_i32 s4, s2, s4
	v_add_u32_e32 v2, v1, v2
	s_and_b32 s5, s4, -8
	s_ashr_i32 s1, s20, 6
	v_ashrrev_i32_e32 v10, 6, v2
	v_and_b32_e32 v2, 0xc0, v2
	s_sub_i32 s5, s2, s5
	s_ashr_i32 s0, s20, 8
	s_lshl_b32 s21, s1, 10
	v_sub_u32_e32 v1, v1, v2
	v_mov_b32_e32 v2, 1
	s_lshl_b32 s7, s5, 5
	s_ashr_i32 s4, s4, 3
	v_ashrrev_i16_sdwa v1, v2, sext(v1) dst_sel:DWORD dst_unused:UNUSED_PAD src0_sel:DWORD src1_sel:BYTE_0
	s_mul_i32 s6, s5, 33
	s_cmp_lt_i32 s5, 0
	v_bfe_i32 v12, v1, 0, 16
	v_bfe_i32 v1, v8, 27, 1
	s_cselect_b32 s5, s6, s7
	v_lshrrev_b32_e32 v1, 22, v1
	s_add_i32 s4, s5, s4
	v_add_u32_e32 v1, v0, v1
	s_ashr_i32 s5, s4, 31
	v_and_b32_e32 v1, 0xfffffc00, v1
	s_lshr_b32 s5, s5, 26
	v_sub_u32_e32 v0, v0, v1
	s_add_i32 s5, s4, s5
	v_lshrrev_b32_e32 v1, 4, v0
	s_ashr_i32 s6, s5, 6
	s_andn2_b32 s5, s5, 63
	v_bitop3_b32 v1, v1, v0, 32 bitop3:0x6c
	v_ashrrev_i32_e32 v0, 31, v0
	s_sub_i32 s5, s4, s5
	v_lshrrev_b32_e32 v0, 26, v0
	s_bfe_i32 s4, s5, 0x80000
	v_add_u32_e32 v0, v1, v0
	s_bfe_u32 s4, s4, 0x3000c
	v_lshlrev_b32_e32 v3, 3, v9
	v_ashrrev_i32_e32 v13, 6, v0
	v_ashrrev_i32_e32 v0, 31, v8
	s_add_i32 s7, s5, s4
	v_and_b32_e32 v3, 0xffff0, v3
	v_lshlrev_b32_e32 v4, 5, v9
	v_lshrrev_b32_e32 v0, 26, v0
	s_bfe_i32 s4, s7, 0x80000
	s_and_b32 s7, s7, 0xf8
	v_add_u32_e32 v3, v10, v3
	v_and_b32_e32 v11, 32, v4
	v_add_u32_e32 v0, v8, v0
	s_sub_i32 s5, s5, s7
	v_lshl_or_b32 v3, v3, 11, v11
	v_ashrrev_i32_e32 v14, 6, v0
	s_lshl_b32 s6, s6, 3
	s_sext_i32_i16 s4, s4
	s_sext_i32_i8 s5, s5
	v_add_lshl_u32 v128, v3, v12, 1
	v_lshlrev_b32_e32 v3, 5, v14
	s_lshr_b32 s4, s4, 3
	s_add_i32 s72, s6, s5
	v_lshlrev_b32_e32 v0, 3, v14
	v_and_b32_e32 v15, 32, v3
	v_mul_i32_i24_e32 v3, 64, v13
	s_ashr_i32 s73, s72, 31
	s_bfe_i64 s[12:13], s[4:5], 0x100000
	v_and_b32_e32 v0, 0xffff0, v0
	v_sub_u32_e32 v1, v1, v3
	s_lshl_b64 s[6:7], s[72:73], 20
	s_lshl_b64 s[12:13], s[12:13], 20
	v_add_u32_e32 v0, v13, v0
	v_ashrrev_i16_sdwa v1, v2, sext(v1) dst_sel:DWORD dst_unused:UNUSED_PAD src0_sel:DWORD src1_sel:BYTE_0
	s_add_u32 s50, s64, s12
	v_lshl_or_b32 v0, v0, 11, v15
	v_bfe_i32 v16, v1, 0, 16
	s_addc_u32 s51, s65, s13
	s_add_i32 s23, s21, 0
	v_add_lshl_u32 v130, v0, v16, 1
	s_add_i32 m0, s23, 0x10000
	s_load_dwordx2 s[12:13], s[88:89], 0x168
	global_load_lds_dwordx4 v130, s[50:51]
	s_add_i32 m0, s23, 0x12000
	s_add_u32 s74, s8, s6
	global_load_lds_dwordx4 v128, s[50:51]
	s_addc_u32 s75, s9, s7
	s_mov_b32 m0, s23
	s_add_i32 s24, s23, 0x2000
	global_load_lds_dwordx4 v130, s[74:75]
	s_mov_b32 m0, s24
	s_add_u32 s6, s50, 0x80000
	global_load_lds_dwordx4 v128, s[74:75]
	s_addc_u32 s7, s51, 0
	s_add_i32 m0, s23, 0x14000
	v_mov_b32_e32 v131, 0
	global_load_lds_dwordx4 v130, s[6:7]
	s_add_i32 m0, s23, 0x16000
	v_mov_b32_e32 v129, v131
	global_load_lds_dwordx4 v128, s[6:7]
	s_add_u32 s6, s74, 0x80000
	s_addc_u32 s7, s75, 0
	s_add_i32 s25, s23, 0x4000
	s_mov_b32 m0, s25
	s_add_i32 s28, s23, 0x6000
	global_load_lds_dwordx4 v130, s[6:7]
	s_mov_b32 m0, s28
	s_mov_b32 s29, 0
	global_load_lds_dwordx4 v128, s[6:7]
	v_lshl_add_u64 v[6:7], s[50:51], 0, v[130:131]
	v_lshl_add_u64 v[4:5], s[50:51], 0, v[128:129]
	v_lshl_add_u64 v[2:3], s[74:75], 0, v[130:131]
	s_cmp_lg_u32 s0, 1
	v_lshl_add_u64 v[0:1], s[74:75], 0, v[128:129]
	s_cbranch_scc1 .LBB0_842
	s_barrier

.LBB0_850:
	ds_read_b128 v[140:143], v147
	ds_read_b128 v[150:153], v147 offset:1024
	ds_read_b128 v[154:157], v147 offset:2048
	ds_read_b128 v[158:161], v147 offset:3072
	s_add_u32 s76, s74, 0x100
	s_addc_u32 s77, s75, 0
	s_cmp_eq_u32 s73, 28
	s_cselect_b32 s5, s0, s77
	s_cselect_b32 s4, s1, s76
	s_cselect_b32 s51, s46, s67
	s_cselect_b32 s50, s47, s61
	v_lshl_add_u64 v[194:195], s[74:75], 0, v[132:133]
	s_add_i32 m0, s23, 0xc000
	ds_read_b128 v[162:165], v148
	ds_read_b128 v[166:169], v148 offset:1024
	ds_read_b128 v[170:173], v148 offset:2048
	ds_read_b128 v[174:177], v148 offset:3072
	ds_read_b128 v[178:181], v148 offset:4096
	ds_read_b128 v[182:185], v148 offset:5120
	ds_read_b128 v[186:189], v148 offset:6144
	ds_read_b128 v[190:193], v148 offset:7168
	global_load_lds_dwordx4 v[194:195], off
	v_lshl_add_u64 v[194:195], s[74:75], 0, v[134:135]
	s_add_i32 m0, s23, 0xe000
	s_nop 0
	global_load_lds_dwordx4 v[194:195], off
	s_waitcnt lgkmcnt(8)
	s_barrier
	s_waitcnt lgkmcnt(0)
	s_waitcnt lgkmcnt(0)
	v_mfma_f32_16x16x32_bf16 v[124:127], v[140:143], v[162:165], v[124:127]
	v_mfma_f32_16x16x32_bf16 v[100:103], v[154:157], v[162:165], v[100:103]
	v_mfma_f32_16x16x32_bf16 v[120:123], v[140:143], v[170:173], v[120:123]
	v_mfma_f32_16x16x32_bf16 v[96:99], v[154:157], v[170:173], v[96:99]
	v_mfma_f32_16x16x32_bf16 v[116:119], v[140:143], v[178:181], v[116:119]
	v_mfma_f32_16x16x32_bf16 v[88:91], v[154:157], v[178:181], v[88:91]
	v_mfma_f32_16x16x32_bf16 v[112:115], v[140:143], v[186:189], v[112:115]
	v_mfma_f32_16x16x32_bf16 v[80:83], v[154:157], v[186:189], v[80:83]
	v_mfma_f32_16x16x32_bf16 v[124:127], v[150:153], v[166:169], v[124:127]
	v_mfma_f32_16x16x32_bf16 v[100:103], v[158:161], v[166:169], v[100:103]
	v_mfma_f32_16x16x32_bf16 v[120:123], v[150:153], v[174:177], v[120:123]
	v_mfma_f32_16x16x32_bf16 v[96:99], v[158:161], v[174:177], v[96:99]
	v_mfma_f32_16x16x32_bf16 v[116:119], v[150:153], v[182:185], v[116:119]
	v_mfma_f32_16x16x32_bf16 v[88:91], v[158:161], v[182:185], v[88:91]
	v_mfma_f32_16x16x32_bf16 v[112:115], v[150:153], v[190:193], v[112:115]
	v_mfma_f32_16x16x32_bf16 v[80:83], v[158:161], v[190:193], v[80:83]
	s_barrier
	s_add_i32 s42, s37, s21
	v_lshl_add_u64 v[210:211], s[50:51], 0, v[130:131]
	s_mov_b32 m0, s42
	ds_read_b128 v[194:197], v149
	ds_read_b128 v[198:201], v149 offset:1024
	ds_read_b128 v[202:205], v149 offset:2048
	ds_read_b128 v[206:209], v149 offset:3072
	global_load_lds_dwordx4 v[210:211], off
	v_lshl_add_u64 v[212:213], s[50:51], 0, v[128:129]
	s_add_i32 m0, s42, 0x2000
	s_nop 0
	global_load_lds_dwordx4 v[212:213], off
	s_barrier
	s_waitcnt lgkmcnt(0)
	s_waitcnt lgkmcnt(0)
	v_mfma_f32_16x16x32_bf16 v[68:71], v[194:197], v[162:165], v[68:71]
	v_mfma_f32_16x16x32_bf16 v[40:43], v[202:205], v[162:165], v[40:43]
	v_mfma_f32_16x16x32_bf16 v[60:63], v[194:197], v[170:173], v[60:63]
	v_mfma_f32_16x16x32_bf16 v[32:35], v[202:205], v[170:173], v[32:35]
	v_mfma_f32_16x16x32_bf16 v[52:55], v[194:197], v[178:181], v[52:55]
	v_mfma_f32_16x16x32_bf16 v[24:27], v[202:205], v[178:181], v[24:27]
	v_mfma_f32_16x16x32_bf16 v[48:51], v[194:197], v[186:189], v[48:51]
	v_mfma_f32_16x16x32_bf16 v[16:19], v[202:205], v[186:189], v[16:19]
	v_mfma_f32_16x16x32_bf16 v[68:71], v[198:201], v[166:169], v[68:71]
	v_mfma_f32_16x16x32_bf16 v[40:43], v[206:209], v[166:169], v[40:43]
	v_mfma_f32_16x16x32_bf16 v[60:63], v[198:201], v[174:177], v[60:63]
	v_mfma_f32_16x16x32_bf16 v[32:35], v[206:209], v[174:177], v[32:35]
	v_mfma_f32_16x16x32_bf16 v[52:55], v[198:201], v[182:185], v[52:55]
	v_mfma_f32_16x16x32_bf16 v[24:27], v[206:209], v[182:185], v[24:27]
	v_mfma_f32_16x16x32_bf16 v[48:51], v[198:201], v[190:193], v[48:51]
	v_mfma_f32_16x16x32_bf16 v[16:19], v[206:209], v[190:193], v[16:19]
	s_mov_b32 m0, s23
	v_lshl_add_u64 v[214:215], s[4:5], 0, v[130:131]
	s_barrier
	ds_read_b128 v[162:165], v148 offset:16384
	ds_read_b128 v[166:169], v148 offset:17408
	ds_read_b128 v[170:173], v148 offset:18432
	ds_read_b128 v[174:177], v148 offset:19456
	ds_read_b128 v[178:181], v148 offset:20480
	ds_read_b128 v[182:185], v148 offset:21504
	ds_read_b128 v[186:189], v148 offset:22528
	ds_read_b128 v[190:193], v148 offset:23552
	global_load_lds_dwordx4 v[214:215], off
	v_lshl_add_u64 v[216:217], s[4:5], 0, v[128:129]
	s_mov_b32 m0, s24
	s_nop 0
	global_load_lds_dwordx4 v[216:217], off
	s_barrier
	s_waitcnt lgkmcnt(0)
	s_waitcnt lgkmcnt(0)
	v_mfma_f32_16x16x32_bf16 v[108:111], v[140:143], v[162:165], v[108:111]
	v_mfma_f32_16x16x32_bf16 v[76:79], v[154:157], v[162:165], v[76:79]
	v_mfma_f32_16x16x32_bf16 v[104:107], v[140:143], v[170:173], v[104:107]
	v_mfma_f32_16x16x32_bf16 v[72:75], v[154:157], v[170:173], v[72:75]
	v_mfma_f32_16x16x32_bf16 v[92:95], v[140:143], v[178:181], v[92:95]
	v_mfma_f32_16x16x32_bf16 v[64:67], v[154:157], v[178:181], v[64:67]
	v_mfma_f32_16x16x32_bf16 v[84:87], v[140:143], v[186:189], v[84:87]
	v_mfma_f32_16x16x32_bf16 v[56:59], v[154:157], v[186:189], v[56:59]
	v_mfma_f32_16x16x32_bf16 v[108:111], v[150:153], v[166:169], v[108:111]
	v_mfma_f32_16x16x32_bf16 v[76:79], v[158:161], v[166:169], v[76:79]
	v_mfma_f32_16x16x32_bf16 v[104:107], v[150:153], v[174:177], v[104:107]
	v_mfma_f32_16x16x32_bf16 v[72:75], v[158:161], v[174:177], v[72:75]
	v_mfma_f32_16x16x32_bf16 v[92:95], v[150:153], v[182:185], v[92:95]
	v_mfma_f32_16x16x32_bf16 v[64:67], v[158:161], v[182:185], v[64:67]
	v_mfma_f32_16x16x32_bf16 v[84:87], v[150:153], v[190:193], v[84:87]
	v_mfma_f32_16x16x32_bf16 v[56:59], v[158:161], v[190:193], v[56:59]
	s_barrier
	s_add_u32 s42, s50, 0x80000
	s_addc_u32 s43, s51, 0
	s_add_i32 s44, s40, s21
	v_lshl_add_u64 v[140:141], s[42:43], 0, v[130:131]
	s_mov_b32 m0, s44
	s_nop 0
	global_load_lds_dwordx4 v[140:141], off
	v_lshl_add_u64 v[140:141], s[42:43], 0, v[128:129]
	s_add_i32 m0, s44, 0x2000
	s_nop 0
	global_load_lds_dwordx4 v[140:141], off
	s_waitcnt vmcnt(6)
	s_barrier
	v_mfma_f32_16x16x32_bf16 v[44:47], v[194:197], v[162:165], v[44:47]
	v_mfma_f32_16x16x32_bf16 v[12:15], v[202:205], v[162:165], v[12:15]
	v_mfma_f32_16x16x32_bf16 v[36:39], v[194:197], v[170:173], v[36:39]
	v_mfma_f32_16x16x32_bf16 v[8:11], v[202:205], v[170:173], v[8:11]
	v_mfma_f32_16x16x32_bf16 v[28:31], v[194:197], v[178:181], v[28:31]
	v_mfma_f32_16x16x32_bf16 v[4:7], v[202:205], v[178:181], v[4:7]
	v_mfma_f32_16x16x32_bf16 v[20:23], v[194:197], v[186:189], v[20:23]
	v_mfma_f32_16x16x32_bf16 v[0:3], v[202:205], v[186:189], v[0:3]
	v_mfma_f32_16x16x32_bf16 v[44:47], v[198:201], v[166:169], v[44:47]
	v_mfma_f32_16x16x32_bf16 v[12:15], v[206:209], v[166:169], v[12:15]
	v_mfma_f32_16x16x32_bf16 v[36:39], v[198:201], v[174:177], v[36:39]
	v_mfma_f32_16x16x32_bf16 v[8:11], v[206:209], v[174:177], v[8:11]
	v_mfma_f32_16x16x32_bf16 v[28:31], v[198:201], v[182:185], v[28:31]
	v_mfma_f32_16x16x32_bf16 v[4:7], v[206:209], v[182:185], v[4:7]
	v_mfma_f32_16x16x32_bf16 v[20:23], v[198:201], v[190:193], v[20:23]
	v_mfma_f32_16x16x32_bf16 v[0:3], v[206:209], v[190:193], v[0:3]
	s_add_i32 s42, 0, 0x18000
	v_add_u32_e32 v158, s42, v145
	s_barrier
	ds_read_b128 v[140:143], v158
	ds_read_b128 v[150:153], v158 offset:1024
	ds_read_b128 v[154:157], v158 offset:2048
	ds_read_b128 v[158:161], v158 offset:3072
	s_add_u32 s4, s4, 0x80000
	s_addc_u32 s5, s5, 0
	s_mov_b32 m0, s25
	v_lshl_add_u64 v[194:195], s[4:5], 0, v[130:131]
	ds_read_b128 v[162:165], v148 offset:32768
	ds_read_b128 v[166:169], v148 offset:33792
	ds_read_b128 v[170:173], v148 offset:34816
	ds_read_b128 v[174:177], v148 offset:35840
	ds_read_b128 v[178:181], v148 offset:36864
	ds_read_b128 v[182:185], v148 offset:37888
	ds_read_b128 v[186:189], v148 offset:38912
	ds_read_b128 v[190:193], v148 offset:39936
	global_load_lds_dwordx4 v[194:195], off
	v_lshl_add_u64 v[194:195], s[4:5], 0, v[128:129]
	s_mov_b32 m0, s28
	s_nop 0
	global_load_lds_dwordx4 v[194:195], off
	s_waitcnt lgkmcnt(8)
	s_barrier
	s_waitcnt lgkmcnt(0)
	s_waitcnt lgkmcnt(0)
	v_mfma_f32_16x16x32_bf16 v[124:127], v[140:143], v[162:165], v[124:127]
	v_mfma_f32_16x16x32_bf16 v[100:103], v[154:157], v[162:165], v[100:103]
	v_mfma_f32_16x16x32_bf16 v[120:123], v[140:143], v[170:173], v[120:123]
	v_mfma_f32_16x16x32_bf16 v[96:99], v[154:157], v[170:173], v[96:99]
	v_mfma_f32_16x16x32_bf16 v[116:119], v[140:143], v[178:181], v[116:119]
	v_mfma_f32_16x16x32_bf16 v[88:91], v[154:157], v[178:181], v[88:91]
	v_mfma_f32_16x16x32_bf16 v[112:115], v[140:143], v[186:189], v[112:115]
	v_mfma_f32_16x16x32_bf16 v[80:83], v[154:157], v[186:189], v[80:83]
	v_mfma_f32_16x16x32_bf16 v[124:127], v[150:153], v[166:169], v[124:127]
	v_mfma_f32_16x16x32_bf16 v[100:103], v[158:161], v[166:169], v[100:103]
	v_mfma_f32_16x16x32_bf16 v[120:123], v[150:153], v[174:177], v[120:123]
	v_mfma_f32_16x16x32_bf16 v[96:99], v[158:161], v[174:177], v[96:99]
	v_mfma_f32_16x16x32_bf16 v[116:119], v[150:153], v[182:185], v[116:119]
	v_mfma_f32_16x16x32_bf16 v[88:91], v[158:161], v[182:185], v[88:91]
	v_mfma_f32_16x16x32_bf16 v[112:115], v[150:153], v[190:193], v[112:115]
	v_mfma_f32_16x16x32_bf16 v[80:83], v[158:161], v[190:193], v[80:83]
	s_barrier
	s_add_i32 s43, 0, 0x1c000
	s_add_i32 s4, s42, s21
	v_add_u32_e32 v206, s43, v145
	v_lshl_add_u64 v[210:211], v[210:211], 0, s[16:17]
	s_mov_b32 m0, s4
	ds_read_b128 v[194:197], v206
	ds_read_b128 v[198:201], v206 offset:1024
	ds_read_b128 v[202:205], v206 offset:2048
	ds_read_b128 v[206:209], v206 offset:3072
	global_load_lds_dwordx4 v[210:211], off
	v_lshl_add_u64 v[210:211], v[212:213], 0, s[16:17]
	s_add_i32 m0, s4, 0x2000
	s_nop 0
	global_load_lds_dwordx4 v[210:211], off
	s_barrier
	s_waitcnt lgkmcnt(0)
	s_waitcnt lgkmcnt(0)
	v_mfma_f32_16x16x32_bf16 v[68:71], v[194:197], v[162:165], v[68:71]
	v_mfma_f32_16x16x32_bf16 v[40:43], v[202:205], v[162:165], v[40:43]
	v_mfma_f32_16x16x32_bf16 v[60:63], v[194:197], v[170:173], v[60:63]
	v_mfma_f32_16x16x32_bf16 v[32:35], v[202:205], v[170:173], v[32:35]
	v_mfma_f32_16x16x32_bf16 v[52:55], v[194:197], v[178:181], v[52:55]
	v_mfma_f32_16x16x32_bf16 v[24:27], v[202:205], v[178:181], v[24:27]
	v_mfma_f32_16x16x32_bf16 v[48:51], v[194:197], v[186:189], v[48:51]
	v_mfma_f32_16x16x32_bf16 v[16:19], v[202:205], v[186:189], v[16:19]
	v_mfma_f32_16x16x32_bf16 v[68:71], v[198:201], v[166:169], v[68:71]
	v_mfma_f32_16x16x32_bf16 v[40:43], v[206:209], v[166:169], v[40:43]
	v_mfma_f32_16x16x32_bf16 v[60:63], v[198:201], v[174:177], v[60:63]
	v_mfma_f32_16x16x32_bf16 v[32:35], v[206:209], v[174:177], v[32:35]
	v_mfma_f32_16x16x32_bf16 v[52:55], v[198:201], v[182:185], v[52:55]
	v_mfma_f32_16x16x32_bf16 v[24:27], v[206:209], v[182:185], v[24:27]
	v_mfma_f32_16x16x32_bf16 v[48:51], v[198:201], v[190:193], v[48:51]
	v_mfma_f32_16x16x32_bf16 v[16:19], v[206:209], v[190:193], v[16:19]
	s_mov_b32 m0, s33
	v_lshl_add_u64 v[210:211], v[214:215], 0, s[16:17]
	s_barrier
	ds_read_b128 v[162:165], v148 offset:49152
	ds_read_b128 v[166:169], v148 offset:50176
	ds_read_b128 v[170:173], v148 offset:51200
	ds_read_b128 v[174:177], v148 offset:52224
	ds_read_b128 v[178:181], v148 offset:53248
	ds_read_b128 v[182:185], v148 offset:54272
	ds_read_b128 v[186:189], v148 offset:55296
	ds_read_b128 v[190:193], v148 offset:56320
	global_load_lds_dwordx4 v[210:211], off
	v_lshl_add_u64 v[210:211], v[216:217], 0, s[16:17]
	s_mov_b32 m0, s36
	s_nop 0
	global_load_lds_dwordx4 v[210:211], off
	s_barrier
	s_waitcnt lgkmcnt(0)
	s_waitcnt lgkmcnt(0)
	v_mfma_f32_16x16x32_bf16 v[108:111], v[140:143], v[162:165], v[108:111]
	v_mfma_f32_16x16x32_bf16 v[76:79], v[154:157], v[162:165], v[76:79]
	v_mfma_f32_16x16x32_bf16 v[104:107], v[140:143], v[170:173], v[104:107]
	v_mfma_f32_16x16x32_bf16 v[72:75], v[154:157], v[170:173], v[72:75]
	v_mfma_f32_16x16x32_bf16 v[92:95], v[140:143], v[178:181], v[92:95]
	v_mfma_f32_16x16x32_bf16 v[64:67], v[154:157], v[178:181], v[64:67]
	v_mfma_f32_16x16x32_bf16 v[84:87], v[140:143], v[186:189], v[84:87]
	v_mfma_f32_16x16x32_bf16 v[56:59], v[154:157], v[186:189], v[56:59]
	v_mfma_f32_16x16x32_bf16 v[108:111], v[150:153], v[166:169], v[108:111]
	v_mfma_f32_16x16x32_bf16 v[76:79], v[158:161], v[166:169], v[76:79]
	v_mfma_f32_16x16x32_bf16 v[104:107], v[150:153], v[174:177], v[104:107]
	v_mfma_f32_16x16x32_bf16 v[72:75], v[158:161], v[174:177], v[72:75]
	v_mfma_f32_16x16x32_bf16 v[92:95], v[150:153], v[182:185], v[92:95]
	v_mfma_f32_16x16x32_bf16 v[64:67], v[158:161], v[182:185], v[64:67]
	v_mfma_f32_16x16x32_bf16 v[84:87], v[150:153], v[190:193], v[84:87]
	v_mfma_f32_16x16x32_bf16 v[56:59], v[158:161], v[190:193], v[56:59]
	s_barrier
	s_add_u32 s4, s50, 0x80080
	s_addc_u32 s5, s51, 0
	s_add_i32 s42, s43, s21
	v_lshl_add_u64 v[140:141], s[4:5], 0, v[130:131]
	s_mov_b32 m0, s42
	s_nop 0
	global_load_lds_dwordx4 v[140:141], off
	v_lshl_add_u64 v[140:141], s[4:5], 0, v[128:129]
	s_add_i32 m0, s42, 0x2000
	s_nop 0
	global_load_lds_dwordx4 v[140:141], off
	s_waitcnt vmcnt(6)
	s_barrier
	v_mfma_f32_16x16x32_bf16 v[44:47], v[194:197], v[162:165], v[44:47]
	v_mfma_f32_16x16x32_bf16 v[12:15], v[202:205], v[162:165], v[12:15]
	v_mfma_f32_16x16x32_bf16 v[36:39], v[194:197], v[170:173], v[36:39]
	v_mfma_f32_16x16x32_bf16 v[8:11], v[202:205], v[170:173], v[8:11]
	v_mfma_f32_16x16x32_bf16 v[28:31], v[194:197], v[178:181], v[28:31]
	v_mfma_f32_16x16x32_bf16 v[4:7], v[202:205], v[178:181], v[4:7]
	v_mfma_f32_16x16x32_bf16 v[20:23], v[194:197], v[186:189], v[20:23]
	v_mfma_f32_16x16x32_bf16 v[0:3], v[202:205], v[186:189], v[0:3]
	v_mfma_f32_16x16x32_bf16 v[44:47], v[198:201], v[166:169], v[44:47]
	v_mfma_f32_16x16x32_bf16 v[12:15], v[206:209], v[166:169], v[12:15]
	v_mfma_f32_16x16x32_bf16 v[36:39], v[198:201], v[174:177], v[36:39]
	v_mfma_f32_16x16x32_bf16 v[8:11], v[206:209], v[174:177], v[8:11]
	v_mfma_f32_16x16x32_bf16 v[28:31], v[198:201], v[182:185], v[28:31]
	v_mfma_f32_16x16x32_bf16 v[4:7], v[206:209], v[182:185], v[4:7]
	v_mfma_f32_16x16x32_bf16 v[20:23], v[198:201], v[190:193], v[20:23]
	v_mfma_f32_16x16x32_bf16 v[0:3], v[206:209], v[190:193], v[0:3]
	s_add_i32 s73, s73, 2
	s_add_u32 s61, s61, 0x100
	s_addc_u32 s67, s67, 0
	s_cmp_gt_u32 s73, 29
	s_mov_b64 s[74:75], s[76:77]
	s_barrier
	s_cbranch_scc0 .LBB0_850
	v_lshl_or_b32 v140, s41, 8, v146
	v_lshl_add_u32 v143, s72, 8, v144
	v_lshlrev_b32_e32 v140, 2, v140
	v_lshl_add_u32 v143, v143, 13, v140
	s_mov_b32 s41, s60
	s_mov_b32 s72, s66
	s_mov_b64 s[50:51], s[70:71]
	s_mov_b64 s[74:75], s[68:69]
	v_mov_b32_e32 v141, v143
	v_mov_b32_e32 v142, v143
	global_load_dwordx4 v[166:169], v140, s[14:15] offset:0
	global_load_dwordx4 v[150:153], v141, s[10:11] offset:0
	v_add_u32_e32 v141, 0x20000, v141
	global_load_dwordx4 v[154:157], v141, s[10:11] offset:0
	v_add_u32_e32 v141, 0x20000, v141
	global_load_dwordx4 v[158:161], v141, s[10:11] offset:0
	v_add_u32_e32 v141, 0x20000, v141
	global_load_dwordx4 v[162:165], v141, s[10:11] offset:0
	v_add_u32_e32 v141, 0xa0000, v141
	s_waitcnt vmcnt(3)
	v_pk_fma_f32 v[150:151], v[124:125], v[166:167], v[150:151]
	v_pk_fma_f32 v[152:153], v[126:127], v[168:169], v[152:153]
	global_store_dwordx4 v142, v[150:153], s[12:13] offset:0
	v_add_u32_e32 v142, 0x20000, v142
	global_load_dwordx4 v[150:153], v141, s[10:11] offset:0
	v_add_u32_e32 v141, 0x20000, v141
	s_waitcnt vmcnt(4)
	v_pk_fma_f32 v[154:155], v[120:121], v[166:167], v[154:155]
	v_pk_fma_f32 v[156:157], v[122:123], v[168:169], v[156:157]
	global_store_dwordx4 v142, v[154:157], s[12:13] offset:0
	v_add_u32_e32 v142, 0x20000, v142
	global_load_dwordx4 v[154:157], v141, s[10:11] offset:0
	v_add_u32_e32 v141, 0x20000, v141
	s_waitcnt vmcnt(5)
	v_pk_fma_f32 v[158:159], v[116:117], v[166:167], v[158:159]
	v_pk_fma_f32 v[160:161], v[118:119], v[168:169], v[160:161]
	global_store_dwordx4 v142, v[158:161], s[12:13] offset:0
	v_add_u32_e32 v142, 0x20000, v142
	global_load_dwordx4 v[158:161], v141, s[10:11] offset:0
	v_add_u32_e32 v141, 0x20000, v141
	s_waitcnt vmcnt(6)
	v_pk_fma_f32 v[162:163], v[112:113], v[166:167], v[162:163]
	v_pk_fma_f32 v[164:165], v[114:115], v[168:169], v[164:165]
	global_store_dwordx4 v142, v[162:165], s[12:13] offset:0
	v_add_u32_e32 v142, 0xa0000, v142
	global_load_dwordx4 v[162:165], v141, s[10:11] offset:0
	v_add_u32_e32 v141, 0x20000, v141
	s_waitcnt vmcnt(6)
	v_pk_fma_f32 v[150:151], v[108:109], v[166:167], v[150:151]
	v_pk_fma_f32 v[152:153], v[110:111], v[168:169], v[152:153]
	global_store_dwordx4 v142, v[150:153], s[12:13] offset:0
	v_add_u32_e32 v142, 0x20000, v142
	s_waitcnt vmcnt(5)
	v_pk_fma_f32 v[154:155], v[104:105], v[166:167], v[154:155]
	v_pk_fma_f32 v[156:157], v[106:107], v[168:169], v[156:157]
	global_store_dwordx4 v142, v[154:157], s[12:13] offset:0
	v_add_u32_e32 v142, 0x20000, v142
	s_waitcnt vmcnt(4)
	v_pk_fma_f32 v[158:159], v[92:93], v[166:167], v[158:159]
	v_pk_fma_f32 v[160:161], v[94:95], v[168:169], v[160:161]
	global_store_dwordx4 v142, v[158:161], s[12:13] offset:0
	v_add_u32_e32 v142, 0x20000, v142
	s_waitcnt vmcnt(3)
	v_pk_fma_f32 v[162:163], v[84:85], v[166:167], v[162:163]
	v_pk_fma_f32 v[164:165], v[86:87], v[168:169], v[164:165]
	global_store_dwordx4 v142, v[162:165], s[12:13] offset:0
	v_add_u32_e32 v142, 0x20000, v142
	v_mov_b32_e32 v141, v143
	v_mov_b32_e32 v142, v143
	global_load_dwordx4 v[166:169], v140, s[14:15] offset:64
	global_load_dwordx4 v[150:153], v141, s[10:11] offset:64
	v_add_u32_e32 v141, 0x20000, v141
	global_load_dwordx4 v[154:157], v141, s[10:11] offset:64
	v_add_u32_e32 v141, 0x20000, v141
	global_load_dwordx4 v[158:161], v141, s[10:11] offset:64
	v_add_u32_e32 v141, 0x20000, v141
	global_load_dwordx4 v[162:165], v141, s[10:11] offset:64
	v_add_u32_e32 v141, 0xa0000, v141
	s_waitcnt vmcnt(3)
	v_pk_fma_f32 v[150:151], v[100:101], v[166:167], v[150:151]
	v_pk_fma_f32 v[152:153], v[102:103], v[168:169], v[152:153]
	global_store_dwordx4 v142, v[150:153], s[12:13] offset:64
	v_add_u32_e32 v142, 0x20000, v142
	global_load_dwordx4 v[150:153], v141, s[10:11] offset:64
	v_add_u32_e32 v141, 0x20000, v141
	s_waitcnt vmcnt(4)
	v_pk_fma_f32 v[154:155], v[96:97], v[166:167], v[154:155]
	v_pk_fma_f32 v[156:157], v[98:99], v[168:169], v[156:157]
	global_store_dwordx4 v142, v[154:157], s[12:13] offset:64
	v_add_u32_e32 v142, 0x20000, v142
	global_load_dwordx4 v[154:157], v141, s[10:11] offset:64
	v_add_u32_e32 v141, 0x20000, v141
	s_waitcnt vmcnt(5)
	v_pk_fma_f32 v[158:159], v[88:89], v[166:167], v[158:159]
	v_pk_fma_f32 v[160:161], v[90:91], v[168:169], v[160:161]
	global_store_dwordx4 v142, v[158:161], s[12:13] offset:64
	v_add_u32_e32 v142, 0x20000, v142
	global_load_dwordx4 v[158:161], v141, s[10:11] offset:64
	v_add_u32_e32 v141, 0x20000, v141
	s_waitcnt vmcnt(6)
	v_pk_fma_f32 v[162:163], v[80:81], v[166:167], v[162:163]
	v_pk_fma_f32 v[164:165], v[82:83], v[168:169], v[164:165]
	global_store_dwordx4 v142, v[162:165], s[12:13] offset:64
	v_add_u32_e32 v142, 0xa0000, v142
	global_load_dwordx4 v[162:165], v141, s[10:11] offset:64
	v_add_u32_e32 v141, 0x20000, v141
	s_waitcnt vmcnt(6)
	v_pk_fma_f32 v[150:151], v[76:77], v[166:167], v[150:151]
	v_pk_fma_f32 v[152:153], v[78:79], v[168:169], v[152:153]
	global_store_dwordx4 v142, v[150:153], s[12:13] offset:64
	v_add_u32_e32 v142, 0x20000, v142
	s_waitcnt vmcnt(5)
	v_pk_fma_f32 v[154:155], v[72:73], v[166:167], v[154:155]
	v_pk_fma_f32 v[156:157], v[74:75], v[168:169], v[156:157]
	global_store_dwordx4 v142, v[154:157], s[12:13] offset:64
	v_add_u32_e32 v142, 0x20000, v142
	s_waitcnt vmcnt(4)
	v_pk_fma_f32 v[158:159], v[64:65], v[166:167], v[158:159]
	v_pk_fma_f32 v[160:161], v[66:67], v[168:169], v[160:161]
	global_store_dwordx4 v142, v[158:161], s[12:13] offset:64
	v_add_u32_e32 v142, 0x20000, v142
	s_waitcnt vmcnt(3)
	v_pk_fma_f32 v[162:163], v[56:57], v[166:167], v[162:163]
	v_pk_fma_f32 v[164:165], v[58:59], v[168:169], v[164:165]
	global_store_dwordx4 v142, v[162:165], s[12:13] offset:64
	v_add_u32_e32 v142, 0x20000, v142
	v_mov_b32_e32 v141, v143
	v_mov_b32_e32 v142, v143
	global_load_dwordx4 v[166:169], v140, s[14:15] offset:512
	global_load_dwordx4 v[150:153], v141, s[10:11] offset:512
	v_add_u32_e32 v141, 0x20000, v141
	global_load_dwordx4 v[154:157], v141, s[10:11] offset:512
	v_add_u32_e32 v141, 0x20000, v141
	global_load_dwordx4 v[158:161], v141, s[10:11] offset:512
	v_add_u32_e32 v141, 0x20000, v141
	global_load_dwordx4 v[162:165], v141, s[10:11] offset:512
	v_add_u32_e32 v141, 0xa0000, v141
	s_waitcnt vmcnt(3)
	v_pk_fma_f32 v[150:151], v[68:69], v[166:167], v[150:151]
	v_pk_fma_f32 v[152:153], v[70:71], v[168:169], v[152:153]
	global_store_dwordx4 v142, v[150:153], s[12:13] offset:512
	v_add_u32_e32 v142, 0x20000, v142
	global_load_dwordx4 v[150:153], v141, s[10:11] offset:512
	v_add_u32_e32 v141, 0x20000, v141
	s_waitcnt vmcnt(4)
	v_pk_fma_f32 v[154:155], v[60:61], v[166:167], v[154:155]
	v_pk_fma_f32 v[156:157], v[62:63], v[168:169], v[156:157]
	global_store_dwordx4 v142, v[154:157], s[12:13] offset:512
	v_add_u32_e32 v142, 0x20000, v142
	global_load_dwordx4 v[154:157], v141, s[10:11] offset:512
	v_add_u32_e32 v141, 0x20000, v141
	s_waitcnt vmcnt(5)
	v_pk_fma_f32 v[158:159], v[52:53], v[166:167], v[158:159]
	v_pk_fma_f32 v[160:161], v[54:55], v[168:169], v[160:161]
	global_store_dwordx4 v142, v[158:161], s[12:13] offset:512
	v_add_u32_e32 v142, 0x20000, v142
	global_load_dwordx4 v[158:161], v141, s[10:11] offset:512
	v_add_u32_e32 v141, 0x20000, v141
	s_waitcnt vmcnt(6)
	v_pk_fma_f32 v[162:163], v[48:49], v[166:167], v[162:163]
	v_pk_fma_f32 v[164:165], v[50:51], v[168:169], v[164:165]
	global_store_dwordx4 v142, v[162:165], s[12:13] offset:512
	v_add_u32_e32 v142, 0xa0000, v142
	global_load_dwordx4 v[162:165], v141, s[10:11] offset:512
	v_add_u32_e32 v141, 0x20000, v141
	s_waitcnt vmcnt(6)
	v_pk_fma_f32 v[150:151], v[44:45], v[166:167], v[150:151]
	v_pk_fma_f32 v[152:153], v[46:47], v[168:169], v[152:153]
	global_store_dwordx4 v142, v[150:153], s[12:13] offset:512
	v_add_u32_e32 v142, 0x20000, v142
	s_waitcnt vmcnt(5)
	v_pk_fma_f32 v[154:155], v[36:37], v[166:167], v[154:155]
	v_pk_fma_f32 v[156:157], v[38:39], v[168:169], v[156:157]
	global_store_dwordx4 v142, v[154:157], s[12:13] offset:512
	v_add_u32_e32 v142, 0x20000, v142
	s_waitcnt vmcnt(4)
	v_pk_fma_f32 v[158:159], v[28:29], v[166:167], v[158:159]
	v_pk_fma_f32 v[160:161], v[30:31], v[168:169], v[160:161]
	global_store_dwordx4 v142, v[158:161], s[12:13] offset:512
	v_add_u32_e32 v142, 0x20000, v142
	s_waitcnt vmcnt(3)
	v_pk_fma_f32 v[162:163], v[20:21], v[166:167], v[162:163]
	v_pk_fma_f32 v[164:165], v[22:23], v[168:169], v[164:165]
	global_store_dwordx4 v142, v[162:165], s[12:13] offset:512
	v_add_u32_e32 v142, 0x20000, v142
	v_mov_b32_e32 v141, v143
	v_mov_b32_e32 v142, v143
	global_load_dwordx4 v[166:169], v140, s[14:15] offset:576
	global_load_dwordx4 v[150:153], v141, s[10:11] offset:576
	v_add_u32_e32 v141, 0x20000, v141
	global_load_dwordx4 v[154:157], v141, s[10:11] offset:576
	v_add_u32_e32 v141, 0x20000, v141
	global_load_dwordx4 v[158:161], v141, s[10:11] offset:576
	v_add_u32_e32 v141, 0x20000, v141
	global_load_dwordx4 v[162:165], v141, s[10:11] offset:576
	v_add_u32_e32 v141, 0xa0000, v141
	s_waitcnt vmcnt(3)
	v_pk_fma_f32 v[150:151], v[40:41], v[166:167], v[150:151]
	v_pk_fma_f32 v[152:153], v[42:43], v[168:169], v[152:153]
	global_store_dwordx4 v142, v[150:153], s[12:13] offset:576
	v_add_u32_e32 v142, 0x20000, v142
	global_load_dwordx4 v[150:153], v141, s[10:11] offset:576
	v_add_u32_e32 v141, 0x20000, v141
	s_waitcnt vmcnt(4)
	v_pk_fma_f32 v[154:155], v[32:33], v[166:167], v[154:155]
	v_pk_fma_f32 v[156:157], v[34:35], v[168:169], v[156:157]
	global_store_dwordx4 v142, v[154:157], s[12:13] offset:576
	v_add_u32_e32 v142, 0x20000, v142
	global_load_dwordx4 v[154:157], v141, s[10:11] offset:576
	v_add_u32_e32 v141, 0x20000, v141
	s_waitcnt vmcnt(5)
	v_pk_fma_f32 v[158:159], v[24:25], v[166:167], v[158:159]
	v_pk_fma_f32 v[160:161], v[26:27], v[168:169], v[160:161]
	global_store_dwordx4 v142, v[158:161], s[12:13] offset:576
	v_add_u32_e32 v142, 0x20000, v142
	global_load_dwordx4 v[158:161], v141, s[10:11] offset:576
	v_add_u32_e32 v141, 0x20000, v141
	s_waitcnt vmcnt(6)
	v_pk_fma_f32 v[162:163], v[16:17], v[166:167], v[162:163]
	v_pk_fma_f32 v[164:165], v[18:19], v[168:169], v[164:165]
	global_store_dwordx4 v142, v[162:165], s[12:13] offset:576
	v_add_u32_e32 v142, 0xa0000, v142
	global_load_dwordx4 v[162:165], v141, s[10:11] offset:576
	v_add_u32_e32 v141, 0x20000, v141
	s_waitcnt vmcnt(6)
	v_pk_fma_f32 v[150:151], v[12:13], v[166:167], v[150:151]
	v_pk_fma_f32 v[152:153], v[14:15], v[168:169], v[152:153]
	global_store_dwordx4 v142, v[150:153], s[12:13] offset:576
	v_add_u32_e32 v142, 0x20000, v142
	s_waitcnt vmcnt(5)
	v_pk_fma_f32 v[154:155], v[8:9], v[166:167], v[154:155]
	v_pk_fma_f32 v[156:157], v[10:11], v[168:169], v[156:157]
	global_store_dwordx4 v142, v[154:157], s[12:13] offset:576
	v_add_u32_e32 v142, 0x20000, v142
	s_waitcnt vmcnt(4)
	v_pk_fma_f32 v[158:159], v[4:5], v[166:167], v[158:159]
	v_pk_fma_f32 v[160:161], v[6:7], v[168:169], v[160:161]
	global_store_dwordx4 v142, v[158:161], s[12:13] offset:576
	v_add_u32_e32 v142, 0x20000, v142
	s_waitcnt vmcnt(3)
	v_pk_fma_f32 v[162:163], v[0:1], v[166:167], v[162:163]
	v_pk_fma_f32 v[164:165], v[2:3], v[168:169], v[164:165]
	global_store_dwordx4 v142, v[162:165], s[12:13] offset:576
	v_add_u32_e32 v142, 0x20000, v142
	s_and_b64 vcc, exec, s[6:7]
	s_cbranch_vccz .LBB0_843
	s_waitcnt vmcnt(0)
	s_cmpk_gt_u32 s20, 0xff
	s_cbranch_scc1 .LBB0_854
	s_barrier

.LBB0_855:
	s_waitcnt vmcnt(0)
	s_setprio 0
	s_barrier
	s_mov_b64 s[0:1], exec
	v_readlane_b32 s4, v255, 4
	v_readlane_b32 s5, v255, 5
	s_and_b64 s[4:5], s[0:1], s[4:5]
	s_xor_b64 s[6:7], s[4:5], s[0:1]
	s_mov_b64 exec, s[4:5]
	s_cbranch_execz .LBB0_908
	s_add_i32 s0, 0, 0x25800
	v_mov_b32_e32 v0, s0
	s_waitcnt vmcnt(0) expcnt(0) lgkmcnt(0)
	ds_read_b32 v2, v0
	s_add_i32 s0, 0, 0x25804
	v_mov_b32_e32 v0, s0
	ds_read_b32 v0, v0
	s_waitcnt lgkmcnt(1)
	v_cmp_ne_u32_e32 vcc, 0, v2
	s_cbranch_vccnz .LBB0_871
	s_add_u32 s8, s26, 0xc0200
	s_addc_u32 s9, s27, 0
	s_add_u32 s4, s26, 0xc0400
	s_addc_u32 s5, s27, 0
	s_add_u32 s10, s26, 0xc0500
	s_addc_u32 s11, s27, 0
	s_add_u32 s12, s26, 0xc0600
	s_addc_u32 s13, s27, 0
	s_add_u32 s14, s26, 0xc0700
	s_addc_u32 s15, s27, 0
	s_add_u32 s16, s26, 0xc0800
	s_addc_u32 s17, s27, 0
	s_add_u32 s18, s26, 0xc0900
	s_addc_u32 s19, s27, 0
	s_add_u32 s36, s26, 0xc0a00
	s_addc_u32 s37, s27, 0
	s_add_u32 s48, s26, 0xc0b00
	s_addc_u32 s49, s27, 0
	s_add_u32 s50, s26, 0xc0c00
	s_addc_u32 s51, s27, 0
	s_add_u32 s52, s26, 0xc0d00
	s_addc_u32 s53, s27, 0
	s_add_u32 s56, s26, 0xc0e00
	s_addc_u32 s57, s27, 0
	s_add_u32 s60, s26, 0xc0f00
	s_addc_u32 s61, s27, 0
	s_add_u32 s64, s26, 0xc1000
	s_addc_u32 s65, s27, 0
	s_add_u32 s66, s26, 0xc1100
	s_addc_u32 s67, s27, 0
	s_add_u32 s68, s26, 0xc1200
	v_readlane_b32 s0, v255, 0
	s_addc_u32 s69, s27, 0
	s_mul_i32 s20, s31, s0
	s_add_u32 s70, s26, 0xc1300
	s_mul_i32 s20, s20, s30
	s_addc_u32 s71, s27, 0
	s_mov_b32 s21, 1
	v_mov_b32_e32 v16, 0
	s_branch .LBB0_859

.LBB0_927:
	s_waitcnt vmcnt(0)
	s_setprio 0
	s_barrier
	s_mov_b64 s[6:7], exec
	v_readlane_b32 s0, v255, 4
	v_readlane_b32 s1, v255, 5
	s_and_b64 s[0:1], s[6:7], s[0:1]
	s_mov_b64 exec, s[0:1]
	s_cbranch_execz .LBB0_979
	s_add_i32 s0, 0, 0x25800
	v_mov_b32_e32 v0, s0
	s_waitcnt vmcnt(0) expcnt(0) lgkmcnt(0)
	ds_read_b32 v2, v0
	s_add_i32 s0, 0, 0x25804
	v_mov_b32_e32 v0, s0
	ds_read_b32 v0, v0
	s_waitcnt lgkmcnt(1)
	v_cmp_ne_u32_e32 vcc, 0, v2
	s_cbranch_vccnz .LBB0_943
	s_add_u32 s8, s26, 0xc0200
	s_addc_u32 s9, s27, 0
	s_add_u32 s4, s26, 0xc0400
	s_addc_u32 s5, s27, 0
	s_add_u32 s10, s26, 0xc0500
	s_addc_u32 s11, s27, 0
	s_add_u32 s12, s26, 0xc0600
	s_addc_u32 s13, s27, 0
	s_add_u32 s14, s26, 0xc0700
	s_addc_u32 s15, s27, 0
	s_add_u32 s16, s26, 0xc0800
	s_addc_u32 s17, s27, 0
	s_add_u32 s18, s26, 0xc0900
	s_addc_u32 s19, s27, 0
	s_add_u32 s36, s26, 0xc0a00
	s_addc_u32 s37, s27, 0
	s_add_u32 s48, s26, 0xc0b00
	s_addc_u32 s49, s27, 0
	s_add_u32 s50, s26, 0xc0c00
	s_addc_u32 s51, s27, 0
	s_add_u32 s56, s26, 0xc0d00
	s_addc_u32 s57, s27, 0
	s_add_u32 s60, s26, 0xc0e00
	s_addc_u32 s61, s27, 0
	s_add_u32 s64, s26, 0xc0f00
	s_addc_u32 s65, s27, 0
	s_add_u32 s66, s26, 0xc1000
	s_addc_u32 s67, s27, 0
	s_add_u32 s68, s26, 0xc1100
	s_addc_u32 s69, s27, 0
	s_add_u32 s70, s26, 0xc1200
	v_readlane_b32 s0, v255, 0
	s_addc_u32 s71, s27, 0
	s_mul_i32 s20, s31, s0
	s_add_u32 s72, s26, 0xc1300
	s_mul_i32 s20, s20, s30
	s_addc_u32 s73, s27, 0
	s_mov_b32 s21, 1
	v_mov_b32_e32 v16, 0
	s_branch .LBB0_931

.LBB0_979:
	s_or_b64 exec, exec, s[6:7]
	s_add_u32 s48, s26, 0x13200000
	s_addc_u32 s49, s27, 0
	s_cmpk_lt_i32 s2, 0x580
	s_cselect_b64 s[56:57], -1, 0
	v_mov_b32_e32 v128, v254
	v_mov_b32_e32 v9, v254
	s_waitcnt lgkmcnt(0)
	s_barrier
	v_cmp_lt_u32_e32 vcc, 0xff, v254
	s_cbranch_vccz .Lprio_skip7
	s_setprio 1
.Lprio_skip7:
	s_and_b64 vcc, exec, s[56:57]
	v_readfirstlane_b32 s20, v9
	s_cbranch_vccz .LBB0_991
	v_lshlrev_b32_e32 v0, 4, v9
	v_add_u32_e32 v1, 0x2000, v0
	v_ashrrev_i32_e32 v2, 31, v1
	v_lshrrev_b32_e32 v2, 22, v2
	v_add_u32_e32 v2, v1, v2
	v_ashrrev_i32_e32 v8, 10, v2
	v_mul_i32_i24_e32 v2, 0x400, v8
	v_sub_u32_e32 v1, v1, v2
	v_lshrrev_b32_e32 v2, 4, v1
	v_bitop3_b32 v1, v2, v1, 32 bitop3:0x6c
	v_ashrrev_i32_e32 v2, 31, v1
	v_lshrrev_b32_e32 v2, 26, v2
	v_add_u32_e32 v2, v1, v2
	v_lshlrev_b32_e32 v3, 3, v8
	v_ashrrev_i32_e32 v10, 6, v2
	v_and_b32_e32 v3, -16, v3
	v_add_u32_e32 v3, v10, v3
	v_and_b32_e32 v4, 3, v10
	s_mov_b32 s4, 0xfffe0
	v_lshrrev_b32_e32 v5, 2, v3
	v_lshlrev_b32_e32 v6, 1, v3
	v_and_b32_e32 v2, 0xc0, v2
	v_and_or_b32 v4, v3, s4, v4
	v_and_b32_e32 v5, 4, v5
	v_and_b32_e32 v6, 24, v6
	v_sub_u32_e32 v1, v1, v2
	v_mov_b32_e32 v2, 1
	v_or3_b32 v4, v4, v5, v6
	v_lshlrev_b32_e32 v5, 5, v8
	v_ashrrev_i16_sdwa v1, v2, sext(v1) dst_sel:DWORD dst_unused:UNUSED_PAD src0_sel:DWORD src1_sel:BYTE_0
	v_and_b32_e32 v5, 32, v5
	v_bfe_i32 v11, v1, 0, 16
	v_add_lshl_u32 v1, v5, v11, 1
	v_lshl_add_u32 v130, v4, 12, v1
	v_lshl_add_u32 v132, v3, 12, v1
	v_bfe_i32 v1, v9, 27, 1
	v_lshrrev_b32_e32 v1, 22, v1
	v_add_u32_e32 v1, v0, v1
	v_and_b32_e32 v1, 0xfffffc00, v1
	v_sub_u32_e32 v0, v0, v1
	v_lshrrev_b32_e32 v1, 4, v0
	v_bitop3_b32 v1, v1, v0, 32 bitop3:0x6c
	v_ashrrev_i32_e32 v0, 31, v0
	v_lshrrev_b32_e32 v0, 26, v0
	v_add_u32_e32 v0, v1, v0
	v_ashrrev_i32_e32 v12, 6, v0
	v_ashrrev_i32_e32 v0, 31, v9
	v_lshrrev_b32_e32 v0, 26, v0
	v_add_u32_e32 v0, v9, v0
	v_ashrrev_i32_e32 v13, 6, v0
	v_lshlrev_b32_e32 v0, 3, v13
	v_and_b32_e32 v0, -16, v0
	v_add_u32_e32 v0, v12, v0
	v_and_b32_e32 v3, 3, v12
	v_and_or_b32 v3, v0, s4, v3
	s_lshr_b32 s4, s3, 29
	s_add_i32 s4, s2, s4
	s_ashr_i32 s1, s20, 6
	s_ashr_i32 s5, s4, 3
	s_and_b32 s4, s4, -8
	s_ashr_i32 s0, s20, 8
	s_lshl_b32 s21, s1, 10
	s_sub_i32 s4, s2, s4
	s_cmp_lt_i32 s4, 0
	s_movk_i32 s23, 0xb1
	s_cselect_b32 s6, s23, 0xb0
	s_mul_i32 s4, s4, s6
	s_add_i32 s4, s4, s5
	s_mul_hi_i32 s5, s4, 0x2e8ba2e9
	s_lshr_b32 s6, s5, 31
	s_ashr_i32 s5, s5, 6
	s_add_i32 s5, s5, s6
	s_lshl_b32 s6, s5, 3
	s_mulk_i32 s5, 0x160
	s_sub_i32 s5, s4, s5
	s_sext_i32_i16 s4, s5
	s_bfe_u32 s4, s4, 0x3001c
	s_add_i32 s7, s5, s4
	s_sext_i32_i16 s4, s7
	s_and_b32 s7, s7, 0xfff8
	v_lshrrev_b32_e32 v4, 2, v0
	v_lshlrev_b32_e32 v5, 1, v0
	s_sub_i32 s5, s5, s7
	v_and_b32_e32 v4, 4, v4
	v_and_b32_e32 v5, 24, v5
	s_sext_i32_i16 s5, s5
	v_or3_b32 v3, v3, v4, v5
	v_mul_i32_i24_e32 v5, 64, v12
	s_lshr_b32 s4, s4, 3
	s_add_i32 s18, s6, s5
	v_sub_u32_e32 v1, v1, v5
	s_ashr_i32 s19, s18, 31
	s_bfe_i64 s[8:9], s[4:5], 0x100000
	v_lshlrev_b32_e32 v4, 5, v13
	v_ashrrev_i16_sdwa v1, v2, sext(v1) dst_sel:DWORD dst_unused:UNUSED_PAD src0_sel:DWORD src1_sel:BYTE_0
	s_lshl_b64 s[6:7], s[18:19], 20
	s_lshl_b64 s[8:9], s[8:9], 20
	v_and_b32_e32 v4, 32, v4
	v_bfe_i32 v14, v1, 0, 16
	s_add_u32 s50, s62, s8
	v_add_lshl_u32 v1, v4, v14, 1
	s_addc_u32 s51, s63, s9
	s_add_i32 s19, s21, 0
	v_lshl_add_u32 v134, v3, 12, v1
	s_add_i32 m0, s19, 0x10000
	v_lshl_add_u32 v136, v0, 12, v1
	global_load_lds_dwordx4 v134, s[50:51]
	s_add_i32 m0, s19, 0x12000
	s_add_u32 s36, s38, s6
	global_load_lds_dwordx4 v130, s[50:51]
	s_addc_u32 s37, s39, s7
	s_mov_b32 m0, s19
	s_add_i32 s24, s19, 0x2000
	global_load_lds_dwordx4 v136, s[36:37]
	s_mov_b32 m0, s24
	s_add_u32 s6, s50, 0x80000
	global_load_lds_dwordx4 v132, s[36:37]
	s_addc_u32 s7, s51, 0
	s_add_i32 m0, s19, 0x14000
	v_mov_b32_e32 v135, 0
	global_load_lds_dwordx4 v134, s[6:7]
	s_add_i32 m0, s19, 0x16000
	v_mov_b32_e32 v131, v135
	global_load_lds_dwordx4 v130, s[6:7]
	s_add_u32 s6, s36, 0x80000
	s_addc_u32 s7, s37, 0
	s_add_i32 s25, s19, 0x4000
	s_mov_b32 m0, s25
	s_add_i32 s28, s19, 0x6000
	global_load_lds_dwordx4 v136, s[6:7]
	s_mov_b32 m0, s28
	v_mov_b32_e32 v137, v135
	global_load_lds_dwordx4 v132, s[6:7]
	v_mov_b32_e32 v133, v135
	s_mov_b32 s29, 0
	v_lshl_add_u64 v[6:7], s[50:51], 0, v[134:135]
	v_lshl_add_u64 v[4:5], s[50:51], 0, v[130:131]
	v_lshl_add_u64 v[2:3], s[36:37], 0, v[136:137]
	s_cmp_lg_u32 s0, 1
	v_lshl_add_u64 v[0:1], s[36:37], 0, v[132:133]
	s_cbranch_scc1 .LBB0_982
	s_barrier

.LBB0_986:
	ds_read_b128 v[152:155], v148
	ds_read_b128 v[156:159], v148 offset:1024
	ds_read_b128 v[160:163], v148 offset:2048
	ds_read_b128 v[164:167], v148 offset:3072
	s_add_u32 s4, s60, 0xfff80080
	s_addc_u32 s5, s61, -1
	s_cmp_eq_u32 s64, 28
	s_cselect_b32 s5, s0, s5
	s_cselect_b32 s4, s1, s4
	s_cselect_b32 s51, s11, s37
	s_cselect_b32 s50, s13, s36
	v_lshl_add_u64 v[200:201], s[60:61], 0, v[138:139]
	s_add_i32 m0, s19, 0xc000
	ds_read_b128 v[168:171], v149
	ds_read_b128 v[172:175], v149 offset:1024
	ds_read_b128 v[176:179], v149 offset:2048
	ds_read_b128 v[180:183], v149 offset:3072
	ds_read_b128 v[184:187], v149 offset:4096
	ds_read_b128 v[188:191], v149 offset:5120
	ds_read_b128 v[192:195], v149 offset:6144
	ds_read_b128 v[196:199], v149 offset:7168
	global_load_lds_dwordx4 v[200:201], off
	v_lshl_add_u64 v[200:201], s[60:61], 0, v[140:141]
	s_add_i32 m0, s19, 0xe000
	s_nop 0
	global_load_lds_dwordx4 v[200:201], off
	s_waitcnt lgkmcnt(8)
	s_barrier
	s_waitcnt lgkmcnt(0)
	s_waitcnt lgkmcnt(0)
	v_mfma_f32_16x16x32_bf16 v[124:127], v[152:155], v[168:171], v[124:127]
	v_mfma_f32_16x16x32_bf16 v[120:123], v[160:163], v[168:171], v[120:123]
	v_mfma_f32_16x16x32_bf16 v[108:111], v[152:155], v[176:179], v[108:111]
	v_mfma_f32_16x16x32_bf16 v[104:107], v[160:163], v[176:179], v[104:107]
	v_mfma_f32_16x16x32_bf16 v[92:95], v[152:155], v[184:187], v[92:95]
	v_mfma_f32_16x16x32_bf16 v[88:91], v[160:163], v[184:187], v[88:91]
	v_mfma_f32_16x16x32_bf16 v[76:79], v[152:155], v[192:195], v[76:79]
	v_mfma_f32_16x16x32_bf16 v[72:75], v[160:163], v[192:195], v[72:75]
	v_mfma_f32_16x16x32_bf16 v[124:127], v[156:159], v[172:175], v[124:127]
	v_mfma_f32_16x16x32_bf16 v[120:123], v[164:167], v[172:175], v[120:123]
	v_mfma_f32_16x16x32_bf16 v[108:111], v[156:159], v[180:183], v[108:111]
	v_mfma_f32_16x16x32_bf16 v[104:107], v[164:167], v[180:183], v[104:107]
	v_mfma_f32_16x16x32_bf16 v[92:95], v[156:159], v[188:191], v[92:95]
	v_mfma_f32_16x16x32_bf16 v[88:91], v[164:167], v[188:191], v[88:91]
	v_mfma_f32_16x16x32_bf16 v[76:79], v[156:159], v[196:199], v[76:79]
	v_mfma_f32_16x16x32_bf16 v[72:75], v[164:167], v[196:199], v[72:75]
	s_barrier
	s_add_i32 s42, s41, s21
	v_lshl_add_u64 v[216:217], s[50:51], 0, v[134:135]
	s_mov_b32 m0, s42
	ds_read_b128 v[200:203], v150
	ds_read_b128 v[204:207], v150 offset:1024
	ds_read_b128 v[208:211], v150 offset:2048
	ds_read_b128 v[212:215], v150 offset:3072
	global_load_lds_dwordx4 v[216:217], off
	v_lshl_add_u64 v[218:219], s[50:51], 0, v[130:131]
	s_add_i32 m0, s42, 0x2000
	s_nop 0
	global_load_lds_dwordx4 v[218:219], off
	s_barrier
	s_waitcnt lgkmcnt(0)
	s_waitcnt lgkmcnt(0)
	v_mfma_f32_16x16x32_bf16 v[116:119], v[200:203], v[168:171], v[116:119]
	v_mfma_f32_16x16x32_bf16 v[112:115], v[208:211], v[168:171], v[112:115]
	v_mfma_f32_16x16x32_bf16 v[100:103], v[200:203], v[176:179], v[100:103]
	v_mfma_f32_16x16x32_bf16 v[96:99], v[208:211], v[176:179], v[96:99]
	v_mfma_f32_16x16x32_bf16 v[84:87], v[200:203], v[184:187], v[84:87]
	v_mfma_f32_16x16x32_bf16 v[80:83], v[208:211], v[184:187], v[80:83]
	v_mfma_f32_16x16x32_bf16 v[68:71], v[200:203], v[192:195], v[68:71]
	v_mfma_f32_16x16x32_bf16 v[64:67], v[208:211], v[192:195], v[64:67]
	v_mfma_f32_16x16x32_bf16 v[116:119], v[204:207], v[172:175], v[116:119]
	v_mfma_f32_16x16x32_bf16 v[112:115], v[212:215], v[172:175], v[112:115]
	v_mfma_f32_16x16x32_bf16 v[100:103], v[204:207], v[180:183], v[100:103]
	v_mfma_f32_16x16x32_bf16 v[96:99], v[212:215], v[180:183], v[96:99]
	v_mfma_f32_16x16x32_bf16 v[84:87], v[204:207], v[188:191], v[84:87]
	v_mfma_f32_16x16x32_bf16 v[80:83], v[212:215], v[188:191], v[80:83]
	v_mfma_f32_16x16x32_bf16 v[68:71], v[204:207], v[196:199], v[68:71]
	v_mfma_f32_16x16x32_bf16 v[64:67], v[212:215], v[196:199], v[64:67]
	s_mov_b32 m0, s19
	v_lshl_add_u64 v[220:221], s[4:5], 0, v[136:137]
	s_barrier
	ds_read_b128 v[168:171], v149 offset:16384
	ds_read_b128 v[172:175], v149 offset:17408
	ds_read_b128 v[176:179], v149 offset:18432
	ds_read_b128 v[180:183], v149 offset:19456
	ds_read_b128 v[184:187], v149 offset:20480
	ds_read_b128 v[188:191], v149 offset:21504
	ds_read_b128 v[192:195], v149 offset:22528
	ds_read_b128 v[196:199], v149 offset:23552
	global_load_lds_dwordx4 v[220:221], off
	v_lshl_add_u64 v[222:223], s[4:5], 0, v[132:133]
	s_mov_b32 m0, s24
	s_nop 0
	global_load_lds_dwordx4 v[222:223], off
	s_barrier
	s_waitcnt lgkmcnt(0)
	s_waitcnt lgkmcnt(0)
	v_mfma_f32_16x16x32_bf16 v[60:63], v[152:155], v[168:171], v[60:63]
	v_mfma_f32_16x16x32_bf16 v[56:59], v[160:163], v[168:171], v[56:59]
	v_mfma_f32_16x16x32_bf16 v[44:47], v[152:155], v[176:179], v[44:47]
	v_mfma_f32_16x16x32_bf16 v[40:43], v[160:163], v[176:179], v[40:43]
	v_mfma_f32_16x16x32_bf16 v[28:31], v[152:155], v[184:187], v[28:31]
	v_mfma_f32_16x16x32_bf16 v[24:27], v[160:163], v[184:187], v[24:27]
	v_mfma_f32_16x16x32_bf16 v[12:15], v[152:155], v[192:195], v[12:15]
	v_mfma_f32_16x16x32_bf16 v[8:11], v[160:163], v[192:195], v[8:11]
	v_mfma_f32_16x16x32_bf16 v[60:63], v[156:159], v[172:175], v[60:63]
	v_mfma_f32_16x16x32_bf16 v[56:59], v[164:167], v[172:175], v[56:59]
	v_mfma_f32_16x16x32_bf16 v[44:47], v[156:159], v[180:183], v[44:47]
	v_mfma_f32_16x16x32_bf16 v[40:43], v[164:167], v[180:183], v[40:43]
	v_mfma_f32_16x16x32_bf16 v[28:31], v[156:159], v[188:191], v[28:31]
	v_mfma_f32_16x16x32_bf16 v[24:27], v[164:167], v[188:191], v[24:27]
	v_mfma_f32_16x16x32_bf16 v[12:15], v[156:159], v[196:199], v[12:15]
	v_mfma_f32_16x16x32_bf16 v[8:11], v[164:167], v[196:199], v[8:11]
	s_barrier
	s_add_u32 s42, s50, 0x80000
	s_addc_u32 s43, s51, 0
	s_add_i32 s44, s46, s21
	v_lshl_add_u64 v[152:153], s[42:43], 0, v[134:135]
	s_mov_b32 m0, s44
	s_nop 0
	global_load_lds_dwordx4 v[152:153], off
	v_lshl_add_u64 v[152:153], s[42:43], 0, v[130:131]
	s_add_i32 m0, s44, 0x2000
	s_nop 0
	global_load_lds_dwordx4 v[152:153], off
	s_waitcnt vmcnt(6)
	s_barrier
	v_mfma_f32_16x16x32_bf16 v[52:55], v[200:203], v[168:171], v[52:55]
	v_mfma_f32_16x16x32_bf16 v[48:51], v[208:211], v[168:171], v[48:51]
	v_mfma_f32_16x16x32_bf16 v[36:39], v[200:203], v[176:179], v[36:39]
	v_mfma_f32_16x16x32_bf16 v[32:35], v[208:211], v[176:179], v[32:35]
	v_mfma_f32_16x16x32_bf16 v[20:23], v[200:203], v[184:187], v[20:23]
	v_mfma_f32_16x16x32_bf16 v[16:19], v[208:211], v[184:187], v[16:19]
	v_mfma_f32_16x16x32_bf16 v[4:7], v[200:203], v[192:195], v[4:7]
	v_mfma_f32_16x16x32_bf16 v[0:3], v[208:211], v[192:195], v[0:3]
	v_mfma_f32_16x16x32_bf16 v[52:55], v[204:207], v[172:175], v[52:55]
	v_mfma_f32_16x16x32_bf16 v[48:51], v[212:215], v[172:175], v[48:51]
	v_mfma_f32_16x16x32_bf16 v[36:39], v[204:207], v[180:183], v[36:39]
	v_mfma_f32_16x16x32_bf16 v[32:35], v[212:215], v[180:183], v[32:35]
	v_mfma_f32_16x16x32_bf16 v[20:23], v[204:207], v[188:191], v[20:23]
	v_mfma_f32_16x16x32_bf16 v[16:19], v[212:215], v[188:191], v[16:19]
	v_mfma_f32_16x16x32_bf16 v[4:7], v[204:207], v[196:199], v[4:7]
	v_mfma_f32_16x16x32_bf16 v[0:3], v[212:215], v[196:199], v[0:3]
	s_add_i32 s42, 0, 0x18000
	v_add_u32_e32 v151, s42, v146
	s_barrier
	ds_read_b128 v[152:155], v151
	ds_read_b128 v[156:159], v151 offset:1024
	ds_read_b128 v[160:163], v151 offset:2048
	ds_read_b128 v[164:167], v151 offset:3072
	s_add_u32 s4, s4, 0x80000
	s_addc_u32 s5, s5, 0
	s_mov_b32 m0, s25
	v_lshl_add_u64 v[200:201], s[4:5], 0, v[136:137]
	ds_read_b128 v[168:171], v149 offset:32768
	ds_read_b128 v[172:175], v149 offset:33792
	ds_read_b128 v[176:179], v149 offset:34816
	ds_read_b128 v[180:183], v149 offset:35840
	ds_read_b128 v[184:187], v149 offset:36864
	ds_read_b128 v[188:191], v149 offset:37888
	ds_read_b128 v[192:195], v149 offset:38912
	ds_read_b128 v[196:199], v149 offset:39936
	global_load_lds_dwordx4 v[200:201], off
	v_lshl_add_u64 v[200:201], s[4:5], 0, v[132:133]
	s_mov_b32 m0, s28
	s_nop 0
	global_load_lds_dwordx4 v[200:201], off
	s_waitcnt lgkmcnt(8)
	s_barrier
	s_waitcnt lgkmcnt(0)
	s_waitcnt lgkmcnt(0)
	v_mfma_f32_16x16x32_bf16 v[124:127], v[152:155], v[168:171], v[124:127]
	v_mfma_f32_16x16x32_bf16 v[120:123], v[160:163], v[168:171], v[120:123]
	v_mfma_f32_16x16x32_bf16 v[108:111], v[152:155], v[176:179], v[108:111]
	v_mfma_f32_16x16x32_bf16 v[104:107], v[160:163], v[176:179], v[104:107]
	v_mfma_f32_16x16x32_bf16 v[92:95], v[152:155], v[184:187], v[92:95]
	v_mfma_f32_16x16x32_bf16 v[88:91], v[160:163], v[184:187], v[88:91]
	v_mfma_f32_16x16x32_bf16 v[76:79], v[152:155], v[192:195], v[76:79]
	v_mfma_f32_16x16x32_bf16 v[72:75], v[160:163], v[192:195], v[72:75]
	v_mfma_f32_16x16x32_bf16 v[124:127], v[156:159], v[172:175], v[124:127]
	v_mfma_f32_16x16x32_bf16 v[120:123], v[164:167], v[172:175], v[120:123]
	v_mfma_f32_16x16x32_bf16 v[108:111], v[156:159], v[180:183], v[108:111]
	v_mfma_f32_16x16x32_bf16 v[104:107], v[164:167], v[180:183], v[104:107]
	v_mfma_f32_16x16x32_bf16 v[92:95], v[156:159], v[188:191], v[92:95]
	v_mfma_f32_16x16x32_bf16 v[88:91], v[164:167], v[188:191], v[88:91]
	v_mfma_f32_16x16x32_bf16 v[76:79], v[156:159], v[196:199], v[76:79]
	v_mfma_f32_16x16x32_bf16 v[72:75], v[164:167], v[196:199], v[72:75]
	s_barrier
	s_add_i32 s43, 0, 0x1c000
	s_add_i32 s4, s42, s21
	v_add_u32_e32 v151, s43, v146
	v_lshl_add_u64 v[216:217], v[216:217], 0, s[8:9]
	s_mov_b32 m0, s4
	ds_read_b128 v[200:203], v151
	ds_read_b128 v[204:207], v151 offset:1024
	ds_read_b128 v[208:211], v151 offset:2048
	ds_read_b128 v[212:215], v151 offset:3072
	global_load_lds_dwordx4 v[216:217], off
	v_lshl_add_u64 v[216:217], v[218:219], 0, s[8:9]
	s_add_i32 m0, s4, 0x2000
	s_nop 0
	global_load_lds_dwordx4 v[216:217], off
	s_barrier
	s_waitcnt lgkmcnt(0)
	s_waitcnt lgkmcnt(0)
	v_mfma_f32_16x16x32_bf16 v[116:119], v[200:203], v[168:171], v[116:119]
	v_mfma_f32_16x16x32_bf16 v[112:115], v[208:211], v[168:171], v[112:115]
	v_mfma_f32_16x16x32_bf16 v[100:103], v[200:203], v[176:179], v[100:103]
	v_mfma_f32_16x16x32_bf16 v[96:99], v[208:211], v[176:179], v[96:99]
	v_mfma_f32_16x16x32_bf16 v[84:87], v[200:203], v[184:187], v[84:87]
	v_mfma_f32_16x16x32_bf16 v[80:83], v[208:211], v[184:187], v[80:83]
	v_mfma_f32_16x16x32_bf16 v[68:71], v[200:203], v[192:195], v[68:71]
	v_mfma_f32_16x16x32_bf16 v[64:67], v[208:211], v[192:195], v[64:67]
	v_mfma_f32_16x16x32_bf16 v[116:119], v[204:207], v[172:175], v[116:119]
	v_mfma_f32_16x16x32_bf16 v[112:115], v[212:215], v[172:175], v[112:115]
	v_mfma_f32_16x16x32_bf16 v[100:103], v[204:207], v[180:183], v[100:103]
	v_mfma_f32_16x16x32_bf16 v[96:99], v[212:215], v[180:183], v[96:99]
	v_mfma_f32_16x16x32_bf16 v[84:87], v[204:207], v[188:191], v[84:87]
	v_mfma_f32_16x16x32_bf16 v[80:83], v[212:215], v[188:191], v[80:83]
	v_mfma_f32_16x16x32_bf16 v[68:71], v[204:207], v[196:199], v[68:71]
	v_mfma_f32_16x16x32_bf16 v[64:67], v[212:215], v[196:199], v[64:67]
	s_mov_b32 m0, s33
	v_lshl_add_u64 v[216:217], v[220:221], 0, s[8:9]
	s_barrier
	ds_read_b128 v[168:171], v149 offset:49152
	ds_read_b128 v[172:175], v149 offset:50176
	ds_read_b128 v[176:179], v149 offset:51200
	ds_read_b128 v[180:183], v149 offset:52224
	ds_read_b128 v[184:187], v149 offset:53248
	ds_read_b128 v[188:191], v149 offset:54272
	ds_read_b128 v[192:195], v149 offset:55296
	ds_read_b128 v[196:199], v149 offset:56320
	global_load_lds_dwordx4 v[216:217], off
	v_lshl_add_u64 v[216:217], v[222:223], 0, s[8:9]
	s_mov_b32 m0, s40
	s_nop 0
	global_load_lds_dwordx4 v[216:217], off
	s_barrier
	s_waitcnt lgkmcnt(0)
	s_waitcnt lgkmcnt(0)
	v_mfma_f32_16x16x32_bf16 v[60:63], v[152:155], v[168:171], v[60:63]
	v_mfma_f32_16x16x32_bf16 v[56:59], v[160:163], v[168:171], v[56:59]
	v_mfma_f32_16x16x32_bf16 v[44:47], v[152:155], v[176:179], v[44:47]
	v_mfma_f32_16x16x32_bf16 v[40:43], v[160:163], v[176:179], v[40:43]
	v_mfma_f32_16x16x32_bf16 v[28:31], v[152:155], v[184:187], v[28:31]
	v_mfma_f32_16x16x32_bf16 v[24:27], v[160:163], v[184:187], v[24:27]
	v_mfma_f32_16x16x32_bf16 v[12:15], v[152:155], v[192:195], v[12:15]
	v_mfma_f32_16x16x32_bf16 v[8:11], v[160:163], v[192:195], v[8:11]
	v_mfma_f32_16x16x32_bf16 v[60:63], v[156:159], v[172:175], v[60:63]
	v_mfma_f32_16x16x32_bf16 v[56:59], v[164:167], v[172:175], v[56:59]
	v_mfma_f32_16x16x32_bf16 v[44:47], v[156:159], v[180:183], v[44:47]
	v_mfma_f32_16x16x32_bf16 v[40:43], v[164:167], v[180:183], v[40:43]
	v_mfma_f32_16x16x32_bf16 v[28:31], v[156:159], v[188:191], v[28:31]
	v_mfma_f32_16x16x32_bf16 v[24:27], v[164:167], v[188:191], v[24:27]
	v_mfma_f32_16x16x32_bf16 v[12:15], v[156:159], v[196:199], v[12:15]
	v_mfma_f32_16x16x32_bf16 v[8:11], v[164:167], v[196:199], v[8:11]
	s_barrier
	s_add_u32 s4, s50, 0x80080
	s_addc_u32 s5, s51, 0
	s_add_i32 s42, s43, s21
	v_lshl_add_u64 v[152:153], s[4:5], 0, v[134:135]
	s_mov_b32 m0, s42
	s_nop 0
	global_load_lds_dwordx4 v[152:153], off
	v_lshl_add_u64 v[152:153], s[4:5], 0, v[130:131]
	s_add_i32 m0, s42, 0x2000
	s_nop 0
	global_load_lds_dwordx4 v[152:153], off
	s_waitcnt vmcnt(6)
	s_barrier
	v_mfma_f32_16x16x32_bf16 v[52:55], v[200:203], v[168:171], v[52:55]
	v_mfma_f32_16x16x32_bf16 v[48:51], v[208:211], v[168:171], v[48:51]
	v_mfma_f32_16x16x32_bf16 v[36:39], v[200:203], v[176:179], v[36:39]
	v_mfma_f32_16x16x32_bf16 v[32:35], v[208:211], v[176:179], v[32:35]
	v_mfma_f32_16x16x32_bf16 v[20:23], v[200:203], v[184:187], v[20:23]
	v_mfma_f32_16x16x32_bf16 v[16:19], v[208:211], v[184:187], v[16:19]
	v_mfma_f32_16x16x32_bf16 v[4:7], v[200:203], v[192:195], v[4:7]
	v_mfma_f32_16x16x32_bf16 v[0:3], v[208:211], v[192:195], v[0:3]
	v_mfma_f32_16x16x32_bf16 v[52:55], v[204:207], v[172:175], v[52:55]
	v_mfma_f32_16x16x32_bf16 v[48:51], v[212:215], v[172:175], v[48:51]
	v_mfma_f32_16x16x32_bf16 v[36:39], v[204:207], v[180:183], v[36:39]
	v_mfma_f32_16x16x32_bf16 v[32:35], v[212:215], v[180:183], v[32:35]
	v_mfma_f32_16x16x32_bf16 v[20:23], v[204:207], v[188:191], v[20:23]
	v_mfma_f32_16x16x32_bf16 v[16:19], v[212:215], v[188:191], v[16:19]
	v_mfma_f32_16x16x32_bf16 v[4:7], v[204:207], v[196:199], v[4:7]
	v_mfma_f32_16x16x32_bf16 v[0:3], v[212:215], v[196:199], v[0:3]
	s_add_i32 s64, s64, 2
	s_add_u32 s60, s60, 0x100
	s_addc_u32 s61, s61, 0
	s_add_u32 s36, s36, 0x100
	s_addc_u32 s37, s37, 0
	s_cmp_gt_u32 s64, 29
	s_barrier
	s_cbranch_scc0 .LBB0_986
	v_mul_f32_e32 v152, 0xbfb8aa3b, v124
	v_exp_f32_e32 v153, v152
	v_mul_f32_e32 v152, 0xbfb8aa3b, v120
	v_exp_f32_e32 v154, v152
	v_lshl_or_b32 v152, s53, 7, v147
	v_add_f32_e32 v153, 1.0, v153
	v_rcp_f32_e32 v155, v153
	v_add_f32_e32 v153, 1.0, v154
	v_rcp_f32_e32 v154, v153
	v_lshl_add_u32 v151, s18, 8, v129
	v_mul_f32_e32 v124, v124, v155
	v_mul_f32_e32 v116, v124, v116
	v_mul_f32_e32 v124, 0xbfb8aa3b, v125
	v_mul_f32_e32 v120, v120, v154
	v_exp_f32_e32 v124, v124
	v_mul_f32_e32 v154, 0xbfb8aa3b, v121
	v_exp_f32_e32 v154, v154
	v_mul_f32_e32 v112, v120, v112
	v_add_f32_e32 v120, 1.0, v124
	v_rcp_f32_e32 v120, v120
	v_add_f32_e32 v124, 1.0, v154
	v_mul_f32_e32 v154, 0xbfb8aa3b, v126
	v_rcp_f32_e32 v124, v124
	v_exp_f32_e32 v154, v154
	v_mul_f32_e32 v120, v125, v120
	v_mul_f32_e32 v117, v120, v117
	v_mul_f32_e32 v120, v121, v124
	v_add_f32_e32 v121, 1.0, v154
	v_rcp_f32_e32 v121, v121
	v_mul_f32_e32 v124, 0xbfb8aa3b, v122
	v_exp_f32_e32 v124, v124
	v_mul_f32_e32 v113, v120, v113
	v_mul_f32_e32 v120, v126, v121
	v_mul_f32_e32 v121, 0xbfb8aa3b, v127
	v_mul_f32_e32 v118, v120, v118
	v_add_f32_e32 v120, 1.0, v124
	v_exp_f32_e32 v121, v121
	v_mul_f32_e32 v124, 0xbfb8aa3b, v123
	v_rcp_f32_e32 v120, v120
	v_exp_f32_e32 v124, v124
	v_add_f32_e32 v121, 1.0, v121
	v_rcp_f32_e32 v121, v121
	v_mul_f32_e32 v120, v122, v120
	v_add_f32_e32 v122, 1.0, v124
	v_rcp_f32_e32 v122, v122
	v_mul_f32_e32 v114, v120, v114
	v_mul_f32_e32 v120, v127, v121
	v_mul_f32_e32 v119, v120, v119
	v_mul_f32_e32 v120, v123, v122
	v_mul_f32_e32 v122, 0xbfb8aa3b, v108
	v_exp_f32_e32 v122, v122
	v_mul_f32_e32 v123, 0xbfb8aa3b, v104
	v_exp_f32_e32 v123, v123
	v_ashrrev_i32_e32 v153, 31, v152
	v_add_f32_e32 v122, 1.0, v122
	v_rcp_f32_e32 v122, v122
	v_mul_f32_e32 v115, v120, v115
	s_nop 1
	v_cvt_pk_bf16_f32 v116, v116, v117
	s_nop 1
	v_cvt_pk_bf16_f32 v117, v118, v119
	s_nop 1
	v_cvt_pk_bf16_f32 v118, v112, v113
	v_mov_b64_e32 v[112:113], s[48:49]
	s_nop 1
	v_cvt_pk_bf16_f32 v119, v114, v115
	v_mad_i64_i32 v[120:121], s[0:1], v151, s47, v[112:113]
	v_lshlrev_b64 v[114:115], 1, v[152:153]
	v_add_f32_e32 v123, 1.0, v123
	v_mul_f32_e32 v108, v108, v122
	v_lshl_add_u64 v[120:121], v[120:121], 0, v[114:115]
	v_rcp_f32_e32 v123, v123
	v_mul_f32_e32 v100, v108, v100
	v_mul_f32_e32 v108, 0xbfb8aa3b, v109
	global_store_dwordx4 v[120:121], v[116:119], off
	v_exp_f32_e32 v108, v108
	v_mul_f32_e32 v104, v104, v123
	v_mul_f32_e32 v116, 0xbfb8aa3b, v105
	v_exp_f32_e32 v116, v116
	v_mul_f32_e32 v104, v104, v96
	v_add_f32_e32 v96, 1.0, v108
	v_rcp_f32_e32 v96, v96
	v_add_f32_e32 v108, 1.0, v116
	v_mul_f32_e32 v116, 0xbfb8aa3b, v110
	v_rcp_f32_e32 v108, v108
	v_exp_f32_e32 v116, v116
	v_mul_f32_e32 v96, v109, v96
	v_mul_f32_e32 v96, v96, v101
	v_mul_f32_e32 v101, v105, v108
	v_add_f32_e32 v105, 1.0, v116
	v_rcp_f32_e32 v105, v105
	v_mul_f32_e32 v108, 0xbfb8aa3b, v106
	v_exp_f32_e32 v108, v108
	v_mul_f32_e32 v101, v101, v97
	v_mul_f32_e32 v97, v110, v105
	v_mul_f32_e32 v105, 0xbfb8aa3b, v111
	v_mul_f32_e32 v97, v97, v102
	v_add_f32_e32 v102, 1.0, v108
	v_exp_f32_e32 v105, v105
	v_mul_f32_e32 v108, 0xbfb8aa3b, v107
	v_rcp_f32_e32 v102, v102
	v_exp_f32_e32 v108, v108
	v_add_f32_e32 v105, 1.0, v105
	v_rcp_f32_e32 v105, v105
	v_mul_f32_e32 v102, v106, v102
	v_add_f32_e32 v106, 1.0, v108
	v_rcp_f32_e32 v106, v106
	v_mul_f32_e32 v102, v102, v98
	v_mul_f32_e32 v98, v111, v105
	v_mul_f32_e32 v98, v98, v103
	v_mul_f32_e32 v103, v107, v106
	v_mul_f32_e32 v99, v103, v99
	s_nop 1
	v_cvt_pk_bf16_f32 v96, v100, v96
	s_nop 1
	v_cvt_pk_bf16_f32 v97, v97, v98
	s_nop 1
	v_cvt_pk_bf16_f32 v98, v104, v101
	s_nop 1
	v_cvt_pk_bf16_f32 v99, v102, v99
	v_mul_f32_e32 v102, 0xbfb8aa3b, v92
	v_exp_f32_e32 v102, v102
	v_mul_f32_e32 v103, 0xbfb8aa3b, v88
	v_exp_f32_e32 v103, v103
	v_or_b32_e32 v100, 16, v151
	v_add_f32_e32 v102, 1.0, v102
	v_rcp_f32_e32 v102, v102
	v_mad_i64_i32 v[100:101], s[0:1], v100, s47, v[112:113]
	v_add_f32_e32 v103, 1.0, v103
	v_mul_f32_e32 v92, v92, v102
	v_lshl_add_u64 v[100:101], v[100:101], 0, v[114:115]
	v_rcp_f32_e32 v103, v103
	v_mul_f32_e32 v84, v92, v84
	v_mul_f32_e32 v92, 0xbfb8aa3b, v93
	global_store_dwordx4 v[100:101], v[96:99], off
	v_exp_f32_e32 v92, v92
	v_mul_f32_e32 v88, v88, v103
	v_mul_f32_e32 v96, 0xbfb8aa3b, v89
	v_exp_f32_e32 v96, v96
	v_mul_f32_e32 v88, v88, v80
	v_add_f32_e32 v80, 1.0, v92
	v_rcp_f32_e32 v80, v80
	v_add_f32_e32 v92, 1.0, v96
	v_mul_f32_e32 v96, 0xbfb8aa3b, v94
	v_rcp_f32_e32 v92, v92
	v_exp_f32_e32 v96, v96
	v_mul_f32_e32 v80, v93, v80
	v_mul_f32_e32 v80, v80, v85
	v_mul_f32_e32 v85, v89, v92
	v_add_f32_e32 v89, 1.0, v96
	v_rcp_f32_e32 v89, v89
	v_mul_f32_e32 v92, 0xbfb8aa3b, v90
	v_exp_f32_e32 v92, v92
	v_mul_f32_e32 v85, v85, v81
	v_mul_f32_e32 v81, v94, v89
	v_mul_f32_e32 v89, 0xbfb8aa3b, v95
	v_mul_f32_e32 v81, v81, v86
	v_add_f32_e32 v86, 1.0, v92
	v_exp_f32_e32 v89, v89
	v_mul_f32_e32 v92, 0xbfb8aa3b, v91
	v_rcp_f32_e32 v86, v86
	v_exp_f32_e32 v92, v92
	v_add_f32_e32 v89, 1.0, v89
	v_rcp_f32_e32 v89, v89
	v_mul_f32_e32 v86, v90, v86
	v_add_f32_e32 v90, 1.0, v92
	v_rcp_f32_e32 v90, v90
	v_mul_f32_e32 v86, v86, v82
	v_mul_f32_e32 v82, v95, v89
	v_mul_f32_e32 v82, v82, v87
	v_mul_f32_e32 v87, v91, v90
	v_mul_f32_e32 v83, v87, v83
	s_nop 1
	v_cvt_pk_bf16_f32 v80, v84, v80
	s_nop 1
	v_cvt_pk_bf16_f32 v81, v81, v82
	s_nop 1
	v_cvt_pk_bf16_f32 v82, v88, v85
	s_nop 1
	v_cvt_pk_bf16_f32 v83, v86, v83
	v_mul_f32_e32 v86, 0xbfb8aa3b, v76
	v_exp_f32_e32 v86, v86
	v_mul_f32_e32 v87, 0xbfb8aa3b, v72
	v_exp_f32_e32 v87, v87
	v_or_b32_e32 v84, 32, v151
	v_add_f32_e32 v86, 1.0, v86
	v_rcp_f32_e32 v86, v86
	v_mad_i64_i32 v[84:85], s[0:1], v84, s47, v[112:113]
	v_add_f32_e32 v87, 1.0, v87
	v_mul_f32_e32 v76, v76, v86
	v_lshl_add_u64 v[84:85], v[84:85], 0, v[114:115]
	v_rcp_f32_e32 v87, v87
	v_mul_f32_e32 v68, v76, v68
	v_mul_f32_e32 v76, 0xbfb8aa3b, v77
	global_store_dwordx4 v[84:85], v[80:83], off
	v_exp_f32_e32 v76, v76
	v_mul_f32_e32 v72, v72, v87
	v_mul_f32_e32 v80, 0xbfb8aa3b, v73
	v_exp_f32_e32 v80, v80
	v_mul_f32_e32 v72, v72, v64
	v_add_f32_e32 v64, 1.0, v76
	v_rcp_f32_e32 v64, v64
	v_add_f32_e32 v76, 1.0, v80
	v_mul_f32_e32 v80, 0xbfb8aa3b, v78
	v_rcp_f32_e32 v76, v76
	v_exp_f32_e32 v80, v80
	v_mul_f32_e32 v64, v77, v64
	v_mul_f32_e32 v64, v64, v69
	v_mul_f32_e32 v69, v73, v76
	v_add_f32_e32 v73, 1.0, v80
	v_rcp_f32_e32 v73, v73
	v_mul_f32_e32 v76, 0xbfb8aa3b, v74
	v_exp_f32_e32 v76, v76
	v_mul_f32_e32 v69, v69, v65
	v_mul_f32_e32 v65, v78, v73
	v_mul_f32_e32 v73, 0xbfb8aa3b, v79
	v_mul_f32_e32 v65, v65, v70
	v_add_f32_e32 v70, 1.0, v76
	v_exp_f32_e32 v73, v73
	v_mul_f32_e32 v76, 0xbfb8aa3b, v75
	v_rcp_f32_e32 v70, v70
	v_exp_f32_e32 v76, v76
	v_add_f32_e32 v73, 1.0, v73
	v_rcp_f32_e32 v73, v73
	v_mul_f32_e32 v70, v74, v70
	v_add_f32_e32 v74, 1.0, v76
	v_rcp_f32_e32 v74, v74
	v_mul_f32_e32 v70, v70, v66
	v_mul_f32_e32 v66, v79, v73
	v_mul_f32_e32 v66, v66, v71
	v_mul_f32_e32 v71, v75, v74
	v_mul_f32_e32 v67, v71, v67
	s_nop 1
	v_cvt_pk_bf16_f32 v64, v68, v64
	s_nop 1
	v_cvt_pk_bf16_f32 v65, v65, v66
	s_nop 1
	v_cvt_pk_bf16_f32 v66, v72, v69
	s_nop 1
	v_cvt_pk_bf16_f32 v67, v70, v67
	v_mul_f32_e32 v70, 0xbfb8aa3b, v60
	v_exp_f32_e32 v70, v70
	v_or_b32_e32 v68, 48, v151
	v_mad_i64_i32 v[68:69], s[0:1], v68, s47, v[112:113]
	v_lshl_add_u64 v[68:69], v[68:69], 0, v[114:115]
	v_mul_f32_e32 v71, 0xbfb8aa3b, v56
	global_store_dwordx4 v[68:69], v[64:67], off
	v_exp_f32_e32 v71, v71
	s_and_b64 vcc, exec, s[6:7]
	v_add_f32_e32 v64, 1.0, v70
	v_rcp_f32_e32 v64, v64
	v_add_f32_e32 v65, 1.0, v71
	v_rcp_f32_e32 v65, v65
	v_add_u32_e32 v66, 0x80, v151
	v_mul_f32_e32 v60, v60, v64
	v_mul_f32_e32 v52, v60, v52
	v_mul_f32_e32 v60, 0xbfb8aa3b, v61
	v_exp_f32_e32 v60, v60
	v_mul_f32_e32 v64, 0xbfb8aa3b, v57
	v_exp_f32_e32 v64, v64
	v_mul_f32_e32 v56, v56, v65
	v_mul_f32_e32 v56, v56, v48
	v_add_f32_e32 v48, 1.0, v60
	v_rcp_f32_e32 v48, v48
	v_add_f32_e32 v60, 1.0, v64
	v_mul_f32_e32 v64, 0xbfb8aa3b, v62
	v_rcp_f32_e32 v60, v60
	v_exp_f32_e32 v64, v64
	v_mul_f32_e32 v48, v61, v48
	v_mul_f32_e32 v48, v48, v53
	v_mul_f32_e32 v53, v57, v60
	v_add_f32_e32 v57, 1.0, v64
	v_rcp_f32_e32 v57, v57
	v_mul_f32_e32 v60, 0xbfb8aa3b, v58
	v_exp_f32_e32 v60, v60
	v_mul_f32_e32 v53, v53, v49
	v_mul_f32_e32 v49, v62, v57
	v_mul_f32_e32 v57, 0xbfb8aa3b, v63
	v_mul_f32_e32 v49, v49, v54
	v_add_f32_e32 v54, 1.0, v60
	v_exp_f32_e32 v57, v57
	v_mul_f32_e32 v60, 0xbfb8aa3b, v59
	v_rcp_f32_e32 v54, v54
	v_exp_f32_e32 v60, v60
	v_add_f32_e32 v57, 1.0, v57
	v_rcp_f32_e32 v57, v57
	v_mul_f32_e32 v54, v58, v54
	v_add_f32_e32 v58, 1.0, v60
	v_rcp_f32_e32 v58, v58
	v_mul_f32_e32 v54, v54, v50
	v_mul_f32_e32 v50, v63, v57
	v_mul_f32_e32 v50, v50, v55
	v_mul_f32_e32 v55, v59, v58
	v_mul_f32_e32 v51, v55, v51
	s_nop 1
	v_cvt_pk_bf16_f32 v48, v52, v48
	s_nop 1
	v_cvt_pk_bf16_f32 v49, v49, v50
	s_nop 1
	v_cvt_pk_bf16_f32 v50, v56, v53
	s_nop 1
	v_cvt_pk_bf16_f32 v51, v54, v51
	v_mul_f32_e32 v54, 0xbfb8aa3b, v44
	v_exp_f32_e32 v54, v54
	v_mul_f32_e32 v55, 0xbfb8aa3b, v40
	v_exp_f32_e32 v55, v55
	v_mad_i64_i32 v[52:53], s[0:1], v66, s47, v[112:113]
	v_add_f32_e32 v54, 1.0, v54
	v_rcp_f32_e32 v54, v54
	v_add_f32_e32 v55, 1.0, v55
	v_lshl_add_u64 v[52:53], v[52:53], 0, v[114:115]
	v_rcp_f32_e32 v55, v55
	v_mul_f32_e32 v44, v44, v54
	v_mul_f32_e32 v36, v44, v36
	v_mul_f32_e32 v44, 0xbfb8aa3b, v45
	global_store_dwordx4 v[52:53], v[48:51], off
	v_exp_f32_e32 v44, v44
	v_mul_f32_e32 v40, v40, v55
	v_mul_f32_e32 v48, 0xbfb8aa3b, v41
	v_exp_f32_e32 v48, v48
	v_mul_f32_e32 v40, v40, v32
	v_add_f32_e32 v32, 1.0, v44
	v_rcp_f32_e32 v32, v32
	v_add_f32_e32 v44, 1.0, v48
	v_mul_f32_e32 v48, 0xbfb8aa3b, v46
	v_rcp_f32_e32 v44, v44
	v_exp_f32_e32 v48, v48
	v_mul_f32_e32 v32, v45, v32
	v_mul_f32_e32 v32, v32, v37
	v_mul_f32_e32 v37, v41, v44
	v_add_f32_e32 v41, 1.0, v48
	v_rcp_f32_e32 v41, v41
	v_mul_f32_e32 v44, 0xbfb8aa3b, v42
	v_exp_f32_e32 v44, v44
	v_mul_f32_e32 v37, v37, v33
	v_mul_f32_e32 v33, v46, v41
	v_mul_f32_e32 v41, 0xbfb8aa3b, v47
	v_mul_f32_e32 v33, v33, v38
	v_add_f32_e32 v38, 1.0, v44
	v_exp_f32_e32 v41, v41
	v_mul_f32_e32 v44, 0xbfb8aa3b, v43
	v_rcp_f32_e32 v38, v38
	v_exp_f32_e32 v44, v44
	v_add_f32_e32 v41, 1.0, v41
	v_rcp_f32_e32 v41, v41
	v_mul_f32_e32 v38, v42, v38
	v_add_f32_e32 v42, 1.0, v44
	v_rcp_f32_e32 v42, v42
	v_mul_f32_e32 v38, v38, v34
	v_mul_f32_e32 v34, v47, v41
	v_mul_f32_e32 v34, v34, v39
	v_mul_f32_e32 v39, v43, v42
	v_mul_f32_e32 v35, v39, v35
	s_nop 1
	v_cvt_pk_bf16_f32 v32, v36, v32
	s_nop 1
	v_cvt_pk_bf16_f32 v33, v33, v34
	s_nop 1
	v_cvt_pk_bf16_f32 v34, v40, v37
	s_nop 1
	v_cvt_pk_bf16_f32 v35, v38, v35
	v_mul_f32_e32 v38, 0xbfb8aa3b, v28
	v_exp_f32_e32 v38, v38
	v_mul_f32_e32 v39, 0xbfb8aa3b, v24
	v_exp_f32_e32 v39, v39
	v_add_u32_e32 v36, 0x90, v151
	v_add_f32_e32 v38, 1.0, v38
	v_rcp_f32_e32 v38, v38
	v_mad_i64_i32 v[36:37], s[0:1], v36, s47, v[112:113]
	v_add_f32_e32 v39, 1.0, v39
	v_mul_f32_e32 v28, v28, v38
	v_lshl_add_u64 v[36:37], v[36:37], 0, v[114:115]
	v_rcp_f32_e32 v39, v39
	v_mul_f32_e32 v20, v28, v20
	v_mul_f32_e32 v28, 0xbfb8aa3b, v29
	global_store_dwordx4 v[36:37], v[32:35], off
	v_exp_f32_e32 v28, v28
	v_mul_f32_e32 v24, v24, v39
	v_mul_f32_e32 v32, 0xbfb8aa3b, v25
	v_exp_f32_e32 v32, v32
	v_mul_f32_e32 v24, v24, v16
	v_add_f32_e32 v16, 1.0, v28
	v_rcp_f32_e32 v16, v16
	v_add_f32_e32 v28, 1.0, v32
	v_mul_f32_e32 v32, 0xbfb8aa3b, v30
	v_rcp_f32_e32 v28, v28
	v_exp_f32_e32 v32, v32
	v_mul_f32_e32 v16, v29, v16
	v_mul_f32_e32 v16, v16, v21
	v_mul_f32_e32 v21, v25, v28
	v_add_f32_e32 v25, 1.0, v32
	v_rcp_f32_e32 v25, v25
	v_mul_f32_e32 v28, 0xbfb8aa3b, v26
	v_exp_f32_e32 v28, v28
	v_mul_f32_e32 v21, v21, v17
	v_mul_f32_e32 v17, v30, v25
	v_mul_f32_e32 v25, 0xbfb8aa3b, v31
	v_mul_f32_e32 v17, v17, v22
	v_add_f32_e32 v22, 1.0, v28
	v_exp_f32_e32 v25, v25
	v_mul_f32_e32 v28, 0xbfb8aa3b, v27
	v_rcp_f32_e32 v22, v22
	v_exp_f32_e32 v28, v28
	v_add_f32_e32 v25, 1.0, v25
	v_rcp_f32_e32 v25, v25
	v_mul_f32_e32 v22, v26, v22
	v_add_f32_e32 v26, 1.0, v28
	v_rcp_f32_e32 v26, v26
	v_mul_f32_e32 v22, v22, v18
	v_mul_f32_e32 v18, v31, v25
	v_mul_f32_e32 v18, v18, v23
	v_mul_f32_e32 v23, v27, v26
	v_mul_f32_e32 v19, v23, v19
	s_nop 1
	v_cvt_pk_bf16_f32 v16, v20, v16
	s_nop 1
	v_cvt_pk_bf16_f32 v17, v17, v18
	s_nop 1
	v_cvt_pk_bf16_f32 v18, v24, v21
	s_nop 1
	v_cvt_pk_bf16_f32 v19, v22, v19
	v_mul_f32_e32 v22, 0xbfb8aa3b, v12
	v_exp_f32_e32 v22, v22
	v_mul_f32_e32 v23, 0xbfb8aa3b, v8
	v_exp_f32_e32 v23, v23
	v_add_u32_e32 v20, 0xa0, v151
	v_add_f32_e32 v22, 1.0, v22
	v_rcp_f32_e32 v22, v22
	v_mad_i64_i32 v[20:21], s[0:1], v20, s47, v[112:113]
	v_add_f32_e32 v23, 1.0, v23
	v_mul_f32_e32 v12, v12, v22
	v_lshl_add_u64 v[20:21], v[20:21], 0, v[114:115]
	v_rcp_f32_e32 v23, v23
	v_mul_f32_e32 v4, v12, v4
	v_mul_f32_e32 v12, 0xbfb8aa3b, v13
	global_store_dwordx4 v[20:21], v[16:19], off
	v_exp_f32_e32 v12, v12
	v_mul_f32_e32 v8, v8, v23
	v_mul_f32_e32 v16, 0xbfb8aa3b, v9
	v_exp_f32_e32 v16, v16
	v_mul_f32_e32 v8, v8, v0
	v_add_f32_e32 v0, 1.0, v12
	v_rcp_f32_e32 v0, v0
	v_add_f32_e32 v12, 1.0, v16
	v_mul_f32_e32 v16, 0xbfb8aa3b, v14
	v_rcp_f32_e32 v12, v12
	v_exp_f32_e32 v16, v16
	v_mul_f32_e32 v0, v13, v0
	v_mul_f32_e32 v0, v0, v5
	v_mul_f32_e32 v5, v9, v12
	v_add_f32_e32 v9, 1.0, v16
	v_rcp_f32_e32 v9, v9
	v_mul_f32_e32 v12, 0xbfb8aa3b, v10
	v_exp_f32_e32 v12, v12
	v_mul_f32_e32 v5, v5, v1
	v_mul_f32_e32 v1, v14, v9
	v_mul_f32_e32 v9, 0xbfb8aa3b, v15
	v_exp_f32_e32 v9, v9
	v_mul_f32_e32 v1, v1, v6
	v_add_f32_e32 v6, 1.0, v12
	v_mul_f32_e32 v12, 0xbfb8aa3b, v11
	v_rcp_f32_e32 v6, v6
	v_exp_f32_e32 v12, v12
	v_add_f32_e32 v9, 1.0, v9
	v_rcp_f32_e32 v9, v9
	v_mul_f32_e32 v6, v10, v6
	v_add_f32_e32 v10, 1.0, v12
	v_rcp_f32_e32 v10, v10
	v_mul_f32_e32 v6, v6, v2
	v_mul_f32_e32 v2, v15, v9
	v_mul_f32_e32 v2, v2, v7
	s_nop 1
	v_cvt_pk_bf16_f32 v0, v4, v0
	v_add_u32_e32 v4, 0xb0, v151
	v_mul_f32_e32 v7, v11, v10
	s_nop 1
	v_cvt_pk_bf16_f32 v1, v1, v2
	s_nop 1
	v_cvt_pk_bf16_f32 v2, v8, v5
	v_mad_i64_i32 v[4:5], s[0:1], v4, s47, v[112:113]
	v_mul_f32_e32 v3, v7, v3
	v_lshl_add_u64 v[4:5], v[4:5], 0, v[114:115]
	s_mov_b32 s53, s10
	s_mov_b32 s18, s12
	s_mov_b64 s[50:51], s[16:17]
	s_mov_b64 s[36:37], s[14:15]
	s_nop 1
	v_cvt_pk_bf16_f32 v3, v6, v3
	global_store_dwordx4 v[4:5], v[0:3], off
	s_cbranch_vccz .LBB0_983
	s_waitcnt vmcnt(0)
	s_cmpk_gt_u32 s20, 0xff
	s_cbranch_scc1 .LBB0_990
	s_barrier

.LBB0_1003:
	s_ashr_i32 s61, s60, 31
	s_lshl_b64 s[0:1], s[60:61], 17
	v_readlane_b32 s42, v255, 18
	v_readlane_b32 s43, v255, 19
	s_add_u32 s62, s42, s0
	v_cmp_lt_i64_e32 vcc, s[16:17], v[124:125]
	s_addc_u32 s63, s43, s1
	ds_read_b128 v[0:3], v136
	ds_read_b128 v[4:7], v136 offset:1024
	ds_read_b128 v[8:11], v136 offset:2048
	ds_read_b128 v[12:15], v136 offset:3072
	s_and_b64 s[0:1], vcc, exec
	s_cselect_b32 s75, s63, s69
	s_cselect_b32 s74, s62, s68
	s_ashr_i32 s19, s18, 31
	s_lshl_b64 s[0:1], s[18:19], 17
	v_readlane_b32 s42, v255, 16
	v_readlane_b32 s43, v255, 17
	s_add_u32 s64, s42, s0
	s_addc_u32 s65, s43, s1
	s_and_b64 s[0:1], vcc, exec
	s_cselect_b32 s71, s65, s73
	s_cselect_b32 s70, s64, s72
	s_add_u32 s0, s68, 0x10080
	s_addc_u32 s1, s69, 0
	s_mov_b32 m0, s37
	v_lshl_add_u64 v[48:49], s[0:1], 0, v[120:121]
	ds_read_b128 v[16:19], v137
	ds_read_b128 v[20:23], v137 offset:1024
	ds_read_b128 v[24:27], v137 offset:2048
	ds_read_b128 v[28:31], v137 offset:3072
	ds_read_b128 v[32:35], v137 offset:4096
	ds_read_b128 v[36:39], v137 offset:5120
	ds_read_b128 v[40:43], v137 offset:6144
	ds_read_b128 v[44:47], v137 offset:7168
	global_load_lds_dwordx4 v[48:49], off
	v_lshl_add_u64 v[48:49], s[0:1], 0, v[122:123]
	s_mov_b32 m0, s40
	s_nop 0
	global_load_lds_dwordx4 v[48:49], off
	s_waitcnt lgkmcnt(8)
	s_barrier
	s_waitcnt lgkmcnt(0)
	s_waitcnt lgkmcnt(0)
	v_mfma_f32_16x16x32_bf16 v[48:51], v[0:3], v[16:19], 0
	v_mfma_f32_16x16x32_bf16 v[52:55], v[8:11], v[16:19], 0
	v_mfma_f32_16x16x32_bf16 v[56:59], v[0:3], v[24:27], 0
	v_mfma_f32_16x16x32_bf16 v[60:63], v[8:11], v[24:27], 0
	v_mfma_f32_16x16x32_bf16 v[64:67], v[0:3], v[32:35], 0
	v_mfma_f32_16x16x32_bf16 v[68:71], v[8:11], v[32:35], 0
	v_mfma_f32_16x16x32_bf16 v[72:75], v[0:3], v[40:43], 0
	v_mfma_f32_16x16x32_bf16 v[76:79], v[8:11], v[40:43], 0
	v_mfma_f32_16x16x32_bf16 v[48:51], v[4:7], v[20:23], v[48:51]
	v_mfma_f32_16x16x32_bf16 v[52:55], v[12:15], v[20:23], v[52:55]
	v_mfma_f32_16x16x32_bf16 v[56:59], v[4:7], v[28:31], v[56:59]
	v_mfma_f32_16x16x32_bf16 v[60:63], v[12:15], v[28:31], v[60:63]
	v_mfma_f32_16x16x32_bf16 v[64:67], v[4:7], v[36:39], v[64:67]
	v_mfma_f32_16x16x32_bf16 v[68:71], v[12:15], v[36:39], v[68:71]
	v_mfma_f32_16x16x32_bf16 v[72:75], v[4:7], v[44:47], v[72:75]
	v_mfma_f32_16x16x32_bf16 v[76:79], v[12:15], v[44:47], v[76:79]
	s_barrier
	v_lshl_add_u64 v[208:209], s[72:73], 0, v[120:121]
	s_add_i32 s15, s36, s5
	v_lshl_add_u64 v[96:97], v[208:209], 0, s[10:11]
	s_mov_b32 m0, s15
	v_lshl_add_u64 v[210:211], s[72:73], 0, v[122:123]
	s_add_i32 s0, s15, 0x2000
	ds_read_b128 v[80:83], v138
	ds_read_b128 v[84:87], v138 offset:1024
	ds_read_b128 v[88:91], v138 offset:2048
	ds_read_b128 v[92:95], v138 offset:3072
	global_load_lds_dwordx4 v[96:97], off
	v_lshl_add_u64 v[96:97], v[210:211], 0, s[10:11]
	s_mov_b32 m0, s0
	s_nop 0
	global_load_lds_dwordx4 v[96:97], off
	s_barrier
	s_waitcnt lgkmcnt(0)
	s_waitcnt lgkmcnt(0)
	v_mfma_f32_16x16x32_bf16 v[96:99], v[80:83], v[16:19], 0
	v_mfma_f32_16x16x32_bf16 v[16:19], v[88:91], v[16:19], 0
	v_mfma_f32_16x16x32_bf16 v[96:99], v[84:87], v[20:23], v[96:99]
	v_mfma_f32_16x16x32_bf16 v[16:19], v[92:95], v[20:23], v[16:19]
	v_mfma_f32_16x16x32_bf16 v[20:23], v[80:83], v[24:27], 0
	v_mfma_f32_16x16x32_bf16 v[24:27], v[88:91], v[24:27], 0
	v_mfma_f32_16x16x32_bf16 v[20:23], v[84:87], v[28:31], v[20:23]
	v_mfma_f32_16x16x32_bf16 v[24:27], v[92:95], v[28:31], v[24:27]
	v_mfma_f32_16x16x32_bf16 v[28:31], v[80:83], v[32:35], 0
	v_mfma_f32_16x16x32_bf16 v[32:35], v[88:91], v[32:35], 0
	v_mfma_f32_16x16x32_bf16 v[28:31], v[84:87], v[36:39], v[28:31]
	v_mfma_f32_16x16x32_bf16 v[32:35], v[92:95], v[36:39], v[32:35]
	v_mfma_f32_16x16x32_bf16 v[36:39], v[80:83], v[40:43], 0
	v_mfma_f32_16x16x32_bf16 v[40:43], v[88:91], v[40:43], 0
	v_mfma_f32_16x16x32_bf16 v[36:39], v[84:87], v[44:47], v[36:39]
	v_mfma_f32_16x16x32_bf16 v[40:43], v[92:95], v[44:47], v[40:43]
	v_lshl_add_u64 v[212:213], s[68:69], 0, v[120:121]
	s_mov_b32 m0, s20
	v_lshl_add_u64 v[144:145], v[212:213], 0, s[10:11]
	v_lshl_add_u64 v[214:215], s[68:69], 0, v[122:123]
	s_barrier
	ds_read_b128 v[44:47], v137 offset:16384
	ds_read_b128 v[100:103], v137 offset:17408
	ds_read_b128 v[104:107], v137 offset:18432
	ds_read_b128 v[108:111], v137 offset:19456
	ds_read_b128 v[112:115], v137 offset:20480
	ds_read_b128 v[116:119], v137 offset:21504
	ds_read_b128 v[130:133], v137 offset:22528
	ds_read_b128 v[140:143], v137 offset:23552
	global_load_lds_dwordx4 v[144:145], off
	v_lshl_add_u64 v[144:145], v[214:215], 0, s[10:11]
	s_mov_b32 m0, s21
	s_nop 0
	global_load_lds_dwordx4 v[144:145], off
	s_barrier
	s_waitcnt lgkmcnt(0)
	s_waitcnt lgkmcnt(0)
	v_mfma_f32_16x16x32_bf16 v[144:147], v[0:3], v[44:47], 0
	v_mfma_f32_16x16x32_bf16 v[152:155], v[0:3], v[104:107], 0
	v_mfma_f32_16x16x32_bf16 v[160:163], v[0:3], v[112:115], 0
	v_mfma_f32_16x16x32_bf16 v[0:3], v[0:3], v[130:133], 0
	v_mfma_f32_16x16x32_bf16 v[144:147], v[4:7], v[100:103], v[144:147]
	v_mfma_f32_16x16x32_bf16 v[148:151], v[8:11], v[44:47], 0
	v_mfma_f32_16x16x32_bf16 v[152:155], v[4:7], v[108:111], v[152:155]
	v_mfma_f32_16x16x32_bf16 v[156:159], v[8:11], v[104:107], 0
	v_mfma_f32_16x16x32_bf16 v[160:163], v[4:7], v[116:119], v[160:163]
	v_mfma_f32_16x16x32_bf16 v[164:167], v[8:11], v[112:115], 0
	v_mfma_f32_16x16x32_bf16 v[0:3], v[4:7], v[140:143], v[0:3]
	v_mfma_f32_16x16x32_bf16 v[4:7], v[8:11], v[130:133], 0
	v_mfma_f32_16x16x32_bf16 v[148:151], v[12:15], v[100:103], v[148:151]
	v_mfma_f32_16x16x32_bf16 v[156:159], v[12:15], v[108:111], v[156:159]
	v_mfma_f32_16x16x32_bf16 v[164:167], v[12:15], v[116:119], v[164:167]
	v_mfma_f32_16x16x32_bf16 v[4:7], v[12:15], v[140:143], v[4:7]
	s_barrier
	s_add_u32 s42, s72, 0x10100
	s_addc_u32 s43, s73, 0
	s_add_i32 s19, s41, s5
	v_lshl_add_u64 v[8:9], s[42:43], 0, v[120:121]
	s_mov_b32 m0, s19
	s_add_i32 s1, s19, 0x2000
	global_load_lds_dwordx4 v[8:9], off
	v_lshl_add_u64 v[8:9], s[42:43], 0, v[122:123]
	s_mov_b32 m0, s1
	s_nop 0
	global_load_lds_dwordx4 v[8:9], off
	s_waitcnt vmcnt(6)
	s_barrier
	v_mfma_f32_16x16x32_bf16 v[8:11], v[80:83], v[44:47], 0
	v_mfma_f32_16x16x32_bf16 v[12:15], v[88:91], v[44:47], 0
	v_mfma_f32_16x16x32_bf16 v[8:11], v[84:87], v[100:103], v[8:11]
	v_mfma_f32_16x16x32_bf16 v[12:15], v[92:95], v[100:103], v[12:15]
	v_mfma_f32_16x16x32_bf16 v[44:47], v[80:83], v[104:107], 0
	v_mfma_f32_16x16x32_bf16 v[100:103], v[88:91], v[104:107], 0
	v_mfma_f32_16x16x32_bf16 v[104:107], v[80:83], v[112:115], 0
	v_mfma_f32_16x16x32_bf16 v[80:83], v[80:83], v[130:133], 0
	v_mfma_f32_16x16x32_bf16 v[44:47], v[84:87], v[108:111], v[44:47]
	v_mfma_f32_16x16x32_bf16 v[100:103], v[92:95], v[108:111], v[100:103]
	v_mfma_f32_16x16x32_bf16 v[104:107], v[84:87], v[116:119], v[104:107]
	v_mfma_f32_16x16x32_bf16 v[108:111], v[88:91], v[112:115], 0
	v_mfma_f32_16x16x32_bf16 v[80:83], v[84:87], v[140:143], v[80:83]
	v_mfma_f32_16x16x32_bf16 v[84:87], v[88:91], v[130:133], 0
	v_mfma_f32_16x16x32_bf16 v[108:111], v[92:95], v[116:119], v[108:111]
	v_mfma_f32_16x16x32_bf16 v[84:87], v[92:95], v[140:143], v[84:87]
	s_add_i32 s76, 0, 0x18000
	v_add_u32_e32 v216, s76, v134
	s_barrier
	ds_read_b128 v[88:91], v216
	ds_read_b128 v[92:95], v216 offset:1024
	ds_read_b128 v[112:115], v216 offset:2048
	ds_read_b128 v[116:119], v216 offset:3072
	s_add_u32 s42, s68, 0x10100
	s_addc_u32 s43, s69, 0
	s_mov_b32 m0, s23
	v_lshl_add_u64 v[192:193], s[42:43], 0, v[120:121]
	ds_read_b128 v[130:133], v137 offset:32768
	ds_read_b128 v[140:143], v137 offset:33792
	ds_read_b128 v[168:171], v137 offset:34816
	ds_read_b128 v[172:175], v137 offset:35840
	ds_read_b128 v[176:179], v137 offset:36864
	ds_read_b128 v[180:183], v137 offset:37888
	ds_read_b128 v[184:187], v137 offset:38912
	ds_read_b128 v[188:191], v137 offset:39936
	global_load_lds_dwordx4 v[192:193], off
	v_lshl_add_u64 v[192:193], s[42:43], 0, v[122:123]
	s_mov_b32 m0, s24
	s_nop 0
	global_load_lds_dwordx4 v[192:193], off
	s_waitcnt lgkmcnt(8)
	s_barrier
	s_waitcnt lgkmcnt(0)
	s_waitcnt lgkmcnt(0)
	v_mfma_f32_16x16x32_bf16 v[48:51], v[88:91], v[130:133], v[48:51]
	v_mfma_f32_16x16x32_bf16 v[52:55], v[112:115], v[130:133], v[52:55]
	v_mfma_f32_16x16x32_bf16 v[56:59], v[88:91], v[168:171], v[56:59]
	v_mfma_f32_16x16x32_bf16 v[60:63], v[112:115], v[168:171], v[60:63]
	v_mfma_f32_16x16x32_bf16 v[64:67], v[88:91], v[176:179], v[64:67]
	v_mfma_f32_16x16x32_bf16 v[68:71], v[112:115], v[176:179], v[68:71]
	v_mfma_f32_16x16x32_bf16 v[72:75], v[88:91], v[184:187], v[72:75]
	v_mfma_f32_16x16x32_bf16 v[76:79], v[112:115], v[184:187], v[76:79]
	v_mfma_f32_16x16x32_bf16 v[48:51], v[92:95], v[140:143], v[48:51]
	v_mfma_f32_16x16x32_bf16 v[52:55], v[116:119], v[140:143], v[52:55]
	v_mfma_f32_16x16x32_bf16 v[56:59], v[92:95], v[172:175], v[56:59]
	v_mfma_f32_16x16x32_bf16 v[60:63], v[116:119], v[172:175], v[60:63]
	v_mfma_f32_16x16x32_bf16 v[64:67], v[92:95], v[180:183], v[64:67]
	v_mfma_f32_16x16x32_bf16 v[68:71], v[116:119], v[180:183], v[68:71]
	v_mfma_f32_16x16x32_bf16 v[72:75], v[92:95], v[188:191], v[72:75]
	v_mfma_f32_16x16x32_bf16 v[76:79], v[116:119], v[188:191], v[76:79]
	s_barrier
	s_add_i32 s44, 0, 0x1c000
	s_add_i32 s76, s76, s5
	v_add_u32_e32 v236, s44, v134
	v_lshl_add_u64 v[208:209], v[208:209], 0, s[12:13]
	s_mov_b32 m0, s76
	s_add_i32 s61, s76, 0x2000
	ds_read_b128 v[192:195], v236
	ds_read_b128 v[196:199], v236 offset:1024
	ds_read_b128 v[200:203], v236 offset:2048
	ds_read_b128 v[204:207], v236 offset:3072
	global_load_lds_dwordx4 v[208:209], off
	v_lshl_add_u64 v[208:209], v[210:211], 0, s[12:13]
	s_mov_b32 m0, s61
	s_nop 0
	global_load_lds_dwordx4 v[208:209], off
	s_barrier
	s_waitcnt lgkmcnt(0)
	s_waitcnt lgkmcnt(0)
	v_mfma_f32_16x16x32_bf16 v[96:99], v[192:195], v[130:133], v[96:99]
	v_mfma_f32_16x16x32_bf16 v[16:19], v[200:203], v[130:133], v[16:19]
	v_mfma_f32_16x16x32_bf16 v[20:23], v[192:195], v[168:171], v[20:23]
	v_mfma_f32_16x16x32_bf16 v[24:27], v[200:203], v[168:171], v[24:27]
	v_mfma_f32_16x16x32_bf16 v[28:31], v[192:195], v[176:179], v[28:31]
	v_mfma_f32_16x16x32_bf16 v[32:35], v[200:203], v[176:179], v[32:35]
	v_mfma_f32_16x16x32_bf16 v[36:39], v[192:195], v[184:187], v[36:39]
	v_mfma_f32_16x16x32_bf16 v[40:43], v[200:203], v[184:187], v[40:43]
	v_mfma_f32_16x16x32_bf16 v[96:99], v[196:199], v[140:143], v[96:99]
	v_mfma_f32_16x16x32_bf16 v[16:19], v[204:207], v[140:143], v[16:19]
	v_mfma_f32_16x16x32_bf16 v[20:23], v[196:199], v[172:175], v[20:23]
	v_mfma_f32_16x16x32_bf16 v[24:27], v[204:207], v[172:175], v[24:27]
	v_mfma_f32_16x16x32_bf16 v[28:31], v[196:199], v[180:183], v[28:31]
	v_mfma_f32_16x16x32_bf16 v[32:35], v[204:207], v[180:183], v[32:35]
	v_mfma_f32_16x16x32_bf16 v[36:39], v[196:199], v[188:191], v[36:39]
	v_mfma_f32_16x16x32_bf16 v[40:43], v[204:207], v[188:191], v[40:43]
	s_mov_b32 m0, s25
	v_lshl_add_u64 v[208:209], v[212:213], 0, s[12:13]
	s_barrier
	ds_read_b128 v[130:133], v137 offset:49152
	ds_read_b128 v[140:143], v137 offset:50176
	ds_read_b128 v[168:171], v137 offset:51200
	ds_read_b128 v[172:175], v137 offset:52224
	ds_read_b128 v[176:179], v137 offset:53248
	ds_read_b128 v[180:183], v137 offset:54272
	ds_read_b128 v[184:187], v137 offset:55296
	ds_read_b128 v[188:191], v137 offset:56320
	global_load_lds_dwordx4 v[208:209], off
	v_lshl_add_u64 v[208:209], v[214:215], 0, s[12:13]
	s_mov_b32 m0, s28
	s_nop 0
	global_load_lds_dwordx4 v[208:209], off
	s_barrier
	s_waitcnt lgkmcnt(0)
	s_waitcnt lgkmcnt(0)
	v_mfma_f32_16x16x32_bf16 v[144:147], v[88:91], v[130:133], v[144:147]
	v_mfma_f32_16x16x32_bf16 v[148:151], v[112:115], v[130:133], v[148:151]
	v_mfma_f32_16x16x32_bf16 v[152:155], v[88:91], v[168:171], v[152:155]
	v_mfma_f32_16x16x32_bf16 v[156:159], v[112:115], v[168:171], v[156:159]
	v_mfma_f32_16x16x32_bf16 v[160:163], v[88:91], v[176:179], v[160:163]
	v_mfma_f32_16x16x32_bf16 v[164:167], v[112:115], v[176:179], v[164:167]
	v_mfma_f32_16x16x32_bf16 v[0:3], v[88:91], v[184:187], v[0:3]
	v_mfma_f32_16x16x32_bf16 v[4:7], v[112:115], v[184:187], v[4:7]
	v_mfma_f32_16x16x32_bf16 v[144:147], v[92:95], v[140:143], v[144:147]
	v_mfma_f32_16x16x32_bf16 v[148:151], v[116:119], v[140:143], v[148:151]
	v_mfma_f32_16x16x32_bf16 v[152:155], v[92:95], v[172:175], v[152:155]
	v_mfma_f32_16x16x32_bf16 v[156:159], v[116:119], v[172:175], v[156:159]
	v_mfma_f32_16x16x32_bf16 v[160:163], v[92:95], v[180:183], v[160:163]
	v_mfma_f32_16x16x32_bf16 v[164:167], v[116:119], v[180:183], v[164:167]
	v_mfma_f32_16x16x32_bf16 v[0:3], v[92:95], v[188:191], v[0:3]
	v_mfma_f32_16x16x32_bf16 v[4:7], v[116:119], v[188:191], v[4:7]
	s_barrier
	s_add_u32 s42, s72, 0x10180
	s_addc_u32 s43, s73, 0
	s_add_i32 s73, s44, s5
	v_lshl_add_u64 v[88:89], s[42:43], 0, v[120:121]
	s_mov_b32 m0, s73
	s_add_i32 s72, s73, 0x2000
	global_load_lds_dwordx4 v[88:89], off
	v_lshl_add_u64 v[88:89], s[42:43], 0, v[122:123]
	s_mov_b32 m0, s72
	s_nop 0
	global_load_lds_dwordx4 v[88:89], off
	s_waitcnt vmcnt(6)
	s_barrier
	v_mfma_f32_16x16x32_bf16 v[8:11], v[192:195], v[130:133], v[8:11]
	v_mfma_f32_16x16x32_bf16 v[12:15], v[200:203], v[130:133], v[12:15]
	v_mfma_f32_16x16x32_bf16 v[44:47], v[192:195], v[168:171], v[44:47]
	v_mfma_f32_16x16x32_bf16 v[88:91], v[200:203], v[168:171], v[100:103]
	v_mfma_f32_16x16x32_bf16 v[92:95], v[192:195], v[176:179], v[104:107]
	v_mfma_f32_16x16x32_bf16 v[100:103], v[200:203], v[176:179], v[108:111]
	v_mfma_f32_16x16x32_bf16 v[80:83], v[192:195], v[184:187], v[80:83]
	v_mfma_f32_16x16x32_bf16 v[84:87], v[200:203], v[184:187], v[84:87]
	v_mfma_f32_16x16x32_bf16 v[8:11], v[196:199], v[140:143], v[8:11]
	v_mfma_f32_16x16x32_bf16 v[12:15], v[204:207], v[140:143], v[12:15]
	v_mfma_f32_16x16x32_bf16 v[44:47], v[196:199], v[172:175], v[44:47]
	v_mfma_f32_16x16x32_bf16 v[88:91], v[204:207], v[172:175], v[88:91]
	v_mfma_f32_16x16x32_bf16 v[92:95], v[196:199], v[180:183], v[92:95]
	v_mfma_f32_16x16x32_bf16 v[100:103], v[204:207], v[180:183], v[100:103]
	v_mfma_f32_16x16x32_bf16 v[80:83], v[196:199], v[188:191], v[80:83]
	v_mfma_f32_16x16x32_bf16 v[84:87], v[204:207], v[188:191], v[84:87]
	s_barrier
	ds_read_b128 v[104:107], v136
	ds_read_b128 v[108:111], v136 offset:1024
	ds_read_b128 v[112:115], v136 offset:2048
	ds_read_b128 v[116:119], v136 offset:3072
	s_add_u32 s42, s68, 0x10180
	s_addc_u32 s43, s69, 0
	s_mov_b32 m0, s37
	v_lshl_add_u64 v[192:193], s[42:43], 0, v[120:121]
	ds_read_b128 v[130:133], v137
	ds_read_b128 v[140:143], v137 offset:1024
	ds_read_b128 v[168:171], v137 offset:2048
	ds_read_b128 v[172:175], v137 offset:3072
	ds_read_b128 v[176:179], v137 offset:4096
	ds_read_b128 v[180:183], v137 offset:5120
	ds_read_b128 v[184:187], v137 offset:6144
	ds_read_b128 v[188:191], v137 offset:7168
	global_load_lds_dwordx4 v[192:193], off
	v_lshl_add_u64 v[192:193], s[42:43], 0, v[122:123]
	s_mov_b32 m0, s40
	s_nop 0
	global_load_lds_dwordx4 v[192:193], off
	s_waitcnt lgkmcnt(8)
	s_barrier
	s_waitcnt lgkmcnt(0)
	s_waitcnt lgkmcnt(0)
	v_mfma_f32_16x16x32_bf16 v[48:51], v[104:107], v[130:133], v[48:51]
	v_mfma_f32_16x16x32_bf16 v[52:55], v[112:115], v[130:133], v[52:55]
	v_mfma_f32_16x16x32_bf16 v[56:59], v[104:107], v[168:171], v[56:59]
	v_mfma_f32_16x16x32_bf16 v[60:63], v[112:115], v[168:171], v[60:63]
	v_mfma_f32_16x16x32_bf16 v[64:67], v[104:107], v[176:179], v[64:67]
	v_mfma_f32_16x16x32_bf16 v[68:71], v[112:115], v[176:179], v[68:71]
	v_mfma_f32_16x16x32_bf16 v[72:75], v[104:107], v[184:187], v[72:75]
	v_mfma_f32_16x16x32_bf16 v[76:79], v[112:115], v[184:187], v[76:79]
	v_mfma_f32_16x16x32_bf16 v[48:51], v[108:111], v[140:143], v[48:51]
	v_mfma_f32_16x16x32_bf16 v[52:55], v[116:119], v[140:143], v[52:55]
	v_mfma_f32_16x16x32_bf16 v[56:59], v[108:111], v[172:175], v[56:59]
	v_mfma_f32_16x16x32_bf16 v[60:63], v[116:119], v[172:175], v[60:63]
	v_mfma_f32_16x16x32_bf16 v[64:67], v[108:111], v[180:183], v[64:67]
	v_mfma_f32_16x16x32_bf16 v[68:71], v[116:119], v[180:183], v[68:71]
	v_mfma_f32_16x16x32_bf16 v[72:75], v[108:111], v[188:191], v[72:75]
	v_mfma_f32_16x16x32_bf16 v[192:195], v[116:119], v[188:191], v[76:79]
	s_barrier
	s_mov_b32 m0, s15
	v_lshl_add_u64 v[240:241], s[70:71], 0, v[120:121]
	ds_read_b128 v[76:79], v138
	ds_read_b128 v[196:199], v138 offset:1024
	ds_read_b128 v[200:203], v138 offset:2048
	ds_read_b128 v[204:207], v138 offset:3072
	global_load_lds_dwordx4 v[240:241], off
	v_lshl_add_u64 v[242:243], s[70:71], 0, v[122:123]
	s_mov_b32 m0, s0
	s_nop 0
	global_load_lds_dwordx4 v[242:243], off
	s_barrier
	s_waitcnt lgkmcnt(0)
	s_waitcnt lgkmcnt(0)
	v_mfma_f32_16x16x32_bf16 v[96:99], v[76:79], v[130:133], v[96:99]
	v_mfma_f32_16x16x32_bf16 v[16:19], v[200:203], v[130:133], v[16:19]
	v_mfma_f32_16x16x32_bf16 v[20:23], v[76:79], v[168:171], v[20:23]
	v_mfma_f32_16x16x32_bf16 v[24:27], v[200:203], v[168:171], v[24:27]
	v_mfma_f32_16x16x32_bf16 v[28:31], v[76:79], v[176:179], v[28:31]
	v_mfma_f32_16x16x32_bf16 v[32:35], v[200:203], v[176:179], v[32:35]
	v_mfma_f32_16x16x32_bf16 v[36:39], v[76:79], v[184:187], v[36:39]
	v_mfma_f32_16x16x32_bf16 v[40:43], v[200:203], v[184:187], v[40:43]
	v_mfma_f32_16x16x32_bf16 v[96:99], v[196:199], v[140:143], v[96:99]
	v_mfma_f32_16x16x32_bf16 v[16:19], v[204:207], v[140:143], v[16:19]
	v_mfma_f32_16x16x32_bf16 v[20:23], v[196:199], v[172:175], v[20:23]
	v_mfma_f32_16x16x32_bf16 v[24:27], v[204:207], v[172:175], v[24:27]
	v_mfma_f32_16x16x32_bf16 v[28:31], v[196:199], v[180:183], v[28:31]
	v_mfma_f32_16x16x32_bf16 v[32:35], v[204:207], v[180:183], v[32:35]
	v_mfma_f32_16x16x32_bf16 v[36:39], v[196:199], v[188:191], v[36:39]
	v_mfma_f32_16x16x32_bf16 v[40:43], v[204:207], v[188:191], v[40:43]
	s_mov_b32 m0, s20
	v_lshl_add_u64 v[244:245], s[74:75], 0, v[120:121]
	s_barrier
	ds_read_b128 v[130:133], v137 offset:16384
	ds_read_b128 v[140:143], v137 offset:17408
	ds_read_b128 v[168:171], v137 offset:18432
	ds_read_b128 v[172:175], v137 offset:19456
	ds_read_b128 v[176:179], v137 offset:20480
	ds_read_b128 v[180:183], v137 offset:21504
	ds_read_b128 v[184:187], v137 offset:22528
	ds_read_b128 v[188:191], v137 offset:23552
	global_load_lds_dwordx4 v[244:245], off
	v_lshl_add_u64 v[246:247], s[74:75], 0, v[122:123]
	s_mov_b32 m0, s21
	s_nop 0
	global_load_lds_dwordx4 v[246:247], off
	s_barrier
	s_waitcnt lgkmcnt(0)
	s_waitcnt lgkmcnt(0)
	v_mfma_f32_16x16x32_bf16 v[144:147], v[104:107], v[130:133], v[144:147]
	v_mfma_f32_16x16x32_bf16 v[148:151], v[112:115], v[130:133], v[148:151]
	v_mfma_f32_16x16x32_bf16 v[152:155], v[104:107], v[168:171], v[152:155]
	v_mfma_f32_16x16x32_bf16 v[156:159], v[112:115], v[168:171], v[156:159]
	v_mfma_f32_16x16x32_bf16 v[160:163], v[104:107], v[176:179], v[160:163]
	v_mfma_f32_16x16x32_bf16 v[164:167], v[112:115], v[176:179], v[164:167]
	v_mfma_f32_16x16x32_bf16 v[0:3], v[104:107], v[184:187], v[0:3]
	v_mfma_f32_16x16x32_bf16 v[4:7], v[112:115], v[184:187], v[4:7]
	v_mfma_f32_16x16x32_bf16 v[144:147], v[108:111], v[140:143], v[144:147]
	v_mfma_f32_16x16x32_bf16 v[148:151], v[116:119], v[140:143], v[148:151]
	v_mfma_f32_16x16x32_bf16 v[152:155], v[108:111], v[172:175], v[152:155]
	v_mfma_f32_16x16x32_bf16 v[156:159], v[116:119], v[172:175], v[156:159]
	v_mfma_f32_16x16x32_bf16 v[160:163], v[108:111], v[180:183], v[160:163]
	v_mfma_f32_16x16x32_bf16 v[164:167], v[116:119], v[180:183], v[164:167]
	v_mfma_f32_16x16x32_bf16 v[0:3], v[108:111], v[188:191], v[0:3]
	v_mfma_f32_16x16x32_bf16 v[4:7], v[116:119], v[188:191], v[4:7]
	s_barrier
	s_add_u32 s42, s70, 0x10000
	s_addc_u32 s43, s71, 0
	s_mov_b32 m0, s19
	v_lshl_add_u64 v[104:105], s[42:43], 0, v[120:121]
	global_load_lds_dwordx4 v[104:105], off
	v_lshl_add_u64 v[104:105], s[42:43], 0, v[122:123]
	s_mov_b32 m0, s1
	s_nop 0
	global_load_lds_dwordx4 v[104:105], off
	s_waitcnt vmcnt(6)
	s_barrier
	v_mfma_f32_16x16x32_bf16 v[8:11], v[76:79], v[130:133], v[8:11]
	v_mfma_f32_16x16x32_bf16 v[208:211], v[196:199], v[140:143], v[8:11]
	v_mfma_f32_16x16x32_bf16 v[8:11], v[200:203], v[130:133], v[12:15]
	v_mfma_f32_16x16x32_bf16 v[130:133], v[204:207], v[140:143], v[8:11]
	v_mfma_f32_16x16x32_bf16 v[8:11], v[76:79], v[168:171], v[44:47]
	v_mfma_f32_16x16x32_bf16 v[140:143], v[196:199], v[172:175], v[8:11]
	v_mfma_f32_16x16x32_bf16 v[8:11], v[200:203], v[168:171], v[88:91]
	v_mfma_f32_16x16x32_bf16 v[168:171], v[204:207], v[172:175], v[8:11]
	v_mfma_f32_16x16x32_bf16 v[8:11], v[76:79], v[176:179], v[92:95]
	v_mfma_f32_16x16x32_bf16 v[172:175], v[196:199], v[180:183], v[8:11]
	v_mfma_f32_16x16x32_bf16 v[8:11], v[200:203], v[176:179], v[100:103]
	v_mfma_f32_16x16x32_bf16 v[176:179], v[204:207], v[180:183], v[8:11]
	v_mfma_f32_16x16x32_bf16 v[8:11], v[76:79], v[184:187], v[80:83]
	v_mfma_f32_16x16x32_bf16 v[180:183], v[196:199], v[188:191], v[8:11]
	v_mfma_f32_16x16x32_bf16 v[8:11], v[200:203], v[184:187], v[84:87]
	v_mfma_f32_16x16x32_bf16 v[184:187], v[204:207], v[188:191], v[8:11]
	s_barrier
	s_nop 4
	ds_read_b128 v[8:11], v216
	ds_read_b128 v[12:15], v216 offset:1024
	ds_read_b128 v[188:191], v216 offset:2048
	ds_read_b128 v[196:199], v216 offset:3072
	s_add_u32 s0, s74, 0x10000
	s_addc_u32 s1, s75, 0
	s_mov_b32 m0, s23
	v_lshl_add_u64 v[76:77], s[0:1], 0, v[120:121]
	ds_read_b128 v[44:47], v137 offset:32768
	ds_read_b128 v[80:83], v137 offset:33792
	ds_read_b128 v[88:91], v137 offset:34816
	ds_read_b128 v[200:203], v137 offset:35840
	ds_read_b128 v[204:207], v137 offset:36864
	ds_read_b128 v[212:215], v137 offset:37888
	ds_read_b128 v[216:219], v137 offset:38912
	ds_read_b128 v[220:223], v137 offset:39936
	global_load_lds_dwordx4 v[76:77], off
	v_lshl_add_u64 v[76:77], s[0:1], 0, v[122:123]
	s_mov_b32 m0, s24
	s_nop 0
	global_load_lds_dwordx4 v[76:77], off
	s_waitcnt lgkmcnt(8)
	s_barrier
	s_waitcnt lgkmcnt(0)
	s_waitcnt lgkmcnt(0)
	v_mfma_f32_16x16x32_bf16 v[48:51], v[8:11], v[44:47], v[48:51]
	v_mfma_f32_16x16x32_bf16 v[224:227], v[12:15], v[80:83], v[48:51]
	v_mfma_f32_16x16x32_bf16 v[48:51], v[188:191], v[44:47], v[52:55]
	v_mfma_f32_16x16x32_bf16 v[116:119], v[196:199], v[80:83], v[48:51]
	v_mfma_f32_16x16x32_bf16 v[48:51], v[8:11], v[88:91], v[56:59]
	v_mfma_f32_16x16x32_bf16 v[108:111], v[12:15], v[200:203], v[48:51]
	v_mfma_f32_16x16x32_bf16 v[48:51], v[188:191], v[88:91], v[60:63]
	v_mfma_f32_16x16x32_bf16 v[100:103], v[196:199], v[200:203], v[48:51]
	v_mfma_f32_16x16x32_bf16 v[48:51], v[8:11], v[204:207], v[64:67]
	v_mfma_f32_16x16x32_bf16 v[92:95], v[12:15], v[212:215], v[48:51]
	v_mfma_f32_16x16x32_bf16 v[48:51], v[188:191], v[204:207], v[68:71]
	v_mfma_f32_16x16x32_bf16 v[84:87], v[196:199], v[212:215], v[48:51]
	v_mfma_f32_16x16x32_bf16 v[48:51], v[8:11], v[216:219], v[72:75]
	v_mfma_f32_16x16x32_bf16 v[76:79], v[12:15], v[220:223], v[48:51]
	v_mfma_f32_16x16x32_bf16 v[48:51], v[188:191], v[216:219], v[192:195]
	v_mfma_f32_16x16x32_bf16 v[68:71], v[196:199], v[220:223], v[48:51]
	s_barrier
	s_mov_b32 m0, s76
	s_nop 3
	v_lshl_add_u64 v[48:49], v[240:241], 0, s[8:9]
	ds_read_b128 v[192:195], v236
	ds_read_b128 v[228:231], v236 offset:1024
	ds_read_b128 v[232:235], v236 offset:2048
	ds_read_b128 v[236:239], v236 offset:3072
	global_load_lds_dwordx4 v[48:49], off
	v_lshl_add_u64 v[48:49], v[242:243], 0, s[8:9]
	s_mov_b32 m0, s61
	s_nop 0
	global_load_lds_dwordx4 v[48:49], off
	s_barrier
	s_waitcnt lgkmcnt(0)
	s_waitcnt lgkmcnt(0)
	v_mfma_f32_16x16x32_bf16 v[16:19], v[232:235], v[44:47], v[16:19]
	v_mfma_f32_16x16x32_bf16 v[112:115], v[236:239], v[80:83], v[16:19]
	v_mfma_f32_16x16x32_bf16 v[16:19], v[192:195], v[88:91], v[20:23]
	v_mfma_f32_16x16x32_bf16 v[104:107], v[228:231], v[200:203], v[16:19]
	v_mfma_f32_16x16x32_bf16 v[16:19], v[232:235], v[88:91], v[24:27]
	v_mfma_f32_16x16x32_bf16 v[48:51], v[192:195], v[44:47], v[96:99]
	v_mfma_f32_16x16x32_bf16 v[96:99], v[236:239], v[200:203], v[16:19]
	v_mfma_f32_16x16x32_bf16 v[16:19], v[192:195], v[204:207], v[28:31]
	v_mfma_f32_16x16x32_bf16 v[88:91], v[228:231], v[212:215], v[16:19]
	v_mfma_f32_16x16x32_bf16 v[16:19], v[232:235], v[204:207], v[32:35]
	v_mfma_f32_16x16x32_bf16 v[240:243], v[228:231], v[80:83], v[48:51]
	v_mfma_f32_16x16x32_bf16 v[80:83], v[236:239], v[212:215], v[16:19]
	v_mfma_f32_16x16x32_bf16 v[16:19], v[192:195], v[216:219], v[36:39]
	v_mfma_f32_16x16x32_bf16 v[72:75], v[228:231], v[220:223], v[16:19]
	v_mfma_f32_16x16x32_bf16 v[16:19], v[232:235], v[216:219], v[40:43]
	v_mfma_f32_16x16x32_bf16 v[64:67], v[236:239], v[220:223], v[16:19]
	s_mov_b32 m0, s25
	v_lshl_add_u64 v[20:21], v[244:245], 0, s[8:9]
	s_barrier
	s_nop 2
	ds_read_b128 v[16:19], v137 offset:49152
	ds_read_b128 v[24:27], v137 offset:50176
	ds_read_b128 v[32:35], v137 offset:51200
	ds_read_b128 v[200:203], v137 offset:52224
	ds_read_b128 v[204:207], v137 offset:53248
	ds_read_b128 v[212:215], v137 offset:54272
	ds_read_b128 v[216:219], v137 offset:55296
	ds_read_b128 v[220:223], v137 offset:56320
	global_load_lds_dwordx4 v[20:21], off
	v_lshl_add_u64 v[20:21], v[246:247], 0, s[8:9]
	s_mov_b32 m0, s28
	s_nop 0
	global_load_lds_dwordx4 v[20:21], off
	s_barrier
	s_waitcnt lgkmcnt(0)
	s_waitcnt lgkmcnt(0)
	v_mfma_f32_16x16x32_bf16 v[20:23], v[8:11], v[16:19], v[144:147]
	v_mfma_f32_16x16x32_bf16 v[60:63], v[12:15], v[24:27], v[20:23]
	v_mfma_f32_16x16x32_bf16 v[20:23], v[188:191], v[16:19], v[148:151]
	v_mfma_f32_16x16x32_bf16 v[52:55], v[196:199], v[24:27], v[20:23]
	v_mfma_f32_16x16x32_bf16 v[20:23], v[8:11], v[32:35], v[152:155]
	v_mfma_f32_16x16x32_bf16 v[44:47], v[12:15], v[200:203], v[20:23]
	v_mfma_f32_16x16x32_bf16 v[20:23], v[188:191], v[32:35], v[156:159]
	v_mfma_f32_16x16x32_bf16 v[36:39], v[196:199], v[200:203], v[20:23]
	v_mfma_f32_16x16x32_bf16 v[20:23], v[8:11], v[204:207], v[160:163]
	v_mfma_f32_16x16x32_bf16 v[0:3], v[8:11], v[216:219], v[0:3]
	v_mfma_f32_16x16x32_bf16 v[28:31], v[12:15], v[212:215], v[20:23]
	v_mfma_f32_16x16x32_bf16 v[20:23], v[188:191], v[204:207], v[164:167]
	v_mfma_f32_16x16x32_bf16 v[12:15], v[12:15], v[220:223], v[0:3]
	v_mfma_f32_16x16x32_bf16 v[0:3], v[188:191], v[216:219], v[4:7]
	v_mfma_f32_16x16x32_bf16 v[20:23], v[196:199], v[212:215], v[20:23]
	v_mfma_f32_16x16x32_bf16 v[8:11], v[196:199], v[220:223], v[0:3]
	s_barrier
	s_add_u32 s0, s70, 0x10080
	s_addc_u32 s1, s71, 0
	s_mov_b32 m0, s73
	s_nop 0
	v_lshl_add_u64 v[0:1], s[0:1], 0, v[120:121]
	global_load_lds_dwordx4 v[0:1], off
	v_lshl_add_u64 v[0:1], s[0:1], 0, v[122:123]
	s_mov_b32 m0, s72
	s_nop 0
	global_load_lds_dwordx4 v[0:1], off
	s_waitcnt vmcnt(6)
	s_barrier
	v_mfma_f32_16x16x32_bf16 v[0:3], v[192:195], v[16:19], v[208:211]
	v_mfma_f32_16x16x32_bf16 v[56:59], v[228:231], v[24:27], v[0:3]
	v_mfma_f32_16x16x32_bf16 v[0:3], v[232:235], v[16:19], v[130:133]
	v_mfma_f32_16x16x32_bf16 v[48:51], v[236:239], v[24:27], v[0:3]
	v_mfma_f32_16x16x32_bf16 v[0:3], v[192:195], v[32:35], v[140:143]
	v_mfma_f32_16x16x32_bf16 v[40:43], v[228:231], v[200:203], v[0:3]
	v_mfma_f32_16x16x32_bf16 v[0:3], v[232:235], v[32:35], v[168:171]
	v_mfma_f32_16x16x32_bf16 v[32:35], v[236:239], v[200:203], v[0:3]
	v_mfma_f32_16x16x32_bf16 v[0:3], v[192:195], v[204:207], v[172:175]
	v_mfma_f32_16x16x32_bf16 v[24:27], v[228:231], v[212:215], v[0:3]
	v_mfma_f32_16x16x32_bf16 v[0:3], v[232:235], v[204:207], v[176:179]
	v_mfma_f32_16x16x32_bf16 v[16:19], v[236:239], v[212:215], v[0:3]
	v_mfma_f32_16x16x32_bf16 v[0:3], v[192:195], v[216:219], v[180:183]
	v_mfma_f32_16x16x32_bf16 v[4:7], v[228:231], v[220:223], v[0:3]
	v_mfma_f32_16x16x32_bf16 v[0:3], v[232:235], v[216:219], v[184:187]
	v_mfma_f32_16x16x32_bf16 v[0:3], v[236:239], v[220:223], v[0:3]
	v_lshl_or_b32 v154, s67, 8, v135
	v_or_b32_e32 v131, 0x90, v154
	v_cvt_f32_i32_e32 v131, v131
	v_lshl_add_u32 v130, s66, 8, v129
	v_and_b32_e32 v132, 0x7cf, v130
	v_cvt_f32_u32_e32 v132, v132
	v_mul_f32_e32 v140, 0xb9000400, v131
	v_or_b32_e32 v131, 1, v154
	v_cvt_f32_i32_e32 v131, v131
	v_cvt_f32_i32_e32 v133, v154
	v_fmamk_f32 v162, v132, 0xbbc49550, v139
	v_or_b32_e32 v145, 17, v154
	v_mul_f32_e32 v142, 0xb9000400, v131
	v_or_b32_e32 v131, 2, v154
	v_cvt_f32_i32_e32 v131, v131
	v_mul_f32_e32 v141, 0xb9000400, v133
	v_mul_f32_e64 v132, v141, |v162|
	v_mul_f32_e64 v133, v142, |v162|
	v_mul_f32_e32 v143, 0xb9000400, v131
	v_or_b32_e32 v131, 3, v154
	v_cvt_f32_i32_e32 v131, v131
	v_mul_f32_e64 v144, v143, |v162|
	v_mul_f32_e32 v144, 0x3fb8aa3b, v144
	v_exp_f32_e32 v148, v144
	v_mul_f32_e32 v144, 0xb9000400, v131
	v_mul_f32_e64 v131, v144, |v162|
	v_mul_f32_e32 v131, 0x3fb8aa3b, v131
	v_mul_f32_e32 v132, 0x3fb8aa3b, v132
	v_mul_f32_e32 v133, 0x3fb8aa3b, v133
	v_exp_f32_e32 v149, v131
	v_ashrrev_i32_e32 v131, 31, v130
	v_exp_f32_e32 v132, v132
	v_exp_f32_e32 v133, v133
	v_lshlrev_b64 v[150:151], 15, v[130:131]
	v_or_b32_e32 v131, 16, v154
	v_cvt_f32_i32_e32 v131, v131
	v_ashrrev_i32_e32 v155, 31, v154
	v_cvt_f32_i32_e32 v145, v145
	v_pk_mul_f32 v[146:147], v[132:133], v[224:225]
	v_lshl_add_u64 v[150:151], s[50:51], 0, v[150:151]
	v_lshlrev_b64 v[132:133], 2, v[154:155]
	v_pk_mul_f32 v[148:149], v[148:149], v[226:227]
	v_lshl_add_u64 v[156:157], v[150:151], 0, v[132:133]
	v_mul_f32_e32 v131, 0xb9000400, v131
	s_barrier
	global_store_dwordx4 v[156:157], v[146:149], off
	v_mul_f32_e32 v145, 0xb9000400, v145
	v_or_b32_e32 v153, 0x80, v154
	v_mul_f32_e64 v146, v131, |v162|
	v_mul_f32_e32 v146, 0x3fb8aa3b, v146
	v_exp_f32_e32 v148, v146
	v_or_b32_e32 v146, 18, v154
	v_mul_f32_e64 v147, v145, |v162|
	v_cvt_f32_i32_e32 v146, v146
	v_mul_f32_e32 v147, 0x3fb8aa3b, v147
	v_exp_f32_e32 v149, v147
	v_or_b32_e32 v147, 19, v154
	v_cvt_f32_i32_e32 v147, v147
	v_mul_f32_e32 v146, 0xb9000400, v146
	v_mul_f32_e64 v150, v146, |v162|
	v_mul_f32_e32 v150, 0x3fb8aa3b, v150
	v_mul_f32_e32 v147, 0xb9000400, v147
	v_exp_f32_e32 v152, v150
	v_mul_f32_e64 v150, v147, |v162|
	v_cvt_f32_i32_e32 v155, v153
	v_mul_f32_e32 v150, 0x3fb8aa3b, v150
	v_exp_f32_e32 v153, v150
	v_pk_mul_f32 v[150:151], v[148:149], v[116:117]
	v_or_b32_e32 v117, 0x81, v154
	v_cvt_f32_i32_e32 v117, v117
	v_mul_f32_e32 v116, 0xb9000400, v155
	v_mul_f32_e64 v148, v116, |v162|
	v_mul_f32_e32 v148, 0x3fb8aa3b, v148
	v_mul_f32_e32 v117, 0xb9000400, v117
	v_exp_f32_e32 v158, v148
	v_or_b32_e32 v148, 0x82, v154
	v_mul_f32_e64 v149, v117, |v162|
	v_cvt_f32_i32_e32 v148, v148
	v_mul_f32_e32 v149, 0x3fb8aa3b, v149
	v_exp_f32_e32 v159, v149
	v_or_b32_e32 v149, 0x83, v154
	v_cvt_f32_i32_e32 v149, v149
	v_mul_f32_e32 v148, 0xb9000400, v148
	v_mul_f32_e64 v155, v148, |v162|
	v_mul_f32_e32 v155, 0x3fb8aa3b, v155
	v_mul_f32_e32 v149, 0xb9000400, v149
	v_exp_f32_e32 v160, v155
	v_mul_f32_e64 v155, v149, |v162|
	v_mul_f32_e32 v155, 0x3fb8aa3b, v155
	v_pk_mul_f32 v[152:153], v[152:153], v[118:119]
	v_or_b32_e32 v118, 0x91, v154
	v_exp_f32_e32 v161, v155
	v_cvt_f32_i32_e32 v118, v118
	v_mul_f32_e64 v119, v140, |v162|
	global_store_dwordx4 v[156:157], v[150:153], off offset:64
	v_mul_f32_e32 v119, 0x3fb8aa3b, v119
	v_mul_f32_e32 v118, 0xb9000400, v118
	v_pk_mul_f32 v[150:151], v[158:159], v[240:241]
	v_pk_mul_f32 v[152:153], v[160:161], v[242:243]
	global_store_dwordx4 v[156:157], v[150:153], off offset:512
	v_readlane_b32 s0, v255, 9
	s_add_i32 s33, s33, s0
	v_exp_f32_e32 v152, v119
	v_or_b32_e32 v119, 0x92, v154
	v_mul_f32_e64 v150, v118, |v162|
	v_cvt_f32_i32_e32 v119, v119
	v_mul_f32_e32 v150, 0x3fb8aa3b, v150
	v_exp_f32_e32 v153, v150
	v_or_b32_e32 v150, 0x93, v154
	v_cvt_f32_i32_e32 v150, v150
	v_mul_f32_e32 v119, 0xb9000400, v119
	v_mul_f32_e64 v151, v119, |v162|
	v_mul_f32_e32 v151, 0x3fb8aa3b, v151
	v_mul_f32_e32 v150, 0xb9000400, v150
	v_exp_f32_e32 v154, v151
	v_mul_f32_e64 v151, v150, |v162|
	v_mul_f32_e32 v151, 0x3fb8aa3b, v151
	v_exp_f32_e32 v155, v151
	v_bitop3_b32 v151, v130, s46, 16 bitop3:0xc8
	v_cvt_f32_u32_e32 v151, v151
	v_pk_mul_f32 v[112:113], v[152:153], v[112:113]
	v_pk_mul_f32 v[114:115], v[154:155], v[114:115]
	global_store_dwordx4 v[156:157], v[112:115], off offset:576
	v_fmamk_f32 v151, v151, 0xbbc49550, v139
	s_andn2_b64 vcc, exec, s[6:7]
	v_mul_f32_e64 v113, v141, |v151|
	v_mul_f32_e32 v113, 0x3fb8aa3b, v113
	v_exp_f32_e32 v114, v113
	v_mul_f32_e64 v113, v142, |v151|
	v_mul_f32_e32 v113, 0x3fb8aa3b, v113
	v_exp_f32_e32 v115, v113
	v_mul_f32_e64 v113, v143, |v151|
	v_mul_f32_e32 v113, 0x3fb8aa3b, v113
	v_exp_f32_e32 v152, v113
	v_mul_f32_e64 v113, v144, |v151|
	v_mul_f32_e32 v113, 0x3fb8aa3b, v113
	v_or_b32_e32 v112, 16, v130
	v_exp_f32_e32 v153, v113
	v_ashrrev_i32_e32 v113, 31, v112
	v_lshlrev_b64 v[112:113], 15, v[112:113]
	v_lshl_add_u64 v[112:113], s[50:51], 0, v[112:113]
	v_pk_mul_f32 v[108:109], v[114:115], v[108:109]
	v_pk_mul_f32 v[110:111], v[152:153], v[110:111]
	v_lshl_add_u64 v[112:113], v[112:113], 0, v[132:133]
	global_store_dwordx4 v[112:113], v[108:111], off
	v_mul_f32_e64 v114, v148, |v151|
	v_mul_f32_e64 v115, v149, |v151|
	v_mul_f32_e64 v108, v131, |v151|
	v_mul_f32_e64 v109, v145, |v151|
	v_mul_f32_e32 v108, 0x3fb8aa3b, v108
	v_mul_f32_e32 v109, 0x3fb8aa3b, v109
	v_exp_f32_e32 v108, v108
	v_exp_f32_e32 v109, v109
	v_mul_f32_e64 v110, v146, |v151|
	v_mul_f32_e64 v111, v147, |v151|
	v_mul_f32_e32 v110, 0x3fb8aa3b, v110
	v_mul_f32_e32 v111, 0x3fb8aa3b, v111
	v_pk_mul_f32 v[100:101], v[108:109], v[100:101]
	v_mul_f32_e64 v108, v116, |v151|
	v_mul_f32_e64 v109, v117, |v151|
	v_exp_f32_e32 v110, v110
	v_exp_f32_e32 v111, v111
	v_mul_f32_e32 v108, 0x3fb8aa3b, v108
	v_mul_f32_e32 v109, 0x3fb8aa3b, v109
	v_mul_f32_e32 v114, 0x3fb8aa3b, v114
	v_mul_f32_e32 v115, 0x3fb8aa3b, v115
	v_exp_f32_e32 v108, v108
	v_exp_f32_e32 v109, v109
	v_exp_f32_e32 v114, v114
	v_exp_f32_e32 v115, v115
	v_pk_mul_f32 v[102:103], v[110:111], v[102:103]
	global_store_dwordx4 v[112:113], v[100:103], off offset:64
	s_mov_b32 s67, s18
	s_mov_b32 s66, s60
	v_pk_mul_f32 v[100:101], v[108:109], v[104:105]
	v_pk_mul_f32 v[102:103], v[114:115], v[106:107]
	global_store_dwordx4 v[112:113], v[100:103], off offset:512
	s_mov_b64 s[72:73], s[64:65]
	s_mov_b64 s[68:69], s[62:63]
	v_mul_f32_e64 v100, v140, |v151|
	v_mul_f32_e64 v101, v118, |v151|
	v_mul_f32_e32 v100, 0x3fb8aa3b, v100
	v_mul_f32_e32 v101, 0x3fb8aa3b, v101
	v_exp_f32_e32 v100, v100
	v_exp_f32_e32 v101, v101
	v_mul_f32_e64 v102, v119, |v151|
	v_mul_f32_e64 v103, v150, |v151|
	v_mul_f32_e32 v102, 0x3fb8aa3b, v102
	v_mul_f32_e32 v103, 0x3fb8aa3b, v103
	v_pk_mul_f32 v[96:97], v[100:101], v[96:97]
	v_bitop3_b32 v100, v130, s47, 32 bitop3:0xc8
	v_exp_f32_e32 v102, v102
	v_exp_f32_e32 v103, v103
	v_cvt_f32_u32_e32 v100, v100
	v_pk_mul_f32 v[98:99], v[102:103], v[98:99]
	v_fmamk_f32 v102, v100, 0xbbc49550, v139
	global_store_dwordx4 v[112:113], v[96:99], off offset:576
	s_nop 1
	v_mul_f32_e64 v97, v141, |v102|
	v_mul_f32_e32 v97, 0x3fb8aa3b, v97
	v_exp_f32_e32 v98, v97
	v_mul_f32_e64 v97, v142, |v102|
	v_mul_f32_e32 v97, 0x3fb8aa3b, v97
	v_exp_f32_e32 v99, v97
	v_mul_f32_e64 v97, v143, |v102|
	v_mul_f32_e32 v97, 0x3fb8aa3b, v97
	v_exp_f32_e32 v100, v97
	v_mul_f32_e64 v97, v144, |v102|
	v_mul_f32_e32 v97, 0x3fb8aa3b, v97
	v_or_b32_e32 v96, 32, v130
	v_exp_f32_e32 v101, v97
	v_ashrrev_i32_e32 v97, 31, v96
	v_lshlrev_b64 v[96:97], 15, v[96:97]
	v_lshl_add_u64 v[96:97], s[50:51], 0, v[96:97]
	v_pk_mul_f32 v[92:93], v[98:99], v[92:93]
	v_pk_mul_f32 v[94:95], v[100:101], v[94:95]
	v_lshl_add_u64 v[96:97], v[96:97], 0, v[132:133]
	global_store_dwordx4 v[96:97], v[92:95], off
	v_mul_f32_e64 v98, v148, |v102|
	v_mul_f32_e64 v99, v149, |v102|
	v_mul_f32_e64 v92, v131, |v102|
	v_mul_f32_e64 v93, v145, |v102|
	v_mul_f32_e32 v92, 0x3fb8aa3b, v92
	v_mul_f32_e32 v93, 0x3fb8aa3b, v93
	v_exp_f32_e32 v92, v92
	v_exp_f32_e32 v93, v93
	v_mul_f32_e64 v94, v146, |v102|
	v_mul_f32_e64 v95, v147, |v102|
	v_mul_f32_e32 v94, 0x3fb8aa3b, v94
	v_mul_f32_e32 v95, 0x3fb8aa3b, v95
	v_pk_mul_f32 v[84:85], v[92:93], v[84:85]
	v_mul_f32_e64 v92, v116, |v102|
	v_mul_f32_e64 v93, v117, |v102|
	v_exp_f32_e32 v94, v94
	v_exp_f32_e32 v95, v95
	v_mul_f32_e32 v92, 0x3fb8aa3b, v92
	v_mul_f32_e32 v93, 0x3fb8aa3b, v93
	v_mul_f32_e32 v98, 0x3fb8aa3b, v98
	v_mul_f32_e32 v99, 0x3fb8aa3b, v99
	v_exp_f32_e32 v92, v92
	v_exp_f32_e32 v93, v93
	v_exp_f32_e32 v98, v98
	v_exp_f32_e32 v99, v99
	v_pk_mul_f32 v[86:87], v[94:95], v[86:87]
	global_store_dwordx4 v[96:97], v[84:87], off offset:64
	s_nop 1
	v_pk_mul_f32 v[84:85], v[92:93], v[88:89]
	v_pk_mul_f32 v[86:87], v[98:99], v[90:91]
	global_store_dwordx4 v[96:97], v[84:87], off offset:512
	s_nop 1
	v_mul_f32_e64 v84, v140, |v102|
	v_mul_f32_e64 v85, v118, |v102|
	v_mul_f32_e32 v84, 0x3fb8aa3b, v84
	v_mul_f32_e32 v85, 0x3fb8aa3b, v85
	v_exp_f32_e32 v84, v84
	v_exp_f32_e32 v85, v85
	v_mul_f32_e64 v86, v119, |v102|
	v_mul_f32_e64 v87, v150, |v102|
	v_mul_f32_e32 v86, 0x3fb8aa3b, v86
	v_mul_f32_e32 v87, 0x3fb8aa3b, v87
	v_pk_mul_f32 v[80:81], v[84:85], v[80:81]
	v_bitop3_b32 v84, v130, s53, 48 bitop3:0xc8
	v_exp_f32_e32 v86, v86
	v_exp_f32_e32 v87, v87
	v_cvt_f32_u32_e32 v84, v84
	v_pk_mul_f32 v[82:83], v[86:87], v[82:83]
	v_fmamk_f32 v86, v84, 0xbbc49550, v139
	global_store_dwordx4 v[96:97], v[80:83], off offset:576
	s_nop 1
	v_mul_f32_e64 v81, v141, |v86|
	v_mul_f32_e32 v81, 0x3fb8aa3b, v81
	v_exp_f32_e32 v82, v81
	v_mul_f32_e64 v81, v142, |v86|
	v_mul_f32_e32 v81, 0x3fb8aa3b, v81
	v_exp_f32_e32 v83, v81
	v_mul_f32_e64 v81, v143, |v86|
	v_mul_f32_e32 v81, 0x3fb8aa3b, v81
	v_exp_f32_e32 v84, v81
	v_mul_f32_e64 v81, v144, |v86|
	v_mul_f32_e32 v81, 0x3fb8aa3b, v81
	v_or_b32_e32 v80, 48, v130
	v_exp_f32_e32 v85, v81
	v_ashrrev_i32_e32 v81, 31, v80
	v_lshlrev_b64 v[80:81], 15, v[80:81]
	v_lshl_add_u64 v[80:81], s[50:51], 0, v[80:81]
	v_pk_mul_f32 v[76:77], v[82:83], v[76:77]
	v_pk_mul_f32 v[78:79], v[84:85], v[78:79]
	v_lshl_add_u64 v[80:81], v[80:81], 0, v[132:133]
	global_store_dwordx4 v[80:81], v[76:79], off
	v_mul_f32_e64 v82, v148, |v86|
	v_mul_f32_e64 v83, v149, |v86|
	v_mul_f32_e64 v76, v131, |v86|
	v_mul_f32_e64 v77, v145, |v86|
	v_mul_f32_e32 v76, 0x3fb8aa3b, v76
	v_mul_f32_e32 v77, 0x3fb8aa3b, v77
	v_exp_f32_e32 v76, v76
	v_exp_f32_e32 v77, v77
	v_mul_f32_e64 v78, v146, |v86|
	v_mul_f32_e64 v79, v147, |v86|
	v_mul_f32_e32 v78, 0x3fb8aa3b, v78
	v_mul_f32_e32 v79, 0x3fb8aa3b, v79
	v_pk_mul_f32 v[68:69], v[76:77], v[68:69]
	v_mul_f32_e64 v76, v116, |v86|
	v_mul_f32_e64 v77, v117, |v86|
	v_exp_f32_e32 v78, v78
	v_exp_f32_e32 v79, v79
	v_mul_f32_e32 v76, 0x3fb8aa3b, v76
	v_mul_f32_e32 v77, 0x3fb8aa3b, v77
	v_mul_f32_e32 v82, 0x3fb8aa3b, v82
	v_mul_f32_e32 v83, 0x3fb8aa3b, v83
	v_exp_f32_e32 v76, v76
	v_exp_f32_e32 v77, v77
	v_exp_f32_e32 v82, v82
	v_exp_f32_e32 v83, v83
	v_pk_mul_f32 v[70:71], v[78:79], v[70:71]
	global_store_dwordx4 v[80:81], v[68:71], off offset:64
	s_nop 1
	v_pk_mul_f32 v[68:69], v[76:77], v[72:73]
	v_pk_mul_f32 v[70:71], v[82:83], v[74:75]
	global_store_dwordx4 v[80:81], v[68:71], off offset:512
	v_add_u32_e32 v72, 0x80, v130
	v_and_b32_e32 v73, 0x7cf, v72
	v_mul_f32_e64 v68, v140, |v86|
	v_mul_f32_e64 v69, v118, |v86|
	v_mul_f32_e64 v70, v119, |v86|
	v_mul_f32_e64 v71, v150, |v86|
	v_mul_f32_e32 v68, 0x3fb8aa3b, v68
	v_mul_f32_e32 v69, 0x3fb8aa3b, v69
	v_mul_f32_e32 v70, 0x3fb8aa3b, v70
	v_mul_f32_e32 v71, 0x3fb8aa3b, v71
	v_exp_f32_e32 v68, v68
	v_exp_f32_e32 v69, v69
	v_exp_f32_e32 v70, v70
	v_exp_f32_e32 v71, v71
	v_cvt_f32_u32_e32 v73, v73
	v_pk_mul_f32 v[64:65], v[68:69], v[64:65]
	v_pk_mul_f32 v[66:67], v[70:71], v[66:67]
	v_fmamk_f32 v70, v73, 0xbbc49550, v139
	global_store_dwordx4 v[80:81], v[64:67], off offset:576
	v_ashrrev_i32_e32 v73, 31, v72
	v_lshlrev_b64 v[68:69], 15, v[72:73]
	v_mul_f32_e64 v64, v141, |v70|
	v_mul_f32_e64 v65, v142, |v70|
	v_mul_f32_e32 v64, 0x3fb8aa3b, v64
	v_mul_f32_e32 v65, 0x3fb8aa3b, v65
	v_mul_f32_e64 v66, v143, |v70|
	v_mul_f32_e64 v67, v144, |v70|
	v_exp_f32_e32 v64, v64
	v_exp_f32_e32 v65, v65
	v_mul_f32_e32 v66, 0x3fb8aa3b, v66
	v_mul_f32_e32 v67, 0x3fb8aa3b, v67
	v_exp_f32_e32 v66, v66
	v_exp_f32_e32 v67, v67
	v_pk_mul_f32 v[60:61], v[64:65], v[60:61]
	v_lshl_add_u64 v[64:65], s[50:51], 0, v[68:69]
	v_lshl_add_u64 v[64:65], v[64:65], 0, v[132:133]
	v_pk_mul_f32 v[62:63], v[66:67], v[62:63]
	global_store_dwordx4 v[64:65], v[60:63], off
	v_mul_f32_e64 v66, v148, |v70|
	v_mul_f32_e64 v67, v149, |v70|
	v_mul_f32_e64 v60, v131, |v70|
	v_mul_f32_e64 v61, v145, |v70|
	v_mul_f32_e32 v60, 0x3fb8aa3b, v60
	v_mul_f32_e32 v61, 0x3fb8aa3b, v61
	v_exp_f32_e32 v60, v60
	v_exp_f32_e32 v61, v61
	v_mul_f32_e64 v62, v146, |v70|
	v_mul_f32_e64 v63, v147, |v70|
	v_mul_f32_e32 v62, 0x3fb8aa3b, v62
	v_mul_f32_e32 v63, 0x3fb8aa3b, v63
	v_pk_mul_f32 v[52:53], v[60:61], v[52:53]
	v_mul_f32_e64 v60, v116, |v70|
	v_mul_f32_e64 v61, v117, |v70|
	v_exp_f32_e32 v62, v62
	v_exp_f32_e32 v63, v63
	v_mul_f32_e32 v60, 0x3fb8aa3b, v60
	v_mul_f32_e32 v61, 0x3fb8aa3b, v61
	v_mul_f32_e32 v66, 0x3fb8aa3b, v66
	v_mul_f32_e32 v67, 0x3fb8aa3b, v67
	v_exp_f32_e32 v60, v60
	v_exp_f32_e32 v61, v61
	v_exp_f32_e32 v66, v66
	v_exp_f32_e32 v67, v67
	v_pk_mul_f32 v[54:55], v[62:63], v[54:55]
	global_store_dwordx4 v[64:65], v[52:55], off offset:64
	s_nop 1
	v_pk_mul_f32 v[52:53], v[60:61], v[56:57]
	v_pk_mul_f32 v[54:55], v[66:67], v[58:59]
	global_store_dwordx4 v[64:65], v[52:55], off offset:512
	v_add_u32_e32 v56, 0x90, v130
	v_and_b32_e32 v57, 0x7df, v56
	v_mul_f32_e64 v52, v140, |v70|
	v_mul_f32_e64 v53, v118, |v70|
	v_mul_f32_e64 v54, v119, |v70|
	v_mul_f32_e64 v55, v150, |v70|
	v_mul_f32_e32 v52, 0x3fb8aa3b, v52
	v_mul_f32_e32 v53, 0x3fb8aa3b, v53
	v_mul_f32_e32 v54, 0x3fb8aa3b, v54
	v_mul_f32_e32 v55, 0x3fb8aa3b, v55
	v_exp_f32_e32 v52, v52
	v_exp_f32_e32 v53, v53
	v_exp_f32_e32 v54, v54
	v_exp_f32_e32 v55, v55
	v_cvt_f32_u32_e32 v57, v57
	v_pk_mul_f32 v[48:49], v[52:53], v[48:49]
	v_pk_mul_f32 v[50:51], v[54:55], v[50:51]
	v_fmamk_f32 v54, v57, 0xbbc49550, v139
	global_store_dwordx4 v[64:65], v[48:51], off offset:576
	v_ashrrev_i32_e32 v57, 31, v56
	v_lshlrev_b64 v[52:53], 15, v[56:57]
	v_mul_f32_e64 v48, v141, |v54|
	v_mul_f32_e64 v49, v142, |v54|
	v_mul_f32_e32 v48, 0x3fb8aa3b, v48
	v_mul_f32_e32 v49, 0x3fb8aa3b, v49
	v_mul_f32_e64 v50, v143, |v54|
	v_mul_f32_e64 v51, v144, |v54|
	v_exp_f32_e32 v48, v48
	v_exp_f32_e32 v49, v49
	v_mul_f32_e32 v50, 0x3fb8aa3b, v50
	v_mul_f32_e32 v51, 0x3fb8aa3b, v51
	v_exp_f32_e32 v50, v50
	v_exp_f32_e32 v51, v51
	v_pk_mul_f32 v[44:45], v[48:49], v[44:45]
	v_lshl_add_u64 v[48:49], s[50:51], 0, v[52:53]
	v_lshl_add_u64 v[48:49], v[48:49], 0, v[132:133]
	v_pk_mul_f32 v[46:47], v[50:51], v[46:47]
	global_store_dwordx4 v[48:49], v[44:47], off
	v_mul_f32_e64 v50, v148, |v54|
	v_mul_f32_e64 v51, v149, |v54|
	v_mul_f32_e64 v44, v131, |v54|
	v_mul_f32_e64 v45, v145, |v54|
	v_mul_f32_e32 v44, 0x3fb8aa3b, v44
	v_mul_f32_e32 v45, 0x3fb8aa3b, v45
	v_exp_f32_e32 v44, v44
	v_exp_f32_e32 v45, v45
	v_mul_f32_e64 v46, v146, |v54|
	v_mul_f32_e64 v47, v147, |v54|
	v_mul_f32_e32 v46, 0x3fb8aa3b, v46
	v_mul_f32_e32 v47, 0x3fb8aa3b, v47
	v_pk_mul_f32 v[36:37], v[44:45], v[36:37]
	v_mul_f32_e64 v44, v116, |v54|
	v_mul_f32_e64 v45, v117, |v54|
	v_exp_f32_e32 v46, v46
	v_exp_f32_e32 v47, v47
	v_mul_f32_e32 v44, 0x3fb8aa3b, v44
	v_mul_f32_e32 v45, 0x3fb8aa3b, v45
	v_mul_f32_e32 v50, 0x3fb8aa3b, v50
	v_mul_f32_e32 v51, 0x3fb8aa3b, v51
	v_exp_f32_e32 v44, v44
	v_exp_f32_e32 v45, v45
	v_exp_f32_e32 v50, v50
	v_exp_f32_e32 v51, v51
	v_pk_mul_f32 v[38:39], v[46:47], v[38:39]
	global_store_dwordx4 v[48:49], v[36:39], off offset:64
	s_nop 1
	v_pk_mul_f32 v[36:37], v[44:45], v[40:41]
	v_pk_mul_f32 v[38:39], v[50:51], v[42:43]
	global_store_dwordx4 v[48:49], v[36:39], off offset:512
	v_add_u32_e32 v40, 0xa0, v130
	v_and_b32_e32 v41, 0x7ef, v40
	v_mul_f32_e64 v36, v140, |v54|
	v_mul_f32_e64 v37, v118, |v54|
	v_mul_f32_e64 v38, v119, |v54|
	v_mul_f32_e64 v39, v150, |v54|
	v_mul_f32_e32 v36, 0x3fb8aa3b, v36
	v_mul_f32_e32 v37, 0x3fb8aa3b, v37
	v_mul_f32_e32 v38, 0x3fb8aa3b, v38
	v_mul_f32_e32 v39, 0x3fb8aa3b, v39
	v_exp_f32_e32 v36, v36
	v_exp_f32_e32 v37, v37
	v_exp_f32_e32 v38, v38
	v_exp_f32_e32 v39, v39
	v_cvt_f32_u32_e32 v41, v41
	v_pk_mul_f32 v[32:33], v[36:37], v[32:33]
	v_pk_mul_f32 v[34:35], v[38:39], v[34:35]
	v_fmamk_f32 v38, v41, 0xbbc49550, v139
	global_store_dwordx4 v[48:49], v[32:35], off offset:576
	v_ashrrev_i32_e32 v41, 31, v40
	v_lshlrev_b64 v[36:37], 15, v[40:41]
	v_mul_f32_e64 v32, v141, |v38|
	v_mul_f32_e64 v33, v142, |v38|
	v_mul_f32_e32 v32, 0x3fb8aa3b, v32
	v_mul_f32_e32 v33, 0x3fb8aa3b, v33
	v_mul_f32_e64 v34, v143, |v38|
	v_mul_f32_e64 v35, v144, |v38|
	v_exp_f32_e32 v32, v32
	v_exp_f32_e32 v33, v33
	v_mul_f32_e32 v34, 0x3fb8aa3b, v34
	v_mul_f32_e32 v35, 0x3fb8aa3b, v35
	v_exp_f32_e32 v34, v34
	v_exp_f32_e32 v35, v35
	v_pk_mul_f32 v[28:29], v[32:33], v[28:29]
	v_lshl_add_u64 v[32:33], s[50:51], 0, v[36:37]
	v_lshl_add_u64 v[32:33], v[32:33], 0, v[132:133]
	v_pk_mul_f32 v[30:31], v[34:35], v[30:31]
	global_store_dwordx4 v[32:33], v[28:31], off
	v_mul_f32_e64 v34, v148, |v38|
	v_mul_f32_e64 v35, v149, |v38|
	v_mul_f32_e64 v28, v131, |v38|
	v_mul_f32_e64 v29, v145, |v38|
	v_mul_f32_e32 v28, 0x3fb8aa3b, v28
	v_mul_f32_e32 v29, 0x3fb8aa3b, v29
	v_exp_f32_e32 v28, v28
	v_exp_f32_e32 v29, v29
	v_mul_f32_e64 v30, v146, |v38|
	v_mul_f32_e64 v31, v147, |v38|
	v_mul_f32_e32 v30, 0x3fb8aa3b, v30
	v_mul_f32_e32 v31, 0x3fb8aa3b, v31
	v_pk_mul_f32 v[20:21], v[28:29], v[20:21]
	v_mul_f32_e64 v28, v116, |v38|
	v_mul_f32_e64 v29, v117, |v38|
	v_exp_f32_e32 v30, v30
	v_exp_f32_e32 v31, v31
	v_mul_f32_e32 v28, 0x3fb8aa3b, v28
	v_mul_f32_e32 v29, 0x3fb8aa3b, v29
	v_mul_f32_e32 v34, 0x3fb8aa3b, v34
	v_mul_f32_e32 v35, 0x3fb8aa3b, v35
	v_exp_f32_e32 v28, v28
	v_exp_f32_e32 v29, v29
	v_exp_f32_e32 v34, v34
	v_exp_f32_e32 v35, v35
	v_pk_mul_f32 v[22:23], v[30:31], v[22:23]
	global_store_dwordx4 v[32:33], v[20:23], off offset:64
	s_nop 1
	v_pk_mul_f32 v[20:21], v[28:29], v[24:25]
	v_pk_mul_f32 v[22:23], v[34:35], v[26:27]
	global_store_dwordx4 v[32:33], v[20:23], off offset:512
	v_add_u32_e32 v24, 0xb0, v130
	v_and_b32_e32 v25, 0x7ff, v24
	v_mul_f32_e64 v20, v140, |v38|
	v_mul_f32_e64 v21, v118, |v38|
	v_mul_f32_e64 v22, v119, |v38|
	v_mul_f32_e64 v23, v150, |v38|
	v_mul_f32_e32 v20, 0x3fb8aa3b, v20
	v_mul_f32_e32 v21, 0x3fb8aa3b, v21
	v_mul_f32_e32 v22, 0x3fb8aa3b, v22
	v_mul_f32_e32 v23, 0x3fb8aa3b, v23
	v_exp_f32_e32 v20, v20
	v_exp_f32_e32 v21, v21
	v_exp_f32_e32 v22, v22
	v_exp_f32_e32 v23, v23
	v_cvt_f32_u32_e32 v25, v25
	v_pk_mul_f32 v[16:17], v[20:21], v[16:17]
	v_pk_mul_f32 v[18:19], v[22:23], v[18:19]
	v_fmamk_f32 v22, v25, 0xbbc49550, v139
	global_store_dwordx4 v[32:33], v[16:19], off offset:576
	v_ashrrev_i32_e32 v25, 31, v24
	v_lshlrev_b64 v[20:21], 15, v[24:25]
	v_mul_f32_e64 v16, v141, |v22|
	v_mul_f32_e64 v17, v142, |v22|
	v_mul_f32_e64 v18, v143, |v22|
	v_mul_f32_e64 v19, v144, |v22|
	v_mul_f32_e32 v16, 0x3fb8aa3b, v16
	v_mul_f32_e32 v17, 0x3fb8aa3b, v17
	v_mul_f32_e32 v18, 0x3fb8aa3b, v18
	v_mul_f32_e32 v19, 0x3fb8aa3b, v19
	v_exp_f32_e32 v16, v16
	v_exp_f32_e32 v17, v17
	v_exp_f32_e32 v18, v18
	v_exp_f32_e32 v19, v19
	v_pk_mul_f32 v[12:13], v[16:17], v[12:13]
	v_lshl_add_u64 v[16:17], s[50:51], 0, v[20:21]
	v_pk_mul_f32 v[14:15], v[18:19], v[14:15]
	v_mul_f32_e64 v18, v131, |v22|
	v_mul_f32_e64 v19, v145, |v22|
	v_mul_f32_e64 v20, v146, |v22|
	v_mul_f32_e64 v21, v147, |v22|
	v_mul_f32_e32 v18, 0x3fb8aa3b, v18
	v_mul_f32_e32 v19, 0x3fb8aa3b, v19
	v_mul_f32_e32 v20, 0x3fb8aa3b, v20
	v_mul_f32_e32 v21, 0x3fb8aa3b, v21
	v_exp_f32_e32 v18, v18
	v_exp_f32_e32 v19, v19
	v_exp_f32_e32 v20, v20
	v_exp_f32_e32 v21, v21
	v_lshl_add_u64 v[16:17], v[16:17], 0, v[132:133]
	v_pk_mul_f32 v[8:9], v[18:19], v[8:9]
	global_store_dwordx4 v[16:17], v[12:15], off
	v_pk_mul_f32 v[10:11], v[20:21], v[10:11]
	global_store_dwordx4 v[16:17], v[8:11], off offset:64
	v_mul_f32_e64 v12, v119, |v22|
	v_mul_f32_e64 v13, v150, |v22|
	v_mul_f32_e64 v8, v116, |v22|
	v_mul_f32_e64 v9, v117, |v22|
	v_mul_f32_e32 v8, 0x3fb8aa3b, v8
	v_mul_f32_e32 v9, 0x3fb8aa3b, v9
	v_exp_f32_e32 v8, v8
	v_exp_f32_e32 v9, v9
	v_mul_f32_e64 v10, v148, |v22|
	v_mul_f32_e64 v11, v149, |v22|
	v_mul_f32_e32 v10, 0x3fb8aa3b, v10
	v_pk_mul_f32 v[4:5], v[8:9], v[4:5]
	v_mul_f32_e64 v8, v140, |v22|
	v_mul_f32_e64 v9, v118, |v22|
	v_mul_f32_e32 v11, 0x3fb8aa3b, v11
	v_mul_f32_e32 v8, 0x3fb8aa3b, v8
	v_mul_f32_e32 v9, 0x3fb8aa3b, v9
	v_mul_f32_e32 v12, 0x3fb8aa3b, v12
	v_mul_f32_e32 v13, 0x3fb8aa3b, v13
	v_exp_f32_e32 v10, v10
	v_exp_f32_e32 v11, v11
	v_exp_f32_e32 v8, v8
	v_exp_f32_e32 v9, v9
	v_exp_f32_e32 v12, v12
	v_exp_f32_e32 v13, v13
	v_pk_mul_f32 v[6:7], v[10:11], v[6:7]
	v_pk_mul_f32 v[0:1], v[8:9], v[0:1]
	global_store_dwordx4 v[16:17], v[4:7], off offset:512
	v_pk_mul_f32 v[2:3], v[12:13], v[2:3]
	global_store_dwordx4 v[16:17], v[0:3], off offset:576
	s_cbranch_vccz .LBB0_1009

.LBB0_1030:
	s_waitcnt vmcnt(0)
	s_waitcnt vmcnt(0) lgkmcnt(0)
	s_setprio 0
	s_barrier
	s_mov_b64 s[0:1], exec
	v_readlane_b32 s4, v255, 4
	v_readlane_b32 s5, v255, 5
	s_and_b64 s[4:5], s[0:1], s[4:5]
	s_xor_b64 s[6:7], s[4:5], s[0:1]
	s_mov_b64 exec, s[4:5]
	s_cbranch_execz .LBB0_1083
	s_add_i32 s0, 0, 0x25800
	v_mov_b32_e32 v0, s0
	s_waitcnt vmcnt(0) expcnt(0) lgkmcnt(0)
	ds_read_b32 v2, v0
	s_add_i32 s0, 0, 0x25804
	v_mov_b32_e32 v0, s0
	ds_read_b32 v0, v0
	s_waitcnt lgkmcnt(1)
	v_cmp_ne_u32_e32 vcc, 0, v2
	s_cbranch_vccnz .LBB0_1046
	s_add_u32 s8, s26, 0xc0200
	s_addc_u32 s9, s27, 0
	s_add_u32 s4, s26, 0xc0400
	s_addc_u32 s5, s27, 0
	s_add_u32 s10, s26, 0xc0500
	s_addc_u32 s11, s27, 0
	s_add_u32 s12, s26, 0xc0600
	s_addc_u32 s13, s27, 0
	s_add_u32 s14, s26, 0xc0700
	s_addc_u32 s15, s27, 0
	s_add_u32 s16, s26, 0xc0800
	s_addc_u32 s17, s27, 0
	s_add_u32 s18, s26, 0xc0900
	s_addc_u32 s19, s27, 0
	s_add_u32 s20, s26, 0xc0a00
	s_addc_u32 s21, s27, 0
	s_add_u32 s36, s26, 0xc0b00
	s_addc_u32 s37, s27, 0
	s_add_u32 s46, s26, 0xc0c00
	s_addc_u32 s47, s27, 0
	s_add_u32 s60, s26, 0xc0d00
	s_addc_u32 s61, s27, 0
	s_add_u32 s62, s26, 0xc0e00
	s_addc_u32 s63, s27, 0
	s_add_u32 s64, s26, 0xc0f00
	s_addc_u32 s65, s27, 0
	s_add_u32 s66, s26, 0xc1000
	s_addc_u32 s67, s27, 0
	s_add_u32 s68, s26, 0xc1100
	s_addc_u32 s69, s27, 0
	s_add_u32 s70, s26, 0xc1200
	v_readlane_b32 s0, v255, 0
	s_addc_u32 s71, s27, 0
	s_mul_i32 s23, s31, s0
	s_add_u32 s72, s26, 0xc1300
	s_mul_i32 s23, s23, s30
	s_addc_u32 s73, s27, 0
	s_mov_b32 s24, 1
	v_mov_b32_e32 v16, 0
	s_branch .LBB0_1034

.LBB0_1083:
	s_or_b64 exec, exec, s[6:7]
	v_readlane_b32 s0, v255, 7
	s_waitcnt lgkmcnt(0)
	v_mov_b32_e32 v0, v254
	v_mov_b32_e32 v8, v254
	v_readlane_b32 s1, v255, 8
	s_barrier
	v_cmp_lt_u32_e32 vcc, 0xff, v254
	s_cbranch_vccz .Lprio_skip8
	s_setprio 1
.Lprio_skip8:
	s_and_b64 vcc, exec, s[0:1]
	v_readfirstlane_b32 s23, v8
	s_cbranch_vccz .LBB0_1103
	v_lshlrev_b32_e32 v0, 4, v8
	v_add_u32_e32 v1, 0x2000, v0
	v_ashrrev_i32_e32 v2, 31, v1
	v_lshrrev_b32_e32 v2, 22, v2
	v_add_u32_e32 v2, v1, v2
	v_ashrrev_i32_e32 v9, 10, v2
	v_mul_i32_i24_e32 v2, 0x400, v9
	v_sub_u32_e32 v1, v1, v2
	v_lshrrev_b32_e32 v2, 4, v1
	v_bitop3_b32 v1, v2, v1, 32 bitop3:0x6c
	v_ashrrev_i32_e32 v2, 31, v1
	v_lshrrev_b32_e32 v2, 26, v2
	v_add_u32_e32 v2, v1, v2
	s_lshr_b32 s5, s3, 29
	v_ashrrev_i32_e32 v10, 6, v2
	v_and_b32_e32 v2, 0xc0, v2
	s_add_i32 s5, s2, s5
	v_sub_u32_e32 v1, v1, v2
	v_mov_b32_e32 v2, 1
	s_and_b32 s6, s5, -8
	s_ashr_i32 s4, s23, 6
	v_ashrrev_i16_sdwa v1, v2, sext(v1) dst_sel:DWORD dst_unused:UNUSED_PAD src0_sel:DWORD src1_sel:BYTE_0
	s_sub_i32 s6, s2, s6
	s_ashr_i32 s1, s23, 8
	s_lshl_b32 s24, s4, 10
	v_bfe_i32 v12, v1, 0, 16
	v_bfe_i32 v1, v8, 27, 1
	s_lshl_b32 s8, s6, 5
	s_ashr_i32 s5, s5, 3
	v_lshrrev_b32_e32 v1, 22, v1
	s_mul_i32 s7, s6, 33
	s_cmp_lt_i32 s6, 0
	v_add_u32_e32 v1, v0, v1
	s_cselect_b32 s6, s7, s8
	v_and_b32_e32 v1, 0xfffffc00, v1
	s_add_i32 s5, s6, s5
	v_sub_u32_e32 v0, v0, v1
	s_ashr_i32 s6, s5, 31
	v_lshrrev_b32_e32 v1, 4, v0
	s_lshr_b32 s6, s6, 26
	v_bitop3_b32 v1, v1, v0, 32 bitop3:0x6c
	v_ashrrev_i32_e32 v0, 31, v0
	s_add_i32 s6, s5, s6
	v_lshrrev_b32_e32 v0, 26, v0
	s_ashr_i32 s7, s6, 6
	s_andn2_b32 s6, s6, 63
	v_lshlrev_b32_e32 v3, 3, v9
	v_add_u32_e32 v0, v1, v0
	s_sub_i32 s6, s5, s6
	v_and_b32_e32 v3, 0x7ffff0, v3
	v_ashrrev_i32_e32 v13, 6, v0
	v_ashrrev_i32_e32 v0, 31, v8
	s_bfe_i32 s5, s6, 0x80000
	v_add_u32_e32 v3, v10, v3
	s_movk_i32 s0, 0x1600
	v_lshlrev_b32_e32 v4, 5, v9
	v_lshrrev_b32_e32 v0, 26, v0
	s_bfe_u32 s5, s5, 0x3000c
	v_mul_lo_u32 v3, v3, s0
	v_and_b32_e32 v11, 32, v4
	v_add_u32_e32 v0, v8, v0
	s_add_i32 s8, s6, s5
	v_or_b32_e32 v3, v3, v11
	v_ashrrev_i32_e32 v14, 6, v0
	s_bfe_i32 s5, s8, 0x80000
	s_and_b32 s8, s8, 0xf8
	v_add_lshl_u32 v164, v3, v12, 1
	v_lshlrev_b32_e32 v0, 3, v14
	v_lshlrev_b32_e32 v3, 5, v14
	s_sext_i32_i16 s9, s5
	s_sub_i32 s6, s6, s8
	v_and_b32_e32 v0, 0x7ffff0, v0
	v_and_b32_e32 v15, 32, v3
	v_mul_i32_i24_e32 v3, 64, v13
	s_lshl_b32 s7, s7, 3
	s_sext_i32_i8 s6, s6
	s_ashr_i32 s8, s9, 3
	v_add_u32_e32 v0, v13, v0
	v_sub_u32_e32 v1, v1, v3
	s_lshr_b32 s5, s9, 3
	s_add_i32 s74, s7, s6
	s_mul_hi_i32 s9, s8, 0x2c0000
	s_mul_i32 s8, s8, 0x2c0000
	v_mul_lo_u32 v0, v0, s0
	v_ashrrev_i16_sdwa v1, v2, sext(v1) dst_sel:DWORD dst_unused:UNUSED_PAD src0_sel:DWORD src1_sel:BYTE_0
	s_add_u32 s64, s58, s8
	v_or_b32_e32 v0, v0, v15
	v_bfe_i32 v16, v1, 0, 16
	s_addc_u32 s65, s59, s9
	s_add_i32 s25, s24, 0
	v_add_lshl_u32 v166, v0, v16, 1
	s_add_i32 m0, s25, 0x10000
	s_mul_i32 s7, s74, 0x2c0000
	global_load_lds_dwordx4 v166, s[64:65]
	s_add_i32 m0, s25, 0x12000
	s_mul_hi_i32 s6, s74, 0x2c0000
	s_add_u32 s62, s48, s7
	global_load_lds_dwordx4 v164, s[64:65]
	s_addc_u32 s63, s49, s6
	s_mov_b32 m0, s25
	s_add_i32 s28, s25, 0x2000
	global_load_lds_dwordx4 v166, s[62:63]
	s_mov_b32 m0, s28
	s_add_u32 s6, s64, 0x160000
	global_load_lds_dwordx4 v164, s[62:63]
	s_addc_u32 s7, s65, 0
	s_add_i32 m0, s25, 0x14000
	s_load_dwordx2 s[12:13], s[88:89], 0x168
	global_load_lds_dwordx4 v166, s[6:7]
	s_add_i32 m0, s25, 0x16000
	v_mov_b32_e32 v167, 0
	global_load_lds_dwordx4 v164, s[6:7]
	s_add_u32 s6, s62, 0x160000
	s_addc_u32 s7, s63, 0
	s_add_i32 s29, s25, 0x4000
	s_mov_b32 m0, s29
	s_add_i32 s33, s25, 0x6000
	global_load_lds_dwordx4 v166, s[6:7]
	s_mov_b32 m0, s33
	v_mov_b32_e32 v165, v167
	global_load_lds_dwordx4 v164, s[6:7]
	s_mov_b32 s36, 0
	v_lshl_add_u64 v[6:7], s[64:65], 0, v[166:167]
	v_lshl_add_u64 v[4:5], s[64:65], 0, v[164:165]
	v_lshl_add_u64 v[2:3], s[62:63], 0, v[166:167]
	v_lshl_add_u64 v[0:1], s[62:63], 0, v[164:165]
	s_mov_b64 s[14:15], 0x160000
	s_cmp_lg_u32 s1, 1
	s_mov_b32 s6, 0x16000
	s_cbranch_scc1 .LBB0_1086
	s_barrier

.LBB0_1098:
	ds_read_b128 v[128:131], v221
	ds_read_b128 v[132:135], v221 offset:1024
	ds_read_b128 v[136:139], v221 offset:2048
	ds_read_b128 v[140:143], v221 offset:3072
	s_add_u32 s64, s62, 0x100
	s_addc_u32 s65, s63, 0
	s_cmpk_eq_i32 s76, 0x54
	s_cselect_b32 s5, s9, s65
	s_cselect_b32 s4, s8, s64
	s_cselect_b32 s67, s11, s1
	s_cselect_b32 s66, s10, s0
	v_lshl_add_u64 v[188:189], s[62:63], 0, v[168:169]
	s_add_i32 m0, s25, 0xc000
	ds_read_b128 v[144:147], v222
	ds_read_b128 v[148:151], v222 offset:1024
	ds_read_b128 v[152:155], v222 offset:2048
	ds_read_b128 v[156:159], v222 offset:3072
	ds_read_b128 v[160:163], v222 offset:4096
	ds_read_b128 v[176:179], v222 offset:5120
	ds_read_b128 v[180:183], v222 offset:6144
	ds_read_b128 v[184:187], v222 offset:7168
	global_load_lds_dwordx4 v[188:189], off
	v_lshl_add_u64 v[188:189], s[62:63], 0, v[170:171]
	s_add_i32 m0, s25, 0xe000
	s_nop 0
	global_load_lds_dwordx4 v[188:189], off
	s_waitcnt lgkmcnt(8)
	s_barrier
	s_waitcnt lgkmcnt(0)
	s_waitcnt lgkmcnt(0)
	v_mfma_f32_16x16x32_bf16 v[124:127], v[128:131], v[144:147], v[124:127]
	v_mfma_f32_16x16x32_bf16 v[100:103], v[136:139], v[144:147], v[100:103]
	v_mfma_f32_16x16x32_bf16 v[120:123], v[128:131], v[152:155], v[120:123]
	v_mfma_f32_16x16x32_bf16 v[96:99], v[136:139], v[152:155], v[96:99]
	v_mfma_f32_16x16x32_bf16 v[116:119], v[128:131], v[160:163], v[116:119]
	v_mfma_f32_16x16x32_bf16 v[92:95], v[136:139], v[160:163], v[92:95]
	v_mfma_f32_16x16x32_bf16 v[112:115], v[128:131], v[180:183], v[112:115]
	v_mfma_f32_16x16x32_bf16 v[84:87], v[136:139], v[180:183], v[84:87]
	v_mfma_f32_16x16x32_bf16 v[124:127], v[132:135], v[148:151], v[124:127]
	v_mfma_f32_16x16x32_bf16 v[100:103], v[140:143], v[148:151], v[100:103]
	v_mfma_f32_16x16x32_bf16 v[120:123], v[132:135], v[156:159], v[120:123]
	v_mfma_f32_16x16x32_bf16 v[96:99], v[140:143], v[156:159], v[96:99]
	v_mfma_f32_16x16x32_bf16 v[116:119], v[132:135], v[176:179], v[116:119]
	v_mfma_f32_16x16x32_bf16 v[92:95], v[140:143], v[176:179], v[92:95]
	v_mfma_f32_16x16x32_bf16 v[112:115], v[132:135], v[184:187], v[112:115]
	v_mfma_f32_16x16x32_bf16 v[84:87], v[140:143], v[184:187], v[84:87]
	s_barrier
	s_add_i32 s42, s41, s24
	v_lshl_add_u64 v[204:205], s[66:67], 0, v[166:167]
	s_mov_b32 m0, s42
	ds_read_b128 v[188:191], v223
	ds_read_b128 v[192:195], v223 offset:1024
	ds_read_b128 v[196:199], v223 offset:2048
	ds_read_b128 v[200:203], v223 offset:3072
	global_load_lds_dwordx4 v[204:205], off
	v_lshl_add_u64 v[206:207], s[66:67], 0, v[164:165]
	s_add_i32 m0, s42, 0x2000
	s_nop 0
	global_load_lds_dwordx4 v[206:207], off
	s_barrier
	s_waitcnt lgkmcnt(0)
	s_waitcnt lgkmcnt(0)
	v_mfma_f32_16x16x32_bf16 v[72:75], v[188:191], v[144:147], v[72:75]
	v_mfma_f32_16x16x32_bf16 v[44:47], v[196:199], v[144:147], v[44:47]
	v_mfma_f32_16x16x32_bf16 v[64:67], v[188:191], v[152:155], v[64:67]
	v_mfma_f32_16x16x32_bf16 v[40:43], v[196:199], v[152:155], v[40:43]
	v_mfma_f32_16x16x32_bf16 v[56:59], v[188:191], v[160:163], v[56:59]
	v_mfma_f32_16x16x32_bf16 v[36:39], v[196:199], v[160:163], v[36:39]
	v_mfma_f32_16x16x32_bf16 v[48:51], v[188:191], v[180:183], v[48:51]
	v_mfma_f32_16x16x32_bf16 v[28:31], v[196:199], v[180:183], v[28:31]
	v_mfma_f32_16x16x32_bf16 v[72:75], v[192:195], v[148:151], v[72:75]
	v_mfma_f32_16x16x32_bf16 v[44:47], v[200:203], v[148:151], v[44:47]
	v_mfma_f32_16x16x32_bf16 v[64:67], v[192:195], v[156:159], v[64:67]
	v_mfma_f32_16x16x32_bf16 v[40:43], v[200:203], v[156:159], v[40:43]
	v_mfma_f32_16x16x32_bf16 v[56:59], v[192:195], v[176:179], v[56:59]
	v_mfma_f32_16x16x32_bf16 v[36:39], v[200:203], v[176:179], v[36:39]
	v_mfma_f32_16x16x32_bf16 v[48:51], v[192:195], v[184:187], v[48:51]
	v_mfma_f32_16x16x32_bf16 v[28:31], v[200:203], v[184:187], v[28:31]
	s_mov_b32 m0, s25
	v_lshl_add_u64 v[208:209], s[4:5], 0, v[166:167]
	s_barrier
	ds_read_b128 v[144:147], v222 offset:16384
	ds_read_b128 v[148:151], v222 offset:17408
	ds_read_b128 v[152:155], v222 offset:18432
	ds_read_b128 v[156:159], v222 offset:19456
	ds_read_b128 v[160:163], v222 offset:20480
	ds_read_b128 v[176:179], v222 offset:21504
	ds_read_b128 v[180:183], v222 offset:22528
	ds_read_b128 v[184:187], v222 offset:23552
	global_load_lds_dwordx4 v[208:209], off
	v_lshl_add_u64 v[210:211], s[4:5], 0, v[164:165]
	s_mov_b32 m0, s28
	s_nop 0
	global_load_lds_dwordx4 v[210:211], off
	s_barrier
	s_waitcnt lgkmcnt(0)
	s_waitcnt lgkmcnt(0)
	v_mfma_f32_16x16x32_bf16 v[108:111], v[128:131], v[144:147], v[108:111]
	v_mfma_f32_16x16x32_bf16 v[76:79], v[136:139], v[144:147], v[76:79]
	v_mfma_f32_16x16x32_bf16 v[104:107], v[128:131], v[152:155], v[104:107]
	v_mfma_f32_16x16x32_bf16 v[68:71], v[136:139], v[152:155], v[68:71]
	v_mfma_f32_16x16x32_bf16 v[88:91], v[128:131], v[160:163], v[88:91]
	v_mfma_f32_16x16x32_bf16 v[60:63], v[136:139], v[160:163], v[60:63]
	v_mfma_f32_16x16x32_bf16 v[80:83], v[128:131], v[180:183], v[80:83]
	v_mfma_f32_16x16x32_bf16 v[52:55], v[136:139], v[180:183], v[52:55]
	v_mfma_f32_16x16x32_bf16 v[108:111], v[132:135], v[148:151], v[108:111]
	v_mfma_f32_16x16x32_bf16 v[76:79], v[140:143], v[148:151], v[76:79]
	v_mfma_f32_16x16x32_bf16 v[104:107], v[132:135], v[156:159], v[104:107]
	v_mfma_f32_16x16x32_bf16 v[68:71], v[140:143], v[156:159], v[68:71]
	v_mfma_f32_16x16x32_bf16 v[88:91], v[132:135], v[176:179], v[88:91]
	v_mfma_f32_16x16x32_bf16 v[60:63], v[140:143], v[176:179], v[60:63]
	v_mfma_f32_16x16x32_bf16 v[80:83], v[132:135], v[184:187], v[80:83]
	v_mfma_f32_16x16x32_bf16 v[52:55], v[140:143], v[184:187], v[52:55]
	s_barrier
	s_add_u32 s42, s66, 0x160000
	s_addc_u32 s43, s67, 0
	s_add_i32 s44, s53, s24
	v_lshl_add_u64 v[128:129], s[42:43], 0, v[166:167]
	s_mov_b32 m0, s44
	s_nop 0
	global_load_lds_dwordx4 v[128:129], off
	v_lshl_add_u64 v[128:129], s[42:43], 0, v[164:165]
	s_add_i32 m0, s44, 0x2000
	s_nop 0
	global_load_lds_dwordx4 v[128:129], off
	s_waitcnt vmcnt(6)
	s_barrier
	v_mfma_f32_16x16x32_bf16 v[32:35], v[188:191], v[144:147], v[32:35]
	v_mfma_f32_16x16x32_bf16 v[12:15], v[196:199], v[144:147], v[12:15]
	v_mfma_f32_16x16x32_bf16 v[24:27], v[188:191], v[152:155], v[24:27]
	v_mfma_f32_16x16x32_bf16 v[8:11], v[196:199], v[152:155], v[8:11]
	v_mfma_f32_16x16x32_bf16 v[20:23], v[188:191], v[160:163], v[20:23]
	v_mfma_f32_16x16x32_bf16 v[4:7], v[196:199], v[160:163], v[4:7]
	v_mfma_f32_16x16x32_bf16 v[16:19], v[188:191], v[180:183], v[16:19]
	v_mfma_f32_16x16x32_bf16 v[0:3], v[196:199], v[180:183], v[0:3]
	v_mfma_f32_16x16x32_bf16 v[32:35], v[192:195], v[148:151], v[32:35]
	v_mfma_f32_16x16x32_bf16 v[12:15], v[200:203], v[148:151], v[12:15]
	v_mfma_f32_16x16x32_bf16 v[24:27], v[192:195], v[156:159], v[24:27]
	v_mfma_f32_16x16x32_bf16 v[8:11], v[200:203], v[156:159], v[8:11]
	v_mfma_f32_16x16x32_bf16 v[20:23], v[192:195], v[176:179], v[20:23]
	v_mfma_f32_16x16x32_bf16 v[4:7], v[200:203], v[176:179], v[4:7]
	v_mfma_f32_16x16x32_bf16 v[16:19], v[192:195], v[184:187], v[16:19]
	v_mfma_f32_16x16x32_bf16 v[0:3], v[200:203], v[184:187], v[0:3]
	s_add_i32 s42, 0, 0x18000
	v_add_u32_e32 v140, s42, v219
	s_barrier
	ds_read_b128 v[128:131], v140
	ds_read_b128 v[132:135], v140 offset:1024
	ds_read_b128 v[136:139], v140 offset:2048
	ds_read_b128 v[140:143], v140 offset:3072
	s_add_u32 s4, s4, 0x160000
	s_addc_u32 s5, s5, 0
	s_mov_b32 m0, s29
	v_lshl_add_u64 v[188:189], s[4:5], 0, v[166:167]
	ds_read_b128 v[144:147], v222 offset:32768
	ds_read_b128 v[148:151], v222 offset:33792
	ds_read_b128 v[152:155], v222 offset:34816
	ds_read_b128 v[156:159], v222 offset:35840
	ds_read_b128 v[160:163], v222 offset:36864
	ds_read_b128 v[176:179], v222 offset:37888
	ds_read_b128 v[180:183], v222 offset:38912
	ds_read_b128 v[184:187], v222 offset:39936
	global_load_lds_dwordx4 v[188:189], off
	v_lshl_add_u64 v[188:189], s[4:5], 0, v[164:165]
	s_mov_b32 m0, s33
	s_nop 0
	global_load_lds_dwordx4 v[188:189], off
	s_waitcnt lgkmcnt(8)
	s_barrier
	s_waitcnt lgkmcnt(0)
	s_waitcnt lgkmcnt(0)
	v_mfma_f32_16x16x32_bf16 v[124:127], v[128:131], v[144:147], v[124:127]
	v_mfma_f32_16x16x32_bf16 v[100:103], v[136:139], v[144:147], v[100:103]
	v_mfma_f32_16x16x32_bf16 v[120:123], v[128:131], v[152:155], v[120:123]
	v_mfma_f32_16x16x32_bf16 v[96:99], v[136:139], v[152:155], v[96:99]
	v_mfma_f32_16x16x32_bf16 v[116:119], v[128:131], v[160:163], v[116:119]
	v_mfma_f32_16x16x32_bf16 v[92:95], v[136:139], v[160:163], v[92:95]
	v_mfma_f32_16x16x32_bf16 v[112:115], v[128:131], v[180:183], v[112:115]
	v_mfma_f32_16x16x32_bf16 v[84:87], v[136:139], v[180:183], v[84:87]
	v_mfma_f32_16x16x32_bf16 v[124:127], v[132:135], v[148:151], v[124:127]
	v_mfma_f32_16x16x32_bf16 v[100:103], v[140:143], v[148:151], v[100:103]
	v_mfma_f32_16x16x32_bf16 v[120:123], v[132:135], v[156:159], v[120:123]
	v_mfma_f32_16x16x32_bf16 v[96:99], v[140:143], v[156:159], v[96:99]
	v_mfma_f32_16x16x32_bf16 v[116:119], v[132:135], v[176:179], v[116:119]
	v_mfma_f32_16x16x32_bf16 v[92:95], v[140:143], v[176:179], v[92:95]
	v_mfma_f32_16x16x32_bf16 v[112:115], v[132:135], v[184:187], v[112:115]
	v_mfma_f32_16x16x32_bf16 v[84:87], v[140:143], v[184:187], v[84:87]
	s_barrier
	s_add_i32 s43, 0, 0x1c000
	s_add_i32 s4, s42, s24
	v_add_u32_e32 v200, s43, v219
	v_lshl_add_u64 v[204:205], v[204:205], 0, s[18:19]
	s_mov_b32 m0, s4
	ds_read_b128 v[188:191], v200
	ds_read_b128 v[192:195], v200 offset:1024
	ds_read_b128 v[196:199], v200 offset:2048
	ds_read_b128 v[200:203], v200 offset:3072
	global_load_lds_dwordx4 v[204:205], off
	v_lshl_add_u64 v[204:205], v[206:207], 0, s[18:19]
	s_add_i32 m0, s4, 0x2000
	s_nop 0
	global_load_lds_dwordx4 v[204:205], off
	s_barrier
	s_waitcnt lgkmcnt(0)
	s_waitcnt lgkmcnt(0)
	v_mfma_f32_16x16x32_bf16 v[72:75], v[188:191], v[144:147], v[72:75]
	v_mfma_f32_16x16x32_bf16 v[44:47], v[196:199], v[144:147], v[44:47]
	v_mfma_f32_16x16x32_bf16 v[64:67], v[188:191], v[152:155], v[64:67]
	v_mfma_f32_16x16x32_bf16 v[40:43], v[196:199], v[152:155], v[40:43]
	v_mfma_f32_16x16x32_bf16 v[56:59], v[188:191], v[160:163], v[56:59]
	v_mfma_f32_16x16x32_bf16 v[36:39], v[196:199], v[160:163], v[36:39]
	v_mfma_f32_16x16x32_bf16 v[48:51], v[188:191], v[180:183], v[48:51]
	v_mfma_f32_16x16x32_bf16 v[28:31], v[196:199], v[180:183], v[28:31]
	v_mfma_f32_16x16x32_bf16 v[72:75], v[192:195], v[148:151], v[72:75]
	v_mfma_f32_16x16x32_bf16 v[44:47], v[200:203], v[148:151], v[44:47]
	v_mfma_f32_16x16x32_bf16 v[64:67], v[192:195], v[156:159], v[64:67]
	v_mfma_f32_16x16x32_bf16 v[40:43], v[200:203], v[156:159], v[40:43]
	v_mfma_f32_16x16x32_bf16 v[56:59], v[192:195], v[176:179], v[56:59]
	v_mfma_f32_16x16x32_bf16 v[36:39], v[200:203], v[176:179], v[36:39]
	v_mfma_f32_16x16x32_bf16 v[48:51], v[192:195], v[184:187], v[48:51]
	v_mfma_f32_16x16x32_bf16 v[28:31], v[200:203], v[184:187], v[28:31]
	s_mov_b32 m0, s37
	v_lshl_add_u64 v[204:205], v[208:209], 0, s[18:19]
	s_barrier
	ds_read_b128 v[144:147], v222 offset:49152
	ds_read_b128 v[148:151], v222 offset:50176
	ds_read_b128 v[152:155], v222 offset:51200
	ds_read_b128 v[156:159], v222 offset:52224
	ds_read_b128 v[160:163], v222 offset:53248
	ds_read_b128 v[176:179], v222 offset:54272
	ds_read_b128 v[180:183], v222 offset:55296
	ds_read_b128 v[184:187], v222 offset:56320
	global_load_lds_dwordx4 v[204:205], off
	v_lshl_add_u64 v[204:205], v[210:211], 0, s[18:19]
	s_mov_b32 m0, s40
	s_nop 0
	global_load_lds_dwordx4 v[204:205], off
	s_barrier
	s_waitcnt lgkmcnt(0)
	s_waitcnt lgkmcnt(0)
	v_mfma_f32_16x16x32_bf16 v[108:111], v[128:131], v[144:147], v[108:111]
	v_mfma_f32_16x16x32_bf16 v[76:79], v[136:139], v[144:147], v[76:79]
	v_mfma_f32_16x16x32_bf16 v[104:107], v[128:131], v[152:155], v[104:107]
	v_mfma_f32_16x16x32_bf16 v[68:71], v[136:139], v[152:155], v[68:71]
	v_mfma_f32_16x16x32_bf16 v[88:91], v[128:131], v[160:163], v[88:91]
	v_mfma_f32_16x16x32_bf16 v[60:63], v[136:139], v[160:163], v[60:63]
	v_mfma_f32_16x16x32_bf16 v[80:83], v[128:131], v[180:183], v[80:83]
	v_mfma_f32_16x16x32_bf16 v[52:55], v[136:139], v[180:183], v[52:55]
	v_mfma_f32_16x16x32_bf16 v[108:111], v[132:135], v[148:151], v[108:111]
	v_mfma_f32_16x16x32_bf16 v[76:79], v[140:143], v[148:151], v[76:79]
	v_mfma_f32_16x16x32_bf16 v[104:107], v[132:135], v[156:159], v[104:107]
	v_mfma_f32_16x16x32_bf16 v[68:71], v[140:143], v[156:159], v[68:71]
	v_mfma_f32_16x16x32_bf16 v[88:91], v[132:135], v[176:179], v[88:91]
	v_mfma_f32_16x16x32_bf16 v[60:63], v[140:143], v[176:179], v[60:63]
	v_mfma_f32_16x16x32_bf16 v[80:83], v[132:135], v[184:187], v[80:83]
	v_mfma_f32_16x16x32_bf16 v[52:55], v[140:143], v[184:187], v[52:55]
	s_barrier
	s_add_u32 s4, s66, 0x160080
	s_addc_u32 s5, s67, 0
	s_add_i32 s42, s43, s24
	v_lshl_add_u64 v[128:129], s[4:5], 0, v[166:167]
	s_mov_b32 m0, s42
	s_nop 0
	global_load_lds_dwordx4 v[128:129], off
	v_lshl_add_u64 v[128:129], s[4:5], 0, v[164:165]
	s_add_i32 m0, s42, 0x2000
	s_nop 0
	global_load_lds_dwordx4 v[128:129], off
	s_waitcnt vmcnt(6)
	s_barrier
	v_mfma_f32_16x16x32_bf16 v[32:35], v[188:191], v[144:147], v[32:35]
	v_mfma_f32_16x16x32_bf16 v[12:15], v[196:199], v[144:147], v[12:15]
	v_mfma_f32_16x16x32_bf16 v[24:27], v[188:191], v[152:155], v[24:27]
	v_mfma_f32_16x16x32_bf16 v[8:11], v[196:199], v[152:155], v[8:11]
	v_mfma_f32_16x16x32_bf16 v[20:23], v[188:191], v[160:163], v[20:23]
	v_mfma_f32_16x16x32_bf16 v[4:7], v[196:199], v[160:163], v[4:7]
	v_mfma_f32_16x16x32_bf16 v[16:19], v[188:191], v[180:183], v[16:19]
	v_mfma_f32_16x16x32_bf16 v[0:3], v[196:199], v[180:183], v[0:3]
	v_mfma_f32_16x16x32_bf16 v[32:35], v[192:195], v[148:151], v[32:35]
	v_mfma_f32_16x16x32_bf16 v[12:15], v[200:203], v[148:151], v[12:15]
	v_mfma_f32_16x16x32_bf16 v[24:27], v[192:195], v[156:159], v[24:27]
	v_mfma_f32_16x16x32_bf16 v[8:11], v[200:203], v[156:159], v[8:11]
	v_mfma_f32_16x16x32_bf16 v[20:23], v[192:195], v[176:179], v[20:23]
	v_mfma_f32_16x16x32_bf16 v[4:7], v[200:203], v[176:179], v[4:7]
	v_mfma_f32_16x16x32_bf16 v[16:19], v[192:195], v[184:187], v[16:19]
	v_mfma_f32_16x16x32_bf16 v[0:3], v[200:203], v[184:187], v[0:3]
	s_add_i32 s76, s76, 2
	s_add_u32 s0, s0, 0x100
	s_addc_u32 s1, s1, 0
	s_cmpk_gt_u32 s76, 0x55
	s_mov_b64 s[62:63], s[64:65]
	s_barrier
	s_cbranch_scc0 .LBB0_1098
	v_lshl_add_u32 v144, s74, 8, v218
	v_lshl_or_b32 v184, s75, 8, v220
	v_ashrrev_i32_e32 v145, 31, v144
	v_ashrrev_i32_e32 v185, 31, v184
	v_lshlrev_b64 v[132:133], 13, v[144:145]
	v_lshlrev_b64 v[146:147], 2, v[184:185]
	v_lshl_add_u64 v[132:133], s[12:13], 0, v[132:133]
	v_lshl_add_u64 v[176:177], v[132:133], 0, v[146:147]
	v_or_b32_e32 v136, 16, v144
	v_add_co_u32_e32 v186, vcc, s68, v176
	v_ashrrev_i32_e32 v137, 31, v136
	v_or_b32_e32 v140, 32, v144
	v_or_b32_e32 v144, 48, v144
	v_addc_co_u32_e32 v187, vcc, 0, v177, vcc
	v_lshlrev_b64 v[136:137], 13, v[136:137]
	v_ashrrev_i32_e32 v141, 31, v140
	v_ashrrev_i32_e32 v145, 31, v144
	v_add_co_u32_e32 v190, vcc, s69, v176
	v_lshl_add_u64 v[128:129], s[16:17], 0, v[146:147]
	v_lshl_add_u64 v[136:137], s[12:13], 0, v[136:137]
	v_lshlrev_b64 v[140:141], 13, v[140:141]
	v_lshlrev_b64 v[144:145], 13, v[144:145]
	v_addc_co_u32_e32 v191, vcc, 0, v177, vcc
	global_load_dwordx4 v[128:131], v[128:129], off
	v_lshl_add_u64 v[178:179], v[136:137], 0, v[146:147]
	global_load_dwordx4 v[132:135], v[176:177], off
	global_load_dwordx4 v[136:139], v[178:179], off
	v_lshl_add_u64 v[140:141], s[12:13], 0, v[140:141]
	v_lshl_add_u64 v[144:145], s[12:13], 0, v[144:145]
	v_add_co_u32_e32 v192, vcc, s70, v176
	v_lshl_add_u64 v[180:181], v[140:141], 0, v[146:147]
	v_lshl_add_u64 v[182:183], v[144:145], 0, v[146:147]
	v_addc_co_u32_e32 v193, vcc, 0, v177, vcc
	global_load_dwordx4 v[140:143], v[180:181], off
	global_load_dwordx4 v[144:147], v[182:183], off
	global_load_dwordx4 v[148:151], v[186:187], off
	global_load_dwordx4 v[160:163], v[190:191], off
	global_load_dwordx4 v[156:159], v[192:193], off
	v_add_co_u32_e32 v188, vcc, s71, v176
	v_pk_add_f32 v[212:213], v[126:127], 0 op_sel_hi:[1,0]
	s_nop 0
	v_addc_co_u32_e32 v189, vcc, 0, v177, vcc
	global_load_dwordx4 v[152:155], v[188:189], off
	v_pk_add_f32 v[214:215], v[124:125], 0 op_sel_hi:[1,0]
	v_pk_add_f32 v[126:127], v[122:123], 0 op_sel_hi:[1,0]
	v_pk_add_f32 v[194:195], v[120:121], 0 op_sel_hi:[1,0]
	v_pk_add_f32 v[196:197], v[118:119], 0 op_sel_hi:[1,0]
	v_pk_add_f32 v[198:199], v[116:117], 0 op_sel_hi:[1,0]
	v_pk_add_f32 v[200:201], v[114:115], 0 op_sel_hi:[1,0]
	v_pk_add_f32 v[202:203], v[112:113], 0 op_sel_hi:[1,0]
	v_pk_add_f32 v[204:205], v[110:111], 0 op_sel_hi:[1,0]
	v_pk_add_f32 v[206:207], v[108:109], 0 op_sel_hi:[1,0]
	v_pk_add_f32 v[208:209], v[106:107], 0 op_sel_hi:[1,0]
	v_pk_add_f32 v[210:211], v[104:105], 0 op_sel_hi:[1,0]
	v_lshl_add_u64 v[120:121], v[176:177], 0, s[20:21]
	v_lshl_add_u64 v[122:123], v[176:177], 0, s[46:47]
	global_load_dwordx4 v[104:107], v[176:177], off offset:64
	global_load_dwordx4 v[108:111], v[178:179], off offset:64
	global_load_dwordx4 v[112:115], v[180:181], off offset:64
	global_load_dwordx4 v[116:119], v[182:183], off offset:64
	global_load_dwordx4 v[224:227], v[120:121], off offset:576
	global_load_dwordx4 v[228:231], v[122:123], off offset:576
	v_lshl_add_u64 v[124:125], v[176:177], 0, s[60:61]
	v_pk_add_f32 v[102:103], v[102:103], 0 op_sel_hi:[1,0]
	v_pk_add_f32 v[100:101], v[100:101], 0 op_sel_hi:[1,0]
	v_pk_add_f32 v[98:99], v[98:99], 0 op_sel_hi:[1,0]
	v_pk_add_f32 v[96:97], v[96:97], 0 op_sel_hi:[1,0]
	v_pk_add_f32 v[74:75], v[74:75], 0 op_sel_hi:[1,0]
	v_pk_add_f32 v[72:73], v[72:73], 0 op_sel_hi:[1,0]
	v_pk_add_f32 v[66:67], v[66:67], 0 op_sel_hi:[1,0]
	v_pk_add_f32 v[64:65], v[64:65], 0 op_sel_hi:[1,0]
	v_pk_add_f32 v[58:59], v[58:59], 0 op_sel_hi:[1,0]
	v_pk_add_f32 v[56:57], v[56:57], 0 op_sel_hi:[1,0]
	v_pk_add_f32 v[46:47], v[46:47], 0 op_sel_hi:[1,0]
	v_pk_add_f32 v[44:45], v[44:45], 0 op_sel_hi:[1,0]
	v_pk_add_f32 v[42:43], v[42:43], 0 op_sel_hi:[1,0]
	v_pk_add_f32 v[40:41], v[40:41], 0 op_sel_hi:[1,0]
	v_pk_add_f32 v[38:39], v[38:39], 0 op_sel_hi:[1,0]
	v_pk_add_f32 v[36:37], v[36:37], 0 op_sel_hi:[1,0]
	v_pk_add_f32 v[30:31], v[30:31], 0 op_sel_hi:[1,0]
	v_pk_add_f32 v[28:29], v[28:29], 0 op_sel_hi:[1,0]
	s_and_b64 vcc, exec, s[6:7]
	s_mov_b32 s75, s72
	s_mov_b32 s74, s73
	s_mov_b64 s[64:65], s[10:11]
	s_mov_b64 s[62:63], s[8:9]
	s_waitcnt vmcnt(0)
	v_pk_fma_f32 v[134:135], v[212:213], v[130:131], v[134:135]
	v_pk_fma_f32 v[132:133], v[214:215], v[128:129], v[132:133]
	global_store_dwordx4 v[176:177], v[132:135], off
	s_nop 1
	v_pk_fma_f32 v[134:135], v[126:127], v[130:131], v[138:139]
	v_pk_fma_f32 v[132:133], v[194:195], v[128:129], v[136:137]
	v_pk_add_f32 v[126:127], v[90:91], 0 op_sel_hi:[1,0]
	v_pk_fma_f32 v[138:139], v[196:197], v[130:131], v[142:143]
	v_pk_fma_f32 v[136:137], v[198:199], v[128:129], v[140:141]
	v_pk_fma_f32 v[142:143], v[200:201], v[130:131], v[146:147]
	v_pk_fma_f32 v[140:141], v[202:203], v[128:129], v[144:145]
	v_pk_fma_f32 v[146:147], v[204:205], v[130:131], v[150:151]
	v_pk_fma_f32 v[144:145], v[206:207], v[128:129], v[148:149]
	v_pk_fma_f32 v[150:151], v[208:209], v[130:131], v[162:163]
	v_pk_fma_f32 v[148:149], v[210:211], v[128:129], v[160:161]
	global_store_dwordx4 v[178:179], v[132:135], off
	global_store_dwordx4 v[180:181], v[136:139], off
	global_store_dwordx4 v[182:183], v[140:143], off
	global_store_dwordx4 v[186:187], v[144:147], off
	global_store_dwordx4 v[190:191], v[148:151], off
	v_pk_add_f32 v[132:133], v[88:89], 0 op_sel_hi:[1,0]
	v_pk_fma_f32 v[134:135], v[126:127], v[130:131], v[158:159]
	v_pk_fma_f32 v[132:133], v[132:133], v[128:129], v[156:157]
	v_pk_add_f32 v[126:127], v[82:83], 0 op_sel_hi:[1,0]
	global_store_dwordx4 v[192:193], v[132:135], off
	v_pk_fma_f32 v[130:131], v[126:127], v[130:131], v[154:155]
	v_or_b32_e32 v126, 16, v184
	v_pk_add_f32 v[132:133], v[80:81], 0 op_sel_hi:[1,0]
	v_ashrrev_i32_e32 v127, 31, v126
	v_pk_fma_f32 v[128:129], v[132:133], v[128:129], v[152:153]
	v_lshl_add_u64 v[146:147], v[176:177], 0, s[14:15]
	global_store_dwordx4 v[188:189], v[128:131], off
	v_lshl_add_u64 v[126:127], v[126:127], 2, s[16:17]
	global_load_dwordx4 v[88:91], v[124:125], off offset:576
	global_load_dwordx4 v[80:83], v[146:147], off offset:576
	s_nop 0
	global_load_dwordx4 v[126:129], v[126:127], off
	s_nop 0
	global_load_dwordx4 v[130:133], v[120:121], off offset:64
	global_load_dwordx4 v[134:137], v[122:123], off offset:64
	global_load_dwordx4 v[138:141], v[124:125], off offset:64
	global_load_dwordx4 v[142:145], v[146:147], off offset:64
	v_pk_add_f32 v[192:193], v[52:53], 0 op_sel_hi:[1,0]
	v_or_b32_e32 v52, 0x80, v184
	v_pk_add_f32 v[148:149], v[94:95], 0 op_sel_hi:[1,0]
	v_pk_add_f32 v[150:151], v[92:93], 0 op_sel_hi:[1,0]
	v_pk_add_f32 v[152:153], v[86:87], 0 op_sel_hi:[1,0]
	v_pk_add_f32 v[154:155], v[84:85], 0 op_sel_hi:[1,0]
	v_pk_add_f32 v[156:157], v[78:79], 0 op_sel_hi:[1,0]
	v_pk_add_f32 v[158:159], v[76:77], 0 op_sel_hi:[1,0]
	v_pk_add_f32 v[160:161], v[70:71], 0 op_sel_hi:[1,0]
	v_pk_add_f32 v[162:163], v[68:69], 0 op_sel_hi:[1,0]
	v_pk_add_f32 v[186:187], v[62:63], 0 op_sel_hi:[1,0]
	v_pk_add_f32 v[188:189], v[60:61], 0 op_sel_hi:[1,0]
	v_pk_add_f32 v[190:191], v[54:55], 0 op_sel_hi:[1,0]
	v_ashrrev_i32_e32 v53, 31, v52
	v_lshl_add_u64 v[194:195], v[52:53], 2, s[16:17]
	global_load_dwordx4 v[52:55], v[176:177], off offset:512
	global_load_dwordx4 v[60:63], v[120:121], off offset:512
	global_load_dwordx4 v[68:71], v[122:123], off offset:512
	global_load_dwordx4 v[76:79], v[124:125], off offset:512
	global_load_dwordx4 v[84:87], v[146:147], off offset:512
	s_waitcnt vmcnt(0)
	v_pk_fma_f32 v[94:95], v[102:103], v[128:129], v[106:107]
	v_pk_fma_f32 v[92:93], v[100:101], v[126:127], v[104:105]
	v_pk_fma_f32 v[98:99], v[98:99], v[128:129], v[110:111]
	v_pk_fma_f32 v[96:97], v[96:97], v[126:127], v[108:109]
	v_pk_fma_f32 v[102:103], v[148:149], v[128:129], v[114:115]
	v_pk_fma_f32 v[100:101], v[150:151], v[126:127], v[112:113]
	v_pk_fma_f32 v[106:107], v[152:153], v[128:129], v[118:119]
	v_pk_fma_f32 v[104:105], v[154:155], v[126:127], v[116:117]
	v_pk_fma_f32 v[110:111], v[156:157], v[128:129], v[132:133]
	v_pk_fma_f32 v[108:109], v[158:159], v[126:127], v[130:131]
	v_pk_fma_f32 v[114:115], v[160:161], v[128:129], v[136:137]
	v_pk_fma_f32 v[112:113], v[162:163], v[126:127], v[134:135]
	v_pk_fma_f32 v[118:119], v[186:187], v[128:129], v[140:141]
	v_pk_fma_f32 v[116:117], v[188:189], v[126:127], v[138:139]
	v_pk_fma_f32 v[128:129], v[190:191], v[128:129], v[144:145]
	v_pk_fma_f32 v[126:127], v[192:193], v[126:127], v[142:143]
	global_store_dwordx4 v[176:177], v[92:95], off offset:64
	global_store_dwordx4 v[178:179], v[96:99], off offset:64
	global_store_dwordx4 v[180:181], v[100:103], off offset:64
	global_store_dwordx4 v[182:183], v[104:107], off offset:64
	global_store_dwordx4 v[120:121], v[108:111], off offset:64
	global_store_dwordx4 v[122:123], v[112:115], off offset:64
	global_store_dwordx4 v[124:125], v[116:119], off offset:64
	global_store_dwordx4 v[146:147], v[126:129], off offset:64
	global_load_dwordx4 v[92:95], v[194:195], off
	global_load_dwordx4 v[96:99], v[178:179], off offset:512
	global_load_dwordx4 v[100:103], v[180:181], off offset:512
	global_load_dwordx4 v[104:107], v[182:183], off offset:512
	v_pk_add_f32 v[132:133], v[16:17], 0 op_sel_hi:[1,0]
	v_or_b32_e32 v16, 0x90, v184
	v_pk_add_f32 v[108:109], v[50:51], 0 op_sel_hi:[1,0]
	v_pk_add_f32 v[110:111], v[48:49], 0 op_sel_hi:[1,0]
	v_pk_add_f32 v[112:113], v[34:35], 0 op_sel_hi:[1,0]
	v_pk_add_f32 v[114:115], v[32:33], 0 op_sel_hi:[1,0]
	v_pk_add_f32 v[116:117], v[26:27], 0 op_sel_hi:[1,0]
	v_pk_add_f32 v[118:119], v[24:25], 0 op_sel_hi:[1,0]
	v_pk_add_f32 v[126:127], v[22:23], 0 op_sel_hi:[1,0]
	v_pk_add_f32 v[128:129], v[20:21], 0 op_sel_hi:[1,0]
	v_pk_add_f32 v[130:131], v[18:19], 0 op_sel_hi:[1,0]
	v_ashrrev_i32_e32 v17, 31, v16
	v_lshl_add_u64 v[134:135], v[16:17], 2, s[16:17]
	global_load_dwordx4 v[16:19], v[176:177], off offset:576
	global_load_dwordx4 v[20:23], v[178:179], off offset:576
	global_load_dwordx4 v[24:27], v[180:181], off offset:576
	global_load_dwordx4 v[32:35], v[182:183], off offset:576
	s_waitcnt vmcnt(0)
	v_pk_fma_f32 v[50:51], v[74:75], v[94:95], v[54:55]
	v_pk_fma_f32 v[48:49], v[72:73], v[92:93], v[52:53]
	v_pk_fma_f32 v[54:55], v[66:67], v[94:95], v[98:99]
	v_pk_fma_f32 v[52:53], v[64:65], v[92:93], v[96:97]
	v_pk_fma_f32 v[58:59], v[58:59], v[94:95], v[102:103]
	v_pk_fma_f32 v[56:57], v[56:57], v[92:93], v[100:101]
	v_pk_fma_f32 v[66:67], v[108:109], v[94:95], v[106:107]
	v_pk_fma_f32 v[64:65], v[110:111], v[92:93], v[104:105]
	v_pk_fma_f32 v[62:63], v[112:113], v[94:95], v[62:63]
	v_pk_fma_f32 v[60:61], v[114:115], v[92:93], v[60:61]
	v_pk_fma_f32 v[70:71], v[116:117], v[94:95], v[70:71]
	v_pk_fma_f32 v[68:69], v[118:119], v[92:93], v[68:69]
	v_pk_fma_f32 v[74:75], v[126:127], v[94:95], v[78:79]
	v_pk_fma_f32 v[72:73], v[128:129], v[92:93], v[76:77]
	v_pk_fma_f32 v[78:79], v[130:131], v[94:95], v[86:87]
	v_pk_fma_f32 v[76:77], v[132:133], v[92:93], v[84:85]
	global_store_dwordx4 v[176:177], v[48:51], off offset:512
	global_store_dwordx4 v[178:179], v[52:55], off offset:512
	global_store_dwordx4 v[180:181], v[56:59], off offset:512
	global_store_dwordx4 v[182:183], v[64:67], off offset:512
	global_store_dwordx4 v[120:121], v[60:63], off offset:512
	global_store_dwordx4 v[122:123], v[68:71], off offset:512
	global_store_dwordx4 v[124:125], v[72:75], off offset:512
	global_store_dwordx4 v[146:147], v[76:79], off offset:512
	global_load_dwordx4 v[48:51], v[134:135], off
	v_pk_add_f32 v[52:53], v[14:15], 0 op_sel_hi:[1,0]
	v_pk_add_f32 v[54:55], v[12:13], 0 op_sel_hi:[1,0]
	v_pk_add_f32 v[56:57], v[10:11], 0 op_sel_hi:[1,0]
	v_pk_add_f32 v[58:59], v[8:9], 0 op_sel_hi:[1,0]
	v_pk_add_f32 v[60:61], v[6:7], 0 op_sel_hi:[1,0]
	v_pk_add_f32 v[62:63], v[4:5], 0 op_sel_hi:[1,0]
	v_pk_add_f32 v[64:65], v[2:3], 0 op_sel_hi:[1,0]
	v_pk_add_f32 v[66:67], v[0:1], 0 op_sel_hi:[1,0]
	s_waitcnt vmcnt(0)
	v_pk_fma_f32 v[2:3], v[46:47], v[50:51], v[18:19]
	v_pk_fma_f32 v[0:1], v[44:45], v[48:49], v[16:17]
	v_pk_fma_f32 v[6:7], v[42:43], v[50:51], v[22:23]
	v_pk_fma_f32 v[4:5], v[40:41], v[48:49], v[20:21]
	v_pk_fma_f32 v[10:11], v[38:39], v[50:51], v[26:27]
	v_pk_fma_f32 v[8:9], v[36:37], v[48:49], v[24:25]
	v_pk_fma_f32 v[14:15], v[30:31], v[50:51], v[34:35]
	v_pk_fma_f32 v[12:13], v[28:29], v[48:49], v[32:33]
	v_pk_fma_f32 v[18:19], v[52:53], v[50:51], v[226:227]
	v_pk_fma_f32 v[16:17], v[54:55], v[48:49], v[224:225]
	v_pk_fma_f32 v[22:23], v[56:57], v[50:51], v[230:231]
	v_pk_fma_f32 v[20:21], v[58:59], v[48:49], v[228:229]
	v_pk_fma_f32 v[26:27], v[60:61], v[50:51], v[90:91]
	v_pk_fma_f32 v[24:25], v[62:63], v[48:49], v[88:89]
	v_pk_fma_f32 v[30:31], v[64:65], v[50:51], v[82:83]
	v_pk_fma_f32 v[28:29], v[66:67], v[48:49], v[80:81]
	global_store_dwordx4 v[176:177], v[0:3], off offset:576
	global_store_dwordx4 v[178:179], v[4:7], off offset:576
	global_store_dwordx4 v[180:181], v[8:11], off offset:576
	global_store_dwordx4 v[182:183], v[12:15], off offset:576
	global_store_dwordx4 v[120:121], v[16:19], off offset:576
	global_store_dwordx4 v[122:123], v[20:23], off offset:576
	global_store_dwordx4 v[124:125], v[24:27], off offset:576
	global_store_dwordx4 v[146:147], v[28:31], off offset:576
	s_cbranch_vccz .LBB0_1087
	s_waitcnt vmcnt(0)
	s_cmpk_gt_u32 s23, 0xff
	s_cbranch_scc1 .LBB0_1102
	s_barrier

.LBB0_1103:
	s_waitcnt vmcnt(0)
	s_waitcnt lgkmcnt(0)
	s_setprio 0
	s_barrier
	s_mov_b64 s[0:1], exec
	v_readlane_b32 s4, v255, 4
	v_readlane_b32 s5, v255, 5
	s_and_b64 s[4:5], s[0:1], s[4:5]
	v_readlane_b32 s40, v255, 10
	s_xor_b64 s[6:7], s[4:5], s[0:1]
	v_readlane_b32 s41, v255, 11
	s_mov_b64 exec, s[4:5]
	s_cbranch_execz .LBB0_1156
	s_add_i32 s0, 0, 0x25800
	v_mov_b32_e32 v0, s0
	s_waitcnt vmcnt(0) expcnt(0) lgkmcnt(0)
	ds_read_b32 v2, v0
	s_add_i32 s0, 0, 0x25804
	v_mov_b32_e32 v0, s0
	ds_read_b32 v0, v0
	s_waitcnt lgkmcnt(1)
	v_cmp_ne_u32_e32 vcc, 0, v2
	s_cbranch_vccnz .LBB0_1119
	s_add_u32 s8, s26, 0xc0200
	s_addc_u32 s9, s27, 0
	s_add_u32 s4, s26, 0xc0400
	s_addc_u32 s5, s27, 0
	s_add_u32 s10, s26, 0xc0500
	s_addc_u32 s11, s27, 0
	s_add_u32 s12, s26, 0xc0600
	s_addc_u32 s13, s27, 0
	s_add_u32 s14, s26, 0xc0700
	s_addc_u32 s15, s27, 0
	s_add_u32 s16, s26, 0xc0800
	s_addc_u32 s17, s27, 0
	s_add_u32 s18, s26, 0xc0900
	s_addc_u32 s19, s27, 0
	s_add_u32 s20, s26, 0xc0a00
	s_addc_u32 s21, s27, 0
	s_add_u32 s36, s26, 0xc0b00
	s_addc_u32 s37, s27, 0
	s_add_u32 s46, s26, 0xc0c00
	s_addc_u32 s47, s27, 0
	s_add_u32 s58, s26, 0xc0d00
	s_addc_u32 s59, s27, 0
	s_add_u32 s60, s26, 0xc0e00
	s_addc_u32 s61, s27, 0
	s_add_u32 s62, s26, 0xc0f00
	s_addc_u32 s63, s27, 0
	s_add_u32 s64, s26, 0xc1000
	s_addc_u32 s65, s27, 0
	s_add_u32 s66, s26, 0xc1100
	s_addc_u32 s67, s27, 0
	s_add_u32 s68, s26, 0xc1200
	v_readlane_b32 s0, v255, 0
	s_addc_u32 s69, s27, 0
	s_mul_i32 s23, s31, s0
	s_add_u32 s70, s26, 0xc1300
	s_mul_i32 s23, s23, s30
	s_addc_u32 s71, s27, 0
	s_mov_b32 s24, 1
	v_mov_b32_e32 v16, 0
	s_branch .LBB0_1107

.LBB0_1175:
	s_waitcnt vmcnt(0)
	s_setprio 0
	s_barrier
	s_mov_b64 s[6:7], exec
	v_readlane_b32 s0, v255, 4
	v_readlane_b32 s1, v255, 5
	s_and_b64 s[0:1], s[6:7], s[0:1]
	s_mov_b64 exec, s[0:1]
	s_cbranch_execz .LBB0_1227
	s_add_i32 s0, 0, 0x25800
	v_mov_b32_e32 v0, s0
	s_waitcnt vmcnt(0) expcnt(0) lgkmcnt(0)
	ds_read_b32 v2, v0
	s_add_i32 s0, 0, 0x25804
	v_mov_b32_e32 v0, s0
	ds_read_b32 v0, v0
	s_waitcnt lgkmcnt(1)
	v_cmp_ne_u32_e32 vcc, 0, v2
	s_cbranch_vccnz .LBB0_1191
	s_add_u32 s8, s26, 0xc0200
	s_addc_u32 s9, s27, 0
	s_add_u32 s4, s26, 0xc0400
	s_addc_u32 s5, s27, 0
	s_add_u32 s10, s26, 0xc0500
	s_addc_u32 s11, s27, 0
	s_add_u32 s12, s26, 0xc0600
	s_addc_u32 s13, s27, 0
	s_add_u32 s14, s26, 0xc0700
	s_addc_u32 s15, s27, 0
	s_add_u32 s16, s26, 0xc0800
	s_addc_u32 s17, s27, 0
	s_add_u32 s18, s26, 0xc0900
	s_addc_u32 s19, s27, 0
	s_add_u32 s20, s26, 0xc0a00
	s_addc_u32 s21, s27, 0
	s_add_u32 s36, s26, 0xc0b00
	s_addc_u32 s37, s27, 0
	s_add_u32 s46, s26, 0xc0c00
	s_addc_u32 s47, s27, 0
	s_add_u32 s58, s26, 0xc0d00
	s_addc_u32 s59, s27, 0
	s_add_u32 s60, s26, 0xc0e00
	s_addc_u32 s61, s27, 0
	s_add_u32 s62, s26, 0xc0f00
	s_addc_u32 s63, s27, 0
	s_add_u32 s64, s26, 0xc1000
	s_addc_u32 s65, s27, 0
	s_add_u32 s66, s26, 0xc1100
	s_addc_u32 s67, s27, 0
	s_add_u32 s68, s26, 0xc1200
	v_readlane_b32 s0, v255, 0
	s_addc_u32 s69, s27, 0
	s_mul_i32 s23, s31, s0
	s_add_u32 s70, s26, 0xc1300
	s_mul_i32 s23, s23, s30
	s_addc_u32 s71, s27, 0
	s_mov_b32 s24, 1
	v_mov_b32_e32 v16, 0
	s_branch .LBB0_1179

.Lprio_skip10:
	v_mov_b32_e32 v9, v254
	v_mov_b64_e32 v[0:1], s[40:41]
	flat_load_dwordx2 v[0:1], v[0:1] offset:240 sc0 sc1
	s_waitcnt vmcnt(0)
	s_cmpk_lt_i32 s2, 0x300
	s_waitcnt lgkmcnt(0)
	v_readfirstlane_b32 s9, v1
	v_readfirstlane_b32 s8, v0
	v_readfirstlane_b32 s23, v9
	s_cbranch_scc0 .LBB0_1239
	v_lshlrev_b32_e32 v0, 4, v9
	v_add_u32_e32 v1, 0x2000, v0
	v_ashrrev_i32_e32 v2, 31, v1
	v_lshrrev_b32_e32 v2, 22, v2
	v_add_u32_e32 v2, v1, v2
	v_ashrrev_i32_e32 v8, 10, v2
	v_mul_i32_i24_e32 v2, 0x400, v8
	v_sub_u32_e32 v1, v1, v2
	v_lshrrev_b32_e32 v2, 4, v1
	v_bitop3_b32 v1, v2, v1, 32 bitop3:0x6c
	v_ashrrev_i32_e32 v2, 31, v1
	v_lshrrev_b32_e32 v2, 26, v2
	v_add_u32_e32 v2, v1, v2
	v_lshlrev_b32_e32 v3, 3, v8
	v_ashrrev_i32_e32 v10, 6, v2
	v_and_b32_e32 v3, -16, v3
	v_add_u32_e32 v3, v10, v3
	v_and_b32_e32 v4, 3, v10
	s_mov_b32 s4, 0xfffe0
	v_lshrrev_b32_e32 v5, 2, v3
	v_lshlrev_b32_e32 v6, 1, v3
	v_and_b32_e32 v2, 0xc0, v2
	v_and_or_b32 v4, v3, s4, v4
	v_and_b32_e32 v5, 4, v5
	v_and_b32_e32 v6, 24, v6
	v_sub_u32_e32 v1, v1, v2
	v_mov_b32_e32 v2, 1
	v_or3_b32 v4, v4, v5, v6
	v_lshlrev_b32_e32 v5, 5, v8
	v_ashrrev_i16_sdwa v1, v2, sext(v1) dst_sel:DWORD dst_unused:UNUSED_PAD src0_sel:DWORD src1_sel:BYTE_0
	v_and_b32_e32 v5, 32, v5
	v_bfe_i32 v11, v1, 0, 16
	v_add_lshl_u32 v1, v5, v11, 1
	v_lshl_add_u32 v136, v4, 12, v1
	v_lshl_add_u32 v138, v3, 12, v1
	v_bfe_i32 v1, v9, 27, 1
	v_lshrrev_b32_e32 v1, 22, v1
	v_add_u32_e32 v1, v0, v1
	v_and_b32_e32 v1, 0xfffffc00, v1
	v_sub_u32_e32 v0, v0, v1
	v_lshrrev_b32_e32 v1, 4, v0
	v_bitop3_b32 v1, v1, v0, 32 bitop3:0x6c
	v_ashrrev_i32_e32 v0, 31, v0
	v_lshrrev_b32_e32 v0, 26, v0
	v_add_u32_e32 v0, v1, v0
	v_ashrrev_i32_e32 v12, 6, v0
	v_ashrrev_i32_e32 v0, 31, v9
	v_lshrrev_b32_e32 v0, 26, v0
	v_add_u32_e32 v0, v9, v0
	v_ashrrev_i32_e32 v13, 6, v0
	v_lshlrev_b32_e32 v0, 3, v13
	v_and_b32_e32 v0, -16, v0
	v_add_u32_e32 v0, v12, v0
	v_and_b32_e32 v3, 3, v12
	v_and_or_b32 v3, v0, s4, v3
	s_lshr_b32 s4, s3, 29
	s_add_i32 s4, s2, s4
	s_ashr_i32 s1, s23, 6
	s_ashr_i32 s5, s4, 3
	s_and_b32 s4, s4, -8
	s_ashr_i32 s0, s23, 8
	s_lshl_b32 s24, s1, 10
	s_sub_i32 s4, s2, s4
	s_cmp_lt_i32 s4, 0
	s_movk_i32 s25, 0x61
	s_cselect_b32 s6, s25, 0x60
	s_mul_i32 s4, s4, s6
	s_add_i32 s4, s4, s5
	s_mul_hi_i32 s5, s4, 0x2aaaaaab
	s_lshr_b32 s6, s5, 31
	s_ashr_i32 s5, s5, 5
	s_add_i32 s5, s5, s6
	s_lshl_b32 s6, s5, 3
	s_mulk_i32 s5, 0xc0
	s_sub_i32 s5, s4, s5
	s_sext_i32_i16 s4, s5
	s_bfe_u32 s4, s4, 0x3001c
	s_add_i32 s7, s5, s4
	s_sext_i32_i16 s4, s7
	s_and_b32 s7, s7, 0xfff8
	v_lshrrev_b32_e32 v4, 2, v0
	v_lshlrev_b32_e32 v5, 1, v0
	s_sub_i32 s5, s5, s7
	v_and_b32_e32 v4, 4, v4
	v_and_b32_e32 v5, 24, v5
	s_sext_i32_i16 s5, s5
	v_or3_b32 v3, v3, v4, v5
	v_mul_i32_i24_e32 v5, 64, v12
	s_lshr_b32 s4, s4, 3
	s_add_i32 s20, s6, s5
	v_sub_u32_e32 v1, v1, v5
	s_ashr_i32 s21, s20, 31
	s_bfe_i64 s[10:11], s[4:5], 0x100000
	v_lshlrev_b32_e32 v4, 5, v13
	v_ashrrev_i16_sdwa v1, v2, sext(v1) dst_sel:DWORD dst_unused:UNUSED_PAD src0_sel:DWORD src1_sel:BYTE_0
	s_lshl_b64 s[6:7], s[20:21], 20
	s_lshl_b64 s[10:11], s[10:11], 20
	v_and_b32_e32 v4, 32, v4
	v_bfe_i32 v14, v1, 0, 16
	s_add_u32 s58, s54, s10
	v_add_lshl_u32 v1, v4, v14, 1
	s_addc_u32 s59, s55, s11
	s_add_i32 s21, s24, 0
	v_lshl_add_u32 v140, v3, 12, v1
	s_add_i32 m0, s21, 0x10000
	v_lshl_add_u32 v142, v0, 12, v1
	global_load_lds_dwordx4 v140, s[58:59]
	s_add_i32 m0, s21, 0x12000
	s_add_u32 s36, s38, s6
	global_load_lds_dwordx4 v136, s[58:59]
	s_addc_u32 s37, s39, s7
	s_mov_b32 m0, s21
	s_add_i32 s28, s21, 0x2000
	global_load_lds_dwordx4 v142, s[36:37]
	s_mov_b32 m0, s28
	s_add_u32 s6, s58, 0x80000
	global_load_lds_dwordx4 v138, s[36:37]
	s_addc_u32 s7, s59, 0
	s_add_i32 m0, s21, 0x14000
	v_mov_b32_e32 v141, 0
	global_load_lds_dwordx4 v140, s[6:7]
	s_add_i32 m0, s21, 0x16000
	v_mov_b32_e32 v137, v141
	global_load_lds_dwordx4 v136, s[6:7]
	s_add_u32 s6, s36, 0x80000
	s_addc_u32 s7, s37, 0
	s_add_i32 s29, s21, 0x4000
	s_mov_b32 m0, s29
	s_add_i32 s33, s21, 0x6000
	global_load_lds_dwordx4 v142, s[6:7]
	s_mov_b32 m0, s33
	v_mov_b32_e32 v143, v141
	global_load_lds_dwordx4 v138, s[6:7]
	v_mov_b32_e32 v139, v141
	s_mov_b32 s40, 0
	v_lshl_add_u64 v[6:7], s[58:59], 0, v[140:141]
	v_lshl_add_u64 v[4:5], s[58:59], 0, v[136:137]
	v_lshl_add_u64 v[2:3], s[36:37], 0, v[142:143]
	s_cmp_lg_u32 s0, 1
	v_lshl_add_u64 v[0:1], s[36:37], 0, v[138:139]
	s_cbranch_scc1 .LBB0_1230
	s_barrier

.LBB0_1234:
	ds_read_b128 v[128:131], v171
	ds_read_b128 v[132:135], v171 offset:1024
	ds_read_b128 v[152:155], v171 offset:2048
	ds_read_b128 v[156:159], v171 offset:3072
	s_add_u32 s4, s46, 0xfff80080
	s_addc_u32 s5, s47, -1
	s_cmp_eq_u32 s64, 28
	s_cselect_b32 s5, s0, s5
	s_cselect_b32 s4, s1, s4
	s_cselect_b32 s59, s13, s37
	s_cselect_b32 s58, s15, s36
	v_lshl_add_u64 v[198:199], s[46:47], 0, v[144:145]
	s_add_i32 m0, s21, 0xc000
	ds_read_b128 v[160:163], v172
	ds_read_b128 v[164:167], v172 offset:1024
	ds_read_b128 v[174:177], v172 offset:2048
	ds_read_b128 v[178:181], v172 offset:3072
	ds_read_b128 v[182:185], v172 offset:4096
	ds_read_b128 v[186:189], v172 offset:5120
	ds_read_b128 v[190:193], v172 offset:6144
	ds_read_b128 v[194:197], v172 offset:7168
	global_load_lds_dwordx4 v[198:199], off
	v_lshl_add_u64 v[198:199], s[46:47], 0, v[146:147]
	s_add_i32 m0, s21, 0xe000
	s_nop 0
	global_load_lds_dwordx4 v[198:199], off
	s_waitcnt lgkmcnt(8)
	s_barrier
	s_waitcnt lgkmcnt(0)
	s_waitcnt lgkmcnt(0)
	v_mfma_f32_16x16x32_bf16 v[124:127], v[128:131], v[160:163], v[124:127]
	v_mfma_f32_16x16x32_bf16 v[120:123], v[152:155], v[160:163], v[120:123]
	v_mfma_f32_16x16x32_bf16 v[116:119], v[128:131], v[174:177], v[116:119]
	v_mfma_f32_16x16x32_bf16 v[112:115], v[152:155], v[174:177], v[112:115]
	v_mfma_f32_16x16x32_bf16 v[108:111], v[128:131], v[182:185], v[108:111]
	v_mfma_f32_16x16x32_bf16 v[104:107], v[152:155], v[182:185], v[104:107]
	v_mfma_f32_16x16x32_bf16 v[100:103], v[128:131], v[190:193], v[100:103]
	v_mfma_f32_16x16x32_bf16 v[96:99], v[152:155], v[190:193], v[96:99]
	v_mfma_f32_16x16x32_bf16 v[124:127], v[132:135], v[164:167], v[124:127]
	v_mfma_f32_16x16x32_bf16 v[120:123], v[156:159], v[164:167], v[120:123]
	v_mfma_f32_16x16x32_bf16 v[116:119], v[132:135], v[178:181], v[116:119]
	v_mfma_f32_16x16x32_bf16 v[112:115], v[156:159], v[178:181], v[112:115]
	v_mfma_f32_16x16x32_bf16 v[108:111], v[132:135], v[186:189], v[108:111]
	v_mfma_f32_16x16x32_bf16 v[104:107], v[156:159], v[186:189], v[104:107]
	v_mfma_f32_16x16x32_bf16 v[100:103], v[132:135], v[194:197], v[100:103]
	v_mfma_f32_16x16x32_bf16 v[96:99], v[156:159], v[194:197], v[96:99]
	s_barrier
	s_add_i32 s42, s60, s24
	v_lshl_add_u64 v[214:215], s[58:59], 0, v[140:141]
	s_mov_b32 m0, s42
	ds_read_b128 v[198:201], v173
	ds_read_b128 v[202:205], v173 offset:1024
	ds_read_b128 v[206:209], v173 offset:2048
	ds_read_b128 v[210:213], v173 offset:3072
	global_load_lds_dwordx4 v[214:215], off
	v_lshl_add_u64 v[216:217], s[58:59], 0, v[136:137]
	s_add_i32 m0, s42, 0x2000
	s_nop 0
	global_load_lds_dwordx4 v[216:217], off
	s_barrier
	s_waitcnt lgkmcnt(0)
	s_waitcnt lgkmcnt(0)
	v_mfma_f32_16x16x32_bf16 v[68:71], v[198:201], v[160:163], v[68:71]
	v_mfma_f32_16x16x32_bf16 v[64:67], v[206:209], v[160:163], v[64:67]
	v_mfma_f32_16x16x32_bf16 v[52:55], v[198:201], v[174:177], v[52:55]
	v_mfma_f32_16x16x32_bf16 v[48:51], v[206:209], v[174:177], v[48:51]
	v_mfma_f32_16x16x32_bf16 v[44:47], v[198:201], v[182:185], v[44:47]
	v_mfma_f32_16x16x32_bf16 v[40:43], v[206:209], v[182:185], v[40:43]
	v_mfma_f32_16x16x32_bf16 v[36:39], v[198:201], v[190:193], v[36:39]
	v_mfma_f32_16x16x32_bf16 v[32:35], v[206:209], v[190:193], v[32:35]
	v_mfma_f32_16x16x32_bf16 v[68:71], v[202:205], v[164:167], v[68:71]
	v_mfma_f32_16x16x32_bf16 v[64:67], v[210:213], v[164:167], v[64:67]
	v_mfma_f32_16x16x32_bf16 v[52:55], v[202:205], v[178:181], v[52:55]
	v_mfma_f32_16x16x32_bf16 v[48:51], v[210:213], v[178:181], v[48:51]
	v_mfma_f32_16x16x32_bf16 v[44:47], v[202:205], v[186:189], v[44:47]
	v_mfma_f32_16x16x32_bf16 v[40:43], v[210:213], v[186:189], v[40:43]
	v_mfma_f32_16x16x32_bf16 v[36:39], v[202:205], v[194:197], v[36:39]
	v_mfma_f32_16x16x32_bf16 v[32:35], v[210:213], v[194:197], v[32:35]
	s_mov_b32 m0, s21
	v_lshl_add_u64 v[218:219], s[4:5], 0, v[142:143]
	s_barrier
	ds_read_b128 v[160:163], v172 offset:16384
	ds_read_b128 v[164:167], v172 offset:17408
	ds_read_b128 v[174:177], v172 offset:18432
	ds_read_b128 v[178:181], v172 offset:19456
	ds_read_b128 v[182:185], v172 offset:20480
	ds_read_b128 v[186:189], v172 offset:21504
	ds_read_b128 v[190:193], v172 offset:22528
	ds_read_b128 v[194:197], v172 offset:23552
	global_load_lds_dwordx4 v[218:219], off
	v_lshl_add_u64 v[220:221], s[4:5], 0, v[138:139]
	s_mov_b32 m0, s28
	s_nop 0
	global_load_lds_dwordx4 v[220:221], off
	s_barrier
	s_waitcnt lgkmcnt(0)
	s_waitcnt lgkmcnt(0)
	v_mfma_f32_16x16x32_bf16 v[92:95], v[128:131], v[160:163], v[92:95]
	v_mfma_f32_16x16x32_bf16 v[88:91], v[152:155], v[160:163], v[88:91]
	v_mfma_f32_16x16x32_bf16 v[84:87], v[128:131], v[174:177], v[84:87]
	v_mfma_f32_16x16x32_bf16 v[80:83], v[152:155], v[174:177], v[80:83]
	v_mfma_f32_16x16x32_bf16 v[76:79], v[128:131], v[182:185], v[76:79]
	v_mfma_f32_16x16x32_bf16 v[72:75], v[152:155], v[182:185], v[72:75]
	v_mfma_f32_16x16x32_bf16 v[60:63], v[128:131], v[190:193], v[60:63]
	v_mfma_f32_16x16x32_bf16 v[56:59], v[152:155], v[190:193], v[56:59]
	v_mfma_f32_16x16x32_bf16 v[92:95], v[132:135], v[164:167], v[92:95]
	v_mfma_f32_16x16x32_bf16 v[88:91], v[156:159], v[164:167], v[88:91]
	v_mfma_f32_16x16x32_bf16 v[84:87], v[132:135], v[178:181], v[84:87]
	v_mfma_f32_16x16x32_bf16 v[80:83], v[156:159], v[178:181], v[80:83]
	v_mfma_f32_16x16x32_bf16 v[76:79], v[132:135], v[186:189], v[76:79]
	v_mfma_f32_16x16x32_bf16 v[72:75], v[156:159], v[186:189], v[72:75]
	v_mfma_f32_16x16x32_bf16 v[60:63], v[132:135], v[194:197], v[60:63]
	v_mfma_f32_16x16x32_bf16 v[56:59], v[156:159], v[194:197], v[56:59]
	s_barrier
	s_add_u32 s42, s58, 0x80000
	s_addc_u32 s43, s59, 0
	s_add_i32 s44, s61, s24
	v_lshl_add_u64 v[128:129], s[42:43], 0, v[140:141]
	s_mov_b32 m0, s44
	s_nop 0
	global_load_lds_dwordx4 v[128:129], off
	v_lshl_add_u64 v[128:129], s[42:43], 0, v[136:137]
	s_add_i32 m0, s44, 0x2000
	s_nop 0
	global_load_lds_dwordx4 v[128:129], off
	s_waitcnt vmcnt(6)
	s_barrier
	v_mfma_f32_16x16x32_bf16 v[28:31], v[198:201], v[160:163], v[28:31]
	v_mfma_f32_16x16x32_bf16 v[24:27], v[206:209], v[160:163], v[24:27]
	v_mfma_f32_16x16x32_bf16 v[20:23], v[198:201], v[174:177], v[20:23]
	v_mfma_f32_16x16x32_bf16 v[16:19], v[206:209], v[174:177], v[16:19]
	v_mfma_f32_16x16x32_bf16 v[12:15], v[198:201], v[182:185], v[12:15]
	v_mfma_f32_16x16x32_bf16 v[8:11], v[206:209], v[182:185], v[8:11]
	v_mfma_f32_16x16x32_bf16 v[4:7], v[198:201], v[190:193], v[4:7]
	v_mfma_f32_16x16x32_bf16 v[0:3], v[206:209], v[190:193], v[0:3]
	v_mfma_f32_16x16x32_bf16 v[28:31], v[202:205], v[164:167], v[28:31]
	v_mfma_f32_16x16x32_bf16 v[24:27], v[210:213], v[164:167], v[24:27]
	v_mfma_f32_16x16x32_bf16 v[20:23], v[202:205], v[178:181], v[20:23]
	v_mfma_f32_16x16x32_bf16 v[16:19], v[210:213], v[178:181], v[16:19]
	v_mfma_f32_16x16x32_bf16 v[12:15], v[202:205], v[186:189], v[12:15]
	v_mfma_f32_16x16x32_bf16 v[8:11], v[210:213], v[186:189], v[8:11]
	v_mfma_f32_16x16x32_bf16 v[4:7], v[202:205], v[194:197], v[4:7]
	v_mfma_f32_16x16x32_bf16 v[0:3], v[210:213], v[194:197], v[0:3]
	s_add_i32 s42, 0, 0x18000
	v_add_u32_e32 v156, s42, v169
	s_barrier
	ds_read_b128 v[128:131], v156
	ds_read_b128 v[132:135], v156 offset:1024
	ds_read_b128 v[152:155], v156 offset:2048
	ds_read_b128 v[156:159], v156 offset:3072
	s_add_u32 s4, s4, 0x80000
	s_addc_u32 s5, s5, 0
	s_mov_b32 m0, s29
	v_lshl_add_u64 v[198:199], s[4:5], 0, v[142:143]
	ds_read_b128 v[160:163], v172 offset:32768
	ds_read_b128 v[164:167], v172 offset:33792
	ds_read_b128 v[174:177], v172 offset:34816
	ds_read_b128 v[178:181], v172 offset:35840
	ds_read_b128 v[182:185], v172 offset:36864
	ds_read_b128 v[186:189], v172 offset:37888
	ds_read_b128 v[190:193], v172 offset:38912
	ds_read_b128 v[194:197], v172 offset:39936
	global_load_lds_dwordx4 v[198:199], off
	v_lshl_add_u64 v[198:199], s[4:5], 0, v[138:139]
	s_mov_b32 m0, s33
	s_nop 0
	global_load_lds_dwordx4 v[198:199], off
	s_waitcnt lgkmcnt(8)
	s_barrier
	s_waitcnt lgkmcnt(0)
	s_waitcnt lgkmcnt(0)
	v_mfma_f32_16x16x32_bf16 v[124:127], v[128:131], v[160:163], v[124:127]
	v_mfma_f32_16x16x32_bf16 v[120:123], v[152:155], v[160:163], v[120:123]
	v_mfma_f32_16x16x32_bf16 v[116:119], v[128:131], v[174:177], v[116:119]
	v_mfma_f32_16x16x32_bf16 v[112:115], v[152:155], v[174:177], v[112:115]
	v_mfma_f32_16x16x32_bf16 v[108:111], v[128:131], v[182:185], v[108:111]
	v_mfma_f32_16x16x32_bf16 v[104:107], v[152:155], v[182:185], v[104:107]
	v_mfma_f32_16x16x32_bf16 v[100:103], v[128:131], v[190:193], v[100:103]
	v_mfma_f32_16x16x32_bf16 v[96:99], v[152:155], v[190:193], v[96:99]
	v_mfma_f32_16x16x32_bf16 v[124:127], v[132:135], v[164:167], v[124:127]
	v_mfma_f32_16x16x32_bf16 v[120:123], v[156:159], v[164:167], v[120:123]
	v_mfma_f32_16x16x32_bf16 v[116:119], v[132:135], v[178:181], v[116:119]
	v_mfma_f32_16x16x32_bf16 v[112:115], v[156:159], v[178:181], v[112:115]
	v_mfma_f32_16x16x32_bf16 v[108:111], v[132:135], v[186:189], v[108:111]
	v_mfma_f32_16x16x32_bf16 v[104:107], v[156:159], v[186:189], v[104:107]
	v_mfma_f32_16x16x32_bf16 v[100:103], v[132:135], v[194:197], v[100:103]
	v_mfma_f32_16x16x32_bf16 v[96:99], v[156:159], v[194:197], v[96:99]
	s_barrier
	s_add_i32 s43, 0, 0x1c000
	s_add_i32 s4, s42, s24
	v_add_u32_e32 v210, s43, v169
	v_lshl_add_u64 v[214:215], v[214:215], 0, s[10:11]
	s_mov_b32 m0, s4
	ds_read_b128 v[198:201], v210
	ds_read_b128 v[202:205], v210 offset:1024
	ds_read_b128 v[206:209], v210 offset:2048
	ds_read_b128 v[210:213], v210 offset:3072
	global_load_lds_dwordx4 v[214:215], off
	v_lshl_add_u64 v[214:215], v[216:217], 0, s[10:11]
	s_add_i32 m0, s4, 0x2000
	s_nop 0
	global_load_lds_dwordx4 v[214:215], off
	s_barrier
	s_waitcnt lgkmcnt(0)
	s_waitcnt lgkmcnt(0)
	v_mfma_f32_16x16x32_bf16 v[68:71], v[198:201], v[160:163], v[68:71]
	v_mfma_f32_16x16x32_bf16 v[64:67], v[206:209], v[160:163], v[64:67]
	v_mfma_f32_16x16x32_bf16 v[52:55], v[198:201], v[174:177], v[52:55]
	v_mfma_f32_16x16x32_bf16 v[48:51], v[206:209], v[174:177], v[48:51]
	v_mfma_f32_16x16x32_bf16 v[44:47], v[198:201], v[182:185], v[44:47]
	v_mfma_f32_16x16x32_bf16 v[40:43], v[206:209], v[182:185], v[40:43]
	v_mfma_f32_16x16x32_bf16 v[36:39], v[198:201], v[190:193], v[36:39]
	v_mfma_f32_16x16x32_bf16 v[32:35], v[206:209], v[190:193], v[32:35]
	v_mfma_f32_16x16x32_bf16 v[68:71], v[202:205], v[164:167], v[68:71]
	v_mfma_f32_16x16x32_bf16 v[64:67], v[210:213], v[164:167], v[64:67]
	v_mfma_f32_16x16x32_bf16 v[52:55], v[202:205], v[178:181], v[52:55]
	v_mfma_f32_16x16x32_bf16 v[48:51], v[210:213], v[178:181], v[48:51]
	v_mfma_f32_16x16x32_bf16 v[44:47], v[202:205], v[186:189], v[44:47]
	v_mfma_f32_16x16x32_bf16 v[40:43], v[210:213], v[186:189], v[40:43]
	v_mfma_f32_16x16x32_bf16 v[36:39], v[202:205], v[194:197], v[36:39]
	v_mfma_f32_16x16x32_bf16 v[32:35], v[210:213], v[194:197], v[32:35]
	s_mov_b32 m0, s41
	v_lshl_add_u64 v[214:215], v[218:219], 0, s[10:11]
	s_barrier
	ds_read_b128 v[160:163], v172 offset:49152
	ds_read_b128 v[164:167], v172 offset:50176
	ds_read_b128 v[174:177], v172 offset:51200
	ds_read_b128 v[178:181], v172 offset:52224
	ds_read_b128 v[182:185], v172 offset:53248
	ds_read_b128 v[186:189], v172 offset:54272
	ds_read_b128 v[190:193], v172 offset:55296
	ds_read_b128 v[194:197], v172 offset:56320
	global_load_lds_dwordx4 v[214:215], off
	v_lshl_add_u64 v[214:215], v[220:221], 0, s[10:11]
	s_mov_b32 m0, s53
	s_nop 0
	global_load_lds_dwordx4 v[214:215], off
	s_barrier
	s_waitcnt lgkmcnt(0)
	s_waitcnt lgkmcnt(0)
	v_mfma_f32_16x16x32_bf16 v[92:95], v[128:131], v[160:163], v[92:95]
	v_mfma_f32_16x16x32_bf16 v[88:91], v[152:155], v[160:163], v[88:91]
	v_mfma_f32_16x16x32_bf16 v[84:87], v[128:131], v[174:177], v[84:87]
	v_mfma_f32_16x16x32_bf16 v[80:83], v[152:155], v[174:177], v[80:83]
	v_mfma_f32_16x16x32_bf16 v[76:79], v[128:131], v[182:185], v[76:79]
	v_mfma_f32_16x16x32_bf16 v[72:75], v[152:155], v[182:185], v[72:75]
	v_mfma_f32_16x16x32_bf16 v[60:63], v[128:131], v[190:193], v[60:63]
	v_mfma_f32_16x16x32_bf16 v[56:59], v[152:155], v[190:193], v[56:59]
	v_mfma_f32_16x16x32_bf16 v[92:95], v[132:135], v[164:167], v[92:95]
	v_mfma_f32_16x16x32_bf16 v[88:91], v[156:159], v[164:167], v[88:91]
	v_mfma_f32_16x16x32_bf16 v[84:87], v[132:135], v[178:181], v[84:87]
	v_mfma_f32_16x16x32_bf16 v[80:83], v[156:159], v[178:181], v[80:83]
	v_mfma_f32_16x16x32_bf16 v[76:79], v[132:135], v[186:189], v[76:79]
	v_mfma_f32_16x16x32_bf16 v[72:75], v[156:159], v[186:189], v[72:75]
	v_mfma_f32_16x16x32_bf16 v[60:63], v[132:135], v[194:197], v[60:63]
	v_mfma_f32_16x16x32_bf16 v[56:59], v[156:159], v[194:197], v[56:59]
	s_barrier
	s_add_u32 s4, s58, 0x80080
	s_addc_u32 s5, s59, 0
	s_add_i32 s42, s43, s24
	v_lshl_add_u64 v[128:129], s[4:5], 0, v[140:141]
	s_mov_b32 m0, s42
	s_nop 0
	global_load_lds_dwordx4 v[128:129], off
	v_lshl_add_u64 v[128:129], s[4:5], 0, v[136:137]
	s_add_i32 m0, s42, 0x2000
	s_nop 0
	global_load_lds_dwordx4 v[128:129], off
	s_waitcnt vmcnt(6)
	s_barrier
	v_mfma_f32_16x16x32_bf16 v[28:31], v[198:201], v[160:163], v[28:31]
	v_mfma_f32_16x16x32_bf16 v[24:27], v[206:209], v[160:163], v[24:27]
	v_mfma_f32_16x16x32_bf16 v[20:23], v[198:201], v[174:177], v[20:23]
	v_mfma_f32_16x16x32_bf16 v[16:19], v[206:209], v[174:177], v[16:19]
	v_mfma_f32_16x16x32_bf16 v[12:15], v[198:201], v[182:185], v[12:15]
	v_mfma_f32_16x16x32_bf16 v[8:11], v[206:209], v[182:185], v[8:11]
	v_mfma_f32_16x16x32_bf16 v[4:7], v[198:201], v[190:193], v[4:7]
	v_mfma_f32_16x16x32_bf16 v[0:3], v[206:209], v[190:193], v[0:3]
	v_mfma_f32_16x16x32_bf16 v[28:31], v[202:205], v[164:167], v[28:31]
	v_mfma_f32_16x16x32_bf16 v[24:27], v[210:213], v[164:167], v[24:27]
	v_mfma_f32_16x16x32_bf16 v[20:23], v[202:205], v[178:181], v[20:23]
	v_mfma_f32_16x16x32_bf16 v[16:19], v[210:213], v[178:181], v[16:19]
	v_mfma_f32_16x16x32_bf16 v[12:15], v[202:205], v[186:189], v[12:15]
	v_mfma_f32_16x16x32_bf16 v[8:11], v[210:213], v[186:189], v[8:11]
	v_mfma_f32_16x16x32_bf16 v[4:7], v[202:205], v[194:197], v[4:7]
	v_mfma_f32_16x16x32_bf16 v[0:3], v[210:213], v[194:197], v[0:3]
	s_add_i32 s64, s64, 2
	s_add_u32 s46, s46, 0x100
	s_addc_u32 s47, s47, 0
	s_add_u32 s36, s36, 0x100
	s_addc_u32 s37, s37, 0
	s_cmp_gt_u32 s64, 29
	s_barrier
	s_cbranch_scc0 .LBB0_1234
	v_lshl_or_b32 v152, s63, 8, v170
	v_ashrrev_i32_e32 v153, 31, v152
	v_lshl_add_u64 v[164:165], v[152:153], 2, s[8:9]
	flat_load_dwordx4 v[132:135], v[164:165]
	flat_load_dwordx4 v[128:131], v[164:165] offset:16
	v_lshl_add_u32 v182, s20, 8, v168
	v_mov_b64_e32 v[166:167], s[48:49]
	v_add_u32_e32 v159, 0x80, v182
	v_mad_i64_i32 v[154:155], s[0:1], v182, s62, v[166:167]
	v_or_b32_e32 v156, 16, v182
	v_or_b32_e32 v157, 32, v182
	v_or_b32_e32 v158, 48, v182
	v_lshlrev_b64 v[174:175], 1, v[152:153]
	v_mad_i64_i32 v[178:179], s[0:1], v159, s62, v[166:167]
	v_add_u32_e32 v160, 0x90, v182
	v_mad_i64_i32 v[152:153], s[0:1], v156, s62, v[166:167]
	v_mad_i64_i32 v[156:157], s[0:1], v157, s62, v[166:167]
	v_mad_i64_i32 v[176:177], s[0:1], v158, s62, v[166:167]
	v_lshl_add_u64 v[162:163], v[154:155], 0, v[174:175]
	v_lshl_add_u64 v[154:155], v[178:179], 0, v[174:175]
	v_mad_i64_i32 v[180:181], s[0:1], v160, s62, v[166:167]
	v_lshl_add_u64 v[160:161], v[152:153], 0, v[174:175]
	v_lshl_add_u64 v[158:159], v[156:157], 0, v[174:175]
	v_lshl_add_u64 v[156:157], v[176:177], 0, v[174:175]
	v_lshl_add_u64 v[152:153], v[180:181], 0, v[174:175]
	s_and_b64 vcc, exec, s[6:7]
	s_mov_b32 s63, s12
	s_mov_b32 s20, s14
	s_mov_b64 s[58:59], s[18:19]
	s_mov_b64 s[36:37], s[16:17]
	s_waitcnt vmcnt(0) lgkmcnt(0)
	v_pk_add_f32 v[124:125], v[124:125], v[132:133]
	v_pk_add_f32 v[178:179], v[72:73], v[128:129]
	s_nop 1
	v_cvt_pk_bf16_f32 v72, v124, v125
	v_pk_add_f32 v[126:127], v[126:127], v[134:135]
	v_pk_add_f32 v[122:123], v[122:123], v[130:131]
	v_pk_add_f32 v[120:121], v[120:121], v[128:129]
	v_pk_add_f32 v[116:117], v[116:117], v[132:133]
	v_pk_add_f32 v[176:177], v[74:75], v[130:131]
	s_nop 1
	v_cvt_pk_bf16_f32 v73, v126, v127
	s_nop 1
	v_cvt_pk_bf16_f32 v74, v120, v121
	s_nop 1
	v_cvt_pk_bf16_f32 v75, v122, v123
	global_store_dwordx4 v[162:163], v[72:75], off
	v_pk_add_f32 v[118:119], v[118:119], v[134:135]
	v_pk_add_f32 v[114:115], v[114:115], v[130:131]
	s_nop 1
	v_cvt_pk_bf16_f32 v72, v116, v117
	v_pk_add_f32 v[112:113], v[112:113], v[128:129]
	v_pk_add_f32 v[108:109], v[108:109], v[132:133]
	s_nop 1
	v_cvt_pk_bf16_f32 v73, v118, v119
	s_nop 1
	v_cvt_pk_bf16_f32 v74, v112, v113
	s_nop 1
	v_cvt_pk_bf16_f32 v75, v114, v115
	global_store_dwordx4 v[160:161], v[72:75], off
	v_pk_add_f32 v[110:111], v[110:111], v[134:135]
	v_pk_add_f32 v[106:107], v[106:107], v[130:131]
	s_nop 1
	v_cvt_pk_bf16_f32 v72, v108, v109
	v_pk_add_f32 v[104:105], v[104:105], v[128:129]
	v_pk_add_f32 v[100:101], v[100:101], v[132:133]
	s_nop 1
	v_cvt_pk_bf16_f32 v73, v110, v111
	s_nop 1
	v_cvt_pk_bf16_f32 v74, v104, v105
	s_nop 1
	v_cvt_pk_bf16_f32 v75, v106, v107
	global_store_dwordx4 v[158:159], v[72:75], off
	v_pk_add_f32 v[102:103], v[102:103], v[134:135]
	v_pk_add_f32 v[98:99], v[98:99], v[130:131]
	s_nop 1
	v_cvt_pk_bf16_f32 v72, v100, v101
	v_pk_add_f32 v[96:97], v[96:97], v[128:129]
	v_pk_add_f32 v[92:93], v[92:93], v[132:133]
	s_nop 1
	v_cvt_pk_bf16_f32 v73, v102, v103
	s_nop 1
	v_cvt_pk_bf16_f32 v74, v96, v97
	s_nop 1
	v_cvt_pk_bf16_f32 v75, v98, v99
	global_store_dwordx4 v[156:157], v[72:75], off
	v_pk_add_f32 v[94:95], v[94:95], v[134:135]
	v_pk_add_f32 v[90:91], v[90:91], v[130:131]
	s_nop 1
	v_cvt_pk_bf16_f32 v72, v92, v93
	v_pk_add_f32 v[88:89], v[88:89], v[128:129]
	v_pk_add_f32 v[84:85], v[84:85], v[132:133]
	v_pk_add_f32 v[76:77], v[76:77], v[132:133]
	s_nop 1
	v_cvt_pk_bf16_f32 v73, v94, v95
	s_nop 1
	v_cvt_pk_bf16_f32 v74, v88, v89
	s_nop 1
	v_cvt_pk_bf16_f32 v75, v90, v91
	global_store_dwordx4 v[154:155], v[72:75], off
	v_pk_add_f32 v[86:87], v[86:87], v[134:135]
	v_pk_add_f32 v[82:83], v[82:83], v[130:131]
	s_nop 1
	v_cvt_pk_bf16_f32 v72, v84, v85
	v_pk_add_f32 v[80:81], v[80:81], v[128:129]
	s_nop 1
	v_cvt_pk_bf16_f32 v73, v86, v87
	v_pk_add_f32 v[78:79], v[78:79], v[134:135]
	s_nop 1
	v_cvt_pk_bf16_f32 v74, v80, v81
	s_nop 1
	v_cvt_pk_bf16_f32 v75, v82, v83
	global_store_dwordx4 v[152:153], v[72:75], off
	v_pk_add_f32 v[60:61], v[60:61], v[132:133]
	v_pk_add_f32 v[62:63], v[62:63], v[134:135]
	s_nop 1
	v_cvt_pk_bf16_f32 v72, v76, v77
	v_add_u32_e32 v76, 0xa0, v182
	v_mad_i64_i32 v[76:77], s[0:1], v76, s62, v[166:167]
	s_nop 1
	v_cvt_pk_bf16_f32 v73, v78, v79
	v_lshl_add_u64 v[76:77], v[76:77], 0, v[174:175]
	s_nop 1
	v_cvt_pk_bf16_f32 v74, v178, v179
	s_nop 1
	v_cvt_pk_bf16_f32 v75, v176, v177
	global_store_dwordx4 v[76:77], v[72:75], off
	s_nop 1
	v_pk_add_f32 v[72:73], v[58:59], v[130:131]
	v_pk_add_f32 v[58:59], v[56:57], v[128:129]
	s_nop 1
	v_cvt_pk_bf16_f32 v56, v60, v61
	v_add_u32_e32 v60, 0xb0, v182
	v_mad_i64_i32 v[60:61], s[0:1], v60, s62, v[166:167]
	s_nop 1
	v_cvt_pk_bf16_f32 v57, v62, v63
	s_nop 1
	v_cvt_pk_bf16_f32 v58, v58, v59
	s_nop 1
	v_cvt_pk_bf16_f32 v59, v72, v73
	v_lshl_add_u64 v[72:73], v[60:61], 0, v[174:175]
	global_store_dwordx4 v[72:73], v[56:59], off
	flat_load_dwordx4 v[56:59], v[164:165] offset:512
	s_nop 0
	flat_load_dwordx4 v[60:63], v[164:165] offset:528
	s_waitcnt vmcnt(0) lgkmcnt(0)
	v_pk_add_f32 v[70:71], v[70:71], v[58:59]
	v_pk_add_f32 v[68:69], v[68:69], v[56:57]
	v_pk_add_f32 v[66:67], v[66:67], v[62:63]
	v_pk_add_f32 v[64:65], v[64:65], v[60:61]
	v_pk_add_f32 v[54:55], v[54:55], v[58:59]
	v_pk_add_f32 v[52:53], v[52:53], v[56:57]
	v_pk_add_f32 v[46:47], v[46:47], v[58:59]
	v_pk_add_f32 v[44:45], v[44:45], v[56:57]
	v_pk_add_f32 v[38:39], v[38:39], v[58:59]
	v_pk_add_f32 v[36:37], v[36:37], v[56:57]
	v_pk_add_f32 v[30:31], v[30:31], v[58:59]
	v_pk_add_f32 v[28:29], v[28:29], v[56:57]
	v_pk_add_f32 v[22:23], v[22:23], v[58:59]
	v_pk_add_f32 v[20:21], v[20:21], v[56:57]
	v_pk_add_f32 v[14:15], v[14:15], v[58:59]
	v_pk_add_f32 v[12:13], v[12:13], v[56:57]
	v_pk_add_f32 v[6:7], v[6:7], v[58:59]
	v_pk_add_f32 v[4:5], v[4:5], v[56:57]
	v_pk_add_f32 v[56:57], v[2:3], v[62:63]
	v_pk_add_f32 v[58:59], v[0:1], v[60:61]
	s_nop 1
	v_cvt_pk_bf16_f32 v0, v68, v69
	s_nop 1
	v_cvt_pk_bf16_f32 v1, v70, v71
	s_nop 1
	v_cvt_pk_bf16_f32 v2, v64, v65
	s_nop 1
	v_cvt_pk_bf16_f32 v3, v66, v67
	v_pk_add_f32 v[50:51], v[50:51], v[62:63]
	v_pk_add_f32 v[48:49], v[48:49], v[60:61]
	global_store_dwordx4 v[162:163], v[0:3], off offset:256
	v_pk_add_f32 v[42:43], v[42:43], v[62:63]
	v_pk_add_f32 v[40:41], v[40:41], v[60:61]
	s_nop 1
	v_cvt_pk_bf16_f32 v0, v52, v53
	s_nop 1
	v_cvt_pk_bf16_f32 v1, v54, v55
	s_nop 1
	v_cvt_pk_bf16_f32 v2, v48, v49
	s_nop 1
	v_cvt_pk_bf16_f32 v3, v50, v51
	global_store_dwordx4 v[160:161], v[0:3], off offset:256
	v_pk_add_f32 v[34:35], v[34:35], v[62:63]
	v_pk_add_f32 v[32:33], v[32:33], v[60:61]
	s_nop 1
	v_cvt_pk_bf16_f32 v0, v44, v45
	s_nop 1
	v_cvt_pk_bf16_f32 v1, v46, v47
	s_nop 1
	v_cvt_pk_bf16_f32 v2, v40, v41
	s_nop 1
	v_cvt_pk_bf16_f32 v3, v42, v43
	global_store_dwordx4 v[158:159], v[0:3], off offset:256
	v_pk_add_f32 v[26:27], v[26:27], v[62:63]
	v_pk_add_f32 v[24:25], v[24:25], v[60:61]
	s_nop 1
	v_cvt_pk_bf16_f32 v0, v36, v37
	s_nop 1
	v_cvt_pk_bf16_f32 v1, v38, v39
	s_nop 1
	v_cvt_pk_bf16_f32 v2, v32, v33
	s_nop 1
	v_cvt_pk_bf16_f32 v3, v34, v35
	global_store_dwordx4 v[156:157], v[0:3], off offset:256
	v_pk_add_f32 v[18:19], v[18:19], v[62:63]
	v_pk_add_f32 v[16:17], v[16:17], v[60:61]
	s_nop 1
	v_cvt_pk_bf16_f32 v0, v28, v29
	s_nop 1
	v_cvt_pk_bf16_f32 v1, v30, v31
	s_nop 1
	v_cvt_pk_bf16_f32 v2, v24, v25
	s_nop 1
	v_cvt_pk_bf16_f32 v3, v26, v27
	global_store_dwordx4 v[154:155], v[0:3], off offset:256
	v_pk_add_f32 v[10:11], v[10:11], v[62:63]
	v_pk_add_f32 v[8:9], v[8:9], v[60:61]
	s_nop 1
	v_cvt_pk_bf16_f32 v0, v20, v21
	s_nop 1
	v_cvt_pk_bf16_f32 v1, v22, v23
	s_nop 1
	v_cvt_pk_bf16_f32 v2, v16, v17
	s_nop 1
	v_cvt_pk_bf16_f32 v3, v18, v19
	global_store_dwordx4 v[152:153], v[0:3], off offset:256
	s_nop 1
	s_nop 1
	v_cvt_pk_bf16_f32 v0, v12, v13
	s_nop 1
	v_cvt_pk_bf16_f32 v1, v14, v15
	s_nop 1
	v_cvt_pk_bf16_f32 v2, v8, v9
	s_nop 1
	v_cvt_pk_bf16_f32 v3, v10, v11
	global_store_dwordx4 v[76:77], v[0:3], off offset:256
	s_nop 1
	s_nop 1
	v_cvt_pk_bf16_f32 v0, v4, v5
	s_nop 1
	v_cvt_pk_bf16_f32 v1, v6, v7
	s_nop 1
	v_cvt_pk_bf16_f32 v2, v58, v59
	s_nop 1
	v_cvt_pk_bf16_f32 v3, v56, v57
	global_store_dwordx4 v[72:73], v[0:3], off offset:256
	s_cbranch_vccz .LBB0_1231
	s_waitcnt vmcnt(0)
	s_cmpk_gt_u32 s23, 0xff
	s_cbranch_scc1 .LBB0_1238
	s_barrier

.LBB0_1239:
	s_waitcnt vmcnt(0)
	s_setprio 0
	s_barrier
	s_mov_b64 s[0:1], exec
	v_readlane_b32 s4, v255, 4
	v_readlane_b32 s5, v255, 5
	s_and_b64 s[4:5], s[0:1], s[4:5]
	s_xor_b64 s[6:7], s[4:5], s[0:1]
	s_mov_b64 exec, s[4:5]
	s_cbranch_execz .LBB0_1292
	s_add_i32 s0, 0, 0x25800
	v_mov_b32_e32 v0, s0
	s_waitcnt vmcnt(0) expcnt(0) lgkmcnt(0)
	ds_read_b32 v2, v0
	s_add_i32 s0, 0, 0x25804
	v_mov_b32_e32 v0, s0
	ds_read_b32 v0, v0
	s_waitcnt lgkmcnt(1)
	v_cmp_ne_u32_e32 vcc, 0, v2
	s_cbranch_vccnz .LBB0_1255
	s_add_u32 s8, s26, 0xc0200
	s_addc_u32 s9, s27, 0
	s_add_u32 s4, s26, 0xc0400
	s_addc_u32 s5, s27, 0
	s_add_u32 s10, s26, 0xc0500
	s_addc_u32 s11, s27, 0
	s_add_u32 s12, s26, 0xc0600
	s_addc_u32 s13, s27, 0
	s_add_u32 s14, s26, 0xc0700
	s_addc_u32 s15, s27, 0
	s_add_u32 s16, s26, 0xc0800
	s_addc_u32 s17, s27, 0
	s_add_u32 s18, s26, 0xc0900
	s_addc_u32 s19, s27, 0
	s_add_u32 s20, s26, 0xc0a00
	s_addc_u32 s21, s27, 0
	s_add_u32 s36, s26, 0xc0b00
	s_addc_u32 s37, s27, 0
	s_add_u32 s46, s26, 0xc0c00
	s_addc_u32 s47, s27, 0
	s_add_u32 s54, s26, 0xc0d00
	s_addc_u32 s55, s27, 0
	s_add_u32 s58, s26, 0xc0e00
	s_addc_u32 s59, s27, 0
	s_add_u32 s60, s26, 0xc0f00
	s_addc_u32 s61, s27, 0
	s_add_u32 s62, s26, 0xc1000
	s_addc_u32 s63, s27, 0
	s_add_u32 s64, s26, 0xc1100
	s_addc_u32 s65, s27, 0
	s_add_u32 s66, s26, 0xc1200
	v_readlane_b32 s0, v255, 0
	s_addc_u32 s67, s27, 0
	s_mul_i32 s23, s31, s0
	s_add_u32 s68, s26, 0xc1300
	s_mul_i32 s23, s23, s30
	s_addc_u32 s69, s27, 0
	s_mov_b32 s24, 1
	v_mov_b32_e32 v16, 0
	s_branch .LBB0_1243

.LBB0_1319:
	s_waitcnt vmcnt(0)
	s_setprio 0
	s_barrier
	s_mov_b64 s[6:7], exec
	v_readlane_b32 s0, v255, 4
	v_readlane_b32 s1, v255, 5
	s_and_b64 s[0:1], s[6:7], s[0:1]
	s_mov_b64 exec, s[0:1]
	s_cbranch_execz .LBB0_1371
	s_add_i32 s0, 0, 0x25800
	v_mov_b32_e32 v0, s0
	s_waitcnt vmcnt(0) expcnt(0) lgkmcnt(0)
	ds_read_b32 v2, v0
	s_add_i32 s0, 0, 0x25804
	v_mov_b32_e32 v0, s0
	ds_read_b32 v0, v0
	s_waitcnt lgkmcnt(1)
	v_cmp_ne_u32_e32 vcc, 0, v2
	s_cbranch_vccnz .LBB0_1335
	s_add_u32 s8, s26, 0xc0200
	s_addc_u32 s9, s27, 0
	s_add_u32 s4, s26, 0xc0400
	s_addc_u32 s5, s27, 0
	s_add_u32 s10, s26, 0xc0500
	s_addc_u32 s11, s27, 0
	s_add_u32 s12, s26, 0xc0600
	s_addc_u32 s13, s27, 0
	s_add_u32 s14, s26, 0xc0700
	s_addc_u32 s15, s27, 0
	s_add_u32 s16, s26, 0xc0800
	s_addc_u32 s17, s27, 0
	s_add_u32 s18, s26, 0xc0900
	s_addc_u32 s19, s27, 0
	s_add_u32 s20, s26, 0xc0a00
	s_addc_u32 s21, s27, 0
	s_add_u32 s36, s26, 0xc0b00
	s_addc_u32 s37, s27, 0
	s_add_u32 s58, s26, 0xc0c00
	s_addc_u32 s59, s27, 0
	s_add_u32 s60, s26, 0xc0d00
	s_addc_u32 s61, s27, 0
	s_add_u32 s62, s26, 0xc0e00
	s_addc_u32 s63, s27, 0
	s_add_u32 s64, s26, 0xc0f00
	s_addc_u32 s65, s27, 0
	s_add_u32 s66, s26, 0xc1000
	s_addc_u32 s67, s27, 0
	s_add_u32 s68, s26, 0xc1100
	s_addc_u32 s69, s27, 0
	s_add_u32 s70, s26, 0xc1200
	v_readlane_b32 s0, v255, 0
	s_addc_u32 s71, s27, 0
	s_mul_i32 s23, s31, s0
	s_add_u32 s72, s26, 0xc1300
	s_mul_i32 s23, s23, s30
	s_addc_u32 s73, s27, 0
	s_mov_b32 s24, 1
	v_mov_b32_e32 v16, 0
	s_branch .LBB0_1323

.LBB0_1413:
	s_waitcnt vmcnt(0)
	s_setprio 0
	s_barrier
	s_mov_b64 s[0:1], exec
	v_readlane_b32 s4, v255, 4
	v_readlane_b32 s5, v255, 5
	s_and_b64 s[4:5], s[0:1], s[4:5]
	s_xor_b64 s[6:7], s[4:5], s[0:1]
	s_mov_b64 exec, s[4:5]
	s_cbranch_execz .LBB0_1466
	s_add_i32 s0, 0, 0x25800
	v_mov_b32_e32 v0, s0
	s_waitcnt vmcnt(0) expcnt(0) lgkmcnt(0)
	ds_read_b32 v2, v0
	s_add_i32 s0, 0, 0x25804
	v_mov_b32_e32 v0, s0
	ds_read_b32 v0, v0
	s_waitcnt lgkmcnt(1)
	v_cmp_ne_u32_e32 vcc, 0, v2
	s_cbranch_vccnz .LBB0_1429
	s_add_u32 s8, s26, 0xc0200
	s_addc_u32 s9, s27, 0
	s_add_u32 s4, s26, 0xc0400
	s_addc_u32 s5, s27, 0
	s_add_u32 s10, s26, 0xc0500
	s_addc_u32 s11, s27, 0
	s_add_u32 s12, s26, 0xc0600
	s_addc_u32 s13, s27, 0
	s_add_u32 s14, s26, 0xc0700
	s_addc_u32 s15, s27, 0
	s_add_u32 s16, s26, 0xc0800
	s_addc_u32 s17, s27, 0
	s_add_u32 s18, s26, 0xc0900
	s_addc_u32 s19, s27, 0
	s_add_u32 s20, s26, 0xc0a00
	s_addc_u32 s21, s27, 0
	s_add_u32 s36, s26, 0xc0b00
	s_addc_u32 s37, s27, 0
	s_add_u32 s46, s26, 0xc0c00
	s_addc_u32 s47, s27, 0
	s_add_u32 s50, s26, 0xc0d00
	s_addc_u32 s51, s27, 0
	s_add_u32 s54, s26, 0xc0e00
	s_addc_u32 s55, s27, 0
	s_add_u32 s58, s26, 0xc0f00
	s_addc_u32 s59, s27, 0
	s_add_u32 s60, s26, 0xc1000
	s_addc_u32 s61, s27, 0
	s_add_u32 s62, s26, 0xc1100
	s_addc_u32 s63, s27, 0
	s_add_u32 s64, s26, 0xc1200
	v_readlane_b32 s0, v255, 0
	s_addc_u32 s65, s27, 0
	s_mul_i32 s23, s31, s0
	s_add_u32 s66, s26, 0xc1300
	s_mul_i32 s23, s23, s30
	s_addc_u32 s67, s27, 0
	s_mov_b32 s24, 1
	v_mov_b32_e32 v16, 0
	s_branch .LBB0_1417

.LBB0_1469:
	s_waitcnt vmcnt(0)
	s_setprio 0
	s_barrier
	s_mov_b64 s[6:7], exec
	v_readlane_b32 s0, v255, 4
	v_readlane_b32 s1, v255, 5
	s_and_b64 s[0:1], s[6:7], s[0:1]
	s_mov_b64 exec, s[0:1]
	s_cbranch_execz .LBB0_1521
	s_add_i32 s0, 0, 0x25800
	v_mov_b32_e32 v0, s0
	s_waitcnt vmcnt(0) expcnt(0) lgkmcnt(0)
	ds_read_b32 v2, v0
	s_add_i32 s0, 0, 0x25804
	v_mov_b32_e32 v0, s0
	ds_read_b32 v0, v0
	s_waitcnt lgkmcnt(1)
	v_cmp_ne_u32_e32 vcc, 0, v2
	s_cbranch_vccnz .LBB0_1485
	s_add_u32 s8, s26, 0xc0200
	s_addc_u32 s9, s27, 0
	s_add_u32 s4, s26, 0xc0400
	s_addc_u32 s5, s27, 0
	s_add_u32 s10, s26, 0xc0500
	s_addc_u32 s11, s27, 0
	s_add_u32 s12, s26, 0xc0600
	s_addc_u32 s13, s27, 0
	s_add_u32 s14, s26, 0xc0700
	s_addc_u32 s15, s27, 0
	s_add_u32 s16, s26, 0xc0800
	s_addc_u32 s17, s27, 0
	s_add_u32 s18, s26, 0xc0900
	s_addc_u32 s19, s27, 0
	s_add_u32 s20, s26, 0xc0a00
	s_addc_u32 s21, s27, 0
	s_add_u32 s36, s26, 0xc0b00
	s_addc_u32 s37, s27, 0
	s_add_u32 s46, s26, 0xc0c00
	s_addc_u32 s47, s27, 0
	s_add_u32 s50, s26, 0xc0d00
	s_addc_u32 s51, s27, 0
	s_add_u32 s54, s26, 0xc0e00
	s_addc_u32 s55, s27, 0
	s_add_u32 s58, s26, 0xc0f00
	s_addc_u32 s59, s27, 0
	s_add_u32 s60, s26, 0xc1000
	s_addc_u32 s61, s27, 0
	s_add_u32 s62, s26, 0xc1100
	s_addc_u32 s63, s27, 0
	s_add_u32 s64, s26, 0xc1200
	v_readlane_b32 s0, v255, 0
	s_addc_u32 s65, s27, 0
	s_mul_i32 s23, s31, s0
	s_add_u32 s66, s26, 0xc1300
	s_mul_i32 s23, s23, s30
	s_addc_u32 s67, s27, 0
	s_mov_b32 s24, 1
	v_mov_b32_e32 v16, 0
	s_branch .LBB0_1473

.Lprio_skip14:
	v_readlane_b32 s0, v255, 7
	v_mov_b64_e32 v[0:1], s[58:59]
	flat_load_dwordx2 v[0:1], v[0:1] offset:344 sc0 sc1
	s_waitcnt vmcnt(0)
	v_mov_b32_e32 v8, v254
	v_readlane_b32 s1, v255, 8
	s_and_b64 vcc, exec, s[0:1]
	s_waitcnt lgkmcnt(0)
	v_readfirstlane_b32 s11, v1
	v_readfirstlane_b32 s23, v8
	v_readfirstlane_b32 s10, v0
	s_cbranch_vccz .LBB0_1545
	v_lshlrev_b32_e32 v0, 4, v8
	v_add_u32_e32 v1, 0x2000, v0
	v_ashrrev_i32_e32 v2, 31, v1
	v_lshrrev_b32_e32 v2, 22, v2
	v_add_u32_e32 v2, v1, v2
	v_ashrrev_i32_e32 v9, 10, v2
	v_mul_i32_i24_e32 v2, 0x400, v9
	v_sub_u32_e32 v1, v1, v2
	v_lshrrev_b32_e32 v2, 4, v1
	v_bitop3_b32 v1, v2, v1, 32 bitop3:0x6c
	v_ashrrev_i32_e32 v2, 31, v1
	s_lshr_b32 s4, s3, 29
	v_lshrrev_b32_e32 v2, 26, v2
	s_add_i32 s4, s2, s4
	v_add_u32_e32 v2, v1, v2
	s_and_b32 s5, s4, -8
	s_ashr_i32 s1, s23, 6
	v_ashrrev_i32_e32 v10, 6, v2
	v_and_b32_e32 v2, 0xc0, v2
	s_sub_i32 s5, s2, s5
	s_ashr_i32 s0, s23, 8
	s_lshl_b32 s24, s1, 10
	v_sub_u32_e32 v1, v1, v2
	v_mov_b32_e32 v2, 1
	s_lshl_b32 s7, s5, 5
	s_ashr_i32 s4, s4, 3
	v_ashrrev_i16_sdwa v1, v2, sext(v1) dst_sel:DWORD dst_unused:UNUSED_PAD src0_sel:DWORD src1_sel:BYTE_0
	s_mul_i32 s6, s5, 33
	s_cmp_lt_i32 s5, 0
	v_bfe_i32 v12, v1, 0, 16
	v_bfe_i32 v1, v8, 27, 1
	s_cselect_b32 s5, s6, s7
	v_lshrrev_b32_e32 v1, 22, v1
	s_add_i32 s4, s5, s4
	v_add_u32_e32 v1, v0, v1
	s_ashr_i32 s5, s4, 31
	v_and_b32_e32 v1, 0xfffffc00, v1
	s_lshr_b32 s5, s5, 26
	v_sub_u32_e32 v0, v0, v1
	s_add_i32 s5, s4, s5
	v_lshrrev_b32_e32 v1, 4, v0
	s_ashr_i32 s6, s5, 6
	s_andn2_b32 s5, s5, 63
	v_bitop3_b32 v1, v1, v0, 32 bitop3:0x6c
	v_ashrrev_i32_e32 v0, 31, v0
	s_sub_i32 s5, s4, s5
	v_lshrrev_b32_e32 v0, 26, v0
	s_bfe_i32 s4, s5, 0x80000
	v_add_u32_e32 v0, v1, v0
	s_bfe_u32 s4, s4, 0x3000c
	v_lshlrev_b32_e32 v3, 3, v9
	v_ashrrev_i32_e32 v13, 6, v0
	v_ashrrev_i32_e32 v0, 31, v8
	s_add_i32 s7, s5, s4
	v_and_b32_e32 v3, 0xffff0, v3
	v_lshlrev_b32_e32 v4, 5, v9
	v_lshrrev_b32_e32 v0, 26, v0
	s_bfe_i32 s4, s7, 0x80000
	s_and_b32 s7, s7, 0xf8
	v_add_u32_e32 v3, v10, v3
	v_and_b32_e32 v11, 32, v4
	v_add_u32_e32 v0, v8, v0
	s_sub_i32 s5, s5, s7
	v_lshl_or_b32 v3, v3, 11, v11
	v_ashrrev_i32_e32 v14, 6, v0
	s_lshl_b32 s6, s6, 3
	s_sext_i32_i16 s4, s4
	s_sext_i32_i8 s5, s5
	v_add_lshl_u32 v138, v3, v12, 1
	v_lshlrev_b32_e32 v3, 5, v14
	s_lshr_b32 s4, s4, 3
	s_add_i32 s66, s6, s5
	v_lshlrev_b32_e32 v0, 3, v14
	v_and_b32_e32 v15, 32, v3
	v_mul_i32_i24_e32 v3, 64, v13
	s_ashr_i32 s67, s66, 31
	s_bfe_i64 s[8:9], s[4:5], 0x100000
	v_and_b32_e32 v0, 0xffff0, v0
	v_sub_u32_e32 v1, v1, v3
	s_lshl_b64 s[6:7], s[66:67], 20
	s_lshl_b64 s[8:9], s[8:9], 20
	v_readlane_b32 s12, v255, 26
	v_add_u32_e32 v0, v13, v0
	v_ashrrev_i16_sdwa v1, v2, sext(v1) dst_sel:DWORD dst_unused:UNUSED_PAD src0_sel:DWORD src1_sel:BYTE_0
	v_readlane_b32 s13, v255, 27
	s_add_u32 s68, s12, s8
	v_lshl_or_b32 v0, v0, 11, v15
	v_bfe_i32 v16, v1, 0, 16
	s_addc_u32 s69, s13, s9
	s_add_i32 s25, s24, 0
	v_add_lshl_u32 v140, v0, v16, 1
	s_add_i32 m0, s25, 0x10000
	s_load_dwordx2 s[12:13], s[88:89], 0x168
	global_load_lds_dwordx4 v140, s[68:69]
	s_add_i32 m0, s25, 0x12000
	s_add_u32 s8, s38, s6
	global_load_lds_dwordx4 v138, s[68:69]
	s_addc_u32 s9, s39, s7
	s_mov_b32 m0, s25
	s_add_i32 s28, s25, 0x2000
	global_load_lds_dwordx4 v140, s[8:9]
	s_mov_b32 m0, s28
	s_add_u32 s6, s68, 0x80000
	global_load_lds_dwordx4 v138, s[8:9]
	s_addc_u32 s7, s69, 0
	s_add_i32 m0, s25, 0x14000
	v_mov_b32_e32 v141, 0
	global_load_lds_dwordx4 v140, s[6:7]
	s_add_i32 m0, s25, 0x16000
	v_mov_b32_e32 v139, v141
	global_load_lds_dwordx4 v138, s[6:7]
	s_add_u32 s6, s8, 0x80000
	s_addc_u32 s7, s9, 0
	s_add_i32 s29, s25, 0x4000
	s_mov_b32 m0, s29
	s_add_i32 s33, s25, 0x6000
	global_load_lds_dwordx4 v140, s[6:7]
	s_mov_b32 m0, s33
	s_mov_b32 s36, 0
	global_load_lds_dwordx4 v138, s[6:7]
	v_lshl_add_u64 v[6:7], s[68:69], 0, v[140:141]
	v_lshl_add_u64 v[4:5], s[68:69], 0, v[138:139]
	v_lshl_add_u64 v[2:3], s[8:9], 0, v[140:141]
	s_cmp_lg_u32 s0, 1
	v_lshl_add_u64 v[0:1], s[8:9], 0, v[138:139]
	s_cbranch_scc1 .LBB0_1524
	s_barrier

.LBB0_1533:
	ds_read_b128 v[128:131], v165
	ds_read_b128 v[132:135], v165 offset:1024
	ds_read_b128 v[150:153], v165 offset:2048
	ds_read_b128 v[154:157], v165 offset:3072
	s_add_u32 s68, s8, 0x100
	s_addc_u32 s69, s9, 0
	s_cmp_eq_u32 s78, 28
	s_cselect_b32 s5, s0, s69
	s_cselect_b32 s4, s1, s68
	s_cselect_b32 s71, s59, s77
	s_cselect_b32 s70, s61, s76
	v_lshl_add_u64 v[136:137], s[8:9], 0, v[142:143]
	s_add_i32 m0, s25, 0xc000
	ds_read_b128 v[158:161], v166
	ds_read_b128 v[168:171], v166 offset:1024
	ds_read_b128 v[172:175], v166 offset:2048
	ds_read_b128 v[176:179], v166 offset:3072
	ds_read_b128 v[180:183], v166 offset:4096
	ds_read_b128 v[184:187], v166 offset:5120
	ds_read_b128 v[188:191], v166 offset:6144
	ds_read_b128 v[192:195], v166 offset:7168
	global_load_lds_dwordx4 v[136:137], off
	v_lshl_add_u64 v[136:137], s[8:9], 0, v[144:145]
	s_add_i32 m0, s25, 0xe000
	s_nop 0
	global_load_lds_dwordx4 v[136:137], off
	s_waitcnt lgkmcnt(8)
	s_barrier
	s_waitcnt lgkmcnt(0)
	s_waitcnt lgkmcnt(0)
	v_mfma_f32_16x16x32_bf16 v[124:127], v[128:131], v[158:161], v[124:127]
	v_mfma_f32_16x16x32_bf16 v[92:95], v[150:153], v[158:161], v[92:95]
	v_mfma_f32_16x16x32_bf16 v[120:123], v[128:131], v[172:175], v[120:123]
	v_mfma_f32_16x16x32_bf16 v[88:91], v[150:153], v[172:175], v[88:91]
	v_mfma_f32_16x16x32_bf16 v[116:119], v[128:131], v[180:183], v[116:119]
	v_mfma_f32_16x16x32_bf16 v[84:87], v[150:153], v[180:183], v[84:87]
	v_mfma_f32_16x16x32_bf16 v[112:115], v[128:131], v[188:191], v[112:115]
	v_mfma_f32_16x16x32_bf16 v[80:83], v[150:153], v[188:191], v[80:83]
	v_mfma_f32_16x16x32_bf16 v[124:127], v[132:135], v[168:171], v[124:127]
	v_mfma_f32_16x16x32_bf16 v[92:95], v[154:157], v[168:171], v[92:95]
	v_mfma_f32_16x16x32_bf16 v[120:123], v[132:135], v[176:179], v[120:123]
	v_mfma_f32_16x16x32_bf16 v[88:91], v[154:157], v[176:179], v[88:91]
	v_mfma_f32_16x16x32_bf16 v[116:119], v[132:135], v[184:187], v[116:119]
	v_mfma_f32_16x16x32_bf16 v[84:87], v[154:157], v[184:187], v[84:87]
	v_mfma_f32_16x16x32_bf16 v[112:115], v[132:135], v[192:195], v[112:115]
	v_mfma_f32_16x16x32_bf16 v[80:83], v[154:157], v[192:195], v[80:83]
	s_barrier
	s_add_i32 s8, s41, s24
	v_lshl_add_u64 v[136:137], s[70:71], 0, v[140:141]
	s_mov_b32 m0, s8
	ds_read_b128 v[196:199], v167
	ds_read_b128 v[200:203], v167 offset:1024
	ds_read_b128 v[204:207], v167 offset:2048
	ds_read_b128 v[208:211], v167 offset:3072
	global_load_lds_dwordx4 v[136:137], off
	v_lshl_add_u64 v[212:213], s[70:71], 0, v[138:139]
	s_add_i32 m0, s8, 0x2000
	s_nop 0
	global_load_lds_dwordx4 v[212:213], off
	s_barrier
	s_waitcnt lgkmcnt(0)
	s_waitcnt lgkmcnt(0)
	v_mfma_f32_16x16x32_bf16 v[60:63], v[196:199], v[158:161], v[60:63]
	v_mfma_f32_16x16x32_bf16 v[28:31], v[204:207], v[158:161], v[28:31]
	v_mfma_f32_16x16x32_bf16 v[56:59], v[196:199], v[172:175], v[56:59]
	v_mfma_f32_16x16x32_bf16 v[24:27], v[204:207], v[172:175], v[24:27]
	v_mfma_f32_16x16x32_bf16 v[52:55], v[196:199], v[180:183], v[52:55]
	v_mfma_f32_16x16x32_bf16 v[20:23], v[204:207], v[180:183], v[20:23]
	v_mfma_f32_16x16x32_bf16 v[48:51], v[196:199], v[188:191], v[48:51]
	v_mfma_f32_16x16x32_bf16 v[16:19], v[204:207], v[188:191], v[16:19]
	v_mfma_f32_16x16x32_bf16 v[60:63], v[200:203], v[168:171], v[60:63]
	v_mfma_f32_16x16x32_bf16 v[28:31], v[208:211], v[168:171], v[28:31]
	v_mfma_f32_16x16x32_bf16 v[56:59], v[200:203], v[176:179], v[56:59]
	v_mfma_f32_16x16x32_bf16 v[24:27], v[208:211], v[176:179], v[24:27]
	v_mfma_f32_16x16x32_bf16 v[52:55], v[200:203], v[184:187], v[52:55]
	v_mfma_f32_16x16x32_bf16 v[20:23], v[208:211], v[184:187], v[20:23]
	v_mfma_f32_16x16x32_bf16 v[48:51], v[200:203], v[192:195], v[48:51]
	v_mfma_f32_16x16x32_bf16 v[16:19], v[208:211], v[192:195], v[16:19]
	s_mov_b32 m0, s25
	v_lshl_add_u64 v[214:215], s[4:5], 0, v[140:141]
	s_barrier
	ds_read_b128 v[158:161], v166 offset:16384
	ds_read_b128 v[168:171], v166 offset:17408
	ds_read_b128 v[172:175], v166 offset:18432
	ds_read_b128 v[176:179], v166 offset:19456
	ds_read_b128 v[180:183], v166 offset:20480
	ds_read_b128 v[184:187], v166 offset:21504
	ds_read_b128 v[188:191], v166 offset:22528
	ds_read_b128 v[192:195], v166 offset:23552
	global_load_lds_dwordx4 v[214:215], off
	v_lshl_add_u64 v[216:217], s[4:5], 0, v[138:139]
	s_mov_b32 m0, s28
	s_nop 0
	global_load_lds_dwordx4 v[216:217], off
	s_barrier
	s_waitcnt lgkmcnt(0)
	s_waitcnt lgkmcnt(0)
	v_mfma_f32_16x16x32_bf16 v[108:111], v[128:131], v[158:161], v[108:111]
	v_mfma_f32_16x16x32_bf16 v[76:79], v[150:153], v[158:161], v[76:79]
	v_mfma_f32_16x16x32_bf16 v[104:107], v[128:131], v[172:175], v[104:107]
	v_mfma_f32_16x16x32_bf16 v[72:75], v[150:153], v[172:175], v[72:75]
	v_mfma_f32_16x16x32_bf16 v[100:103], v[128:131], v[180:183], v[100:103]
	v_mfma_f32_16x16x32_bf16 v[68:71], v[150:153], v[180:183], v[68:71]
	v_mfma_f32_16x16x32_bf16 v[96:99], v[128:131], v[188:191], v[96:99]
	v_mfma_f32_16x16x32_bf16 v[64:67], v[150:153], v[188:191], v[64:67]
	v_mfma_f32_16x16x32_bf16 v[108:111], v[132:135], v[168:171], v[108:111]
	v_mfma_f32_16x16x32_bf16 v[76:79], v[154:157], v[168:171], v[76:79]
	v_mfma_f32_16x16x32_bf16 v[104:107], v[132:135], v[176:179], v[104:107]
	v_mfma_f32_16x16x32_bf16 v[72:75], v[154:157], v[176:179], v[72:75]
	v_mfma_f32_16x16x32_bf16 v[100:103], v[132:135], v[184:187], v[100:103]
	v_mfma_f32_16x16x32_bf16 v[68:71], v[154:157], v[184:187], v[68:71]
	v_mfma_f32_16x16x32_bf16 v[96:99], v[132:135], v[192:195], v[96:99]
	v_mfma_f32_16x16x32_bf16 v[64:67], v[154:157], v[192:195], v[64:67]
	s_barrier
	s_add_u32 s8, s70, 0x80000
	s_addc_u32 s9, s71, 0
	s_add_i32 s42, s53, s24
	v_lshl_add_u64 v[128:129], s[8:9], 0, v[140:141]
	s_mov_b32 m0, s42
	s_nop 0
	global_load_lds_dwordx4 v[128:129], off
	v_lshl_add_u64 v[128:129], s[8:9], 0, v[138:139]
	s_add_i32 m0, s42, 0x2000
	s_nop 0
	global_load_lds_dwordx4 v[128:129], off
	s_waitcnt vmcnt(6)
	s_barrier
	v_mfma_f32_16x16x32_bf16 v[44:47], v[196:199], v[158:161], v[44:47]
	v_mfma_f32_16x16x32_bf16 v[12:15], v[204:207], v[158:161], v[12:15]
	v_mfma_f32_16x16x32_bf16 v[40:43], v[196:199], v[172:175], v[40:43]
	v_mfma_f32_16x16x32_bf16 v[8:11], v[204:207], v[172:175], v[8:11]
	v_mfma_f32_16x16x32_bf16 v[36:39], v[196:199], v[180:183], v[36:39]
	v_mfma_f32_16x16x32_bf16 v[4:7], v[204:207], v[180:183], v[4:7]
	v_mfma_f32_16x16x32_bf16 v[32:35], v[196:199], v[188:191], v[32:35]
	v_mfma_f32_16x16x32_bf16 v[0:3], v[204:207], v[188:191], v[0:3]
	v_mfma_f32_16x16x32_bf16 v[44:47], v[200:203], v[168:171], v[44:47]
	v_mfma_f32_16x16x32_bf16 v[12:15], v[208:211], v[168:171], v[12:15]
	v_mfma_f32_16x16x32_bf16 v[40:43], v[200:203], v[176:179], v[40:43]
	v_mfma_f32_16x16x32_bf16 v[8:11], v[208:211], v[176:179], v[8:11]
	v_mfma_f32_16x16x32_bf16 v[36:39], v[200:203], v[184:187], v[36:39]
	v_mfma_f32_16x16x32_bf16 v[4:7], v[208:211], v[184:187], v[4:7]
	v_mfma_f32_16x16x32_bf16 v[32:35], v[200:203], v[192:195], v[32:35]
	v_mfma_f32_16x16x32_bf16 v[0:3], v[208:211], v[192:195], v[0:3]
	s_add_i32 s8, 0, 0x18000
	v_add_u32_e32 v154, s8, v163
	s_barrier
	ds_read_b128 v[128:131], v154
	ds_read_b128 v[132:135], v154 offset:1024
	ds_read_b128 v[150:153], v154 offset:2048
	ds_read_b128 v[154:157], v154 offset:3072
	s_add_u32 s4, s4, 0x80000
	s_addc_u32 s5, s5, 0
	s_mov_b32 m0, s29
	v_lshl_add_u64 v[196:197], s[4:5], 0, v[140:141]
	ds_read_b128 v[158:161], v166 offset:32768
	ds_read_b128 v[168:171], v166 offset:33792
	ds_read_b128 v[172:175], v166 offset:34816
	ds_read_b128 v[176:179], v166 offset:35840
	ds_read_b128 v[180:183], v166 offset:36864
	ds_read_b128 v[184:187], v166 offset:37888
	ds_read_b128 v[188:191], v166 offset:38912
	ds_read_b128 v[192:195], v166 offset:39936
	global_load_lds_dwordx4 v[196:197], off
	v_lshl_add_u64 v[196:197], s[4:5], 0, v[138:139]
	s_mov_b32 m0, s33
	s_nop 0
	global_load_lds_dwordx4 v[196:197], off
	s_waitcnt lgkmcnt(8)
	s_barrier
	s_waitcnt lgkmcnt(0)
	s_waitcnt lgkmcnt(0)
	v_mfma_f32_16x16x32_bf16 v[124:127], v[128:131], v[158:161], v[124:127]
	v_mfma_f32_16x16x32_bf16 v[92:95], v[150:153], v[158:161], v[92:95]
	v_mfma_f32_16x16x32_bf16 v[120:123], v[128:131], v[172:175], v[120:123]
	v_mfma_f32_16x16x32_bf16 v[88:91], v[150:153], v[172:175], v[88:91]
	v_mfma_f32_16x16x32_bf16 v[116:119], v[128:131], v[180:183], v[116:119]
	v_mfma_f32_16x16x32_bf16 v[84:87], v[150:153], v[180:183], v[84:87]
	v_mfma_f32_16x16x32_bf16 v[112:115], v[128:131], v[188:191], v[112:115]
	v_mfma_f32_16x16x32_bf16 v[80:83], v[150:153], v[188:191], v[80:83]
	v_mfma_f32_16x16x32_bf16 v[124:127], v[132:135], v[168:171], v[124:127]
	v_mfma_f32_16x16x32_bf16 v[92:95], v[154:157], v[168:171], v[92:95]
	v_mfma_f32_16x16x32_bf16 v[120:123], v[132:135], v[176:179], v[120:123]
	v_mfma_f32_16x16x32_bf16 v[88:91], v[154:157], v[176:179], v[88:91]
	v_mfma_f32_16x16x32_bf16 v[116:119], v[132:135], v[184:187], v[116:119]
	v_mfma_f32_16x16x32_bf16 v[84:87], v[154:157], v[184:187], v[84:87]
	v_mfma_f32_16x16x32_bf16 v[112:115], v[132:135], v[192:195], v[112:115]
	v_mfma_f32_16x16x32_bf16 v[80:83], v[154:157], v[192:195], v[80:83]
	s_barrier
	s_add_i32 s9, 0, 0x1c000
	s_add_i32 s4, s8, s24
	v_add_u32_e32 v208, s9, v163
	v_lshl_add_u64 v[136:137], v[136:137], 0, s[16:17]
	s_mov_b32 m0, s4
	ds_read_b128 v[196:199], v208
	ds_read_b128 v[200:203], v208 offset:1024
	ds_read_b128 v[204:207], v208 offset:2048
	ds_read_b128 v[208:211], v208 offset:3072
	global_load_lds_dwordx4 v[136:137], off
	v_lshl_add_u64 v[136:137], v[212:213], 0, s[16:17]
	s_add_i32 m0, s4, 0x2000
	s_nop 0
	global_load_lds_dwordx4 v[136:137], off
	s_barrier
	s_waitcnt lgkmcnt(0)
	s_waitcnt lgkmcnt(0)
	v_mfma_f32_16x16x32_bf16 v[60:63], v[196:199], v[158:161], v[60:63]
	v_mfma_f32_16x16x32_bf16 v[28:31], v[204:207], v[158:161], v[28:31]
	v_mfma_f32_16x16x32_bf16 v[56:59], v[196:199], v[172:175], v[56:59]
	v_mfma_f32_16x16x32_bf16 v[24:27], v[204:207], v[172:175], v[24:27]
	v_mfma_f32_16x16x32_bf16 v[52:55], v[196:199], v[180:183], v[52:55]
	v_mfma_f32_16x16x32_bf16 v[20:23], v[204:207], v[180:183], v[20:23]
	v_mfma_f32_16x16x32_bf16 v[48:51], v[196:199], v[188:191], v[48:51]
	v_mfma_f32_16x16x32_bf16 v[16:19], v[204:207], v[188:191], v[16:19]
	v_mfma_f32_16x16x32_bf16 v[60:63], v[200:203], v[168:171], v[60:63]
	v_mfma_f32_16x16x32_bf16 v[28:31], v[208:211], v[168:171], v[28:31]
	v_mfma_f32_16x16x32_bf16 v[56:59], v[200:203], v[176:179], v[56:59]
	v_mfma_f32_16x16x32_bf16 v[24:27], v[208:211], v[176:179], v[24:27]
	v_mfma_f32_16x16x32_bf16 v[52:55], v[200:203], v[184:187], v[52:55]
	v_mfma_f32_16x16x32_bf16 v[20:23], v[208:211], v[184:187], v[20:23]
	v_mfma_f32_16x16x32_bf16 v[48:51], v[200:203], v[192:195], v[48:51]
	v_mfma_f32_16x16x32_bf16 v[16:19], v[208:211], v[192:195], v[16:19]
	s_mov_b32 m0, s37
	v_lshl_add_u64 v[136:137], v[214:215], 0, s[16:17]
	s_barrier
	ds_read_b128 v[158:161], v166 offset:49152
	ds_read_b128 v[168:171], v166 offset:50176
	ds_read_b128 v[172:175], v166 offset:51200
	ds_read_b128 v[176:179], v166 offset:52224
	ds_read_b128 v[180:183], v166 offset:53248
	ds_read_b128 v[184:187], v166 offset:54272
	ds_read_b128 v[188:191], v166 offset:55296
	ds_read_b128 v[192:195], v166 offset:56320
	global_load_lds_dwordx4 v[136:137], off
	v_lshl_add_u64 v[136:137], v[216:217], 0, s[16:17]
	s_mov_b32 m0, s40
	s_nop 0
	global_load_lds_dwordx4 v[136:137], off
	s_barrier
	s_waitcnt lgkmcnt(0)
	s_waitcnt lgkmcnt(0)
	v_mfma_f32_16x16x32_bf16 v[108:111], v[128:131], v[158:161], v[108:111]
	v_mfma_f32_16x16x32_bf16 v[76:79], v[150:153], v[158:161], v[76:79]
	v_mfma_f32_16x16x32_bf16 v[104:107], v[128:131], v[172:175], v[104:107]
	v_mfma_f32_16x16x32_bf16 v[72:75], v[150:153], v[172:175], v[72:75]
	v_mfma_f32_16x16x32_bf16 v[100:103], v[128:131], v[180:183], v[100:103]
	v_mfma_f32_16x16x32_bf16 v[68:71], v[150:153], v[180:183], v[68:71]
	v_mfma_f32_16x16x32_bf16 v[96:99], v[128:131], v[188:191], v[96:99]
	v_mfma_f32_16x16x32_bf16 v[64:67], v[150:153], v[188:191], v[64:67]
	v_mfma_f32_16x16x32_bf16 v[108:111], v[132:135], v[168:171], v[108:111]
	v_mfma_f32_16x16x32_bf16 v[76:79], v[154:157], v[168:171], v[76:79]
	v_mfma_f32_16x16x32_bf16 v[104:107], v[132:135], v[176:179], v[104:107]
	v_mfma_f32_16x16x32_bf16 v[72:75], v[154:157], v[176:179], v[72:75]
	v_mfma_f32_16x16x32_bf16 v[100:103], v[132:135], v[184:187], v[100:103]
	v_mfma_f32_16x16x32_bf16 v[68:71], v[154:157], v[184:187], v[68:71]
	v_mfma_f32_16x16x32_bf16 v[96:99], v[132:135], v[192:195], v[96:99]
	v_mfma_f32_16x16x32_bf16 v[64:67], v[154:157], v[192:195], v[64:67]
	s_barrier
	s_add_u32 s4, s70, 0x80080
	s_addc_u32 s5, s71, 0
	s_add_i32 s8, s9, s24
	v_lshl_add_u64 v[128:129], s[4:5], 0, v[140:141]
	s_mov_b32 m0, s8
	s_nop 0
	global_load_lds_dwordx4 v[128:129], off
	v_lshl_add_u64 v[128:129], s[4:5], 0, v[138:139]
	s_add_i32 m0, s8, 0x2000
	s_nop 0
	global_load_lds_dwordx4 v[128:129], off
	s_waitcnt vmcnt(6)
	s_barrier
	v_mfma_f32_16x16x32_bf16 v[44:47], v[196:199], v[158:161], v[44:47]
	v_mfma_f32_16x16x32_bf16 v[12:15], v[204:207], v[158:161], v[12:15]
	v_mfma_f32_16x16x32_bf16 v[40:43], v[196:199], v[172:175], v[40:43]
	v_mfma_f32_16x16x32_bf16 v[8:11], v[204:207], v[172:175], v[8:11]
	v_mfma_f32_16x16x32_bf16 v[36:39], v[196:199], v[180:183], v[36:39]
	v_mfma_f32_16x16x32_bf16 v[4:7], v[204:207], v[180:183], v[4:7]
	v_mfma_f32_16x16x32_bf16 v[32:35], v[196:199], v[188:191], v[32:35]
	v_mfma_f32_16x16x32_bf16 v[0:3], v[204:207], v[188:191], v[0:3]
	v_mfma_f32_16x16x32_bf16 v[44:47], v[200:203], v[168:171], v[44:47]
	v_mfma_f32_16x16x32_bf16 v[12:15], v[208:211], v[168:171], v[12:15]
	v_mfma_f32_16x16x32_bf16 v[40:43], v[200:203], v[176:179], v[40:43]
	v_mfma_f32_16x16x32_bf16 v[8:11], v[208:211], v[176:179], v[8:11]
	v_mfma_f32_16x16x32_bf16 v[36:39], v[200:203], v[184:187], v[36:39]
	v_mfma_f32_16x16x32_bf16 v[4:7], v[208:211], v[184:187], v[4:7]
	v_mfma_f32_16x16x32_bf16 v[32:35], v[200:203], v[192:195], v[32:35]
	v_mfma_f32_16x16x32_bf16 v[0:3], v[208:211], v[192:195], v[0:3]
	s_add_i32 s78, s78, 2
	s_add_u32 s76, s76, 0x100
	s_addc_u32 s77, s77, 0
	s_cmp_gt_u32 s78, 29
	s_mov_b64 s[8:9], s[68:69]
	s_barrier
	s_cbranch_scc0 .LBB0_1533
	v_lshl_or_b32 v160, s75, 8, v164
	v_ashrrev_i32_e32 v161, 31, v160
	v_lshl_add_u64 v[128:129], v[160:161], 2, s[14:15]
	global_load_dwordx4 v[130:133], v[128:129], off
	v_cndmask_b32_e64 v129, 0, 1, s[18:19]
	v_mov_b32_e32 v128, 0
	v_cmp_ne_u32_e64 s[8:9], 1, v129
	s_andn2_b64 vcc, exec, s[18:19]
	v_lshl_add_u64 v[158:159], v[160:161], 2, s[10:11]
	v_mov_b32_e32 v134, 0
	v_mov_b32_e32 v135, 0
	v_mov_b32_e32 v136, 0
	v_mov_b32_e32 v137, 0
	s_cbranch_vccnz .LBB0_1536
	flat_load_dwordx4 v[134:137], v[158:159]

.LBB0_1545:
	s_waitcnt vmcnt(0)
	s_setprio 0
	s_barrier
	s_mov_b64 s[0:1], exec
	v_readlane_b32 s4, v255, 4
	v_readlane_b32 s5, v255, 5
	s_and_b64 s[4:5], s[0:1], s[4:5]
	s_xor_b64 s[6:7], s[4:5], s[0:1]
	s_mov_b64 exec, s[4:5]
	s_cbranch_execz .LBB0_1598
	s_add_i32 s0, 0, 0x25800
	v_mov_b32_e32 v0, s0
	s_waitcnt vmcnt(0) expcnt(0) lgkmcnt(0)
	ds_read_b32 v2, v0
	s_add_i32 s0, 0, 0x25804
	v_mov_b32_e32 v0, s0
	ds_read_b32 v0, v0
	s_waitcnt lgkmcnt(1)
	v_cmp_ne_u32_e32 vcc, 0, v2
	s_cbranch_vccnz .LBB0_1561
	s_add_u32 s8, s26, 0xc0200
	s_addc_u32 s9, s27, 0
	s_add_u32 s4, s26, 0xc0400
	s_addc_u32 s5, s27, 0
	s_add_u32 s10, s26, 0xc0500
	s_addc_u32 s11, s27, 0
	s_add_u32 s12, s26, 0xc0600
	s_addc_u32 s13, s27, 0
	s_add_u32 s14, s26, 0xc0700
	s_addc_u32 s15, s27, 0
	s_add_u32 s16, s26, 0xc0800
	s_addc_u32 s17, s27, 0
	s_add_u32 s18, s26, 0xc0900
	s_addc_u32 s19, s27, 0
	s_add_u32 s20, s26, 0xc0a00
	s_addc_u32 s21, s27, 0
	s_add_u32 s36, s26, 0xc0b00
	s_addc_u32 s37, s27, 0
	s_add_u32 s44, s26, 0xc0c00
	s_addc_u32 s45, s27, 0
	s_add_u32 s46, s26, 0xc0d00
	s_addc_u32 s47, s27, 0
	s_add_u32 s50, s26, 0xc0e00
	s_addc_u32 s51, s27, 0
	s_add_u32 s54, s26, 0xc0f00
	s_addc_u32 s55, s27, 0
	s_add_u32 s58, s26, 0xc1000
	s_addc_u32 s59, s27, 0
	s_add_u32 s60, s26, 0xc1100
	s_addc_u32 s61, s27, 0
	s_add_u32 s62, s26, 0xc1200
	v_readlane_b32 s0, v255, 0
	s_addc_u32 s63, s27, 0
	s_mul_i32 s23, s31, s0
	s_add_u32 s64, s26, 0xc1300
	s_mul_i32 s23, s23, s30
	s_addc_u32 s65, s27, 0
	s_mov_b32 s24, 1
	v_mov_b32_e32 v16, 0
	s_branch .LBB0_1549

.LBB0_1617:
	s_waitcnt vmcnt(0)
	s_setprio 0
	s_barrier
	s_mov_b64 s[6:7], exec
	v_readlane_b32 s0, v255, 4
	v_readlane_b32 s1, v255, 5
	s_and_b64 s[0:1], s[6:7], s[0:1]
	s_mov_b64 exec, s[0:1]
	s_cbranch_execz .LBB0_1669
	s_add_i32 s0, 0, 0x25800
	v_mov_b32_e32 v0, s0
	s_waitcnt vmcnt(0) expcnt(0) lgkmcnt(0)
	ds_read_b32 v2, v0
	s_add_i32 s0, 0, 0x25804
	v_mov_b32_e32 v0, s0
	ds_read_b32 v0, v0
	s_waitcnt lgkmcnt(1)
	v_cmp_ne_u32_e32 vcc, 0, v2
	s_cbranch_vccnz .LBB0_1633
	s_add_u32 s8, s26, 0xc0200
	s_addc_u32 s9, s27, 0
	s_add_u32 s4, s26, 0xc0400
	s_addc_u32 s5, s27, 0
	s_add_u32 s10, s26, 0xc0500
	s_addc_u32 s11, s27, 0
	s_add_u32 s12, s26, 0xc0600
	s_addc_u32 s13, s27, 0
	s_add_u32 s14, s26, 0xc0700
	s_addc_u32 s15, s27, 0
	s_add_u32 s16, s26, 0xc0800
	s_addc_u32 s17, s27, 0
	s_add_u32 s18, s26, 0xc0900
	s_addc_u32 s19, s27, 0
	s_add_u32 s20, s26, 0xc0a00
	s_addc_u32 s21, s27, 0
	s_add_u32 s36, s26, 0xc0b00
	s_addc_u32 s37, s27, 0
	s_add_u32 s44, s26, 0xc0c00
	s_addc_u32 s45, s27, 0
	s_add_u32 s46, s26, 0xc0d00
	s_addc_u32 s47, s27, 0
	s_add_u32 s50, s26, 0xc0e00
	s_addc_u32 s51, s27, 0
	s_add_u32 s52, s26, 0xc0f00
	s_addc_u32 s53, s27, 0
	s_add_u32 s54, s26, 0xc1000
	s_addc_u32 s55, s27, 0
	s_add_u32 s58, s26, 0xc1100
	s_addc_u32 s59, s27, 0
	s_add_u32 s60, s26, 0xc1200
	v_readlane_b32 s0, v255, 0
	s_addc_u32 s61, s27, 0
	s_mul_i32 s23, s31, s0
	s_add_u32 s62, s26, 0xc1300
	s_mul_i32 s23, s23, s30
	s_addc_u32 s63, s27, 0
	s_mov_b32 s24, 1
	v_mov_b32_e32 v16, 0
	s_branch .LBB0_1621

.LBB0_1669:
	s_or_b64 exec, exec, s[6:7]
	s_waitcnt lgkmcnt(0)
	v_mov_b32_e32 v0, v254
	v_mov_b32_e32 v9, v254
	s_barrier
	v_cmp_lt_u32_e32 vcc, 0xff, v254
	s_cbranch_vccz .Lprio_skip16
	s_setprio 1
.Lprio_skip16:
	s_and_b64 vcc, exec, s[56:57]
	v_readfirstlane_b32 s23, v9
	s_cbranch_vccz .LBB0_1681
	v_lshlrev_b32_e32 v0, 4, v9
	v_add_u32_e32 v1, 0x2000, v0
	v_ashrrev_i32_e32 v2, 31, v1
	v_lshrrev_b32_e32 v2, 22, v2
	v_add_u32_e32 v2, v1, v2
	v_ashrrev_i32_e32 v8, 10, v2
	v_mul_i32_i24_e32 v2, 0x400, v8
	v_sub_u32_e32 v1, v1, v2
	v_lshrrev_b32_e32 v2, 4, v1
	v_bitop3_b32 v1, v2, v1, 32 bitop3:0x6c
	v_ashrrev_i32_e32 v2, 31, v1
	v_lshrrev_b32_e32 v2, 26, v2
	v_add_u32_e32 v2, v1, v2
	v_lshlrev_b32_e32 v3, 3, v8
	v_ashrrev_i32_e32 v10, 6, v2
	v_and_b32_e32 v3, -16, v3
	v_add_u32_e32 v3, v10, v3
	v_and_b32_e32 v4, 3, v10
	s_mov_b32 s4, 0xfffe0
	v_lshrrev_b32_e32 v5, 2, v3
	v_lshlrev_b32_e32 v6, 1, v3
	v_and_b32_e32 v2, 0xc0, v2
	v_and_or_b32 v4, v3, s4, v4
	v_and_b32_e32 v5, 4, v5
	v_and_b32_e32 v6, 24, v6
	v_sub_u32_e32 v1, v1, v2
	v_mov_b32_e32 v2, 1
	v_or3_b32 v4, v4, v5, v6
	v_lshlrev_b32_e32 v5, 5, v8
	v_ashrrev_i16_sdwa v1, v2, sext(v1) dst_sel:DWORD dst_unused:UNUSED_PAD src0_sel:DWORD src1_sel:BYTE_0
	v_and_b32_e32 v5, 32, v5
	v_bfe_i32 v11, v1, 0, 16
	v_add_lshl_u32 v1, v5, v11, 1
	v_lshl_add_u32 v128, v4, 12, v1
	v_lshl_add_u32 v130, v3, 12, v1
	v_bfe_i32 v1, v9, 27, 1
	v_lshrrev_b32_e32 v1, 22, v1
	v_add_u32_e32 v1, v0, v1
	v_and_b32_e32 v1, 0xfffffc00, v1
	v_sub_u32_e32 v0, v0, v1
	v_lshrrev_b32_e32 v1, 4, v0
	v_bitop3_b32 v1, v1, v0, 32 bitop3:0x6c
	v_ashrrev_i32_e32 v0, 31, v0
	v_lshrrev_b32_e32 v0, 26, v0
	v_add_u32_e32 v0, v1, v0
	v_ashrrev_i32_e32 v12, 6, v0
	v_ashrrev_i32_e32 v0, 31, v9
	v_lshrrev_b32_e32 v0, 26, v0
	v_add_u32_e32 v0, v9, v0
	v_ashrrev_i32_e32 v13, 6, v0
	v_lshlrev_b32_e32 v0, 3, v13
	v_and_b32_e32 v0, -16, v0
	v_add_u32_e32 v0, v12, v0
	v_and_b32_e32 v3, 3, v12
	v_and_or_b32 v3, v0, s4, v3
	s_lshr_b32 s4, s3, 29
	s_add_i32 s4, s2, s4
	s_ashr_i32 s1, s23, 6
	s_ashr_i32 s5, s4, 3
	s_and_b32 s4, s4, -8
	s_ashr_i32 s0, s23, 8
	s_lshl_b32 s24, s1, 10
	s_sub_i32 s4, s2, s4
	s_cmp_lt_i32 s4, 0
	s_movk_i32 s25, 0xb1
	s_cselect_b32 s6, s25, 0xb0
	s_mul_i32 s4, s4, s6
	s_add_i32 s4, s4, s5
	s_mul_hi_i32 s5, s4, 0x2e8ba2e9
	s_lshr_b32 s6, s5, 31
	s_ashr_i32 s5, s5, 6
	s_add_i32 s5, s5, s6
	s_lshl_b32 s6, s5, 3
	s_mulk_i32 s5, 0x160
	s_sub_i32 s5, s4, s5
	s_sext_i32_i16 s4, s5
	s_bfe_u32 s4, s4, 0x3001c
	s_add_i32 s7, s5, s4
	s_sext_i32_i16 s4, s7
	s_and_b32 s7, s7, 0xfff8
	v_lshrrev_b32_e32 v4, 2, v0
	v_lshlrev_b32_e32 v5, 1, v0
	s_sub_i32 s5, s5, s7
	v_and_b32_e32 v4, 4, v4
	v_and_b32_e32 v5, 24, v5
	s_sext_i32_i16 s5, s5
	v_or3_b32 v3, v3, v4, v5
	v_mul_i32_i24_e32 v5, 64, v12
	s_lshr_b32 s4, s4, 3
	s_add_i32 s18, s6, s5
	v_sub_u32_e32 v1, v1, v5
	s_ashr_i32 s19, s18, 31
	s_bfe_i64 s[8:9], s[4:5], 0x100000
	v_lshlrev_b32_e32 v4, 5, v13
	v_ashrrev_i16_sdwa v1, v2, sext(v1) dst_sel:DWORD dst_unused:UNUSED_PAD src0_sel:DWORD src1_sel:BYTE_0
	s_lshl_b64 s[6:7], s[18:19], 20
	s_lshl_b64 s[8:9], s[8:9], 20
	v_readlane_b32 s56, v255, 24
	v_and_b32_e32 v4, 32, v4
	v_bfe_i32 v14, v1, 0, 16
	v_readlane_b32 s57, v255, 25
	s_add_u32 s44, s56, s8
	v_add_lshl_u32 v1, v4, v14, 1
	s_addc_u32 s45, s57, s9
	s_add_i32 s19, s24, 0
	v_lshl_add_u32 v132, v3, 12, v1
	s_add_i32 m0, s19, 0x10000
	v_lshl_add_u32 v134, v0, 12, v1
	global_load_lds_dwordx4 v132, s[44:45]
	s_add_i32 m0, s19, 0x12000
	s_add_u32 s20, s38, s6
	global_load_lds_dwordx4 v128, s[44:45]
	s_addc_u32 s21, s39, s7
	s_mov_b32 m0, s19
	s_add_i32 s28, s19, 0x2000
	global_load_lds_dwordx4 v134, s[20:21]
	s_mov_b32 m0, s28
	s_add_u32 s6, s44, 0x80000
	global_load_lds_dwordx4 v130, s[20:21]
	s_addc_u32 s7, s45, 0
	s_add_i32 m0, s19, 0x14000
	v_mov_b32_e32 v133, 0
	global_load_lds_dwordx4 v132, s[6:7]
	s_add_i32 m0, s19, 0x16000
	v_mov_b32_e32 v129, v133
	global_load_lds_dwordx4 v128, s[6:7]
	s_add_u32 s6, s20, 0x80000
	s_addc_u32 s7, s21, 0
	s_add_i32 s29, s19, 0x4000
	s_mov_b32 m0, s29
	s_add_i32 s33, s19, 0x6000
	global_load_lds_dwordx4 v134, s[6:7]
	s_mov_b32 m0, s33
	v_mov_b32_e32 v135, v133
	global_load_lds_dwordx4 v130, s[6:7]
	v_mov_b32_e32 v131, v133
	s_mov_b32 s36, 0
	v_lshl_add_u64 v[6:7], s[44:45], 0, v[132:133]
	v_lshl_add_u64 v[4:5], s[44:45], 0, v[128:129]
	v_lshl_add_u64 v[2:3], s[20:21], 0, v[134:135]
	s_cmp_lg_u32 s0, 1
	v_lshl_add_u64 v[0:1], s[20:21], 0, v[130:131]
	s_cbranch_scc1 .LBB0_1672
	s_barrier

.LBB0_1676:
	ds_read_b128 v[150:153], v147
	ds_read_b128 v[154:157], v147 offset:1024
	ds_read_b128 v[158:161], v147 offset:2048
	ds_read_b128 v[162:165], v147 offset:3072
	s_add_u32 s4, s20, 0xfff80080
	s_addc_u32 s5, s21, -1
	s_cmp_eq_u32 s53, 28
	s_cselect_b32 s5, s0, s5
	s_cselect_b32 s4, s1, s4
	s_cselect_b32 s45, s11, s52
	s_cselect_b32 s44, s13, s51
	v_lshl_add_u64 v[198:199], s[20:21], 0, v[136:137]
	s_add_i32 m0, s19, 0xc000
	ds_read_b128 v[166:169], v148
	ds_read_b128 v[170:173], v148 offset:1024
	ds_read_b128 v[174:177], v148 offset:2048
	ds_read_b128 v[178:181], v148 offset:3072
	ds_read_b128 v[182:185], v148 offset:4096
	ds_read_b128 v[186:189], v148 offset:5120
	ds_read_b128 v[190:193], v148 offset:6144
	ds_read_b128 v[194:197], v148 offset:7168
	global_load_lds_dwordx4 v[198:199], off
	v_lshl_add_u64 v[198:199], s[20:21], 0, v[138:139]
	s_add_i32 m0, s19, 0xe000
	s_nop 0
	global_load_lds_dwordx4 v[198:199], off
	s_waitcnt lgkmcnt(8)
	s_barrier
	s_waitcnt lgkmcnt(0)
	s_waitcnt lgkmcnt(0)
	v_mfma_f32_16x16x32_bf16 v[124:127], v[150:153], v[166:169], v[124:127]
	v_mfma_f32_16x16x32_bf16 v[120:123], v[158:161], v[166:169], v[120:123]
	v_mfma_f32_16x16x32_bf16 v[108:111], v[150:153], v[174:177], v[108:111]
	v_mfma_f32_16x16x32_bf16 v[104:107], v[158:161], v[174:177], v[104:107]
	v_mfma_f32_16x16x32_bf16 v[92:95], v[150:153], v[182:185], v[92:95]
	v_mfma_f32_16x16x32_bf16 v[88:91], v[158:161], v[182:185], v[88:91]
	v_mfma_f32_16x16x32_bf16 v[76:79], v[150:153], v[190:193], v[76:79]
	v_mfma_f32_16x16x32_bf16 v[72:75], v[158:161], v[190:193], v[72:75]
	v_mfma_f32_16x16x32_bf16 v[124:127], v[154:157], v[170:173], v[124:127]
	v_mfma_f32_16x16x32_bf16 v[120:123], v[162:165], v[170:173], v[120:123]
	v_mfma_f32_16x16x32_bf16 v[108:111], v[154:157], v[178:181], v[108:111]
	v_mfma_f32_16x16x32_bf16 v[104:107], v[162:165], v[178:181], v[104:107]
	v_mfma_f32_16x16x32_bf16 v[92:95], v[154:157], v[186:189], v[92:95]
	v_mfma_f32_16x16x32_bf16 v[88:91], v[162:165], v[186:189], v[88:91]
	v_mfma_f32_16x16x32_bf16 v[76:79], v[154:157], v[194:197], v[76:79]
	v_mfma_f32_16x16x32_bf16 v[72:75], v[162:165], v[194:197], v[72:75]
	s_barrier
	s_add_i32 s42, s41, s24
	v_lshl_add_u64 v[214:215], s[44:45], 0, v[132:133]
	s_mov_b32 m0, s42
	ds_read_b128 v[198:201], v149
	ds_read_b128 v[202:205], v149 offset:1024
	ds_read_b128 v[206:209], v149 offset:2048
	ds_read_b128 v[210:213], v149 offset:3072
	global_load_lds_dwordx4 v[214:215], off
	v_lshl_add_u64 v[216:217], s[44:45], 0, v[128:129]
	s_add_i32 m0, s42, 0x2000
	s_nop 0
	global_load_lds_dwordx4 v[216:217], off
	s_barrier
	s_waitcnt lgkmcnt(0)
	s_waitcnt lgkmcnt(0)
	v_mfma_f32_16x16x32_bf16 v[116:119], v[198:201], v[166:169], v[116:119]
	v_mfma_f32_16x16x32_bf16 v[112:115], v[206:209], v[166:169], v[112:115]
	v_mfma_f32_16x16x32_bf16 v[100:103], v[198:201], v[174:177], v[100:103]
	v_mfma_f32_16x16x32_bf16 v[96:99], v[206:209], v[174:177], v[96:99]
	v_mfma_f32_16x16x32_bf16 v[84:87], v[198:201], v[182:185], v[84:87]
	v_mfma_f32_16x16x32_bf16 v[80:83], v[206:209], v[182:185], v[80:83]
	v_mfma_f32_16x16x32_bf16 v[68:71], v[198:201], v[190:193], v[68:71]
	v_mfma_f32_16x16x32_bf16 v[64:67], v[206:209], v[190:193], v[64:67]
	v_mfma_f32_16x16x32_bf16 v[116:119], v[202:205], v[170:173], v[116:119]
	v_mfma_f32_16x16x32_bf16 v[112:115], v[210:213], v[170:173], v[112:115]
	v_mfma_f32_16x16x32_bf16 v[100:103], v[202:205], v[178:181], v[100:103]
	v_mfma_f32_16x16x32_bf16 v[96:99], v[210:213], v[178:181], v[96:99]
	v_mfma_f32_16x16x32_bf16 v[84:87], v[202:205], v[186:189], v[84:87]
	v_mfma_f32_16x16x32_bf16 v[80:83], v[210:213], v[186:189], v[80:83]
	v_mfma_f32_16x16x32_bf16 v[68:71], v[202:205], v[194:197], v[68:71]
	v_mfma_f32_16x16x32_bf16 v[64:67], v[210:213], v[194:197], v[64:67]
	s_mov_b32 m0, s19
	v_lshl_add_u64 v[218:219], s[4:5], 0, v[134:135]
	s_barrier
	ds_read_b128 v[166:169], v148 offset:16384
	ds_read_b128 v[170:173], v148 offset:17408
	ds_read_b128 v[174:177], v148 offset:18432
	ds_read_b128 v[178:181], v148 offset:19456
	ds_read_b128 v[182:185], v148 offset:20480
	ds_read_b128 v[186:189], v148 offset:21504
	ds_read_b128 v[190:193], v148 offset:22528
	ds_read_b128 v[194:197], v148 offset:23552
	global_load_lds_dwordx4 v[218:219], off
	v_lshl_add_u64 v[220:221], s[4:5], 0, v[130:131]
	s_mov_b32 m0, s28
	s_nop 0
	global_load_lds_dwordx4 v[220:221], off
	s_barrier
	s_waitcnt lgkmcnt(0)
	s_waitcnt lgkmcnt(0)
	v_mfma_f32_16x16x32_bf16 v[60:63], v[150:153], v[166:169], v[60:63]
	v_mfma_f32_16x16x32_bf16 v[56:59], v[158:161], v[166:169], v[56:59]
	v_mfma_f32_16x16x32_bf16 v[44:47], v[150:153], v[174:177], v[44:47]
	v_mfma_f32_16x16x32_bf16 v[40:43], v[158:161], v[174:177], v[40:43]
	v_mfma_f32_16x16x32_bf16 v[28:31], v[150:153], v[182:185], v[28:31]
	v_mfma_f32_16x16x32_bf16 v[24:27], v[158:161], v[182:185], v[24:27]
	v_mfma_f32_16x16x32_bf16 v[12:15], v[150:153], v[190:193], v[12:15]
	v_mfma_f32_16x16x32_bf16 v[8:11], v[158:161], v[190:193], v[8:11]
	v_mfma_f32_16x16x32_bf16 v[60:63], v[154:157], v[170:173], v[60:63]
	v_mfma_f32_16x16x32_bf16 v[56:59], v[162:165], v[170:173], v[56:59]
	v_mfma_f32_16x16x32_bf16 v[44:47], v[154:157], v[178:181], v[44:47]
	v_mfma_f32_16x16x32_bf16 v[40:43], v[162:165], v[178:181], v[40:43]
	v_mfma_f32_16x16x32_bf16 v[28:31], v[154:157], v[186:189], v[28:31]
	v_mfma_f32_16x16x32_bf16 v[24:27], v[162:165], v[186:189], v[24:27]
	v_mfma_f32_16x16x32_bf16 v[12:15], v[154:157], v[194:197], v[12:15]
	v_mfma_f32_16x16x32_bf16 v[8:11], v[162:165], v[194:197], v[8:11]
	s_barrier
	s_add_u32 s42, s44, 0x80000
	s_addc_u32 s43, s45, 0
	s_add_i32 s54, s46, s24
	v_lshl_add_u64 v[150:151], s[42:43], 0, v[132:133]
	s_mov_b32 m0, s54
	s_nop 0
	global_load_lds_dwordx4 v[150:151], off
	v_lshl_add_u64 v[150:151], s[42:43], 0, v[128:129]
	s_add_i32 m0, s54, 0x2000
	s_nop 0
	global_load_lds_dwordx4 v[150:151], off
	s_waitcnt vmcnt(6)
	s_barrier
	v_mfma_f32_16x16x32_bf16 v[52:55], v[198:201], v[166:169], v[52:55]
	v_mfma_f32_16x16x32_bf16 v[48:51], v[206:209], v[166:169], v[48:51]
	v_mfma_f32_16x16x32_bf16 v[36:39], v[198:201], v[174:177], v[36:39]
	v_mfma_f32_16x16x32_bf16 v[32:35], v[206:209], v[174:177], v[32:35]
	v_mfma_f32_16x16x32_bf16 v[20:23], v[198:201], v[182:185], v[20:23]
	v_mfma_f32_16x16x32_bf16 v[16:19], v[206:209], v[182:185], v[16:19]
	v_mfma_f32_16x16x32_bf16 v[4:7], v[198:201], v[190:193], v[4:7]
	v_mfma_f32_16x16x32_bf16 v[0:3], v[206:209], v[190:193], v[0:3]
	v_mfma_f32_16x16x32_bf16 v[52:55], v[202:205], v[170:173], v[52:55]
	v_mfma_f32_16x16x32_bf16 v[48:51], v[210:213], v[170:173], v[48:51]
	v_mfma_f32_16x16x32_bf16 v[36:39], v[202:205], v[178:181], v[36:39]
	v_mfma_f32_16x16x32_bf16 v[32:35], v[210:213], v[178:181], v[32:35]
	v_mfma_f32_16x16x32_bf16 v[20:23], v[202:205], v[186:189], v[20:23]
	v_mfma_f32_16x16x32_bf16 v[16:19], v[210:213], v[186:189], v[16:19]
	v_mfma_f32_16x16x32_bf16 v[4:7], v[202:205], v[194:197], v[4:7]
	v_mfma_f32_16x16x32_bf16 v[0:3], v[210:213], v[194:197], v[0:3]
	s_add_i32 s42, 0, 0x18000
	v_add_u32_e32 v162, s42, v145
	s_barrier
	ds_read_b128 v[150:153], v162
	ds_read_b128 v[154:157], v162 offset:1024
	ds_read_b128 v[158:161], v162 offset:2048
	ds_read_b128 v[162:165], v162 offset:3072
	s_add_u32 s4, s4, 0x80000
	s_addc_u32 s5, s5, 0
	s_mov_b32 m0, s29
	v_lshl_add_u64 v[198:199], s[4:5], 0, v[134:135]
	ds_read_b128 v[166:169], v148 offset:32768
	ds_read_b128 v[170:173], v148 offset:33792
	ds_read_b128 v[174:177], v148 offset:34816
	ds_read_b128 v[178:181], v148 offset:35840
	ds_read_b128 v[182:185], v148 offset:36864
	ds_read_b128 v[186:189], v148 offset:37888
	ds_read_b128 v[190:193], v148 offset:38912
	ds_read_b128 v[194:197], v148 offset:39936
	global_load_lds_dwordx4 v[198:199], off
	v_lshl_add_u64 v[198:199], s[4:5], 0, v[130:131]
	s_mov_b32 m0, s33
	s_nop 0
	global_load_lds_dwordx4 v[198:199], off
	s_waitcnt lgkmcnt(8)
	s_barrier
	s_waitcnt lgkmcnt(0)
	s_waitcnt lgkmcnt(0)
	v_mfma_f32_16x16x32_bf16 v[124:127], v[150:153], v[166:169], v[124:127]
	v_mfma_f32_16x16x32_bf16 v[120:123], v[158:161], v[166:169], v[120:123]
	v_mfma_f32_16x16x32_bf16 v[108:111], v[150:153], v[174:177], v[108:111]
	v_mfma_f32_16x16x32_bf16 v[104:107], v[158:161], v[174:177], v[104:107]
	v_mfma_f32_16x16x32_bf16 v[92:95], v[150:153], v[182:185], v[92:95]
	v_mfma_f32_16x16x32_bf16 v[88:91], v[158:161], v[182:185], v[88:91]
	v_mfma_f32_16x16x32_bf16 v[76:79], v[150:153], v[190:193], v[76:79]
	v_mfma_f32_16x16x32_bf16 v[72:75], v[158:161], v[190:193], v[72:75]
	v_mfma_f32_16x16x32_bf16 v[124:127], v[154:157], v[170:173], v[124:127]
	v_mfma_f32_16x16x32_bf16 v[120:123], v[162:165], v[170:173], v[120:123]
	v_mfma_f32_16x16x32_bf16 v[108:111], v[154:157], v[178:181], v[108:111]
	v_mfma_f32_16x16x32_bf16 v[104:107], v[162:165], v[178:181], v[104:107]
	v_mfma_f32_16x16x32_bf16 v[92:95], v[154:157], v[186:189], v[92:95]
	v_mfma_f32_16x16x32_bf16 v[88:91], v[162:165], v[186:189], v[88:91]
	v_mfma_f32_16x16x32_bf16 v[76:79], v[154:157], v[194:197], v[76:79]
	v_mfma_f32_16x16x32_bf16 v[72:75], v[162:165], v[194:197], v[72:75]
	s_barrier
	s_add_i32 s43, 0, 0x1c000
	s_add_i32 s4, s42, s24
	v_add_u32_e32 v210, s43, v145
	v_lshl_add_u64 v[214:215], v[214:215], 0, s[8:9]
	s_mov_b32 m0, s4
	ds_read_b128 v[198:201], v210
	ds_read_b128 v[202:205], v210 offset:1024
	ds_read_b128 v[206:209], v210 offset:2048
	ds_read_b128 v[210:213], v210 offset:3072
	global_load_lds_dwordx4 v[214:215], off
	v_lshl_add_u64 v[214:215], v[216:217], 0, s[8:9]
	s_add_i32 m0, s4, 0x2000
	s_nop 0
	global_load_lds_dwordx4 v[214:215], off
	s_barrier
	s_waitcnt lgkmcnt(0)
	s_waitcnt lgkmcnt(0)
	v_mfma_f32_16x16x32_bf16 v[116:119], v[198:201], v[166:169], v[116:119]
	v_mfma_f32_16x16x32_bf16 v[112:115], v[206:209], v[166:169], v[112:115]
	v_mfma_f32_16x16x32_bf16 v[100:103], v[198:201], v[174:177], v[100:103]
	v_mfma_f32_16x16x32_bf16 v[96:99], v[206:209], v[174:177], v[96:99]
	v_mfma_f32_16x16x32_bf16 v[84:87], v[198:201], v[182:185], v[84:87]
	v_mfma_f32_16x16x32_bf16 v[80:83], v[206:209], v[182:185], v[80:83]
	v_mfma_f32_16x16x32_bf16 v[68:71], v[198:201], v[190:193], v[68:71]
	v_mfma_f32_16x16x32_bf16 v[64:67], v[206:209], v[190:193], v[64:67]
	v_mfma_f32_16x16x32_bf16 v[116:119], v[202:205], v[170:173], v[116:119]
	v_mfma_f32_16x16x32_bf16 v[112:115], v[210:213], v[170:173], v[112:115]
	v_mfma_f32_16x16x32_bf16 v[100:103], v[202:205], v[178:181], v[100:103]
	v_mfma_f32_16x16x32_bf16 v[96:99], v[210:213], v[178:181], v[96:99]
	v_mfma_f32_16x16x32_bf16 v[84:87], v[202:205], v[186:189], v[84:87]
	v_mfma_f32_16x16x32_bf16 v[80:83], v[210:213], v[186:189], v[80:83]
	v_mfma_f32_16x16x32_bf16 v[68:71], v[202:205], v[194:197], v[68:71]
	v_mfma_f32_16x16x32_bf16 v[64:67], v[210:213], v[194:197], v[64:67]
	s_mov_b32 m0, s37
	v_lshl_add_u64 v[214:215], v[218:219], 0, s[8:9]
	s_barrier
	ds_read_b128 v[166:169], v148 offset:49152
	ds_read_b128 v[170:173], v148 offset:50176
	ds_read_b128 v[174:177], v148 offset:51200
	ds_read_b128 v[178:181], v148 offset:52224
	ds_read_b128 v[182:185], v148 offset:53248
	ds_read_b128 v[186:189], v148 offset:54272
	ds_read_b128 v[190:193], v148 offset:55296
	ds_read_b128 v[194:197], v148 offset:56320
	global_load_lds_dwordx4 v[214:215], off
	v_lshl_add_u64 v[214:215], v[220:221], 0, s[8:9]
	s_mov_b32 m0, s40
	s_nop 0
	global_load_lds_dwordx4 v[214:215], off
	s_barrier
	s_waitcnt lgkmcnt(0)
	s_waitcnt lgkmcnt(0)
	v_mfma_f32_16x16x32_bf16 v[60:63], v[150:153], v[166:169], v[60:63]
	v_mfma_f32_16x16x32_bf16 v[56:59], v[158:161], v[166:169], v[56:59]
	v_mfma_f32_16x16x32_bf16 v[44:47], v[150:153], v[174:177], v[44:47]
	v_mfma_f32_16x16x32_bf16 v[40:43], v[158:161], v[174:177], v[40:43]
	v_mfma_f32_16x16x32_bf16 v[28:31], v[150:153], v[182:185], v[28:31]
	v_mfma_f32_16x16x32_bf16 v[24:27], v[158:161], v[182:185], v[24:27]
	v_mfma_f32_16x16x32_bf16 v[12:15], v[150:153], v[190:193], v[12:15]
	v_mfma_f32_16x16x32_bf16 v[8:11], v[158:161], v[190:193], v[8:11]
	v_mfma_f32_16x16x32_bf16 v[60:63], v[154:157], v[170:173], v[60:63]
	v_mfma_f32_16x16x32_bf16 v[56:59], v[162:165], v[170:173], v[56:59]
	v_mfma_f32_16x16x32_bf16 v[44:47], v[154:157], v[178:181], v[44:47]
	v_mfma_f32_16x16x32_bf16 v[40:43], v[162:165], v[178:181], v[40:43]
	v_mfma_f32_16x16x32_bf16 v[28:31], v[154:157], v[186:189], v[28:31]
	v_mfma_f32_16x16x32_bf16 v[24:27], v[162:165], v[186:189], v[24:27]
	v_mfma_f32_16x16x32_bf16 v[12:15], v[154:157], v[194:197], v[12:15]
	v_mfma_f32_16x16x32_bf16 v[8:11], v[162:165], v[194:197], v[8:11]
	s_barrier
	s_add_u32 s4, s44, 0x80080
	s_addc_u32 s5, s45, 0
	s_add_i32 s42, s43, s24
	v_lshl_add_u64 v[150:151], s[4:5], 0, v[132:133]
	s_mov_b32 m0, s42
	s_nop 0
	global_load_lds_dwordx4 v[150:151], off
	v_lshl_add_u64 v[150:151], s[4:5], 0, v[128:129]
	s_add_i32 m0, s42, 0x2000
	s_nop 0
	global_load_lds_dwordx4 v[150:151], off
	s_waitcnt vmcnt(6)
	s_barrier
	v_mfma_f32_16x16x32_bf16 v[52:55], v[198:201], v[166:169], v[52:55]
	v_mfma_f32_16x16x32_bf16 v[48:51], v[206:209], v[166:169], v[48:51]
	v_mfma_f32_16x16x32_bf16 v[36:39], v[198:201], v[174:177], v[36:39]
	v_mfma_f32_16x16x32_bf16 v[32:35], v[206:209], v[174:177], v[32:35]
	v_mfma_f32_16x16x32_bf16 v[20:23], v[198:201], v[182:185], v[20:23]
	v_mfma_f32_16x16x32_bf16 v[16:19], v[206:209], v[182:185], v[16:19]
	v_mfma_f32_16x16x32_bf16 v[4:7], v[198:201], v[190:193], v[4:7]
	v_mfma_f32_16x16x32_bf16 v[0:3], v[206:209], v[190:193], v[0:3]
	v_mfma_f32_16x16x32_bf16 v[52:55], v[202:205], v[170:173], v[52:55]
	v_mfma_f32_16x16x32_bf16 v[48:51], v[210:213], v[170:173], v[48:51]
	v_mfma_f32_16x16x32_bf16 v[36:39], v[202:205], v[178:181], v[36:39]
	v_mfma_f32_16x16x32_bf16 v[32:35], v[210:213], v[178:181], v[32:35]
	v_mfma_f32_16x16x32_bf16 v[20:23], v[202:205], v[186:189], v[20:23]
	v_mfma_f32_16x16x32_bf16 v[16:19], v[210:213], v[186:189], v[16:19]
	v_mfma_f32_16x16x32_bf16 v[4:7], v[202:205], v[194:197], v[4:7]
	v_mfma_f32_16x16x32_bf16 v[0:3], v[210:213], v[194:197], v[0:3]
	s_add_i32 s53, s53, 2
	s_add_u32 s20, s20, 0x100
	s_addc_u32 s21, s21, 0
	s_add_u32 s51, s51, 0x100
	s_addc_u32 s52, s52, 0
	s_cmp_gt_u32 s53, 29
	s_barrier
	s_cbranch_scc0 .LBB0_1676
	v_mul_f32_e32 v151, 0xbfb8aa3b, v124
	v_exp_f32_e32 v151, v151
	v_mul_f32_e32 v152, 0xbfb8aa3b, v120
	v_exp_f32_e32 v153, v152
	v_lshl_or_b32 v152, s50, 7, v146
	v_add_f32_e32 v151, 1.0, v151
	v_rcp_f32_e32 v151, v151
	v_add_f32_e32 v153, 1.0, v153
	v_rcp_f32_e32 v154, v153
	v_lshl_add_u32 v150, s18, 8, v144
	v_mul_f32_e32 v124, v124, v151
	v_mul_f32_e32 v116, v124, v116
	v_mul_f32_e32 v124, 0xbfb8aa3b, v125
	v_exp_f32_e32 v124, v124
	v_mul_f32_e32 v151, 0xbfb8aa3b, v121
	v_exp_f32_e32 v151, v151
	v_mul_f32_e32 v120, v120, v154
	v_mul_f32_e32 v112, v120, v112
	v_add_f32_e32 v120, 1.0, v124
	v_rcp_f32_e32 v120, v120
	v_add_f32_e32 v124, 1.0, v151
	v_mul_f32_e32 v151, 0xbfb8aa3b, v126
	v_rcp_f32_e32 v124, v124
	v_exp_f32_e32 v151, v151
	v_mul_f32_e32 v120, v125, v120
	v_mul_f32_e32 v117, v120, v117
	v_mul_f32_e32 v120, v121, v124
	v_add_f32_e32 v121, 1.0, v151
	v_rcp_f32_e32 v121, v121
	v_mul_f32_e32 v124, 0xbfb8aa3b, v122
	v_exp_f32_e32 v124, v124
	v_mul_f32_e32 v113, v120, v113
	v_mul_f32_e32 v120, v126, v121
	v_mul_f32_e32 v121, 0xbfb8aa3b, v127
	v_mul_f32_e32 v118, v120, v118
	v_add_f32_e32 v120, 1.0, v124
	v_exp_f32_e32 v121, v121
	v_mul_f32_e32 v124, 0xbfb8aa3b, v123
	v_rcp_f32_e32 v120, v120
	v_exp_f32_e32 v124, v124
	v_add_f32_e32 v121, 1.0, v121
	v_rcp_f32_e32 v121, v121
	v_mul_f32_e32 v120, v122, v120
	v_add_f32_e32 v122, 1.0, v124
	v_rcp_f32_e32 v122, v122
	v_mul_f32_e32 v114, v120, v114
	v_mul_f32_e32 v120, v127, v121
	v_mul_f32_e32 v119, v120, v119
	v_mul_f32_e32 v120, v123, v122
	v_mul_f32_e32 v122, 0xbfb8aa3b, v108
	v_exp_f32_e32 v122, v122
	v_mul_f32_e32 v123, 0xbfb8aa3b, v104
	v_exp_f32_e32 v123, v123
	v_ashrrev_i32_e32 v153, 31, v152
	v_add_f32_e32 v122, 1.0, v122
	v_rcp_f32_e32 v122, v122
	v_mul_f32_e32 v115, v120, v115
	s_nop 1
	v_cvt_pk_bf16_f32 v116, v116, v117
	s_nop 1
	v_cvt_pk_bf16_f32 v117, v118, v119
	s_nop 1
	v_cvt_pk_bf16_f32 v118, v112, v113
	v_mov_b64_e32 v[112:113], s[48:49]
	s_nop 1
	v_cvt_pk_bf16_f32 v119, v114, v115
	v_mad_i64_i32 v[120:121], s[0:1], v150, s47, v[112:113]
	v_lshlrev_b64 v[114:115], 1, v[152:153]
	v_add_f32_e32 v123, 1.0, v123
	v_mul_f32_e32 v108, v108, v122
	v_lshl_add_u64 v[120:121], v[120:121], 0, v[114:115]
	v_rcp_f32_e32 v123, v123
	v_mul_f32_e32 v100, v108, v100
	v_mul_f32_e32 v108, 0xbfb8aa3b, v109
	global_store_dwordx4 v[120:121], v[116:119], off
	v_exp_f32_e32 v108, v108
	v_mul_f32_e32 v104, v104, v123
	v_mul_f32_e32 v116, 0xbfb8aa3b, v105
	v_exp_f32_e32 v116, v116
	v_mul_f32_e32 v104, v104, v96
	v_add_f32_e32 v96, 1.0, v108
	v_rcp_f32_e32 v96, v96
	v_add_f32_e32 v108, 1.0, v116
	v_mul_f32_e32 v116, 0xbfb8aa3b, v110
	v_rcp_f32_e32 v108, v108
	v_exp_f32_e32 v116, v116
	v_mul_f32_e32 v96, v109, v96
	v_mul_f32_e32 v96, v96, v101
	v_mul_f32_e32 v101, v105, v108
	v_add_f32_e32 v105, 1.0, v116
	v_rcp_f32_e32 v105, v105
	v_mul_f32_e32 v108, 0xbfb8aa3b, v106
	v_exp_f32_e32 v108, v108
	v_mul_f32_e32 v101, v101, v97
	v_mul_f32_e32 v97, v110, v105
	v_mul_f32_e32 v105, 0xbfb8aa3b, v111
	v_mul_f32_e32 v97, v97, v102
	v_add_f32_e32 v102, 1.0, v108
	v_exp_f32_e32 v105, v105
	v_mul_f32_e32 v108, 0xbfb8aa3b, v107
	v_rcp_f32_e32 v102, v102
	v_exp_f32_e32 v108, v108
	v_add_f32_e32 v105, 1.0, v105
	v_rcp_f32_e32 v105, v105
	v_mul_f32_e32 v102, v106, v102
	v_add_f32_e32 v106, 1.0, v108
	v_rcp_f32_e32 v106, v106
	v_mul_f32_e32 v102, v102, v98
	v_mul_f32_e32 v98, v111, v105
	v_mul_f32_e32 v98, v98, v103
	v_mul_f32_e32 v103, v107, v106
	v_mul_f32_e32 v99, v103, v99
	s_nop 1
	v_cvt_pk_bf16_f32 v96, v100, v96
	s_nop 1
	v_cvt_pk_bf16_f32 v97, v97, v98
	s_nop 1
	v_cvt_pk_bf16_f32 v98, v104, v101
	s_nop 1
	v_cvt_pk_bf16_f32 v99, v102, v99
	v_mul_f32_e32 v102, 0xbfb8aa3b, v92
	v_exp_f32_e32 v102, v102
	v_mul_f32_e32 v103, 0xbfb8aa3b, v88
	v_exp_f32_e32 v103, v103
	v_or_b32_e32 v100, 16, v150
	v_add_f32_e32 v102, 1.0, v102
	v_rcp_f32_e32 v102, v102
	v_mad_i64_i32 v[100:101], s[0:1], v100, s47, v[112:113]
	v_add_f32_e32 v103, 1.0, v103
	v_mul_f32_e32 v92, v92, v102
	v_lshl_add_u64 v[100:101], v[100:101], 0, v[114:115]
	v_rcp_f32_e32 v103, v103
	v_mul_f32_e32 v84, v92, v84
	v_mul_f32_e32 v92, 0xbfb8aa3b, v93
	global_store_dwordx4 v[100:101], v[96:99], off
	v_exp_f32_e32 v92, v92
	v_mul_f32_e32 v88, v88, v103
	v_mul_f32_e32 v96, 0xbfb8aa3b, v89
	v_exp_f32_e32 v96, v96
	v_mul_f32_e32 v88, v88, v80
	v_add_f32_e32 v80, 1.0, v92
	v_rcp_f32_e32 v80, v80
	v_add_f32_e32 v92, 1.0, v96
	v_mul_f32_e32 v96, 0xbfb8aa3b, v94
	v_rcp_f32_e32 v92, v92
	v_exp_f32_e32 v96, v96
	v_mul_f32_e32 v80, v93, v80
	v_mul_f32_e32 v80, v80, v85
	v_mul_f32_e32 v85, v89, v92
	v_add_f32_e32 v89, 1.0, v96
	v_rcp_f32_e32 v89, v89
	v_mul_f32_e32 v92, 0xbfb8aa3b, v90
	v_exp_f32_e32 v92, v92
	v_mul_f32_e32 v85, v85, v81
	v_mul_f32_e32 v81, v94, v89
	v_mul_f32_e32 v89, 0xbfb8aa3b, v95
	v_mul_f32_e32 v81, v81, v86
	v_add_f32_e32 v86, 1.0, v92
	v_exp_f32_e32 v89, v89
	v_mul_f32_e32 v92, 0xbfb8aa3b, v91
	v_rcp_f32_e32 v86, v86
	v_exp_f32_e32 v92, v92
	v_add_f32_e32 v89, 1.0, v89
	v_rcp_f32_e32 v89, v89
	v_mul_f32_e32 v86, v90, v86
	v_add_f32_e32 v90, 1.0, v92
	v_rcp_f32_e32 v90, v90
	v_mul_f32_e32 v86, v86, v82
	v_mul_f32_e32 v82, v95, v89
	v_mul_f32_e32 v82, v82, v87
	v_mul_f32_e32 v87, v91, v90
	v_mul_f32_e32 v83, v87, v83
	s_nop 1
	v_cvt_pk_bf16_f32 v80, v84, v80
	s_nop 1
	v_cvt_pk_bf16_f32 v81, v81, v82
	s_nop 1
	v_cvt_pk_bf16_f32 v82, v88, v85
	s_nop 1
	v_cvt_pk_bf16_f32 v83, v86, v83
	v_mul_f32_e32 v86, 0xbfb8aa3b, v76
	v_exp_f32_e32 v86, v86
	v_mul_f32_e32 v87, 0xbfb8aa3b, v72
	v_exp_f32_e32 v87, v87
	v_or_b32_e32 v84, 32, v150
	v_add_f32_e32 v86, 1.0, v86
	v_rcp_f32_e32 v86, v86
	v_mad_i64_i32 v[84:85], s[0:1], v84, s47, v[112:113]
	v_add_f32_e32 v87, 1.0, v87
	v_mul_f32_e32 v76, v76, v86
	v_lshl_add_u64 v[84:85], v[84:85], 0, v[114:115]
	v_rcp_f32_e32 v87, v87
	v_mul_f32_e32 v68, v76, v68
	v_mul_f32_e32 v76, 0xbfb8aa3b, v77
	global_store_dwordx4 v[84:85], v[80:83], off
	v_exp_f32_e32 v76, v76
	v_mul_f32_e32 v72, v72, v87
	v_mul_f32_e32 v80, 0xbfb8aa3b, v73
	v_exp_f32_e32 v80, v80
	v_mul_f32_e32 v72, v72, v64
	v_add_f32_e32 v64, 1.0, v76
	v_rcp_f32_e32 v64, v64
	v_add_f32_e32 v76, 1.0, v80
	v_mul_f32_e32 v80, 0xbfb8aa3b, v78
	v_rcp_f32_e32 v76, v76
	v_exp_f32_e32 v80, v80
	v_mul_f32_e32 v64, v77, v64
	v_mul_f32_e32 v64, v64, v69
	v_mul_f32_e32 v69, v73, v76
	v_add_f32_e32 v73, 1.0, v80
	v_rcp_f32_e32 v73, v73
	v_mul_f32_e32 v76, 0xbfb8aa3b, v74
	v_exp_f32_e32 v76, v76
	v_mul_f32_e32 v69, v69, v65
	v_mul_f32_e32 v65, v78, v73
	v_mul_f32_e32 v73, 0xbfb8aa3b, v79
	v_mul_f32_e32 v65, v65, v70
	v_add_f32_e32 v70, 1.0, v76
	v_exp_f32_e32 v73, v73
	v_mul_f32_e32 v76, 0xbfb8aa3b, v75
	v_rcp_f32_e32 v70, v70
	v_exp_f32_e32 v76, v76
	v_add_f32_e32 v73, 1.0, v73
	v_rcp_f32_e32 v73, v73
	v_mul_f32_e32 v70, v74, v70
	v_add_f32_e32 v74, 1.0, v76
	v_rcp_f32_e32 v74, v74
	v_mul_f32_e32 v70, v70, v66
	v_mul_f32_e32 v66, v79, v73
	v_mul_f32_e32 v66, v66, v71
	v_mul_f32_e32 v71, v75, v74
	v_mul_f32_e32 v67, v71, v67
	s_nop 1
	v_cvt_pk_bf16_f32 v64, v68, v64
	s_nop 1
	v_cvt_pk_bf16_f32 v65, v65, v66
	s_nop 1
	v_cvt_pk_bf16_f32 v66, v72, v69
	s_nop 1
	v_cvt_pk_bf16_f32 v67, v70, v67
	v_mul_f32_e32 v70, 0xbfb8aa3b, v60
	v_exp_f32_e32 v70, v70
	v_or_b32_e32 v68, 48, v150
	v_mad_i64_i32 v[68:69], s[0:1], v68, s47, v[112:113]
	v_lshl_add_u64 v[68:69], v[68:69], 0, v[114:115]
	v_mul_f32_e32 v71, 0xbfb8aa3b, v56
	global_store_dwordx4 v[68:69], v[64:67], off
	v_exp_f32_e32 v71, v71
	s_and_b64 vcc, exec, s[6:7]
	v_add_f32_e32 v64, 1.0, v70
	v_rcp_f32_e32 v64, v64
	v_add_f32_e32 v65, 1.0, v71
	v_rcp_f32_e32 v65, v65
	v_add_u32_e32 v66, 0x80, v150
	v_mul_f32_e32 v60, v60, v64
	v_mul_f32_e32 v52, v60, v52
	v_mul_f32_e32 v60, 0xbfb8aa3b, v61
	v_exp_f32_e32 v60, v60
	v_mul_f32_e32 v64, 0xbfb8aa3b, v57
	v_exp_f32_e32 v64, v64
	v_mul_f32_e32 v56, v56, v65
	v_mul_f32_e32 v56, v56, v48
	v_add_f32_e32 v48, 1.0, v60
	v_rcp_f32_e32 v48, v48
	v_add_f32_e32 v60, 1.0, v64
	v_mul_f32_e32 v64, 0xbfb8aa3b, v62
	v_rcp_f32_e32 v60, v60
	v_exp_f32_e32 v64, v64
	v_mul_f32_e32 v48, v61, v48
	v_mul_f32_e32 v48, v48, v53
	v_mul_f32_e32 v53, v57, v60
	v_add_f32_e32 v57, 1.0, v64
	v_rcp_f32_e32 v57, v57
	v_mul_f32_e32 v60, 0xbfb8aa3b, v58
	v_exp_f32_e32 v60, v60
	v_mul_f32_e32 v53, v53, v49
	v_mul_f32_e32 v49, v62, v57
	v_mul_f32_e32 v57, 0xbfb8aa3b, v63
	v_mul_f32_e32 v49, v49, v54
	v_add_f32_e32 v54, 1.0, v60
	v_exp_f32_e32 v57, v57
	v_mul_f32_e32 v60, 0xbfb8aa3b, v59
	v_rcp_f32_e32 v54, v54
	v_exp_f32_e32 v60, v60
	v_add_f32_e32 v57, 1.0, v57
	v_rcp_f32_e32 v57, v57
	v_mul_f32_e32 v54, v58, v54
	v_add_f32_e32 v58, 1.0, v60
	v_rcp_f32_e32 v58, v58
	v_mul_f32_e32 v54, v54, v50
	v_mul_f32_e32 v50, v63, v57
	v_mul_f32_e32 v50, v50, v55
	v_mul_f32_e32 v55, v59, v58
	v_mul_f32_e32 v51, v55, v51
	s_nop 1
	v_cvt_pk_bf16_f32 v48, v52, v48
	s_nop 1
	v_cvt_pk_bf16_f32 v49, v49, v50
	s_nop 1
	v_cvt_pk_bf16_f32 v50, v56, v53
	s_nop 1
	v_cvt_pk_bf16_f32 v51, v54, v51
	v_mul_f32_e32 v54, 0xbfb8aa3b, v44
	v_exp_f32_e32 v54, v54
	v_mul_f32_e32 v55, 0xbfb8aa3b, v40
	v_exp_f32_e32 v55, v55
	v_mad_i64_i32 v[52:53], s[0:1], v66, s47, v[112:113]
	v_add_f32_e32 v54, 1.0, v54
	v_rcp_f32_e32 v54, v54
	v_add_f32_e32 v55, 1.0, v55
	v_lshl_add_u64 v[52:53], v[52:53], 0, v[114:115]
	v_rcp_f32_e32 v55, v55
	v_mul_f32_e32 v44, v44, v54
	v_mul_f32_e32 v36, v44, v36
	v_mul_f32_e32 v44, 0xbfb8aa3b, v45
	global_store_dwordx4 v[52:53], v[48:51], off
	v_exp_f32_e32 v44, v44
	v_mul_f32_e32 v40, v40, v55
	v_mul_f32_e32 v48, 0xbfb8aa3b, v41
	v_exp_f32_e32 v48, v48
	v_mul_f32_e32 v40, v40, v32
	v_add_f32_e32 v32, 1.0, v44
	v_rcp_f32_e32 v32, v32
	v_add_f32_e32 v44, 1.0, v48
	v_mul_f32_e32 v48, 0xbfb8aa3b, v46
	v_rcp_f32_e32 v44, v44
	v_exp_f32_e32 v48, v48
	v_mul_f32_e32 v32, v45, v32
	v_mul_f32_e32 v32, v32, v37
	v_mul_f32_e32 v37, v41, v44
	v_add_f32_e32 v41, 1.0, v48
	v_rcp_f32_e32 v41, v41
	v_mul_f32_e32 v44, 0xbfb8aa3b, v42
	v_exp_f32_e32 v44, v44
	v_mul_f32_e32 v37, v37, v33
	v_mul_f32_e32 v33, v46, v41
	v_mul_f32_e32 v41, 0xbfb8aa3b, v47
	v_mul_f32_e32 v33, v33, v38
	v_add_f32_e32 v38, 1.0, v44
	v_exp_f32_e32 v41, v41
	v_mul_f32_e32 v44, 0xbfb8aa3b, v43
	v_rcp_f32_e32 v38, v38
	v_exp_f32_e32 v44, v44
	v_add_f32_e32 v41, 1.0, v41
	v_rcp_f32_e32 v41, v41
	v_mul_f32_e32 v38, v42, v38
	v_add_f32_e32 v42, 1.0, v44
	v_rcp_f32_e32 v42, v42
	v_mul_f32_e32 v38, v38, v34
	v_mul_f32_e32 v34, v47, v41
	v_mul_f32_e32 v34, v34, v39
	v_mul_f32_e32 v39, v43, v42
	v_mul_f32_e32 v35, v39, v35
	s_nop 1
	v_cvt_pk_bf16_f32 v32, v36, v32
	s_nop 1
	v_cvt_pk_bf16_f32 v33, v33, v34
	s_nop 1
	v_cvt_pk_bf16_f32 v34, v40, v37
	s_nop 1
	v_cvt_pk_bf16_f32 v35, v38, v35
	v_mul_f32_e32 v38, 0xbfb8aa3b, v28
	v_exp_f32_e32 v38, v38
	v_mul_f32_e32 v39, 0xbfb8aa3b, v24
	v_exp_f32_e32 v39, v39
	v_add_u32_e32 v36, 0x90, v150
	v_add_f32_e32 v38, 1.0, v38
	v_rcp_f32_e32 v38, v38
	v_mad_i64_i32 v[36:37], s[0:1], v36, s47, v[112:113]
	v_add_f32_e32 v39, 1.0, v39
	v_mul_f32_e32 v28, v28, v38
	v_lshl_add_u64 v[36:37], v[36:37], 0, v[114:115]
	v_rcp_f32_e32 v39, v39
	v_mul_f32_e32 v20, v28, v20
	v_mul_f32_e32 v28, 0xbfb8aa3b, v29
	global_store_dwordx4 v[36:37], v[32:35], off
	v_exp_f32_e32 v28, v28
	v_mul_f32_e32 v24, v24, v39
	v_mul_f32_e32 v32, 0xbfb8aa3b, v25
	v_exp_f32_e32 v32, v32
	v_mul_f32_e32 v24, v24, v16
	v_add_f32_e32 v16, 1.0, v28
	v_rcp_f32_e32 v16, v16
	v_add_f32_e32 v28, 1.0, v32
	v_mul_f32_e32 v32, 0xbfb8aa3b, v30
	v_rcp_f32_e32 v28, v28
	v_exp_f32_e32 v32, v32
	v_mul_f32_e32 v16, v29, v16
	v_mul_f32_e32 v16, v16, v21
	v_mul_f32_e32 v21, v25, v28
	v_add_f32_e32 v25, 1.0, v32
	v_rcp_f32_e32 v25, v25
	v_mul_f32_e32 v28, 0xbfb8aa3b, v26
	v_exp_f32_e32 v28, v28
	v_mul_f32_e32 v21, v21, v17
	v_mul_f32_e32 v17, v30, v25
	v_mul_f32_e32 v25, 0xbfb8aa3b, v31
	v_mul_f32_e32 v17, v17, v22
	v_add_f32_e32 v22, 1.0, v28
	v_exp_f32_e32 v25, v25
	v_mul_f32_e32 v28, 0xbfb8aa3b, v27
	v_rcp_f32_e32 v22, v22
	v_exp_f32_e32 v28, v28
	v_add_f32_e32 v25, 1.0, v25
	v_rcp_f32_e32 v25, v25
	v_mul_f32_e32 v22, v26, v22
	v_add_f32_e32 v26, 1.0, v28
	v_rcp_f32_e32 v26, v26
	v_mul_f32_e32 v22, v22, v18
	v_mul_f32_e32 v18, v31, v25
	v_mul_f32_e32 v18, v18, v23
	v_mul_f32_e32 v23, v27, v26
	v_mul_f32_e32 v19, v23, v19
	s_nop 1
	v_cvt_pk_bf16_f32 v16, v20, v16
	s_nop 1
	v_cvt_pk_bf16_f32 v17, v17, v18
	s_nop 1
	v_cvt_pk_bf16_f32 v18, v24, v21
	s_nop 1
	v_cvt_pk_bf16_f32 v19, v22, v19
	v_mul_f32_e32 v22, 0xbfb8aa3b, v12
	v_exp_f32_e32 v22, v22
	v_mul_f32_e32 v23, 0xbfb8aa3b, v8
	v_exp_f32_e32 v23, v23
	v_add_u32_e32 v20, 0xa0, v150
	v_add_f32_e32 v22, 1.0, v22
	v_rcp_f32_e32 v22, v22
	v_mad_i64_i32 v[20:21], s[0:1], v20, s47, v[112:113]
	v_add_f32_e32 v23, 1.0, v23
	v_mul_f32_e32 v12, v12, v22
	v_lshl_add_u64 v[20:21], v[20:21], 0, v[114:115]
	v_rcp_f32_e32 v23, v23
	v_mul_f32_e32 v4, v12, v4
	v_mul_f32_e32 v12, 0xbfb8aa3b, v13
	global_store_dwordx4 v[20:21], v[16:19], off
	v_exp_f32_e32 v12, v12
	v_mul_f32_e32 v8, v8, v23
	v_mul_f32_e32 v16, 0xbfb8aa3b, v9
	v_exp_f32_e32 v16, v16
	v_mul_f32_e32 v8, v8, v0
	v_add_f32_e32 v0, 1.0, v12
	v_rcp_f32_e32 v0, v0
	v_add_f32_e32 v12, 1.0, v16
	v_mul_f32_e32 v16, 0xbfb8aa3b, v14
	v_rcp_f32_e32 v12, v12
	v_exp_f32_e32 v16, v16
	v_mul_f32_e32 v0, v13, v0
	v_mul_f32_e32 v0, v0, v5
	v_mul_f32_e32 v5, v9, v12
	v_add_f32_e32 v9, 1.0, v16
	v_rcp_f32_e32 v9, v9
	v_mul_f32_e32 v12, 0xbfb8aa3b, v10
	v_exp_f32_e32 v12, v12
	v_mul_f32_e32 v5, v5, v1
	v_mul_f32_e32 v1, v14, v9
	v_mul_f32_e32 v9, 0xbfb8aa3b, v15
	v_exp_f32_e32 v9, v9
	v_mul_f32_e32 v1, v1, v6
	v_add_f32_e32 v6, 1.0, v12
	v_mul_f32_e32 v12, 0xbfb8aa3b, v11
	v_rcp_f32_e32 v6, v6
	v_exp_f32_e32 v12, v12
	v_add_f32_e32 v9, 1.0, v9
	v_rcp_f32_e32 v9, v9
	v_mul_f32_e32 v6, v10, v6
	v_add_f32_e32 v10, 1.0, v12
	v_rcp_f32_e32 v10, v10
	v_mul_f32_e32 v6, v6, v2
	v_mul_f32_e32 v2, v15, v9
	v_mul_f32_e32 v2, v2, v7
	s_nop 1
	v_cvt_pk_bf16_f32 v0, v4, v0
	v_add_u32_e32 v4, 0xb0, v150
	v_mul_f32_e32 v7, v11, v10
	s_nop 1
	v_cvt_pk_bf16_f32 v1, v1, v2
	s_nop 1
	v_cvt_pk_bf16_f32 v2, v8, v5
	v_mad_i64_i32 v[4:5], s[0:1], v4, s47, v[112:113]
	v_mul_f32_e32 v3, v7, v3
	v_lshl_add_u64 v[4:5], v[4:5], 0, v[114:115]
	s_mov_b32 s50, s10
	s_mov_b32 s18, s12
	s_mov_b64 s[44:45], s[16:17]
	s_mov_b64 s[20:21], s[14:15]
	s_nop 1
	v_cvt_pk_bf16_f32 v3, v6, v3
	global_store_dwordx4 v[4:5], v[0:3], off
	s_cbranch_vccz .LBB0_1673
	s_waitcnt vmcnt(0)
	s_cmpk_gt_u32 s23, 0xff
	s_cbranch_scc1 .LBB0_1680
	s_barrier

.LBB0_1681:
	s_waitcnt vmcnt(0)
	s_waitcnt vmcnt(0) lgkmcnt(0)
	s_setprio 0
	s_barrier
	s_mov_b64 s[0:1], exec
	v_readlane_b32 s4, v255, 4
	v_readlane_b32 s5, v255, 5
	s_and_b64 s[4:5], s[0:1], s[4:5]
	s_xor_b64 s[6:7], s[4:5], s[0:1]
	s_mov_b64 exec, s[4:5]
	s_cbranch_execz .LBB0_1734
	s_add_i32 s0, 0, 0x25800
	v_mov_b32_e32 v0, s0
	s_waitcnt vmcnt(0) expcnt(0) lgkmcnt(0)
	ds_read_b32 v2, v0
	s_add_i32 s0, 0, 0x25804
	v_mov_b32_e32 v0, s0
	ds_read_b32 v0, v0
	s_waitcnt lgkmcnt(1)
	v_cmp_ne_u32_e32 vcc, 0, v2
	s_cbranch_vccnz .LBB0_1697
	s_add_u32 s8, s26, 0xc0200
	s_addc_u32 s9, s27, 0
	s_add_u32 s4, s26, 0xc0400
	s_addc_u32 s5, s27, 0
	s_add_u32 s10, s26, 0xc0500
	s_addc_u32 s11, s27, 0
	s_add_u32 s12, s26, 0xc0600
	s_addc_u32 s13, s27, 0
	s_add_u32 s14, s26, 0xc0700
	s_addc_u32 s15, s27, 0
	s_add_u32 s16, s26, 0xc0800
	s_addc_u32 s17, s27, 0
	s_add_u32 s18, s26, 0xc0900
	s_addc_u32 s19, s27, 0
	s_add_u32 s20, s26, 0xc0a00
	s_addc_u32 s21, s27, 0
	s_add_u32 s36, s26, 0xc0b00
	s_addc_u32 s37, s27, 0
	s_add_u32 s38, s26, 0xc0c00
	s_addc_u32 s39, s27, 0
	s_add_u32 s42, s26, 0xc0d00
	s_addc_u32 s43, s27, 0
	s_add_u32 s44, s26, 0xc0e00
	s_addc_u32 s45, s27, 0
	s_add_u32 s46, s26, 0xc0f00
	s_addc_u32 s47, s27, 0
	s_add_u32 s50, s26, 0xc1000
	s_addc_u32 s51, s27, 0
	s_add_u32 s52, s26, 0xc1100
	s_addc_u32 s53, s27, 0
	s_add_u32 s54, s26, 0xc1200
	v_readlane_b32 s0, v255, 0
	s_addc_u32 s55, s27, 0
	s_mul_i32 s23, s31, s0
	s_add_u32 s56, s26, 0xc1300
	s_mul_i32 s23, s23, s30
	s_addc_u32 s57, s27, 0
	s_mov_b32 s24, 1
	v_mov_b32_e32 v16, 0
	s_branch .LBB0_1685

.Lprio_skip17:
	s_and_b64 vcc, exec, s[0:1]
	v_readfirstlane_b32 s23, v8
	s_cbranch_vccz .LBB0_1754
	v_lshlrev_b32_e32 v0, 4, v8
	v_add_u32_e32 v1, 0x2000, v0
	v_ashrrev_i32_e32 v2, 31, v1
	v_lshrrev_b32_e32 v2, 22, v2
	v_add_u32_e32 v2, v1, v2
	v_ashrrev_i32_e32 v9, 10, v2
	v_mul_i32_i24_e32 v2, 0x400, v9
	v_sub_u32_e32 v1, v1, v2
	v_lshrrev_b32_e32 v2, 4, v1
	v_bitop3_b32 v1, v2, v1, 32 bitop3:0x6c
	v_ashrrev_i32_e32 v2, 31, v1
	v_lshrrev_b32_e32 v2, 26, v2
	v_add_u32_e32 v2, v1, v2
	s_lshr_b32 s5, s3, 29
	v_ashrrev_i32_e32 v10, 6, v2
	v_and_b32_e32 v2, 0xc0, v2
	s_add_i32 s5, s2, s5
	v_sub_u32_e32 v1, v1, v2
	v_mov_b32_e32 v2, 1
	s_ashr_i32 s6, s5, 3
	s_and_b32 s5, s5, -8
	s_ashr_i32 s4, s23, 6
	v_ashrrev_i16_sdwa v1, v2, sext(v1) dst_sel:DWORD dst_unused:UNUSED_PAD src0_sel:DWORD src1_sel:BYTE_0
	s_sub_i32 s5, s2, s5
	s_ashr_i32 s1, s23, 8
	s_lshl_b32 s24, s4, 10
	v_bfe_i32 v12, v1, 0, 16
	v_bfe_i32 v1, v8, 27, 1
	s_lshl_b32 s8, s5, 5
	v_lshrrev_b32_e32 v1, 22, v1
	s_mul_i32 s7, s5, 33
	s_cmp_lt_i32 s5, 0
	v_add_u32_e32 v1, v0, v1
	s_cselect_b32 s5, s7, s8
	v_and_b32_e32 v1, 0xfffffc00, v1
	s_add_i32 s5, s5, s6
	v_sub_u32_e32 v0, v0, v1
	s_ashr_i32 s6, s5, 31
	v_lshrrev_b32_e32 v1, 4, v0
	s_lshr_b32 s6, s6, 26
	v_bitop3_b32 v1, v1, v0, 32 bitop3:0x6c
	v_ashrrev_i32_e32 v0, 31, v0
	s_add_i32 s6, s5, s6
	v_lshrrev_b32_e32 v0, 26, v0
	s_ashr_i32 s7, s6, 6
	s_and_b32 s6, s6, 0xffc0
	v_lshlrev_b32_e32 v3, 3, v9
	v_add_u32_e32 v0, v1, v0
	s_sub_i32 s6, s5, s6
	v_and_b32_e32 v3, 0x7ffff0, v3
	v_ashrrev_i32_e32 v13, 6, v0
	v_ashrrev_i32_e32 v0, 31, v8
	s_bfe_i32 s5, s6, 0x80000
	v_add_u32_e32 v3, v10, v3
	s_movk_i32 s0, 0x1600
	v_lshlrev_b32_e32 v4, 5, v9
	v_lshrrev_b32_e32 v0, 26, v0
	s_bfe_u32 s5, s5, 0x3000c
	v_mul_lo_u32 v3, v3, s0
	v_and_b32_e32 v11, 32, v4
	v_add_u32_e32 v0, v8, v0
	s_add_i32 s8, s6, s5
	v_or_b32_e32 v3, v3, v11
	v_ashrrev_i32_e32 v14, 6, v0
	s_bfe_i32 s5, s8, 0x80000
	s_and_b32 s8, s8, 0xf8
	v_add_lshl_u32 v164, v3, v12, 1
	v_lshlrev_b32_e32 v0, 3, v14
	v_lshlrev_b32_e32 v3, 5, v14
	s_sext_i32_i16 s9, s5
	s_sub_i32 s6, s6, s8
	v_and_b32_e32 v0, 0x7ffff0, v0
	v_and_b32_e32 v15, 32, v3
	v_mul_i32_i24_e32 v3, 64, v13
	s_lshl_b32 s7, s7, 3
	s_sext_i32_i8 s6, s6
	s_ashr_i32 s8, s9, 3
	v_add_u32_e32 v0, v13, v0
	v_sub_u32_e32 v1, v1, v3
	s_lshr_b32 s5, s9, 3
	s_add_i32 s59, s7, s6
	s_mul_hi_i32 s9, s8, 0x2c0000
	s_mul_i32 s8, s8, 0x2c0000
	v_readlane_b32 s10, v255, 22
	v_mul_lo_u32 v0, v0, s0
	v_ashrrev_i16_sdwa v1, v2, sext(v1) dst_sel:DWORD dst_unused:UNUSED_PAD src0_sel:DWORD src1_sel:BYTE_0
	v_readlane_b32 s11, v255, 23
	s_add_u32 s44, s10, s8
	v_or_b32_e32 v0, v0, v15
	v_bfe_i32 v16, v1, 0, 16
	s_addc_u32 s45, s11, s9
	s_add_i32 s25, s24, 0
	v_add_lshl_u32 v166, v0, v16, 1
	s_add_i32 m0, s25, 0x10000
	s_mul_i32 s7, s59, 0x2c0000
	global_load_lds_dwordx4 v166, s[44:45]
	s_add_i32 m0, s25, 0x12000
	s_mul_hi_i32 s6, s59, 0x2c0000
	s_add_u32 s42, s48, s7
	global_load_lds_dwordx4 v164, s[44:45]
	s_addc_u32 s43, s49, s6
	s_mov_b32 m0, s25
	s_add_i32 s28, s25, 0x2000
	global_load_lds_dwordx4 v166, s[42:43]
	s_mov_b32 m0, s28
	s_add_u32 s6, s44, 0x160000
	global_load_lds_dwordx4 v164, s[42:43]
	s_addc_u32 s7, s45, 0
	s_add_i32 m0, s25, 0x14000
	s_load_dwordx2 s[12:13], s[88:89], 0x168
	global_load_lds_dwordx4 v166, s[6:7]
	s_add_i32 m0, s25, 0x16000
	v_mov_b32_e32 v167, 0
	global_load_lds_dwordx4 v164, s[6:7]
	s_add_u32 s6, s42, 0x160000
	s_addc_u32 s7, s43, 0
	s_add_i32 s29, s25, 0x4000
	s_mov_b32 m0, s29
	s_add_i32 s33, s25, 0x6000
	global_load_lds_dwordx4 v166, s[6:7]
	s_mov_b32 m0, s33
	v_mov_b32_e32 v165, v167
	global_load_lds_dwordx4 v164, s[6:7]
	s_mov_b32 s40, 0
	v_lshl_add_u64 v[6:7], s[44:45], 0, v[166:167]
	v_lshl_add_u64 v[4:5], s[44:45], 0, v[164:165]
	v_lshl_add_u64 v[2:3], s[42:43], 0, v[166:167]
	v_lshl_add_u64 v[0:1], s[42:43], 0, v[164:165]
	s_mov_b64 s[14:15], 0x160000
	s_cmp_lg_u32 s1, 1
	s_mov_b32 s6, 0x16000
	s_cbranch_scc1 .LBB0_1737
	s_barrier

.LBB0_1749:
	ds_read_b128 v[128:131], v221
	ds_read_b128 v[132:135], v221 offset:1024
	ds_read_b128 v[136:139], v221 offset:2048
	ds_read_b128 v[140:143], v221 offset:3072
	s_add_u32 s44, s42, 0x100
	s_addc_u32 s45, s43, 0
	s_cmpk_eq_i32 s61, 0x54
	s_cselect_b32 s5, s9, s45
	s_cselect_b32 s4, s8, s44
	s_cselect_b32 s47, s11, s1
	s_cselect_b32 s46, s10, s0
	v_lshl_add_u64 v[188:189], s[42:43], 0, v[168:169]
	s_add_i32 m0, s25, 0xc000
	ds_read_b128 v[144:147], v222
	ds_read_b128 v[148:151], v222 offset:1024
	ds_read_b128 v[152:155], v222 offset:2048
	ds_read_b128 v[156:159], v222 offset:3072
	ds_read_b128 v[160:163], v222 offset:4096
	ds_read_b128 v[176:179], v222 offset:5120
	ds_read_b128 v[180:183], v222 offset:6144
	ds_read_b128 v[184:187], v222 offset:7168
	global_load_lds_dwordx4 v[188:189], off
	v_lshl_add_u64 v[188:189], s[42:43], 0, v[170:171]
	s_add_i32 m0, s25, 0xe000
	s_nop 0
	global_load_lds_dwordx4 v[188:189], off
	s_waitcnt lgkmcnt(8)
	s_barrier
	s_waitcnt lgkmcnt(0)
	s_waitcnt lgkmcnt(0)
	v_mfma_f32_16x16x32_bf16 v[124:127], v[128:131], v[144:147], v[124:127]
	v_mfma_f32_16x16x32_bf16 v[100:103], v[136:139], v[144:147], v[100:103]
	v_mfma_f32_16x16x32_bf16 v[120:123], v[128:131], v[152:155], v[120:123]
	v_mfma_f32_16x16x32_bf16 v[96:99], v[136:139], v[152:155], v[96:99]
	v_mfma_f32_16x16x32_bf16 v[116:119], v[128:131], v[160:163], v[116:119]
	v_mfma_f32_16x16x32_bf16 v[92:95], v[136:139], v[160:163], v[92:95]
	v_mfma_f32_16x16x32_bf16 v[112:115], v[128:131], v[180:183], v[112:115]
	v_mfma_f32_16x16x32_bf16 v[84:87], v[136:139], v[180:183], v[84:87]
	v_mfma_f32_16x16x32_bf16 v[124:127], v[132:135], v[148:151], v[124:127]
	v_mfma_f32_16x16x32_bf16 v[100:103], v[140:143], v[148:151], v[100:103]
	v_mfma_f32_16x16x32_bf16 v[120:123], v[132:135], v[156:159], v[120:123]
	v_mfma_f32_16x16x32_bf16 v[96:99], v[140:143], v[156:159], v[96:99]
	v_mfma_f32_16x16x32_bf16 v[116:119], v[132:135], v[176:179], v[116:119]
	v_mfma_f32_16x16x32_bf16 v[92:95], v[140:143], v[176:179], v[92:95]
	v_mfma_f32_16x16x32_bf16 v[112:115], v[132:135], v[184:187], v[112:115]
	v_mfma_f32_16x16x32_bf16 v[84:87], v[140:143], v[184:187], v[84:87]
	s_barrier
	s_add_i32 s42, s51, s24
	v_lshl_add_u64 v[204:205], s[46:47], 0, v[166:167]
	s_mov_b32 m0, s42
	ds_read_b128 v[188:191], v223
	ds_read_b128 v[192:195], v223 offset:1024
	ds_read_b128 v[196:199], v223 offset:2048
	ds_read_b128 v[200:203], v223 offset:3072
	global_load_lds_dwordx4 v[204:205], off
	v_lshl_add_u64 v[206:207], s[46:47], 0, v[164:165]
	s_add_i32 m0, s42, 0x2000
	s_nop 0
	global_load_lds_dwordx4 v[206:207], off
	s_barrier
	s_waitcnt lgkmcnt(0)
	s_waitcnt lgkmcnt(0)
	v_mfma_f32_16x16x32_bf16 v[72:75], v[188:191], v[144:147], v[72:75]
	v_mfma_f32_16x16x32_bf16 v[44:47], v[196:199], v[144:147], v[44:47]
	v_mfma_f32_16x16x32_bf16 v[64:67], v[188:191], v[152:155], v[64:67]
	v_mfma_f32_16x16x32_bf16 v[40:43], v[196:199], v[152:155], v[40:43]
	v_mfma_f32_16x16x32_bf16 v[56:59], v[188:191], v[160:163], v[56:59]
	v_mfma_f32_16x16x32_bf16 v[36:39], v[196:199], v[160:163], v[36:39]
	v_mfma_f32_16x16x32_bf16 v[48:51], v[188:191], v[180:183], v[48:51]
	v_mfma_f32_16x16x32_bf16 v[28:31], v[196:199], v[180:183], v[28:31]
	v_mfma_f32_16x16x32_bf16 v[72:75], v[192:195], v[148:151], v[72:75]
	v_mfma_f32_16x16x32_bf16 v[44:47], v[200:203], v[148:151], v[44:47]
	v_mfma_f32_16x16x32_bf16 v[64:67], v[192:195], v[156:159], v[64:67]
	v_mfma_f32_16x16x32_bf16 v[40:43], v[200:203], v[156:159], v[40:43]
	v_mfma_f32_16x16x32_bf16 v[56:59], v[192:195], v[176:179], v[56:59]
	v_mfma_f32_16x16x32_bf16 v[36:39], v[200:203], v[176:179], v[36:39]
	v_mfma_f32_16x16x32_bf16 v[48:51], v[192:195], v[184:187], v[48:51]
	v_mfma_f32_16x16x32_bf16 v[28:31], v[200:203], v[184:187], v[28:31]
	s_mov_b32 m0, s25
	v_lshl_add_u64 v[208:209], s[4:5], 0, v[166:167]
	s_barrier
	ds_read_b128 v[144:147], v222 offset:16384
	ds_read_b128 v[148:151], v222 offset:17408
	ds_read_b128 v[152:155], v222 offset:18432
	ds_read_b128 v[156:159], v222 offset:19456
	ds_read_b128 v[160:163], v222 offset:20480
	ds_read_b128 v[176:179], v222 offset:21504
	ds_read_b128 v[180:183], v222 offset:22528
	ds_read_b128 v[184:187], v222 offset:23552
	global_load_lds_dwordx4 v[208:209], off
	v_lshl_add_u64 v[210:211], s[4:5], 0, v[164:165]
	s_mov_b32 m0, s28
	s_nop 0
	global_load_lds_dwordx4 v[210:211], off
	s_barrier
	s_waitcnt lgkmcnt(0)
	s_waitcnt lgkmcnt(0)
	v_mfma_f32_16x16x32_bf16 v[108:111], v[128:131], v[144:147], v[108:111]
	v_mfma_f32_16x16x32_bf16 v[76:79], v[136:139], v[144:147], v[76:79]
	v_mfma_f32_16x16x32_bf16 v[104:107], v[128:131], v[152:155], v[104:107]
	v_mfma_f32_16x16x32_bf16 v[68:71], v[136:139], v[152:155], v[68:71]
	v_mfma_f32_16x16x32_bf16 v[88:91], v[128:131], v[160:163], v[88:91]
	v_mfma_f32_16x16x32_bf16 v[60:63], v[136:139], v[160:163], v[60:63]
	v_mfma_f32_16x16x32_bf16 v[80:83], v[128:131], v[180:183], v[80:83]
	v_mfma_f32_16x16x32_bf16 v[52:55], v[136:139], v[180:183], v[52:55]
	v_mfma_f32_16x16x32_bf16 v[108:111], v[132:135], v[148:151], v[108:111]
	v_mfma_f32_16x16x32_bf16 v[76:79], v[140:143], v[148:151], v[76:79]
	v_mfma_f32_16x16x32_bf16 v[104:107], v[132:135], v[156:159], v[104:107]
	v_mfma_f32_16x16x32_bf16 v[68:71], v[140:143], v[156:159], v[68:71]
	v_mfma_f32_16x16x32_bf16 v[88:91], v[132:135], v[176:179], v[88:91]
	v_mfma_f32_16x16x32_bf16 v[60:63], v[140:143], v[176:179], v[60:63]
	v_mfma_f32_16x16x32_bf16 v[80:83], v[132:135], v[184:187], v[80:83]
	v_mfma_f32_16x16x32_bf16 v[52:55], v[140:143], v[184:187], v[52:55]
	s_barrier
	s_add_u32 s42, s46, 0x160000
	s_addc_u32 s43, s47, 0
	s_add_i32 s62, s52, s24
	v_lshl_add_u64 v[128:129], s[42:43], 0, v[166:167]
	s_mov_b32 m0, s62
	s_nop 0
	global_load_lds_dwordx4 v[128:129], off
	v_lshl_add_u64 v[128:129], s[42:43], 0, v[164:165]
	s_add_i32 m0, s62, 0x2000
	s_nop 0
	global_load_lds_dwordx4 v[128:129], off
	s_waitcnt vmcnt(6)
	s_barrier
	v_mfma_f32_16x16x32_bf16 v[32:35], v[188:191], v[144:147], v[32:35]
	v_mfma_f32_16x16x32_bf16 v[12:15], v[196:199], v[144:147], v[12:15]
	v_mfma_f32_16x16x32_bf16 v[24:27], v[188:191], v[152:155], v[24:27]
	v_mfma_f32_16x16x32_bf16 v[8:11], v[196:199], v[152:155], v[8:11]
	v_mfma_f32_16x16x32_bf16 v[20:23], v[188:191], v[160:163], v[20:23]
	v_mfma_f32_16x16x32_bf16 v[4:7], v[196:199], v[160:163], v[4:7]
	v_mfma_f32_16x16x32_bf16 v[16:19], v[188:191], v[180:183], v[16:19]
	v_mfma_f32_16x16x32_bf16 v[0:3], v[196:199], v[180:183], v[0:3]
	v_mfma_f32_16x16x32_bf16 v[32:35], v[192:195], v[148:151], v[32:35]
	v_mfma_f32_16x16x32_bf16 v[12:15], v[200:203], v[148:151], v[12:15]
	v_mfma_f32_16x16x32_bf16 v[24:27], v[192:195], v[156:159], v[24:27]
	v_mfma_f32_16x16x32_bf16 v[8:11], v[200:203], v[156:159], v[8:11]
	v_mfma_f32_16x16x32_bf16 v[20:23], v[192:195], v[176:179], v[20:23]
	v_mfma_f32_16x16x32_bf16 v[4:7], v[200:203], v[176:179], v[4:7]
	v_mfma_f32_16x16x32_bf16 v[16:19], v[192:195], v[184:187], v[16:19]
	v_mfma_f32_16x16x32_bf16 v[0:3], v[200:203], v[184:187], v[0:3]
	s_add_i32 s42, 0, 0x18000
	v_add_u32_e32 v140, s42, v219
	s_barrier
	ds_read_b128 v[128:131], v140
	ds_read_b128 v[132:135], v140 offset:1024
	ds_read_b128 v[136:139], v140 offset:2048
	ds_read_b128 v[140:143], v140 offset:3072
	s_add_u32 s4, s4, 0x160000
	s_addc_u32 s5, s5, 0
	s_mov_b32 m0, s29
	v_lshl_add_u64 v[188:189], s[4:5], 0, v[166:167]
	ds_read_b128 v[144:147], v222 offset:32768
	ds_read_b128 v[148:151], v222 offset:33792
	ds_read_b128 v[152:155], v222 offset:34816
	ds_read_b128 v[156:159], v222 offset:35840
	ds_read_b128 v[160:163], v222 offset:36864
	ds_read_b128 v[176:179], v222 offset:37888
	ds_read_b128 v[180:183], v222 offset:38912
	ds_read_b128 v[184:187], v222 offset:39936
	global_load_lds_dwordx4 v[188:189], off
	v_lshl_add_u64 v[188:189], s[4:5], 0, v[164:165]
	s_mov_b32 m0, s33
	s_nop 0
	global_load_lds_dwordx4 v[188:189], off
	s_waitcnt lgkmcnt(8)
	s_barrier
	s_waitcnt lgkmcnt(0)
	s_waitcnt lgkmcnt(0)
	v_mfma_f32_16x16x32_bf16 v[124:127], v[128:131], v[144:147], v[124:127]
	v_mfma_f32_16x16x32_bf16 v[100:103], v[136:139], v[144:147], v[100:103]
	v_mfma_f32_16x16x32_bf16 v[120:123], v[128:131], v[152:155], v[120:123]
	v_mfma_f32_16x16x32_bf16 v[96:99], v[136:139], v[152:155], v[96:99]
	v_mfma_f32_16x16x32_bf16 v[116:119], v[128:131], v[160:163], v[116:119]
	v_mfma_f32_16x16x32_bf16 v[92:95], v[136:139], v[160:163], v[92:95]
	v_mfma_f32_16x16x32_bf16 v[112:115], v[128:131], v[180:183], v[112:115]
	v_mfma_f32_16x16x32_bf16 v[84:87], v[136:139], v[180:183], v[84:87]
	v_mfma_f32_16x16x32_bf16 v[124:127], v[132:135], v[148:151], v[124:127]
	v_mfma_f32_16x16x32_bf16 v[100:103], v[140:143], v[148:151], v[100:103]
	v_mfma_f32_16x16x32_bf16 v[120:123], v[132:135], v[156:159], v[120:123]
	v_mfma_f32_16x16x32_bf16 v[96:99], v[140:143], v[156:159], v[96:99]
	v_mfma_f32_16x16x32_bf16 v[116:119], v[132:135], v[176:179], v[116:119]
	v_mfma_f32_16x16x32_bf16 v[92:95], v[140:143], v[176:179], v[92:95]
	v_mfma_f32_16x16x32_bf16 v[112:115], v[132:135], v[184:187], v[112:115]
	v_mfma_f32_16x16x32_bf16 v[84:87], v[140:143], v[184:187], v[84:87]
	s_barrier
	s_add_i32 s43, 0, 0x1c000
	s_add_i32 s4, s42, s24
	v_add_u32_e32 v200, s43, v219
	v_lshl_add_u64 v[204:205], v[204:205], 0, s[18:19]
	s_mov_b32 m0, s4
	ds_read_b128 v[188:191], v200
	ds_read_b128 v[192:195], v200 offset:1024
	ds_read_b128 v[196:199], v200 offset:2048
	ds_read_b128 v[200:203], v200 offset:3072
	global_load_lds_dwordx4 v[204:205], off
	v_lshl_add_u64 v[204:205], v[206:207], 0, s[18:19]
	s_add_i32 m0, s4, 0x2000
	s_nop 0
	global_load_lds_dwordx4 v[204:205], off
	s_barrier
	s_waitcnt lgkmcnt(0)
	s_waitcnt lgkmcnt(0)
	v_mfma_f32_16x16x32_bf16 v[72:75], v[188:191], v[144:147], v[72:75]
	v_mfma_f32_16x16x32_bf16 v[44:47], v[196:199], v[144:147], v[44:47]
	v_mfma_f32_16x16x32_bf16 v[64:67], v[188:191], v[152:155], v[64:67]
	v_mfma_f32_16x16x32_bf16 v[40:43], v[196:199], v[152:155], v[40:43]
	v_mfma_f32_16x16x32_bf16 v[56:59], v[188:191], v[160:163], v[56:59]
	v_mfma_f32_16x16x32_bf16 v[36:39], v[196:199], v[160:163], v[36:39]
	v_mfma_f32_16x16x32_bf16 v[48:51], v[188:191], v[180:183], v[48:51]
	v_mfma_f32_16x16x32_bf16 v[28:31], v[196:199], v[180:183], v[28:31]
	v_mfma_f32_16x16x32_bf16 v[72:75], v[192:195], v[148:151], v[72:75]
	v_mfma_f32_16x16x32_bf16 v[44:47], v[200:203], v[148:151], v[44:47]
	v_mfma_f32_16x16x32_bf16 v[64:67], v[192:195], v[156:159], v[64:67]
	v_mfma_f32_16x16x32_bf16 v[40:43], v[200:203], v[156:159], v[40:43]
	v_mfma_f32_16x16x32_bf16 v[56:59], v[192:195], v[176:179], v[56:59]
	v_mfma_f32_16x16x32_bf16 v[36:39], v[200:203], v[176:179], v[36:39]
	v_mfma_f32_16x16x32_bf16 v[48:51], v[192:195], v[184:187], v[48:51]
	v_mfma_f32_16x16x32_bf16 v[28:31], v[200:203], v[184:187], v[28:31]
	s_mov_b32 m0, s41
	v_lshl_add_u64 v[204:205], v[208:209], 0, s[18:19]
	s_barrier
	ds_read_b128 v[144:147], v222 offset:49152
	ds_read_b128 v[148:151], v222 offset:50176
	ds_read_b128 v[152:155], v222 offset:51200
	ds_read_b128 v[156:159], v222 offset:52224
	ds_read_b128 v[160:163], v222 offset:53248
	ds_read_b128 v[176:179], v222 offset:54272
	ds_read_b128 v[180:183], v222 offset:55296
	ds_read_b128 v[184:187], v222 offset:56320
	global_load_lds_dwordx4 v[204:205], off
	v_lshl_add_u64 v[204:205], v[210:211], 0, s[18:19]
	s_mov_b32 m0, s50
	s_nop 0
	global_load_lds_dwordx4 v[204:205], off
	s_barrier
	s_waitcnt lgkmcnt(0)
	s_waitcnt lgkmcnt(0)
	v_mfma_f32_16x16x32_bf16 v[108:111], v[128:131], v[144:147], v[108:111]
	v_mfma_f32_16x16x32_bf16 v[76:79], v[136:139], v[144:147], v[76:79]
	v_mfma_f32_16x16x32_bf16 v[104:107], v[128:131], v[152:155], v[104:107]
	v_mfma_f32_16x16x32_bf16 v[68:71], v[136:139], v[152:155], v[68:71]
	v_mfma_f32_16x16x32_bf16 v[88:91], v[128:131], v[160:163], v[88:91]
	v_mfma_f32_16x16x32_bf16 v[60:63], v[136:139], v[160:163], v[60:63]
	v_mfma_f32_16x16x32_bf16 v[80:83], v[128:131], v[180:183], v[80:83]
	v_mfma_f32_16x16x32_bf16 v[52:55], v[136:139], v[180:183], v[52:55]
	v_mfma_f32_16x16x32_bf16 v[108:111], v[132:135], v[148:151], v[108:111]
	v_mfma_f32_16x16x32_bf16 v[76:79], v[140:143], v[148:151], v[76:79]
	v_mfma_f32_16x16x32_bf16 v[104:107], v[132:135], v[156:159], v[104:107]
	v_mfma_f32_16x16x32_bf16 v[68:71], v[140:143], v[156:159], v[68:71]
	v_mfma_f32_16x16x32_bf16 v[88:91], v[132:135], v[176:179], v[88:91]
	v_mfma_f32_16x16x32_bf16 v[60:63], v[140:143], v[176:179], v[60:63]
	v_mfma_f32_16x16x32_bf16 v[80:83], v[132:135], v[184:187], v[80:83]
	v_mfma_f32_16x16x32_bf16 v[52:55], v[140:143], v[184:187], v[52:55]
	s_barrier
	s_add_u32 s4, s46, 0x160080
	s_addc_u32 s5, s47, 0
	s_add_i32 s42, s43, s24
	v_lshl_add_u64 v[128:129], s[4:5], 0, v[166:167]
	s_mov_b32 m0, s42
	s_nop 0
	global_load_lds_dwordx4 v[128:129], off
	v_lshl_add_u64 v[128:129], s[4:5], 0, v[164:165]
	s_add_i32 m0, s42, 0x2000
	s_nop 0
	global_load_lds_dwordx4 v[128:129], off
	s_waitcnt vmcnt(6)
	s_barrier
	v_mfma_f32_16x16x32_bf16 v[32:35], v[188:191], v[144:147], v[32:35]
	v_mfma_f32_16x16x32_bf16 v[12:15], v[196:199], v[144:147], v[12:15]
	v_mfma_f32_16x16x32_bf16 v[24:27], v[188:191], v[152:155], v[24:27]
	v_mfma_f32_16x16x32_bf16 v[8:11], v[196:199], v[152:155], v[8:11]
	v_mfma_f32_16x16x32_bf16 v[20:23], v[188:191], v[160:163], v[20:23]
	v_mfma_f32_16x16x32_bf16 v[4:7], v[196:199], v[160:163], v[4:7]
	v_mfma_f32_16x16x32_bf16 v[16:19], v[188:191], v[180:183], v[16:19]
	v_mfma_f32_16x16x32_bf16 v[0:3], v[196:199], v[180:183], v[0:3]
	v_mfma_f32_16x16x32_bf16 v[32:35], v[192:195], v[148:151], v[32:35]
	v_mfma_f32_16x16x32_bf16 v[12:15], v[200:203], v[148:151], v[12:15]
	v_mfma_f32_16x16x32_bf16 v[24:27], v[192:195], v[156:159], v[24:27]
	v_mfma_f32_16x16x32_bf16 v[8:11], v[200:203], v[156:159], v[8:11]
	v_mfma_f32_16x16x32_bf16 v[20:23], v[192:195], v[176:179], v[20:23]
	v_mfma_f32_16x16x32_bf16 v[4:7], v[200:203], v[176:179], v[4:7]
	v_mfma_f32_16x16x32_bf16 v[16:19], v[192:195], v[184:187], v[16:19]
	v_mfma_f32_16x16x32_bf16 v[0:3], v[200:203], v[184:187], v[0:3]
	s_add_i32 s61, s61, 2
	s_add_u32 s0, s0, 0x100
	s_addc_u32 s1, s1, 0
	s_cmpk_gt_u32 s61, 0x55
	s_mov_b64 s[42:43], s[44:45]
	s_barrier
	s_cbranch_scc0 .LBB0_1749
	v_lshl_add_u32 v144, s59, 8, v218
	v_lshl_or_b32 v184, s60, 8, v220
	v_ashrrev_i32_e32 v145, 31, v144
	v_ashrrev_i32_e32 v185, 31, v184
	v_lshlrev_b64 v[132:133], 13, v[144:145]
	v_lshlrev_b64 v[146:147], 2, v[184:185]
	v_lshl_add_u64 v[132:133], s[12:13], 0, v[132:133]
	v_lshl_add_u64 v[176:177], v[132:133], 0, v[146:147]
	v_or_b32_e32 v136, 16, v144
	v_add_co_u32_e32 v186, vcc, s53, v176
	v_ashrrev_i32_e32 v137, 31, v136
	v_or_b32_e32 v140, 32, v144
	v_or_b32_e32 v144, 48, v144
	v_addc_co_u32_e32 v187, vcc, 0, v177, vcc
	v_lshlrev_b64 v[136:137], 13, v[136:137]
	v_ashrrev_i32_e32 v141, 31, v140
	v_ashrrev_i32_e32 v145, 31, v144
	v_add_co_u32_e32 v190, vcc, s54, v176
	v_lshl_add_u64 v[128:129], s[16:17], 0, v[146:147]
	v_lshl_add_u64 v[136:137], s[12:13], 0, v[136:137]
	v_lshlrev_b64 v[140:141], 13, v[140:141]
	v_lshlrev_b64 v[144:145], 13, v[144:145]
	v_addc_co_u32_e32 v191, vcc, 0, v177, vcc
	global_load_dwordx4 v[128:131], v[128:129], off
	v_lshl_add_u64 v[178:179], v[136:137], 0, v[146:147]
	global_load_dwordx4 v[132:135], v[176:177], off
	global_load_dwordx4 v[136:139], v[178:179], off
	v_lshl_add_u64 v[140:141], s[12:13], 0, v[140:141]
	v_lshl_add_u64 v[144:145], s[12:13], 0, v[144:145]
	v_add_co_u32_e32 v192, vcc, s55, v176
	v_lshl_add_u64 v[180:181], v[140:141], 0, v[146:147]
	v_lshl_add_u64 v[182:183], v[144:145], 0, v[146:147]
	v_addc_co_u32_e32 v193, vcc, 0, v177, vcc
	global_load_dwordx4 v[140:143], v[180:181], off
	global_load_dwordx4 v[144:147], v[182:183], off
	global_load_dwordx4 v[148:151], v[186:187], off
	global_load_dwordx4 v[160:163], v[190:191], off
	global_load_dwordx4 v[156:159], v[192:193], off
	v_add_co_u32_e32 v188, vcc, s56, v176
	v_pk_add_f32 v[212:213], v[126:127], 0 op_sel_hi:[1,0]
	s_nop 0
	v_addc_co_u32_e32 v189, vcc, 0, v177, vcc
	global_load_dwordx4 v[152:155], v[188:189], off
	v_pk_add_f32 v[214:215], v[124:125], 0 op_sel_hi:[1,0]
	v_pk_add_f32 v[126:127], v[122:123], 0 op_sel_hi:[1,0]
	v_pk_add_f32 v[194:195], v[120:121], 0 op_sel_hi:[1,0]
	v_pk_add_f32 v[196:197], v[118:119], 0 op_sel_hi:[1,0]
	v_pk_add_f32 v[198:199], v[116:117], 0 op_sel_hi:[1,0]
	v_pk_add_f32 v[200:201], v[114:115], 0 op_sel_hi:[1,0]
	v_pk_add_f32 v[202:203], v[112:113], 0 op_sel_hi:[1,0]
	v_pk_add_f32 v[204:205], v[110:111], 0 op_sel_hi:[1,0]
	v_pk_add_f32 v[206:207], v[108:109], 0 op_sel_hi:[1,0]
	v_pk_add_f32 v[208:209], v[106:107], 0 op_sel_hi:[1,0]
	v_pk_add_f32 v[210:211], v[104:105], 0 op_sel_hi:[1,0]
	v_lshl_add_u64 v[120:121], v[176:177], 0, s[20:21]
	v_lshl_add_u64 v[122:123], v[176:177], 0, s[36:37]
	global_load_dwordx4 v[104:107], v[176:177], off offset:64
	global_load_dwordx4 v[108:111], v[178:179], off offset:64
	global_load_dwordx4 v[112:115], v[180:181], off offset:64
	global_load_dwordx4 v[116:119], v[182:183], off offset:64
	global_load_dwordx4 v[224:227], v[120:121], off offset:576
	global_load_dwordx4 v[228:231], v[122:123], off offset:576
	v_lshl_add_u64 v[124:125], v[176:177], 0, s[38:39]
	v_pk_add_f32 v[102:103], v[102:103], 0 op_sel_hi:[1,0]
	v_pk_add_f32 v[100:101], v[100:101], 0 op_sel_hi:[1,0]
	v_pk_add_f32 v[98:99], v[98:99], 0 op_sel_hi:[1,0]
	v_pk_add_f32 v[96:97], v[96:97], 0 op_sel_hi:[1,0]
	v_pk_add_f32 v[74:75], v[74:75], 0 op_sel_hi:[1,0]
	v_pk_add_f32 v[72:73], v[72:73], 0 op_sel_hi:[1,0]
	v_pk_add_f32 v[66:67], v[66:67], 0 op_sel_hi:[1,0]
	v_pk_add_f32 v[64:65], v[64:65], 0 op_sel_hi:[1,0]
	v_pk_add_f32 v[58:59], v[58:59], 0 op_sel_hi:[1,0]
	v_pk_add_f32 v[56:57], v[56:57], 0 op_sel_hi:[1,0]
	v_pk_add_f32 v[46:47], v[46:47], 0 op_sel_hi:[1,0]
	v_pk_add_f32 v[44:45], v[44:45], 0 op_sel_hi:[1,0]
	v_pk_add_f32 v[42:43], v[42:43], 0 op_sel_hi:[1,0]
	v_pk_add_f32 v[40:41], v[40:41], 0 op_sel_hi:[1,0]
	v_pk_add_f32 v[38:39], v[38:39], 0 op_sel_hi:[1,0]
	v_pk_add_f32 v[36:37], v[36:37], 0 op_sel_hi:[1,0]
	v_pk_add_f32 v[30:31], v[30:31], 0 op_sel_hi:[1,0]
	v_pk_add_f32 v[28:29], v[28:29], 0 op_sel_hi:[1,0]
	s_and_b64 vcc, exec, s[6:7]
	s_mov_b32 s60, s57
	s_mov_b32 s59, s58
	s_mov_b64 s[44:45], s[10:11]
	s_mov_b64 s[42:43], s[8:9]
	s_waitcnt vmcnt(0)
	v_pk_fma_f32 v[134:135], v[212:213], v[130:131], v[134:135]
	v_pk_fma_f32 v[132:133], v[214:215], v[128:129], v[132:133]
	global_store_dwordx4 v[176:177], v[132:135], off
	s_nop 1
	v_pk_fma_f32 v[134:135], v[126:127], v[130:131], v[138:139]
	v_pk_fma_f32 v[132:133], v[194:195], v[128:129], v[136:137]
	v_pk_add_f32 v[126:127], v[90:91], 0 op_sel_hi:[1,0]
	v_pk_fma_f32 v[138:139], v[196:197], v[130:131], v[142:143]
	v_pk_fma_f32 v[136:137], v[198:199], v[128:129], v[140:141]
	v_pk_fma_f32 v[142:143], v[200:201], v[130:131], v[146:147]
	v_pk_fma_f32 v[140:141], v[202:203], v[128:129], v[144:145]
	v_pk_fma_f32 v[146:147], v[204:205], v[130:131], v[150:151]
	v_pk_fma_f32 v[144:145], v[206:207], v[128:129], v[148:149]
	v_pk_fma_f32 v[150:151], v[208:209], v[130:131], v[162:163]
	v_pk_fma_f32 v[148:149], v[210:211], v[128:129], v[160:161]
	global_store_dwordx4 v[178:179], v[132:135], off
	global_store_dwordx4 v[180:181], v[136:139], off
	global_store_dwordx4 v[182:183], v[140:143], off
	global_store_dwordx4 v[186:187], v[144:147], off
	global_store_dwordx4 v[190:191], v[148:151], off
	v_pk_add_f32 v[132:133], v[88:89], 0 op_sel_hi:[1,0]
	v_pk_fma_f32 v[134:135], v[126:127], v[130:131], v[158:159]
	v_pk_fma_f32 v[132:133], v[132:133], v[128:129], v[156:157]
	v_pk_add_f32 v[126:127], v[82:83], 0 op_sel_hi:[1,0]
	global_store_dwordx4 v[192:193], v[132:135], off
	v_pk_fma_f32 v[130:131], v[126:127], v[130:131], v[154:155]
	v_or_b32_e32 v126, 16, v184
	v_pk_add_f32 v[132:133], v[80:81], 0 op_sel_hi:[1,0]
	v_ashrrev_i32_e32 v127, 31, v126
	v_pk_fma_f32 v[128:129], v[132:133], v[128:129], v[152:153]
	v_lshl_add_u64 v[146:147], v[176:177], 0, s[14:15]
	global_store_dwordx4 v[188:189], v[128:131], off
	v_lshl_add_u64 v[126:127], v[126:127], 2, s[16:17]
	global_load_dwordx4 v[88:91], v[124:125], off offset:576
	global_load_dwordx4 v[80:83], v[146:147], off offset:576
	s_nop 0
	global_load_dwordx4 v[126:129], v[126:127], off
	s_nop 0
	global_load_dwordx4 v[130:133], v[120:121], off offset:64
	global_load_dwordx4 v[134:137], v[122:123], off offset:64
	global_load_dwordx4 v[138:141], v[124:125], off offset:64
	global_load_dwordx4 v[142:145], v[146:147], off offset:64
	v_pk_add_f32 v[192:193], v[52:53], 0 op_sel_hi:[1,0]
	v_or_b32_e32 v52, 0x80, v184
	v_pk_add_f32 v[148:149], v[94:95], 0 op_sel_hi:[1,0]
	v_pk_add_f32 v[150:151], v[92:93], 0 op_sel_hi:[1,0]
	v_pk_add_f32 v[152:153], v[86:87], 0 op_sel_hi:[1,0]
	v_pk_add_f32 v[154:155], v[84:85], 0 op_sel_hi:[1,0]
	v_pk_add_f32 v[156:157], v[78:79], 0 op_sel_hi:[1,0]
	v_pk_add_f32 v[158:159], v[76:77], 0 op_sel_hi:[1,0]
	v_pk_add_f32 v[160:161], v[70:71], 0 op_sel_hi:[1,0]
	v_pk_add_f32 v[162:163], v[68:69], 0 op_sel_hi:[1,0]
	v_pk_add_f32 v[186:187], v[62:63], 0 op_sel_hi:[1,0]
	v_pk_add_f32 v[188:189], v[60:61], 0 op_sel_hi:[1,0]
	v_pk_add_f32 v[190:191], v[54:55], 0 op_sel_hi:[1,0]
	v_ashrrev_i32_e32 v53, 31, v52
	v_lshl_add_u64 v[194:195], v[52:53], 2, s[16:17]
	global_load_dwordx4 v[52:55], v[176:177], off offset:512
	global_load_dwordx4 v[60:63], v[120:121], off offset:512
	global_load_dwordx4 v[68:71], v[122:123], off offset:512
	global_load_dwordx4 v[76:79], v[124:125], off offset:512
	global_load_dwordx4 v[84:87], v[146:147], off offset:512
	s_waitcnt vmcnt(0)
	v_pk_fma_f32 v[94:95], v[102:103], v[128:129], v[106:107]
	v_pk_fma_f32 v[92:93], v[100:101], v[126:127], v[104:105]
	v_pk_fma_f32 v[98:99], v[98:99], v[128:129], v[110:111]
	v_pk_fma_f32 v[96:97], v[96:97], v[126:127], v[108:109]
	v_pk_fma_f32 v[102:103], v[148:149], v[128:129], v[114:115]
	v_pk_fma_f32 v[100:101], v[150:151], v[126:127], v[112:113]
	v_pk_fma_f32 v[106:107], v[152:153], v[128:129], v[118:119]
	v_pk_fma_f32 v[104:105], v[154:155], v[126:127], v[116:117]
	v_pk_fma_f32 v[110:111], v[156:157], v[128:129], v[132:133]
	v_pk_fma_f32 v[108:109], v[158:159], v[126:127], v[130:131]
	v_pk_fma_f32 v[114:115], v[160:161], v[128:129], v[136:137]
	v_pk_fma_f32 v[112:113], v[162:163], v[126:127], v[134:135]
	v_pk_fma_f32 v[118:119], v[186:187], v[128:129], v[140:141]
	v_pk_fma_f32 v[116:117], v[188:189], v[126:127], v[138:139]
	v_pk_fma_f32 v[128:129], v[190:191], v[128:129], v[144:145]
	v_pk_fma_f32 v[126:127], v[192:193], v[126:127], v[142:143]
	global_store_dwordx4 v[176:177], v[92:95], off offset:64
	global_store_dwordx4 v[178:179], v[96:99], off offset:64
	global_store_dwordx4 v[180:181], v[100:103], off offset:64
	global_store_dwordx4 v[182:183], v[104:107], off offset:64
	global_store_dwordx4 v[120:121], v[108:111], off offset:64
	global_store_dwordx4 v[122:123], v[112:115], off offset:64
	global_store_dwordx4 v[124:125], v[116:119], off offset:64
	global_store_dwordx4 v[146:147], v[126:129], off offset:64
	global_load_dwordx4 v[92:95], v[194:195], off
	global_load_dwordx4 v[96:99], v[178:179], off offset:512
	global_load_dwordx4 v[100:103], v[180:181], off offset:512
	global_load_dwordx4 v[104:107], v[182:183], off offset:512
	v_pk_add_f32 v[132:133], v[16:17], 0 op_sel_hi:[1,0]
	v_or_b32_e32 v16, 0x90, v184
	v_pk_add_f32 v[108:109], v[50:51], 0 op_sel_hi:[1,0]
	v_pk_add_f32 v[110:111], v[48:49], 0 op_sel_hi:[1,0]
	v_pk_add_f32 v[112:113], v[34:35], 0 op_sel_hi:[1,0]
	v_pk_add_f32 v[114:115], v[32:33], 0 op_sel_hi:[1,0]
	v_pk_add_f32 v[116:117], v[26:27], 0 op_sel_hi:[1,0]
	v_pk_add_f32 v[118:119], v[24:25], 0 op_sel_hi:[1,0]
	v_pk_add_f32 v[126:127], v[22:23], 0 op_sel_hi:[1,0]
	v_pk_add_f32 v[128:129], v[20:21], 0 op_sel_hi:[1,0]
	v_pk_add_f32 v[130:131], v[18:19], 0 op_sel_hi:[1,0]
	v_ashrrev_i32_e32 v17, 31, v16
	v_lshl_add_u64 v[134:135], v[16:17], 2, s[16:17]
	global_load_dwordx4 v[16:19], v[176:177], off offset:576
	global_load_dwordx4 v[20:23], v[178:179], off offset:576
	global_load_dwordx4 v[24:27], v[180:181], off offset:576
	global_load_dwordx4 v[32:35], v[182:183], off offset:576
	s_waitcnt vmcnt(0)
	v_pk_fma_f32 v[50:51], v[74:75], v[94:95], v[54:55]
	v_pk_fma_f32 v[48:49], v[72:73], v[92:93], v[52:53]
	v_pk_fma_f32 v[54:55], v[66:67], v[94:95], v[98:99]
	v_pk_fma_f32 v[52:53], v[64:65], v[92:93], v[96:97]
	v_pk_fma_f32 v[58:59], v[58:59], v[94:95], v[102:103]
	v_pk_fma_f32 v[56:57], v[56:57], v[92:93], v[100:101]
	v_pk_fma_f32 v[66:67], v[108:109], v[94:95], v[106:107]
	v_pk_fma_f32 v[64:65], v[110:111], v[92:93], v[104:105]
	v_pk_fma_f32 v[62:63], v[112:113], v[94:95], v[62:63]
	v_pk_fma_f32 v[60:61], v[114:115], v[92:93], v[60:61]
	v_pk_fma_f32 v[70:71], v[116:117], v[94:95], v[70:71]
	v_pk_fma_f32 v[68:69], v[118:119], v[92:93], v[68:69]
	v_pk_fma_f32 v[74:75], v[126:127], v[94:95], v[78:79]
	v_pk_fma_f32 v[72:73], v[128:129], v[92:93], v[76:77]
	v_pk_fma_f32 v[78:79], v[130:131], v[94:95], v[86:87]
	v_pk_fma_f32 v[76:77], v[132:133], v[92:93], v[84:85]
	global_store_dwordx4 v[176:177], v[48:51], off offset:512
	global_store_dwordx4 v[178:179], v[52:55], off offset:512
	global_store_dwordx4 v[180:181], v[56:59], off offset:512
	global_store_dwordx4 v[182:183], v[64:67], off offset:512
	global_store_dwordx4 v[120:121], v[60:63], off offset:512
	global_store_dwordx4 v[122:123], v[68:71], off offset:512
	global_store_dwordx4 v[124:125], v[72:75], off offset:512
	global_store_dwordx4 v[146:147], v[76:79], off offset:512
	global_load_dwordx4 v[48:51], v[134:135], off
	v_pk_add_f32 v[52:53], v[14:15], 0 op_sel_hi:[1,0]
	v_pk_add_f32 v[54:55], v[12:13], 0 op_sel_hi:[1,0]
	v_pk_add_f32 v[56:57], v[10:11], 0 op_sel_hi:[1,0]
	v_pk_add_f32 v[58:59], v[8:9], 0 op_sel_hi:[1,0]
	v_pk_add_f32 v[60:61], v[6:7], 0 op_sel_hi:[1,0]
	v_pk_add_f32 v[62:63], v[4:5], 0 op_sel_hi:[1,0]
	v_pk_add_f32 v[64:65], v[2:3], 0 op_sel_hi:[1,0]
	v_pk_add_f32 v[66:67], v[0:1], 0 op_sel_hi:[1,0]
	s_waitcnt vmcnt(0)
	v_pk_fma_f32 v[2:3], v[46:47], v[50:51], v[18:19]
	v_pk_fma_f32 v[0:1], v[44:45], v[48:49], v[16:17]
	v_pk_fma_f32 v[6:7], v[42:43], v[50:51], v[22:23]
	v_pk_fma_f32 v[4:5], v[40:41], v[48:49], v[20:21]
	v_pk_fma_f32 v[10:11], v[38:39], v[50:51], v[26:27]
	v_pk_fma_f32 v[8:9], v[36:37], v[48:49], v[24:25]
	v_pk_fma_f32 v[14:15], v[30:31], v[50:51], v[34:35]
	v_pk_fma_f32 v[12:13], v[28:29], v[48:49], v[32:33]
	v_pk_fma_f32 v[18:19], v[52:53], v[50:51], v[226:227]
	v_pk_fma_f32 v[16:17], v[54:55], v[48:49], v[224:225]
	v_pk_fma_f32 v[22:23], v[56:57], v[50:51], v[230:231]
	v_pk_fma_f32 v[20:21], v[58:59], v[48:49], v[228:229]
	v_pk_fma_f32 v[26:27], v[60:61], v[50:51], v[90:91]
	v_pk_fma_f32 v[24:25], v[62:63], v[48:49], v[88:89]
	v_pk_fma_f32 v[30:31], v[64:65], v[50:51], v[82:83]
	v_pk_fma_f32 v[28:29], v[66:67], v[48:49], v[80:81]
	global_store_dwordx4 v[176:177], v[0:3], off offset:576
	global_store_dwordx4 v[178:179], v[4:7], off offset:576
	global_store_dwordx4 v[180:181], v[8:11], off offset:576
	global_store_dwordx4 v[182:183], v[12:15], off offset:576
	global_store_dwordx4 v[120:121], v[16:19], off offset:576
	global_store_dwordx4 v[122:123], v[20:23], off offset:576
	global_store_dwordx4 v[124:125], v[24:27], off offset:576
	global_store_dwordx4 v[146:147], v[28:31], off offset:576
	s_cbranch_vccz .LBB0_1738
	s_waitcnt vmcnt(0)
	s_cmpk_gt_u32 s23, 0xff
	s_cbranch_scc1 .LBB0_1753
	s_barrier

.LBB0_1754:
	s_waitcnt vmcnt(0)
	v_readlane_b32 s2, v255, 4
	v_readlane_b32 s3, v255, 5
	s_waitcnt lgkmcnt(0)
	s_setprio 0
	s_barrier
	s_and_saveexec_b64 s[0:1], s[2:3]
	s_xor_b64 s[2:3], exec, s[0:1]
	s_cbranch_execz .LBB0_1807
	s_add_i32 s0, 0, 0x25800
	v_mov_b32_e32 v0, s0
	s_waitcnt vmcnt(0) expcnt(0) lgkmcnt(0)
	ds_read_b32 v2, v0
	s_add_i32 s0, 0, 0x25804
	v_mov_b32_e32 v0, s0
	ds_read_b32 v0, v0
	s_waitcnt lgkmcnt(1)
	v_cmp_ne_u32_e32 vcc, 0, v2
	s_cbranch_vccnz .LBB0_1770
	s_add_u32 s4, s26, 0xc0200
	v_readlane_b32 s0, v255, 0
	s_addc_u32 s5, s27, 0
	s_mul_i32 s23, s31, s0
	s_add_u32 s0, s26, 0xc0400
	s_addc_u32 s1, s27, 0
	s_add_u32 s6, s26, 0xc0500
	s_addc_u32 s7, s27, 0
	s_add_u32 s8, s26, 0xc0600
	s_addc_u32 s9, s27, 0
	s_add_u32 s10, s26, 0xc0700
	s_addc_u32 s11, s27, 0
	s_add_u32 s12, s26, 0xc0800
	s_addc_u32 s13, s27, 0
	s_add_u32 s14, s26, 0xc0900
	s_addc_u32 s15, s27, 0
	s_add_u32 s16, s26, 0xc0a00
	s_addc_u32 s17, s27, 0
	s_add_u32 s18, s26, 0xc0b00
	s_addc_u32 s19, s27, 0
	s_add_u32 s20, s26, 0xc0c00
	s_addc_u32 s21, s27, 0
	s_mul_i32 s23, s23, s30
	s_add_u32 s30, s26, 0xc0d00
	s_addc_u32 s31, s27, 0
	s_add_u32 s34, s26, 0xc0e00
	s_addc_u32 s35, s27, 0
	s_add_u32 s36, s26, 0xc0f00
	s_addc_u32 s37, s27, 0
	s_add_u32 s38, s26, 0xc1000
	s_addc_u32 s39, s27, 0
	s_add_u32 s40, s26, 0xc1100
	s_addc_u32 s41, s27, 0
	s_add_u32 s42, s26, 0xc1200
	s_addc_u32 s43, s27, 0
	s_add_u32 s44, s26, 0xc1300
	s_addc_u32 s45, s27, 0
	s_mov_b32 s24, 1
	v_mov_b32_e32 v16, 0
	s_branch .LBB0_1758
